# hand-written token-shift tile: 18 row loads up front, constant counted vmcnt, single per-lane store pointer/stride, wave-uniform fast path without activations
# baseline (speedup 1.0000x reference)
; #define PG8_STAGE(bufoff, gbase, voff) do { _Pragma("unroll") for (int _i = 0; _i < 2; ++_i) \
;         __builtin_amdgcn_global_load_lds((const unsigned*)((const char*)(gbase) + (voff)[_i]), (PG8_LAS unsigned*)(lds + (bufoff) + ldsw + _i * 8192), 16, 0, 0); } while (0)
; #define PG8_LDA(dst, b, h) do { _Pragma("unroll") for (int m = 0; m < 4; ++m) _Pragma("unroll") for (int k = 0; k < 2; ++k) dst[m][k] = *(const PG8_LAS bf16x8*)(lds + PG8_SA(b, h) + aoff + m * 2048 + k * 1024); } while (0)
; #define PG8_LDB(dst, b, h) do { _Pragma("unroll") for (int n = 0; n < 2; ++n) _Pragma("unroll") for (int k = 0; k < 2; ++k) dst[n][k] = *(const PG8_LAS bf16x8*)(lds + PG8_SB(b, h) + boff + n * 2048 + k * 1024); } while (0)
; #define PG8_MMA(ai, bj, At, Bt) do { __builtin_amdgcn_s_setprio(1); _Pragma("unroll") for (int m = 0; m < 4; ++m) _Pragma("unroll") for (int n = 0; n < 2; ++n) _Pragma("unroll") for (int k = 0; k < 2; ++k) \
;         acc[ai][bj][m][n] = __builtin_amdgcn_mfma_f32_16x16x32_bf16(Bt[n][k], At[m][k], acc[ai][bj][m][n], 0, 0, 0); __builtin_amdgcn_s_setprio(0); } while (0)
; #define PG8_WAIT_L(n) asm volatile("s_waitcnt lgkmcnt(" #n ")" ::: "memory")
; #define PG8_BAR __builtin_amdgcn_s_barrier()
; #define PG8_SCHED __builtin_amdgcn_sched_barrier(0)
; template <class Epi, class Sched>
; __device__ __forceinline__ void gemm_phase(PG8_LAS unsigned char* lds, const Gemm g, const Sched& S, const Epi& E) {
;     ...
;             PG8_LDB(B0, 0, 0); PG8_SCHED; PG8_LDA(At, 0, 0); PG8_STAGE(PG8_SA(1, 1), a1 + hstep, voffA);
;             PG8_WAIT_L(8); PG8_BAR; PG8_WAIT_L(0); PG8_MMA(0, 0, At, B0); PG8_BAR; PG8_SCHED;
;             PG8_LDB(B1, 0, 1); PG8_STAGE(PG8_SB(0, 0), b2, voffB);
;             PG8_BAR; PG8_WAIT_L(0); PG8_MMA(0, 1, At, B1); PG8_BAR;
;             PG8_LDA(At, 0, 1); PG8_STAGE(PG8_SA(0, 0), a2, voffA);
;             PG8_BAR; PG8_WAIT_L(0); PG8_MMA(1, 0, At, B0); PG8_BAR; PG8_SCHED;
.Lgp_1873:
.LBB0_47:
	s_add_u32 s52, s50, 0x100
	s_addc_u32 s53, s51, 0
	s_add_i32 s42, 0, 0x10000
	v_add_u32_e32 v134, s42, v225
	ds_read_b128 v[118:121], v134
	ds_read_b128 v[126:129], v134 offset:1024
	ds_read_b128 v[130:133], v134 offset:2048
	ds_read_b128 v[134:137], v134 offset:3072
	s_cmp_eq_u32 s94, 60
	s_cselect_b32 s1, s41, s53
	s_cselect_b32 s0, s68, s52
	s_cselect_b32 vcc_hi, s39, s71
	s_cselect_b32 vcc_lo, s69, s70
	v_lshl_add_u64 v[178:179], s[50:51], 0, v[210:211]
	s_add_i32 m0, s49, 0xc000
	ds_read_b128 v[146:149], v240
	ds_read_b128 v[150:153], v240 offset:1024
	ds_read_b128 v[154:157], v240 offset:2048
	ds_read_b128 v[158:161], v240 offset:3072
	ds_read_b128 v[162:165], v240 offset:4096
	ds_read_b128 v[166:169], v240 offset:5120
	ds_read_b128 v[170:173], v240 offset:6144
	ds_read_b128 v[174:177], v240 offset:7168
	global_load_lds_dwordx4 v[178:179], off
	v_lshl_add_u64 v[178:179], s[50:51], 0, v[212:213]
	s_add_i32 m0, s49, 0xe000
	s_nop 0
	global_load_lds_dwordx4 v[178:179], off
	s_waitcnt lgkmcnt(8)
	s_barrier
	s_waitcnt lgkmcnt(0)
	v_mfma_f32_16x16x32_bf16 v[142:145], v[118:121], v[146:149], v[142:145]
	v_mfma_f32_16x16x32_bf16 v[138:141], v[130:133], v[146:149], v[138:141]
	v_mfma_f32_16x16x32_bf16 v[114:117], v[118:121], v[154:157], v[114:117]
	v_mfma_f32_16x16x32_bf16 v[106:109], v[130:133], v[154:157], v[106:109]
	v_mfma_f32_16x16x32_bf16 v[102:105], v[118:121], v[162:165], v[102:105]
	v_mfma_f32_16x16x32_bf16 v[92:95], v[130:133], v[162:165], v[92:95]
	v_mfma_f32_16x16x32_bf16 v[84:87], v[118:121], v[170:173], v[84:87]
	v_mfma_f32_16x16x32_bf16 v[76:79], v[130:133], v[170:173], v[76:79]
	v_mfma_f32_16x16x32_bf16 v[142:145], v[126:129], v[150:153], v[142:145]
	v_mfma_f32_16x16x32_bf16 v[138:141], v[134:137], v[150:153], v[138:141]
	v_mfma_f32_16x16x32_bf16 v[114:117], v[126:129], v[158:161], v[114:117]
	v_mfma_f32_16x16x32_bf16 v[106:109], v[134:137], v[158:161], v[106:109]
	v_mfma_f32_16x16x32_bf16 v[102:105], v[126:129], v[166:169], v[102:105]
	v_mfma_f32_16x16x32_bf16 v[92:95], v[134:137], v[166:169], v[92:95]
	v_mfma_f32_16x16x32_bf16 v[84:87], v[126:129], v[174:177], v[84:87]
	v_mfma_f32_16x16x32_bf16 v[76:79], v[134:137], v[174:177], v[76:79]
	s_barrier
	s_add_i32 s43, 0, 0x14000
	s_add_i32 s42, s42, s58
	v_add_u32_e32 v190, s43, v225
	v_lshl_add_u64 v[194:195], vcc, 0, v[96:97]
	s_mov_b32 m0, s42
	ds_read_b128 v[178:181], v190
	ds_read_b128 v[182:185], v190 offset:1024
	ds_read_b128 v[186:189], v190 offset:2048
	ds_read_b128 v[190:193], v190 offset:3072
	global_load_lds_dwordx4 v[194:195], off
	v_lshl_add_u64 v[196:197], vcc, 0, v[208:209]
	s_add_i32 m0, s42, 0x2000
	s_nop 0
	global_load_lds_dwordx4 v[196:197], off
	s_barrier
	s_waitcnt lgkmcnt(0)
	v_mfma_f32_16x16x32_bf16 v[122:125], v[178:181], v[146:149], v[122:125]
	v_mfma_f32_16x16x32_bf16 v[110:113], v[186:189], v[146:149], v[110:113]
	v_mfma_f32_16x16x32_bf16 v[98:101], v[178:181], v[154:157], v[98:101]
	v_mfma_f32_16x16x32_bf16 v[88:91], v[186:189], v[154:157], v[88:91]
	v_mfma_f32_16x16x32_bf16 v[80:83], v[178:181], v[162:165], v[80:83]
	v_mfma_f32_16x16x32_bf16 v[72:75], v[186:189], v[162:165], v[72:75]
	v_mfma_f32_16x16x32_bf16 v[68:71], v[178:181], v[170:173], v[68:71]
	v_mfma_f32_16x16x32_bf16 v[64:67], v[186:189], v[170:173], v[64:67]
	v_mfma_f32_16x16x32_bf16 v[122:125], v[182:185], v[150:153], v[122:125]
	v_mfma_f32_16x16x32_bf16 v[110:113], v[190:193], v[150:153], v[110:113]
	v_mfma_f32_16x16x32_bf16 v[98:101], v[182:185], v[158:161], v[98:101]
	v_mfma_f32_16x16x32_bf16 v[88:91], v[190:193], v[158:161], v[88:91]
	v_mfma_f32_16x16x32_bf16 v[80:83], v[182:185], v[166:169], v[80:83]
	v_mfma_f32_16x16x32_bf16 v[72:75], v[190:193], v[166:169], v[72:75]
	v_mfma_f32_16x16x32_bf16 v[68:71], v[182:185], v[174:177], v[68:71]
	v_mfma_f32_16x16x32_bf16 v[64:67], v[190:193], v[174:177], v[64:67]
	s_mov_b32 m0, s49
	v_lshl_add_u64 v[198:199], s[0:1], 0, v[96:97]
	s_barrier
	ds_read_b128 v[146:149], v240 offset:16384
	ds_read_b128 v[150:153], v240 offset:17408
	ds_read_b128 v[154:157], v240 offset:18432
	ds_read_b128 v[158:161], v240 offset:19456
	ds_read_b128 v[162:165], v240 offset:20480
	ds_read_b128 v[166:169], v240 offset:21504
	ds_read_b128 v[170:173], v240 offset:22528
	ds_read_b128 v[174:177], v240 offset:23552
	global_load_lds_dwordx4 v[198:199], off
	v_lshl_add_u64 v[200:201], s[0:1], 0, v[208:209]
	s_mov_b32 m0, s61
	s_nop 0
	global_load_lds_dwordx4 v[200:201], off
	s_barrier
	s_waitcnt lgkmcnt(0)
	v_mfma_f32_16x16x32_bf16 v[60:63], v[118:121], v[146:149], v[60:63]
	v_mfma_f32_16x16x32_bf16 v[56:59], v[130:133], v[146:149], v[56:59]
	v_mfma_f32_16x16x32_bf16 v[52:55], v[118:121], v[154:157], v[52:55]
	v_mfma_f32_16x16x32_bf16 v[44:47], v[130:133], v[154:157], v[44:47]
	v_mfma_f32_16x16x32_bf16 v[36:39], v[118:121], v[162:165], v[36:39]
	v_mfma_f32_16x16x32_bf16 v[28:31], v[130:133], v[162:165], v[28:31]
	v_mfma_f32_16x16x32_bf16 v[20:23], v[118:121], v[170:173], v[20:23]
	v_mfma_f32_16x16x32_bf16 v[12:15], v[130:133], v[170:173], v[12:15]
	v_mfma_f32_16x16x32_bf16 v[60:63], v[126:129], v[150:153], v[60:63]
	v_mfma_f32_16x16x32_bf16 v[56:59], v[134:137], v[150:153], v[56:59]
	v_mfma_f32_16x16x32_bf16 v[52:55], v[126:129], v[158:161], v[52:55]
	v_mfma_f32_16x16x32_bf16 v[44:47], v[134:137], v[158:161], v[44:47]
	v_mfma_f32_16x16x32_bf16 v[36:39], v[126:129], v[166:169], v[36:39]
	v_mfma_f32_16x16x32_bf16 v[28:31], v[134:137], v[166:169], v[28:31]
	v_mfma_f32_16x16x32_bf16 v[20:23], v[126:129], v[174:177], v[20:23]
	v_mfma_f32_16x16x32_bf16 v[12:15], v[134:137], v[174:177], v[12:15]
	s_barrier
; #define PG8_STAGE(bufoff, gbase, voff) do { _Pragma("unroll") for (int _i = 0; _i < 2; ++_i) \
;         __builtin_amdgcn_global_load_lds((const unsigned*)((const char*)(gbase) + (voff)[_i]), (PG8_LAS unsigned*)(lds + (bufoff) + ldsw + _i * 8192), 16, 0, 0); } while (0)
; #define PG8_LDA(dst, b, h) do { _Pragma("unroll") for (int m = 0; m < 4; ++m) _Pragma("unroll") for (int k = 0; k < 2; ++k) dst[m][k] = *(const PG8_LAS bf16x8*)(lds + PG8_SA(b, h) + aoff + m * 2048 + k * 1024); } while (0)
; #define PG8_LDB(dst, b, h) do { _Pragma("unroll") for (int n = 0; n < 2; ++n) _Pragma("unroll") for (int k = 0; k < 2; ++k) dst[n][k] = *(const PG8_LAS bf16x8*)(lds + PG8_SB(b, h) + boff + n * 2048 + k * 1024); } while (0)
; #define PG8_MMA(ai, bj, At, Bt) do { __builtin_amdgcn_s_setprio(1); _Pragma("unroll") for (int m = 0; m < 4; ++m) _Pragma("unroll") for (int n = 0; n < 2; ++n) _Pragma("unroll") for (int k = 0; k < 2; ++k) \
;         acc[ai][bj][m][n] = __builtin_amdgcn_mfma_f32_16x16x32_bf16(Bt[n][k], At[m][k], acc[ai][bj][m][n], 0, 0, 0); __builtin_amdgcn_s_setprio(0); } while (0)
; #define PG8_WAIT_V(n) asm volatile("s_waitcnt vmcnt(" #n ")" ::: "memory")
; #define PG8_WAIT_L(n) asm volatile("s_waitcnt lgkmcnt(" #n ")" ::: "memory")
; #define PG8_BAR __builtin_amdgcn_s_barrier()
; #define PG8_SCHED __builtin_amdgcn_sched_barrier(0)
; template <class Epi, class Sched>
; __device__ __forceinline__ void gemm_phase(PG8_LAS unsigned char* lds, const Gemm g, const Sched& S, const Epi& E) {
;     ...
;             PG8_STAGE(PG8_SB(0, 1), b2 + hstep, voffB);
;             PG8_WAIT_V(6); PG8_BAR; PG8_MMA(1, 1, At, B1); PG8_BAR;
;             PG8_LDB(B0, 1, 0); PG8_SCHED; PG8_LDA(At, 1, 0); PG8_STAGE(PG8_SA(0, 1), a2 + hstep, voffA);
;             PG8_WAIT_L(8); PG8_BAR; PG8_WAIT_L(0); PG8_MMA(0, 0, At, B0); PG8_BAR; PG8_SCHED;
;             PG8_LDB(B1, 1, 1); PG8_STAGE(PG8_SB(1, 0), b3, voffB);
;             PG8_BAR; PG8_WAIT_L(0); PG8_MMA(0, 1, At, B1); PG8_BAR;
	s_add_u32 s50, vcc_lo, 0x100000
	s_addc_u32 s51, vcc_hi, 0
	s_add_i32 s42, s43, s58
	v_lshl_add_u64 v[118:119], s[50:51], 0, v[96:97]
	s_mov_b32 m0, s42
	s_nop 0
	global_load_lds_dwordx4 v[118:119], off
	v_lshl_add_u64 v[118:119], s[50:51], 0, v[208:209]
	s_add_i32 m0, s42, 0x2000
	s_nop 0
	global_load_lds_dwordx4 v[118:119], off
	s_waitcnt vmcnt(6)
	s_barrier
	v_mfma_f32_16x16x32_bf16 v[48:51], v[178:181], v[146:149], v[48:51]
	v_mfma_f32_16x16x32_bf16 v[40:43], v[186:189], v[146:149], v[40:43]
	v_mfma_f32_16x16x32_bf16 v[32:35], v[178:181], v[154:157], v[32:35]
	v_mfma_f32_16x16x32_bf16 v[24:27], v[186:189], v[154:157], v[24:27]
	v_mfma_f32_16x16x32_bf16 v[16:19], v[178:181], v[162:165], v[16:19]
	v_mfma_f32_16x16x32_bf16 v[8:11], v[186:189], v[162:165], v[8:11]
	v_mfma_f32_16x16x32_bf16 v[4:7], v[178:181], v[170:173], v[4:7]
	v_mfma_f32_16x16x32_bf16 v[0:3], v[186:189], v[170:173], v[0:3]
	v_mfma_f32_16x16x32_bf16 v[48:51], v[182:185], v[150:153], v[48:51]
	v_mfma_f32_16x16x32_bf16 v[40:43], v[190:193], v[150:153], v[40:43]
	v_mfma_f32_16x16x32_bf16 v[32:35], v[182:185], v[158:161], v[32:35]
	v_mfma_f32_16x16x32_bf16 v[24:27], v[190:193], v[158:161], v[24:27]
	v_mfma_f32_16x16x32_bf16 v[16:19], v[182:185], v[166:169], v[16:19]
	v_mfma_f32_16x16x32_bf16 v[8:11], v[190:193], v[166:169], v[8:11]
	v_mfma_f32_16x16x32_bf16 v[4:7], v[182:185], v[174:177], v[4:7]
	v_mfma_f32_16x16x32_bf16 v[0:3], v[190:193], v[174:177], v[0:3]
	s_add_i32 s42, 0, 0x18000
	v_add_u32_e32 v134, s42, v225
	s_barrier
	ds_read_b128 v[118:121], v134
	ds_read_b128 v[126:129], v134 offset:1024
	ds_read_b128 v[130:133], v134 offset:2048
	ds_read_b128 v[134:137], v134 offset:3072
	s_add_u32 s0, s0, 0x100000
	s_addc_u32 s1, s1, 0
	s_mov_b32 m0, s62
	v_lshl_add_u64 v[178:179], s[0:1], 0, v[96:97]
	ds_read_b128 v[146:149], v240 offset:32768
	ds_read_b128 v[150:153], v240 offset:33792
	ds_read_b128 v[154:157], v240 offset:34816
	ds_read_b128 v[158:161], v240 offset:35840
	ds_read_b128 v[162:165], v240 offset:36864
	ds_read_b128 v[166:169], v240 offset:37888
	ds_read_b128 v[170:173], v240 offset:38912
	ds_read_b128 v[174:177], v240 offset:39936
	global_load_lds_dwordx4 v[178:179], off
	v_lshl_add_u64 v[178:179], s[0:1], 0, v[208:209]
	s_mov_b32 m0, s63
	s_nop 0
	global_load_lds_dwordx4 v[178:179], off
	s_waitcnt lgkmcnt(8)
	s_barrier
	s_waitcnt lgkmcnt(0)
	v_mfma_f32_16x16x32_bf16 v[142:145], v[118:121], v[146:149], v[142:145]
	v_mfma_f32_16x16x32_bf16 v[138:141], v[130:133], v[146:149], v[138:141]
	v_mfma_f32_16x16x32_bf16 v[114:117], v[118:121], v[154:157], v[114:117]
	v_mfma_f32_16x16x32_bf16 v[106:109], v[130:133], v[154:157], v[106:109]
	v_mfma_f32_16x16x32_bf16 v[102:105], v[118:121], v[162:165], v[102:105]
	v_mfma_f32_16x16x32_bf16 v[92:95], v[130:133], v[162:165], v[92:95]
	v_mfma_f32_16x16x32_bf16 v[84:87], v[118:121], v[170:173], v[84:87]
	v_mfma_f32_16x16x32_bf16 v[76:79], v[130:133], v[170:173], v[76:79]
	v_mfma_f32_16x16x32_bf16 v[142:145], v[126:129], v[150:153], v[142:145]
	v_mfma_f32_16x16x32_bf16 v[138:141], v[134:137], v[150:153], v[138:141]
	v_mfma_f32_16x16x32_bf16 v[114:117], v[126:129], v[158:161], v[114:117]
	v_mfma_f32_16x16x32_bf16 v[106:109], v[134:137], v[158:161], v[106:109]
	v_mfma_f32_16x16x32_bf16 v[102:105], v[126:129], v[166:169], v[102:105]
	v_mfma_f32_16x16x32_bf16 v[92:95], v[134:137], v[166:169], v[92:95]
	v_mfma_f32_16x16x32_bf16 v[84:87], v[126:129], v[174:177], v[84:87]
	v_mfma_f32_16x16x32_bf16 v[76:79], v[134:137], v[174:177], v[76:79]
	s_barrier
	s_add_i32 s43, 0, 0x1c000
	s_add_i32 s0, s42, s58
	v_add_u32_e32 v190, s43, v225
	v_lshl_add_u64 v[194:195], v[194:195], 0, s[2:3]
	s_mov_b32 m0, s0
	ds_read_b128 v[178:181], v190
	ds_read_b128 v[182:185], v190 offset:1024
	ds_read_b128 v[186:189], v190 offset:2048
	ds_read_b128 v[190:193], v190 offset:3072
	global_load_lds_dwordx4 v[194:195], off
	v_lshl_add_u64 v[194:195], v[196:197], 0, s[2:3]
	s_add_i32 m0, s0, 0x2000
	s_nop 0
	global_load_lds_dwordx4 v[194:195], off
	s_barrier
	s_waitcnt lgkmcnt(0)
	v_mfma_f32_16x16x32_bf16 v[122:125], v[178:181], v[146:149], v[122:125]
	v_mfma_f32_16x16x32_bf16 v[110:113], v[186:189], v[146:149], v[110:113]
	v_mfma_f32_16x16x32_bf16 v[98:101], v[178:181], v[154:157], v[98:101]
	v_mfma_f32_16x16x32_bf16 v[88:91], v[186:189], v[154:157], v[88:91]
	v_mfma_f32_16x16x32_bf16 v[80:83], v[178:181], v[162:165], v[80:83]
	v_mfma_f32_16x16x32_bf16 v[72:75], v[186:189], v[162:165], v[72:75]
	v_mfma_f32_16x16x32_bf16 v[68:71], v[178:181], v[170:173], v[68:71]
	v_mfma_f32_16x16x32_bf16 v[64:67], v[186:189], v[170:173], v[64:67]
	v_mfma_f32_16x16x32_bf16 v[122:125], v[182:185], v[150:153], v[122:125]
	v_mfma_f32_16x16x32_bf16 v[110:113], v[190:193], v[150:153], v[110:113]
	v_mfma_f32_16x16x32_bf16 v[98:101], v[182:185], v[158:161], v[98:101]
	v_mfma_f32_16x16x32_bf16 v[88:91], v[190:193], v[158:161], v[88:91]
	v_mfma_f32_16x16x32_bf16 v[80:83], v[182:185], v[166:169], v[80:83]
	v_mfma_f32_16x16x32_bf16 v[72:75], v[190:193], v[166:169], v[72:75]
	v_mfma_f32_16x16x32_bf16 v[68:71], v[182:185], v[174:177], v[68:71]
	v_mfma_f32_16x16x32_bf16 v[64:67], v[190:193], v[174:177], v[64:67]
	s_mov_b32 m0, s64
	v_lshl_add_u64 v[194:195], v[198:199], 0, s[2:3]
	s_barrier
	ds_read_b128 v[146:149], v240 offset:49152
	ds_read_b128 v[150:153], v240 offset:50176
	ds_read_b128 v[154:157], v240 offset:51200
	ds_read_b128 v[158:161], v240 offset:52224
	ds_read_b128 v[162:165], v240 offset:53248
	ds_read_b128 v[166:169], v240 offset:54272
	ds_read_b128 v[170:173], v240 offset:55296
	ds_read_b128 v[174:177], v240 offset:56320
	global_load_lds_dwordx4 v[194:195], off
	v_lshl_add_u64 v[194:195], v[200:201], 0, s[2:3]
	s_mov_b32 m0, s65
	s_nop 0
	global_load_lds_dwordx4 v[194:195], off
	s_barrier
; #define PG8_STAGE(bufoff, gbase, voff) do { _Pragma("unroll") for (int _i = 0; _i < 2; ++_i) \
;         __builtin_amdgcn_global_load_lds((const unsigned*)((const char*)(gbase) + (voff)[_i]), (PG8_LAS unsigned*)(lds + (bufoff) + ldsw + _i * 8192), 16, 0, 0); } while (0)
; #define PG8_LDA(dst, b, h) do { _Pragma("unroll") for (int m = 0; m < 4; ++m) _Pragma("unroll") for (int k = 0; k < 2; ++k) dst[m][k] = *(const PG8_LAS bf16x8*)(lds + PG8_SA(b, h) + aoff + m * 2048 + k * 1024); } while (0)
; #define PG8_MMA(ai, bj, At, Bt) do { __builtin_amdgcn_s_setprio(1); _Pragma("unroll") for (int m = 0; m < 4; ++m) _Pragma("unroll") for (int n = 0; n < 2; ++n) _Pragma("unroll") for (int k = 0; k < 2; ++k) \
;         acc[ai][bj][m][n] = __builtin_amdgcn_mfma_f32_16x16x32_bf16(Bt[n][k], At[m][k], acc[ai][bj][m][n], 0, 0, 0); __builtin_amdgcn_s_setprio(0); } while (0)
; #define PG8_WAIT_V(n) asm volatile("s_waitcnt vmcnt(" #n ")" ::: "memory")
; #define PG8_BAR __builtin_amdgcn_s_barrier()
; template <class Epi, class Sched>
; __device__ __forceinline__ void gemm_phase(PG8_LAS unsigned char* lds, const Gemm g, const Sched& S, const Epi& E) {
;     ...
;             PG8_LDA(At, 1, 1); PG8_STAGE(PG8_SA(1, 0), a3, voffA);
;             PG8_BAR; PG8_WAIT_L(0); PG8_MMA(1, 0, At, B0); PG8_BAR; PG8_SCHED;
;             PG8_STAGE(PG8_SB(1, 1), b3 + hstep, voffB);
;             PG8_WAIT_V(6); PG8_BAR; PG8_MMA(1, 1, At, B1); PG8_BAR;
;         }
;   DEV void operator()(const f32x4 (&acc)[2][2][4][2], const pg8::Unit& u, int wr, int wc, int fr, int fq) const {
;     const int row0 = u.pm * 256 + wr * 64 + fr, col0 = u.pn * 256 + wc * 32 + 4 * fq;
;     const float* gt = mod + (size_t)modrow(row0) * 6144;
;     f32x4 g4[2][2];
; #pragma unroll
;     for (int bj = 0; bj < 2; ++bj)
; #pragma unroll
;       for (int n = 0; n < 2; ++n) g4[bj][n] = *(const f32x4*)(gt + col0 + bj * 128 + n * 16);
; #pragma unroll
;     for (int ai = 0; ai < 2; ++ai) {
;       f32x4 xv[4][2][2];
; #pragma unroll
;       for (int m = 0; m < 4; ++m) {
;         const int row = row0 + ai * 128 + m * 16;
;         const float* xi = row < T_LAT ? rin_lat + (size_t)row * DM : rin_ctx + (size_t)(row - T_LAT) * DM;
; #pragma unroll
;         for (int bj = 0; bj < 2; ++bj)
; #pragma unroll
;           for (int n = 0; n < 2; ++n) xv[m][bj][n] = *(const f32x4*)(xi + col0 + bj * 128 + n * 16);
;       }
	s_waitcnt lgkmcnt(0)
	v_mfma_f32_16x16x32_bf16 v[60:63], v[118:121], v[146:149], v[60:63]
	v_mfma_f32_16x16x32_bf16 v[56:59], v[130:133], v[146:149], v[56:59]
	v_mfma_f32_16x16x32_bf16 v[52:55], v[118:121], v[154:157], v[52:55]
	v_mfma_f32_16x16x32_bf16 v[44:47], v[130:133], v[154:157], v[44:47]
	v_mfma_f32_16x16x32_bf16 v[36:39], v[118:121], v[162:165], v[36:39]
	v_mfma_f32_16x16x32_bf16 v[28:31], v[130:133], v[162:165], v[28:31]
	v_mfma_f32_16x16x32_bf16 v[20:23], v[118:121], v[170:173], v[20:23]
	v_mfma_f32_16x16x32_bf16 v[12:15], v[130:133], v[170:173], v[12:15]
	v_mfma_f32_16x16x32_bf16 v[60:63], v[126:129], v[150:153], v[60:63]
	v_mfma_f32_16x16x32_bf16 v[56:59], v[134:137], v[150:153], v[56:59]
	v_mfma_f32_16x16x32_bf16 v[52:55], v[126:129], v[158:161], v[52:55]
	v_mfma_f32_16x16x32_bf16 v[44:47], v[134:137], v[158:161], v[44:47]
	v_mfma_f32_16x16x32_bf16 v[36:39], v[126:129], v[166:169], v[36:39]
	v_mfma_f32_16x16x32_bf16 v[28:31], v[134:137], v[166:169], v[28:31]
	v_mfma_f32_16x16x32_bf16 v[20:23], v[126:129], v[174:177], v[20:23]
	v_mfma_f32_16x16x32_bf16 v[12:15], v[134:137], v[174:177], v[12:15]
	s_barrier
	s_add_u32 s0, vcc_lo, 0x100080
	s_addc_u32 s1, vcc_hi, 0
	s_add_i32 s42, s43, s58
	v_lshl_add_u64 v[118:119], s[0:1], 0, v[96:97]
	s_mov_b32 m0, s42
	s_nop 0
	global_load_lds_dwordx4 v[118:119], off
	v_lshl_add_u64 v[118:119], s[0:1], 0, v[208:209]
	s_add_i32 m0, s42, 0x2000
	s_nop 0
	global_load_lds_dwordx4 v[118:119], off
	s_waitcnt vmcnt(6)
	s_barrier
	v_mfma_f32_16x16x32_bf16 v[48:51], v[178:181], v[146:149], v[48:51]
	v_mfma_f32_16x16x32_bf16 v[40:43], v[186:189], v[146:149], v[40:43]
	v_mfma_f32_16x16x32_bf16 v[32:35], v[178:181], v[154:157], v[32:35]
	v_mfma_f32_16x16x32_bf16 v[24:27], v[186:189], v[154:157], v[24:27]
	v_mfma_f32_16x16x32_bf16 v[16:19], v[178:181], v[162:165], v[16:19]
	v_mfma_f32_16x16x32_bf16 v[8:11], v[186:189], v[162:165], v[8:11]
	v_mfma_f32_16x16x32_bf16 v[4:7], v[178:181], v[170:173], v[4:7]
	v_mfma_f32_16x16x32_bf16 v[0:3], v[186:189], v[170:173], v[0:3]
	v_mfma_f32_16x16x32_bf16 v[48:51], v[182:185], v[150:153], v[48:51]
	v_mfma_f32_16x16x32_bf16 v[40:43], v[190:193], v[150:153], v[40:43]
	v_mfma_f32_16x16x32_bf16 v[32:35], v[182:185], v[158:161], v[32:35]
	v_mfma_f32_16x16x32_bf16 v[24:27], v[190:193], v[158:161], v[24:27]
	v_mfma_f32_16x16x32_bf16 v[16:19], v[182:185], v[166:169], v[16:19]
	v_mfma_f32_16x16x32_bf16 v[8:11], v[190:193], v[166:169], v[8:11]
	v_mfma_f32_16x16x32_bf16 v[4:7], v[182:185], v[174:177], v[4:7]
	v_mfma_f32_16x16x32_bf16 v[0:3], v[190:193], v[174:177], v[0:3]
	s_add_i32 s94, s94, 2
	s_add_u32 s70, s70, 0x100
	s_addc_u32 s71, s71, 0
	s_cmp_gt_u32 s94, 61
	s_mov_b64 s[50:51], s[52:53]
	s_barrier
	s_cbranch_scc0 .LBB0_47
	v_lshl_add_u32 v238, s48, 8, v224
	s_mov_b32 s71, 0x8000
	v_readlane_b32 s0, v251, 52
	v_min_i32_e32 v119, 0x8000, v238
	v_cmp_gt_i32_e32 vcc, s71, v238
	v_add_u32_e32 v146, 0xffff8000, v238
	v_ashrrev_i32_e32 v147, 31, v238
	v_mov_b32_e32 v241, s0
	v_readlane_b32 s0, v251, 51
	v_lshl_or_b32 v118, s67, 8, v239
	v_ashrrev_i32_e32 v119, 12, v119
	v_cndmask_b32_e32 v147, 0, v147, vcc
	v_cndmask_b32_e32 v146, v146, v238, vcc
	v_mov_b32_e32 v242, s73
	v_mov_b32_e32 v243, s0
	v_mov_b32_e32 v244, s72
	v_mul_hi_i32_i24_e32 v121, 0x6000, v119
	v_mul_i32_i24_e32 v120, 0x6000, v119
	v_ashrrev_i32_e32 v119, 31, v118
	v_cndmask_b32_e32 v149, v241, v242, vcc
	v_cndmask_b32_e32 v148, v243, v244, vcc
	v_lshlrev_b64 v[146:147], 12, v[146:147]
	v_lshlrev_b64 v[214:215], 2, v[118:119]
	v_lshl_add_u64 v[146:147], v[148:149], 0, v[146:147]
	v_lshl_add_u64 v[222:223], v[146:147], 0, v[214:215]
	v_or_b32_e32 v146, 16, v238
	v_cmp_gt_i32_e32 vcc, s71, v146
	v_ashrrev_i32_e32 v147, 31, v146
	v_add_u32_e32 v148, 0xffff8010, v238
	v_cndmask_b32_e32 v147, 0, v147, vcc
	v_cndmask_b32_e32 v146, v148, v146, vcc
	v_cndmask_b32_e32 v149, v241, v242, vcc
	v_cndmask_b32_e32 v148, v243, v244, vcc
	v_lshlrev_b64 v[146:147], 12, v[146:147]
	v_lshl_add_u64 v[146:147], v[148:149], 0, v[146:147]
	v_lshl_add_u64 v[220:221], v[146:147], 0, v[214:215]
	v_or_b32_e32 v146, 32, v238
	v_cmp_gt_i32_e32 vcc, s71, v146
	v_ashrrev_i32_e32 v147, 31, v146
	v_add_u32_e32 v148, 0xffff8020, v238
	v_cndmask_b32_e32 v147, 0, v147, vcc
	v_cndmask_b32_e32 v146, v148, v146, vcc
	v_cndmask_b32_e32 v149, v241, v242, vcc
	v_cndmask_b32_e32 v148, v243, v244, vcc
	v_lshlrev_b64 v[146:147], 12, v[146:147]
	v_lshl_add_u64 v[146:147], v[148:149], 0, v[146:147]
	v_lshl_add_u64 v[218:219], v[146:147], 0, v[214:215]
	v_or_b32_e32 v146, 48, v238
	v_cmp_gt_i32_e32 vcc, s71, v146
	v_ashrrev_i32_e32 v147, 31, v146
	v_add_u32_e32 v148, 0xffff8030, v238
	v_cndmask_b32_e32 v147, 0, v147, vcc
	v_cndmask_b32_e32 v146, v148, v146, vcc
	v_cndmask_b32_e32 v149, v241, v242, vcc
	v_cndmask_b32_e32 v148, v243, v244, vcc
	v_lshlrev_b64 v[146:147], 12, v[146:147]
	v_lshl_add_u64 v[120:121], s[30:31], 0, v[120:121]
	v_lshl_add_u64 v[146:147], v[148:149], 0, v[146:147]
	v_lshl_add_u64 v[118:119], v[120:121], 0, v[214:215]
	v_lshl_add_u64 v[216:217], v[146:147], 0, v[214:215]
	global_load_dwordx4 v[134:137], v[118:119], off
	global_load_dwordx4 v[130:133], v[118:119], off offset:64
	global_load_dwordx4 v[126:129], v[118:119], off offset:512
	s_nop 0
	global_load_dwordx4 v[118:121], v[118:119], off offset:576
	s_nop 0
	global_load_dwordx4 v[202:205], v[222:223], off offset:64
	global_load_dwordx4 v[198:201], v[222:223], off offset:512
	global_load_dwordx4 v[194:197], v[222:223], off offset:576
	global_load_dwordx4 v[190:193], v[220:221], off
	global_load_dwordx4 v[186:189], v[220:221], off offset:64
	global_load_dwordx4 v[182:185], v[220:221], off offset:512
	global_load_dwordx4 v[174:177], v[220:221], off offset:576
	global_load_dwordx4 v[178:181], v[218:219], off
	global_load_dwordx4 v[170:173], v[218:219], off offset:64
	global_load_dwordx4 v[166:169], v[218:219], off offset:512
	global_load_dwordx4 v[158:161], v[218:219], off offset:576
	global_load_dwordx4 v[162:165], v[216:217], off
	global_load_dwordx4 v[154:157], v[216:217], off offset:64
	global_load_dwordx4 v[150:153], v[216:217], off offset:512
	global_load_dwordx4 v[146:149], v[216:217], off offset:576
	global_load_dwordx4 v[228:231], v[222:223], off
	s_movk_i32 s0, 0x7f80
	v_cmp_gt_i32_e32 vcc, s0, v238
	s_movk_i32 s0, 0x7f70
	s_mov_b32 s67, s38
	s_mov_b32 s48, s40
	s_mov_b64 s[52:53], s[46:47]
	s_mov_b64 s[50:51], s[44:45]
	s_waitcnt vmcnt(0)
;   DEV void operator()(const f32x4 (&acc)[2][2][4][2], const pg8::Unit& u, int wr, int wc, int fr, int fq) const {
;     ...
;     for (int ai = 0; ai < 2; ++ai) {
;       f32x4 xv[4][2][2];
; #pragma unroll
;       for (int m = 0; m < 4; ++m) {
;         const int row = row0 + ai * 128 + m * 16;
;         const float* xi = row < T_LAT ? rin_lat + (size_t)row * DM : rin_ctx + (size_t)(row - T_LAT) * DM;
; #pragma unroll
;         for (int bj = 0; bj < 2; ++bj)
; #pragma unroll
;           for (int n = 0; n < 2; ++n) xv[m][bj][n] = *(const f32x4*)(xi + col0 + bj * 128 + n * 16);
;       }
; #pragma unroll
;       for (int m = 0; m < 4; ++m) {
;         const int row = row0 + ai * 128 + m * 16;
;         float* xr = row < T_LAT ? out + (size_t)row * DM : xc + (size_t)(row - T_LAT) * DM;
; #pragma unroll
;         for (int bj = 0; bj < 2; ++bj)
; #pragma unroll
;           for (int n = 0; n < 2; ++n) {
;             const f32x4 r = xv[m][bj][n] + g4[bj][n] * acc[ai][bj][m][n];
;             if (store) *(f32x4*)(xr + col0 + bj * 128 + n * 16) = r;
;           }
;       }
	v_pk_fma_f32 v[140:141], v[140:141], v[132:133], v[204:205]
	v_pk_fma_f32 v[138:139], v[138:139], v[130:131], v[202:203]
	v_pk_fma_f32 v[124:125], v[124:125], v[128:129], v[200:201]
	v_pk_fma_f32 v[122:123], v[122:123], v[126:127], v[198:199]
	v_pk_fma_f32 v[112:113], v[112:113], v[120:121], v[196:197]
	v_pk_fma_f32 v[144:145], v[144:145], v[136:137], v[230:231]
	v_pk_fma_f32 v[142:143], v[142:143], v[134:135], v[228:229]
	v_pk_fma_f32 v[110:111], v[110:111], v[118:119], v[194:195]
	v_pk_fma_f32 v[90:91], v[90:91], v[120:121], v[176:177]
	v_pk_fma_f32 v[88:89], v[88:89], v[118:119], v[174:175]
	global_store_dwordx4 v[222:223], v[142:145], off
	global_store_dwordx4 v[222:223], v[138:141], off offset:64
	global_store_dwordx4 v[222:223], v[122:125], off offset:512
	global_store_dwordx4 v[222:223], v[110:113], off offset:576
	v_pk_fma_f32 v[108:109], v[108:109], v[132:133], v[188:189]
	v_pk_fma_f32 v[106:107], v[106:107], v[130:131], v[186:187]
	v_pk_fma_f32 v[112:113], v[116:117], v[136:137], v[192:193]
	v_pk_fma_f32 v[110:111], v[114:115], v[134:135], v[190:191]
	v_pk_fma_f32 v[100:101], v[100:101], v[128:129], v[184:185]
	v_pk_fma_f32 v[98:99], v[98:99], v[126:127], v[182:183]
	global_store_dwordx4 v[220:221], v[88:91], off offset:576
	global_store_dwordx4 v[220:221], v[110:113], off
	global_store_dwordx4 v[220:221], v[106:109], off offset:64
	v_pk_fma_f32 v[90:91], v[104:105], v[136:137], v[180:181]
	v_pk_fma_f32 v[88:89], v[102:103], v[134:135], v[178:179]
	global_store_dwordx4 v[220:221], v[98:101], off offset:512
	global_store_dwordx4 v[218:219], v[88:91], off
	v_pk_fma_f32 v[82:83], v[82:83], v[128:129], v[168:169]
	v_pk_fma_f32 v[80:81], v[80:81], v[126:127], v[166:167]
	v_pk_fma_f32 v[90:91], v[94:95], v[132:133], v[172:173]
	v_pk_fma_f32 v[88:89], v[92:93], v[130:131], v[170:171]
	v_pk_fma_f32 v[74:75], v[74:75], v[120:121], v[160:161]
	v_pk_fma_f32 v[72:73], v[72:73], v[118:119], v[158:159]
	v_pk_fma_f32 v[66:67], v[66:67], v[120:121], v[148:149]
	v_pk_fma_f32 v[64:65], v[64:65], v[118:119], v[146:147]
	global_store_dwordx4 v[218:219], v[88:91], off offset:64
	global_store_dwordx4 v[218:219], v[80:83], off offset:512
	global_store_dwordx4 v[218:219], v[72:75], off offset:576
	global_store_dwordx4 v[216:217], v[64:67], off offset:576
	v_pk_fma_f32 v[70:71], v[70:71], v[128:129], v[152:153]
	v_pk_fma_f32 v[74:75], v[86:87], v[136:137], v[164:165]
	v_add_u32_e32 v64, 0x80, v238
	v_ashrrev_i32_e32 v65, 31, v64
	v_add_u32_e32 v66, 0xffff8080, v238
	v_cndmask_b32_e32 v65, 0, v65, vcc
	v_cndmask_b32_e32 v64, v66, v64, vcc
	v_cndmask_b32_e32 v67, v241, v242, vcc
	v_cndmask_b32_e32 v66, v243, v244, vcc
	v_lshlrev_b64 v[64:65], 12, v[64:65]
	v_lshl_add_u64 v[64:65], v[66:67], 0, v[64:65]
	v_lshl_add_u64 v[148:149], v[64:65], 0, v[214:215]
	v_add_u32_e32 v64, 0x90, v238
	v_cmp_gt_i32_e32 vcc, s0, v238
	v_ashrrev_i32_e32 v65, 31, v64
	v_add_u32_e32 v66, 0xffff8090, v238
	v_cndmask_b32_e32 v65, 0, v65, vcc
	v_cndmask_b32_e32 v64, v66, v64, vcc
	v_cndmask_b32_e32 v67, v241, v242, vcc
	v_cndmask_b32_e32 v66, v243, v244, vcc
	v_lshlrev_b64 v[64:65], 12, v[64:65]
	v_lshl_add_u64 v[64:65], v[66:67], 0, v[64:65]
	v_lshl_add_u64 v[146:147], v[64:65], 0, v[214:215]
	v_add_u32_e32 v64, 0xa0, v238
	s_movk_i32 s0, 0x7f60
	v_cmp_gt_i32_e32 vcc, s0, v238
	v_ashrrev_i32_e32 v65, 31, v64
	v_add_u32_e32 v66, 0xffff80a0, v238
	v_cndmask_b32_e32 v65, 0, v65, vcc
	v_cndmask_b32_e32 v64, v66, v64, vcc
	v_cndmask_b32_e32 v67, v241, v242, vcc
	v_cndmask_b32_e32 v66, v243, v244, vcc
	v_lshlrev_b64 v[64:65], 12, v[64:65]
	v_lshl_add_u64 v[64:65], v[66:67], 0, v[64:65]
	v_lshl_add_u64 v[144:145], v[64:65], 0, v[214:215]
	v_add_u32_e32 v64, 0xb0, v238
	s_movk_i32 s0, 0x7f50
	v_cmp_gt_i32_e32 vcc, s0, v238
	v_ashrrev_i32_e32 v65, 31, v64
	v_add_u32_e32 v66, 0xffff80b0, v238
	v_pk_fma_f32 v[72:73], v[84:85], v[134:135], v[162:163]
	v_cndmask_b32_e32 v65, 0, v65, vcc
	v_cndmask_b32_e32 v64, v66, v64, vcc
	global_store_dwordx4 v[216:217], v[72:75], off
	v_pk_fma_f32 v[68:69], v[68:69], v[126:127], v[150:151]
	v_cndmask_b32_e32 v67, v241, v242, vcc
	v_pk_fma_f32 v[74:75], v[78:79], v[132:133], v[156:157]
	v_pk_fma_f32 v[72:73], v[76:77], v[130:131], v[154:155]
	v_cndmask_b32_e32 v66, v243, v244, vcc
	v_lshlrev_b64 v[64:65], 12, v[64:65]
	global_store_dwordx4 v[216:217], v[72:75], off offset:64
	global_store_dwordx4 v[216:217], v[68:71], off offset:512
	v_lshl_add_u64 v[64:65], v[66:67], 0, v[64:65]
	global_load_dwordx4 v[138:141], v[148:149], off offset:64
	global_load_dwordx4 v[122:125], v[148:149], off offset:512
	global_load_dwordx4 v[110:113], v[148:149], off offset:576
	v_lshl_add_u64 v[142:143], v[64:65], 0, v[214:215]
	global_load_dwordx4 v[114:117], v[146:147], off
	global_load_dwordx4 v[106:109], v[146:147], off offset:64
	global_load_dwordx4 v[102:105], v[146:147], off offset:512
	global_load_dwordx4 v[92:95], v[146:147], off offset:576
	global_load_dwordx4 v[98:101], v[144:145], off
	global_load_dwordx4 v[88:91], v[144:145], off offset:64
	global_load_dwordx4 v[84:87], v[144:145], off offset:512
	global_load_dwordx4 v[76:79], v[144:145], off offset:576
	global_load_dwordx4 v[80:83], v[142:143], off
	global_load_dwordx4 v[72:75], v[142:143], off offset:64
	global_load_dwordx4 v[68:71], v[142:143], off offset:512
	global_load_dwordx4 v[64:67], v[142:143], off offset:576
	global_load_dwordx4 v[150:153], v[148:149], off
	s_and_b64 vcc, exec, s[36:37]
	s_waitcnt vmcnt(0)
; #define PG8_WAIT_V(n) asm volatile("s_waitcnt vmcnt(" #n ")" ::: "memory")
; #define PG8_BAR __builtin_amdgcn_s_barrier()
; template <class Epi, class Sched>
; __device__ __forceinline__ void gemm_phase(PG8_LAS unsigned char* lds, const Gemm g, const Sched& S, const Epi& E) {
;     ...
;     PG8_WAIT_V(0);
;     if (wr == 0) PG8_BAR;
;     PG8_BAR;
;   DEV void operator()(const f32x4 (&acc)[2][2][4][2], const pg8::Unit& u, int wr, int wc, int fr, int fq) const {
;     ...
; #pragma unroll
;       for (int m = 0; m < 4; ++m) {
;         const int row = row0 + ai * 128 + m * 16;
;         float* xr = row < T_LAT ? out + (size_t)row * DM : xc + (size_t)(row - T_LAT) * DM;
; #pragma unroll
;         for (int bj = 0; bj < 2; ++bj)
; #pragma unroll
;           for (int n = 0; n < 2; ++n) {
;             const f32x4 r = xv[m][bj][n] + g4[bj][n] * acc[ai][bj][m][n];
;             if (store) *(f32x4*)(xr + col0 + bj * 128 + n * 16) = r;
;           }
;       }
;     }
	v_pk_fma_f32 v[58:59], v[58:59], v[132:133], v[140:141]
	v_pk_fma_f32 v[56:57], v[56:57], v[130:131], v[138:139]
	v_pk_fma_f32 v[42:43], v[42:43], v[120:121], v[112:113]
	v_pk_fma_f32 v[40:41], v[40:41], v[118:119], v[110:111]
	v_pk_fma_f32 v[50:51], v[50:51], v[128:129], v[124:125]
	v_pk_fma_f32 v[48:49], v[48:49], v[126:127], v[122:123]
	v_pk_fma_f32 v[62:63], v[62:63], v[136:137], v[152:153]
	v_pk_fma_f32 v[60:61], v[60:61], v[134:135], v[150:151]
	global_store_dwordx4 v[148:149], v[40:43], off offset:576
	v_pk_fma_f32 v[26:27], v[26:27], v[120:121], v[94:95]
	v_pk_fma_f32 v[24:25], v[24:25], v[118:119], v[92:93]
	v_pk_fma_f32 v[42:43], v[54:55], v[136:137], v[116:117]
	v_pk_fma_f32 v[40:41], v[52:53], v[134:135], v[114:115]
	global_store_dwordx4 v[148:149], v[60:63], off
	global_store_dwordx4 v[148:149], v[56:59], off offset:64
	global_store_dwordx4 v[148:149], v[48:51], off offset:512
	global_store_dwordx4 v[146:147], v[40:43], off
	v_pk_fma_f32 v[34:35], v[34:35], v[128:129], v[104:105]
	v_pk_fma_f32 v[32:33], v[32:33], v[126:127], v[102:103]
	v_pk_fma_f32 v[42:43], v[46:47], v[132:133], v[108:109]
	v_pk_fma_f32 v[40:41], v[44:45], v[130:131], v[106:107]
	global_store_dwordx4 v[146:147], v[24:27], off offset:576
	v_pk_fma_f32 v[10:11], v[10:11], v[120:121], v[78:79]
	v_pk_fma_f32 v[8:9], v[8:9], v[118:119], v[76:77]
	v_pk_fma_f32 v[26:27], v[38:39], v[136:137], v[100:101]
	v_pk_fma_f32 v[24:25], v[36:37], v[134:135], v[98:99]
	global_store_dwordx4 v[146:147], v[40:43], off offset:64
	global_store_dwordx4 v[146:147], v[32:35], off offset:512
	global_store_dwordx4 v[144:145], v[24:27], off
	v_pk_fma_f32 v[18:19], v[18:19], v[128:129], v[86:87]
	v_pk_fma_f32 v[16:17], v[16:17], v[126:127], v[84:85]
	v_pk_fma_f32 v[26:27], v[30:31], v[132:133], v[90:91]
	v_pk_fma_f32 v[24:25], v[28:29], v[130:131], v[88:89]
	global_store_dwordx4 v[144:145], v[8:11], off offset:576
	global_store_dwordx4 v[144:145], v[24:27], off offset:64
	global_store_dwordx4 v[144:145], v[16:19], off offset:512
	v_pk_fma_f32 v[10:11], v[22:23], v[136:137], v[82:83]
	v_pk_fma_f32 v[8:9], v[20:21], v[134:135], v[80:81]
	global_store_dwordx4 v[142:143], v[8:11], off
	v_pk_fma_f32 v[6:7], v[6:7], v[128:129], v[70:71]
	v_pk_fma_f32 v[4:5], v[4:5], v[126:127], v[68:69]
	v_pk_fma_f32 v[10:11], v[14:15], v[132:133], v[74:75]
	v_pk_fma_f32 v[8:9], v[12:13], v[130:131], v[72:73]
	v_pk_fma_f32 v[2:3], v[2:3], v[120:121], v[66:67]
	v_pk_fma_f32 v[0:1], v[0:1], v[118:119], v[64:65]
	global_store_dwordx4 v[142:143], v[8:11], off offset:64
	global_store_dwordx4 v[142:143], v[4:7], off offset:512
	global_store_dwordx4 v[142:143], v[0:3], off offset:576
	s_cbranch_vccz .LBB0_44
	s_waitcnt vmcnt(0)
	v_readlane_b32 s66, v255, 34
	v_readlane_b32 s64, v255, 38
	s_cmpk_gt_u32 s56, 0xff
	v_readlane_b32 s67, v255, 35
	v_readlane_b32 s65, v255, 39
	s_cbranch_scc1 .LBB0_51
	s_barrier

; #define PG8_STAGE(bufoff, gbase, voff) do { _Pragma("unroll") for (int _i = 0; _i < 2; ++_i) \
;         __builtin_amdgcn_global_load_lds((const unsigned*)((const char*)(gbase) + (voff)[_i]), (PG8_LAS unsigned*)(lds + (bufoff) + ldsw + _i * 8192), 16, 0, 0); } while (0)
; #define PG8_LDA(dst, b, h) do { _Pragma("unroll") for (int m = 0; m < 4; ++m) _Pragma("unroll") for (int k = 0; k < 2; ++k) dst[m][k] = *(const PG8_LAS bf16x8*)(lds + PG8_SA(b, h) + aoff + m * 2048 + k * 1024); } while (0)
; #define PG8_LDB(dst, b, h) do { _Pragma("unroll") for (int n = 0; n < 2; ++n) _Pragma("unroll") for (int k = 0; k < 2; ++k) dst[n][k] = *(const PG8_LAS bf16x8*)(lds + PG8_SB(b, h) + boff + n * 2048 + k * 1024); } while (0)
; #define PG8_MMA(ai, bj, At, Bt) do { __builtin_amdgcn_s_setprio(1); _Pragma("unroll") for (int m = 0; m < 4; ++m) _Pragma("unroll") for (int n = 0; n < 2; ++n) _Pragma("unroll") for (int k = 0; k < 2; ++k) \
;         acc[ai][bj][m][n] = __builtin_amdgcn_mfma_f32_16x16x32_bf16(Bt[n][k], At[m][k], acc[ai][bj][m][n], 0, 0, 0); __builtin_amdgcn_s_setprio(0); } while (0)
; #define PG8_WAIT_L(n) asm volatile("s_waitcnt lgkmcnt(" #n ")" ::: "memory")
; #define PG8_BAR __builtin_amdgcn_s_barrier()
; #define PG8_SCHED __builtin_amdgcn_sched_barrier(0)
; template <class Epi, class Sched>
; __device__ __forceinline__ void gemm_phase(PG8_LAS unsigned char* lds, const Gemm g, const Sched& S, const Epi& E) {
;     ...
;             PG8_LDB(B0, 0, 0); PG8_SCHED; PG8_LDA(At, 0, 0); PG8_STAGE(PG8_SA(1, 1), a1 + hstep, voffA);
;             PG8_WAIT_L(8); PG8_BAR; PG8_WAIT_L(0); PG8_MMA(0, 0, At, B0); PG8_BAR; PG8_SCHED;
;             PG8_LDB(B1, 0, 1); PG8_STAGE(PG8_SB(0, 0), b2, voffB);
;             PG8_BAR; PG8_WAIT_L(0); PG8_MMA(0, 1, At, B1); PG8_BAR;
;             PG8_LDA(At, 0, 1); PG8_STAGE(PG8_SA(0, 0), a2, voffA);
;             PG8_BAR; PG8_WAIT_L(0); PG8_MMA(1, 0, At, B0); PG8_BAR; PG8_SCHED;
.Lgp_2972:
.LBB0_65:
	s_add_u32 s42, s46, 0xfffc0080
	s_addc_u32 s43, s47, -1
	s_add_i32 s71, 0, 0x10000
	v_add_u32_e32 v156, s71, v141
	ds_read_b128 v[144:147], v156
	ds_read_b128 v[148:151], v156 offset:1024
	ds_read_b128 v[152:155], v156 offset:2048
	ds_read_b128 v[156:159], v156 offset:3072
	s_cmp_eq_u32 s70, 12
	s_cselect_b32 s51, s31, s43
	s_cselect_b32 s50, s66, s42
	s_cselect_b32 s49, s1, s69
	s_cselect_b32 s48, s67, s68
	v_lshl_add_u64 v[192:193], s[46:47], 0, v[136:137]
	s_add_i32 m0, s45, 0xc000
	ds_read_b128 v[160:163], v143
	ds_read_b128 v[164:167], v143 offset:1024
	ds_read_b128 v[168:171], v143 offset:2048
	ds_read_b128 v[172:175], v143 offset:3072
	ds_read_b128 v[176:179], v143 offset:4096
	ds_read_b128 v[180:183], v143 offset:5120
	ds_read_b128 v[184:187], v143 offset:6144
	ds_read_b128 v[188:191], v143 offset:7168
	global_load_lds_dwordx4 v[192:193], off
	v_lshl_add_u64 v[192:193], s[46:47], 0, v[138:139]
	s_add_i32 m0, s45, 0xe000
	s_nop 0
	global_load_lds_dwordx4 v[192:193], off
	s_waitcnt lgkmcnt(8)
	s_barrier
	s_waitcnt lgkmcnt(0)
	v_mfma_f32_16x16x32_bf16 v[126:129], v[144:147], v[160:163], v[126:129]
	v_mfma_f32_16x16x32_bf16 v[122:125], v[152:155], v[160:163], v[122:125]
	v_mfma_f32_16x16x32_bf16 v[110:113], v[144:147], v[168:171], v[110:113]
	v_mfma_f32_16x16x32_bf16 v[106:109], v[152:155], v[168:171], v[106:109]
	v_mfma_f32_16x16x32_bf16 v[92:95], v[144:147], v[176:179], v[92:95]
	v_mfma_f32_16x16x32_bf16 v[88:91], v[152:155], v[176:179], v[88:91]
	v_mfma_f32_16x16x32_bf16 v[76:79], v[144:147], v[184:187], v[76:79]
	v_mfma_f32_16x16x32_bf16 v[72:75], v[152:155], v[184:187], v[72:75]
	v_mfma_f32_16x16x32_bf16 v[126:129], v[148:151], v[164:167], v[126:129]
	v_mfma_f32_16x16x32_bf16 v[122:125], v[156:159], v[164:167], v[122:125]
	v_mfma_f32_16x16x32_bf16 v[110:113], v[148:151], v[172:175], v[110:113]
	v_mfma_f32_16x16x32_bf16 v[106:109], v[156:159], v[172:175], v[106:109]
	v_mfma_f32_16x16x32_bf16 v[92:95], v[148:151], v[180:183], v[92:95]
	v_mfma_f32_16x16x32_bf16 v[88:91], v[156:159], v[180:183], v[88:91]
	v_mfma_f32_16x16x32_bf16 v[76:79], v[148:151], v[188:191], v[76:79]
	v_mfma_f32_16x16x32_bf16 v[72:75], v[156:159], v[188:191], v[72:75]
	s_barrier
	s_add_i32 s42, 0, 0x14000
	v_add_u32_e32 v204, s42, v141
	s_add_i32 s43, s71, s56
	ds_read_b128 v[192:195], v204
	ds_read_b128 v[196:199], v204 offset:1024
	ds_read_b128 v[200:203], v204 offset:2048
	ds_read_b128 v[208:211], v204 offset:3072
	v_lshl_add_u64 v[204:205], s[48:49], 0, v[96:97]
	s_mov_b32 m0, s43
	v_lshl_add_u64 v[212:213], s[48:49], 0, v[130:131]
	global_load_lds_dwordx4 v[204:205], off
	s_add_i32 m0, s43, 0x2000
	s_nop 0
	global_load_lds_dwordx4 v[212:213], off
	s_barrier
	s_waitcnt lgkmcnt(0)
	v_mfma_f32_16x16x32_bf16 v[118:121], v[192:195], v[160:163], v[118:121]
	v_mfma_f32_16x16x32_bf16 v[114:117], v[200:203], v[160:163], v[114:117]
	v_mfma_f32_16x16x32_bf16 v[102:105], v[192:195], v[168:171], v[102:105]
	v_mfma_f32_16x16x32_bf16 v[98:101], v[200:203], v[168:171], v[98:101]
	v_mfma_f32_16x16x32_bf16 v[84:87], v[192:195], v[176:179], v[84:87]
	v_mfma_f32_16x16x32_bf16 v[80:83], v[200:203], v[176:179], v[80:83]
	v_mfma_f32_16x16x32_bf16 v[68:71], v[192:195], v[184:187], v[68:71]
	v_mfma_f32_16x16x32_bf16 v[64:67], v[200:203], v[184:187], v[64:67]
	v_mfma_f32_16x16x32_bf16 v[118:121], v[196:199], v[164:167], v[118:121]
	v_mfma_f32_16x16x32_bf16 v[114:117], v[208:211], v[164:167], v[114:117]
	v_mfma_f32_16x16x32_bf16 v[102:105], v[196:199], v[172:175], v[102:105]
	v_mfma_f32_16x16x32_bf16 v[98:101], v[208:211], v[172:175], v[98:101]
	v_mfma_f32_16x16x32_bf16 v[84:87], v[196:199], v[180:183], v[84:87]
	v_mfma_f32_16x16x32_bf16 v[80:83], v[208:211], v[180:183], v[80:83]
	v_mfma_f32_16x16x32_bf16 v[68:71], v[196:199], v[188:191], v[68:71]
	v_mfma_f32_16x16x32_bf16 v[64:67], v[208:211], v[188:191], v[64:67]
	s_mov_b32 m0, s45
	v_lshl_add_u64 v[214:215], s[50:51], 0, v[134:135]
	s_barrier
	ds_read_b128 v[160:163], v143 offset:16384
	ds_read_b128 v[164:167], v143 offset:17408
	ds_read_b128 v[168:171], v143 offset:18432
	ds_read_b128 v[172:175], v143 offset:19456
	ds_read_b128 v[176:179], v143 offset:20480
	ds_read_b128 v[180:183], v143 offset:21504
	ds_read_b128 v[184:187], v143 offset:22528
	ds_read_b128 v[188:191], v143 offset:23552
	global_load_lds_dwordx4 v[214:215], off
	v_lshl_add_u64 v[216:217], s[50:51], 0, v[132:133]
	s_mov_b32 m0, s59
	s_nop 0
	global_load_lds_dwordx4 v[216:217], off
	s_barrier
	s_waitcnt lgkmcnt(0)
	v_mfma_f32_16x16x32_bf16 v[60:63], v[144:147], v[160:163], v[60:63]
	v_mfma_f32_16x16x32_bf16 v[56:59], v[152:155], v[160:163], v[56:59]
	v_mfma_f32_16x16x32_bf16 v[44:47], v[144:147], v[168:171], v[44:47]
	v_mfma_f32_16x16x32_bf16 v[40:43], v[152:155], v[168:171], v[40:43]
	v_mfma_f32_16x16x32_bf16 v[28:31], v[144:147], v[176:179], v[28:31]
	v_mfma_f32_16x16x32_bf16 v[24:27], v[152:155], v[176:179], v[24:27]
	v_mfma_f32_16x16x32_bf16 v[12:15], v[144:147], v[184:187], v[12:15]
	v_mfma_f32_16x16x32_bf16 v[8:11], v[152:155], v[184:187], v[8:11]
	v_mfma_f32_16x16x32_bf16 v[60:63], v[148:151], v[164:167], v[60:63]
	v_mfma_f32_16x16x32_bf16 v[56:59], v[156:159], v[164:167], v[56:59]
	v_mfma_f32_16x16x32_bf16 v[44:47], v[148:151], v[172:175], v[44:47]
	v_mfma_f32_16x16x32_bf16 v[40:43], v[156:159], v[172:175], v[40:43]
	v_mfma_f32_16x16x32_bf16 v[28:31], v[148:151], v[180:183], v[28:31]
	v_mfma_f32_16x16x32_bf16 v[24:27], v[156:159], v[180:183], v[24:27]
	v_mfma_f32_16x16x32_bf16 v[12:15], v[148:151], v[188:191], v[12:15]
	v_mfma_f32_16x16x32_bf16 v[8:11], v[156:159], v[188:191], v[8:11]
	s_barrier
; #define PG8_STAGE(bufoff, gbase, voff) do { _Pragma("unroll") for (int _i = 0; _i < 2; ++_i) \
;         __builtin_amdgcn_global_load_lds((const unsigned*)((const char*)(gbase) + (voff)[_i]), (PG8_LAS unsigned*)(lds + (bufoff) + ldsw + _i * 8192), 16, 0, 0); } while (0)
; #define PG8_LDA(dst, b, h) do { _Pragma("unroll") for (int m = 0; m < 4; ++m) _Pragma("unroll") for (int k = 0; k < 2; ++k) dst[m][k] = *(const PG8_LAS bf16x8*)(lds + PG8_SA(b, h) + aoff + m * 2048 + k * 1024); } while (0)
; #define PG8_LDB(dst, b, h) do { _Pragma("unroll") for (int n = 0; n < 2; ++n) _Pragma("unroll") for (int k = 0; k < 2; ++k) dst[n][k] = *(const PG8_LAS bf16x8*)(lds + PG8_SB(b, h) + boff + n * 2048 + k * 1024); } while (0)
; #define PG8_MMA(ai, bj, At, Bt) do { __builtin_amdgcn_s_setprio(1); _Pragma("unroll") for (int m = 0; m < 4; ++m) _Pragma("unroll") for (int n = 0; n < 2; ++n) _Pragma("unroll") for (int k = 0; k < 2; ++k) \
;         acc[ai][bj][m][n] = __builtin_amdgcn_mfma_f32_16x16x32_bf16(Bt[n][k], At[m][k], acc[ai][bj][m][n], 0, 0, 0); __builtin_amdgcn_s_setprio(0); } while (0)
; #define PG8_WAIT_V(n) asm volatile("s_waitcnt vmcnt(" #n ")" ::: "memory")
; #define PG8_WAIT_L(n) asm volatile("s_waitcnt lgkmcnt(" #n ")" ::: "memory")
; #define PG8_BAR __builtin_amdgcn_s_barrier()
; #define PG8_SCHED __builtin_amdgcn_sched_barrier(0)
; template <class Epi, class Sched>
; __device__ __forceinline__ void gemm_phase(PG8_LAS unsigned char* lds, const Gemm g, const Sched& S, const Epi& E) {
;     ...
;             PG8_STAGE(PG8_SB(0, 1), b2 + hstep, voffB);
;             PG8_WAIT_V(6); PG8_BAR; PG8_MMA(1, 1, At, B1); PG8_BAR;
;             PG8_LDB(B0, 1, 0); PG8_SCHED; PG8_LDA(At, 1, 0); PG8_STAGE(PG8_SA(0, 1), a2 + hstep, voffA);
;             PG8_WAIT_L(8); PG8_BAR; PG8_WAIT_L(0); PG8_MMA(0, 0, At, B0); PG8_BAR; PG8_SCHED;
;             PG8_LDB(B1, 1, 1); PG8_STAGE(PG8_SB(1, 0), b3, voffB);
;             PG8_BAR; PG8_WAIT_L(0); PG8_MMA(0, 1, At, B1); PG8_BAR;
	s_add_u32 vcc_lo, s48, 0x40000
	s_addc_u32 vcc_hi, s49, 0
	s_add_i32 s42, s42, s56
	v_lshl_add_u64 v[144:145], vcc, 0, v[96:97]
	s_mov_b32 m0, s42
	s_nop 0
	global_load_lds_dwordx4 v[144:145], off
	v_lshl_add_u64 v[144:145], vcc, 0, v[130:131]
	s_add_i32 m0, s42, 0x2000
	s_nop 0
	global_load_lds_dwordx4 v[144:145], off
	s_waitcnt vmcnt(6)
	s_barrier
	v_mfma_f32_16x16x32_bf16 v[52:55], v[192:195], v[160:163], v[52:55]
	v_mfma_f32_16x16x32_bf16 v[48:51], v[200:203], v[160:163], v[48:51]
	v_mfma_f32_16x16x32_bf16 v[36:39], v[192:195], v[168:171], v[36:39]
	v_mfma_f32_16x16x32_bf16 v[32:35], v[200:203], v[168:171], v[32:35]
	v_mfma_f32_16x16x32_bf16 v[20:23], v[192:195], v[176:179], v[20:23]
	v_mfma_f32_16x16x32_bf16 v[16:19], v[200:203], v[176:179], v[16:19]
	v_mfma_f32_16x16x32_bf16 v[4:7], v[192:195], v[184:187], v[4:7]
	v_mfma_f32_16x16x32_bf16 v[0:3], v[200:203], v[184:187], v[0:3]
	v_mfma_f32_16x16x32_bf16 v[52:55], v[196:199], v[164:167], v[52:55]
	v_mfma_f32_16x16x32_bf16 v[48:51], v[208:211], v[164:167], v[48:51]
	v_mfma_f32_16x16x32_bf16 v[36:39], v[196:199], v[172:175], v[36:39]
	v_mfma_f32_16x16x32_bf16 v[32:35], v[208:211], v[172:175], v[32:35]
	v_mfma_f32_16x16x32_bf16 v[20:23], v[196:199], v[180:183], v[20:23]
	v_mfma_f32_16x16x32_bf16 v[16:19], v[208:211], v[180:183], v[16:19]
	v_mfma_f32_16x16x32_bf16 v[4:7], v[196:199], v[188:191], v[4:7]
	v_mfma_f32_16x16x32_bf16 v[0:3], v[208:211], v[188:191], v[0:3]
	s_add_i32 s42, 0, 0x18000
	v_add_u32_e32 v156, s42, v141
	s_barrier
	ds_read_b128 v[144:147], v156
	ds_read_b128 v[148:151], v156 offset:1024
	ds_read_b128 v[152:155], v156 offset:2048
	ds_read_b128 v[156:159], v156 offset:3072
	s_add_u32 s50, s50, 0x40000
	s_addc_u32 s51, s51, 0
	s_mov_b32 m0, s60
	v_lshl_add_u64 v[192:193], s[50:51], 0, v[134:135]
	ds_read_b128 v[160:163], v143 offset:32768
	ds_read_b128 v[164:167], v143 offset:33792
	ds_read_b128 v[168:171], v143 offset:34816
	ds_read_b128 v[172:175], v143 offset:35840
	ds_read_b128 v[176:179], v143 offset:36864
	ds_read_b128 v[180:183], v143 offset:37888
	ds_read_b128 v[184:187], v143 offset:38912
	ds_read_b128 v[188:191], v143 offset:39936
	global_load_lds_dwordx4 v[192:193], off
	v_lshl_add_u64 v[192:193], s[50:51], 0, v[132:133]
	s_mov_b32 m0, s61
	s_nop 0
	global_load_lds_dwordx4 v[192:193], off
	s_waitcnt lgkmcnt(8)
	s_barrier
	s_waitcnt lgkmcnt(0)
	v_mfma_f32_16x16x32_bf16 v[126:129], v[144:147], v[160:163], v[126:129]
	v_mfma_f32_16x16x32_bf16 v[122:125], v[152:155], v[160:163], v[122:125]
	v_mfma_f32_16x16x32_bf16 v[110:113], v[144:147], v[168:171], v[110:113]
	v_mfma_f32_16x16x32_bf16 v[106:109], v[152:155], v[168:171], v[106:109]
	v_mfma_f32_16x16x32_bf16 v[92:95], v[144:147], v[176:179], v[92:95]
	v_mfma_f32_16x16x32_bf16 v[88:91], v[152:155], v[176:179], v[88:91]
	v_mfma_f32_16x16x32_bf16 v[76:79], v[144:147], v[184:187], v[76:79]
	v_mfma_f32_16x16x32_bf16 v[72:75], v[152:155], v[184:187], v[72:75]
	v_mfma_f32_16x16x32_bf16 v[126:129], v[148:151], v[164:167], v[126:129]
	v_mfma_f32_16x16x32_bf16 v[122:125], v[156:159], v[164:167], v[122:125]
	v_mfma_f32_16x16x32_bf16 v[110:113], v[148:151], v[172:175], v[110:113]
	v_mfma_f32_16x16x32_bf16 v[106:109], v[156:159], v[172:175], v[106:109]
	v_mfma_f32_16x16x32_bf16 v[92:95], v[148:151], v[180:183], v[92:95]
	v_mfma_f32_16x16x32_bf16 v[88:91], v[156:159], v[180:183], v[88:91]
	v_mfma_f32_16x16x32_bf16 v[76:79], v[148:151], v[188:191], v[76:79]
	v_mfma_f32_16x16x32_bf16 v[72:75], v[156:159], v[188:191], v[72:75]
	s_barrier
	s_add_i32 s43, 0, 0x1c000
	s_add_i32 s42, s42, s56
	v_add_u32_e32 v208, s43, v141
	v_lshl_add_u64 v[204:205], v[204:205], 0, s[2:3]
	s_mov_b32 m0, s42
	ds_read_b128 v[192:195], v208
	ds_read_b128 v[196:199], v208 offset:1024
	ds_read_b128 v[200:203], v208 offset:2048
	ds_read_b128 v[208:211], v208 offset:3072
	global_load_lds_dwordx4 v[204:205], off
	v_lshl_add_u64 v[204:205], v[212:213], 0, s[2:3]
	s_add_i32 m0, s42, 0x2000
	s_nop 0
	global_load_lds_dwordx4 v[204:205], off
	s_barrier
	s_waitcnt lgkmcnt(0)
	v_mfma_f32_16x16x32_bf16 v[118:121], v[192:195], v[160:163], v[118:121]
	v_mfma_f32_16x16x32_bf16 v[114:117], v[200:203], v[160:163], v[114:117]
	v_mfma_f32_16x16x32_bf16 v[102:105], v[192:195], v[168:171], v[102:105]
	v_mfma_f32_16x16x32_bf16 v[98:101], v[200:203], v[168:171], v[98:101]
	v_mfma_f32_16x16x32_bf16 v[84:87], v[192:195], v[176:179], v[84:87]
	v_mfma_f32_16x16x32_bf16 v[80:83], v[200:203], v[176:179], v[80:83]
	v_mfma_f32_16x16x32_bf16 v[68:71], v[192:195], v[184:187], v[68:71]
	v_mfma_f32_16x16x32_bf16 v[64:67], v[200:203], v[184:187], v[64:67]
	v_mfma_f32_16x16x32_bf16 v[118:121], v[196:199], v[164:167], v[118:121]
	v_mfma_f32_16x16x32_bf16 v[114:117], v[208:211], v[164:167], v[114:117]
	v_mfma_f32_16x16x32_bf16 v[102:105], v[196:199], v[172:175], v[102:105]
	v_mfma_f32_16x16x32_bf16 v[98:101], v[208:211], v[172:175], v[98:101]
	v_mfma_f32_16x16x32_bf16 v[84:87], v[196:199], v[180:183], v[84:87]
	v_mfma_f32_16x16x32_bf16 v[80:83], v[208:211], v[180:183], v[80:83]
	v_mfma_f32_16x16x32_bf16 v[68:71], v[196:199], v[188:191], v[68:71]
	v_mfma_f32_16x16x32_bf16 v[64:67], v[208:211], v[188:191], v[64:67]
	s_mov_b32 m0, s62
	v_lshl_add_u64 v[204:205], v[214:215], 0, s[2:3]
	s_barrier
	ds_read_b128 v[160:163], v143 offset:49152
	ds_read_b128 v[164:167], v143 offset:50176
	ds_read_b128 v[168:171], v143 offset:51200
	ds_read_b128 v[172:175], v143 offset:52224
	ds_read_b128 v[176:179], v143 offset:53248
	ds_read_b128 v[180:183], v143 offset:54272
	ds_read_b128 v[184:187], v143 offset:55296
	ds_read_b128 v[188:191], v143 offset:56320
	global_load_lds_dwordx4 v[204:205], off
	v_lshl_add_u64 v[204:205], v[216:217], 0, s[2:3]
	s_mov_b32 m0, s63
	s_nop 0
	global_load_lds_dwordx4 v[204:205], off
	s_barrier
; #define PG8_STAGE(bufoff, gbase, voff) do { _Pragma("unroll") for (int _i = 0; _i < 2; ++_i) \
;         __builtin_amdgcn_global_load_lds((const unsigned*)((const char*)(gbase) + (voff)[_i]), (PG8_LAS unsigned*)(lds + (bufoff) + ldsw + _i * 8192), 16, 0, 0); } while (0)
; #define PG8_LDA(dst, b, h) do { _Pragma("unroll") for (int m = 0; m < 4; ++m) _Pragma("unroll") for (int k = 0; k < 2; ++k) dst[m][k] = *(const PG8_LAS bf16x8*)(lds + PG8_SA(b, h) + aoff + m * 2048 + k * 1024); } while (0)
; #define PG8_MMA(ai, bj, At, Bt) do { __builtin_amdgcn_s_setprio(1); _Pragma("unroll") for (int m = 0; m < 4; ++m) _Pragma("unroll") for (int n = 0; n < 2; ++n) _Pragma("unroll") for (int k = 0; k < 2; ++k) \
;         acc[ai][bj][m][n] = __builtin_amdgcn_mfma_f32_16x16x32_bf16(Bt[n][k], At[m][k], acc[ai][bj][m][n], 0, 0, 0); __builtin_amdgcn_s_setprio(0); } while (0)
; #define PG8_WAIT_V(n) asm volatile("s_waitcnt vmcnt(" #n ")" ::: "memory")
; #define PG8_WAIT_L(n) asm volatile("s_waitcnt lgkmcnt(" #n ")" ::: "memory")
; template <class Epi, class Sched>
; __device__ __forceinline__ void gemm_phase(PG8_LAS unsigned char* lds, const Gemm g, const Sched& S, const Epi& E) {
;     ...
;             PG8_LDA(At, 1, 1); PG8_STAGE(PG8_SA(1, 0), a3, voffA);
;             PG8_BAR; PG8_WAIT_L(0); PG8_MMA(1, 0, At, B0); PG8_BAR; PG8_SCHED;
;             PG8_STAGE(PG8_SB(1, 1), b3 + hstep, voffB);
;             PG8_WAIT_V(6); PG8_BAR; PG8_MMA(1, 1, At, B1); PG8_BAR;
;         }
;   DEV void operator()(const f32x4 (&acc)[2][2][4][2], const pg8::Unit& u, int wr, int wc, int fr, int fq) const {
;     const int row0 = u.pm * 256 + wr * 64 + fr, col0 = u.pn * 256 + wc * 32 + 8 * fq;
; #pragma unroll
;     for (int ai = 0; ai < 2; ++ai)
; #pragma unroll
;       for (int m = 0; m < 4; ++m) {
;         const int row = row0 + ai * 128 + m * 16;
; #pragma unroll
;         for (int bj = 0; bj < 2; ++bj) {
;           float v[8];
; #pragma unroll
;           for (int j = 0; j < 4; ++j) {
;             const float r0 = fmaxf(acc[ai][bj][m][0][j], 0.f), r1 = fmaxf(acc[ai][bj][m][1][j], 0.f);
;             v[j] = r0 * r0; v[4 + j] = r1 * r1;
;           }
;           u32x4 o;
;           o[0] = pk2(v[0], v[1]); o[1] = pk2(v[2], v[3]); o[2] = pk2(v[4], v[5]); o[3] = pk2(v[6], v[7]);
;           *(u32x4*)(HID + (size_t)row * 4096 + col0 + bj * 128) = o;
;         }
;       }
	s_waitcnt lgkmcnt(0)
	v_mfma_f32_16x16x32_bf16 v[60:63], v[144:147], v[160:163], v[60:63]
	v_mfma_f32_16x16x32_bf16 v[56:59], v[152:155], v[160:163], v[56:59]
	v_mfma_f32_16x16x32_bf16 v[44:47], v[144:147], v[168:171], v[44:47]
	v_mfma_f32_16x16x32_bf16 v[40:43], v[152:155], v[168:171], v[40:43]
	v_mfma_f32_16x16x32_bf16 v[28:31], v[144:147], v[176:179], v[28:31]
	v_mfma_f32_16x16x32_bf16 v[24:27], v[152:155], v[176:179], v[24:27]
	v_mfma_f32_16x16x32_bf16 v[12:15], v[144:147], v[184:187], v[12:15]
	v_mfma_f32_16x16x32_bf16 v[8:11], v[152:155], v[184:187], v[8:11]
	v_mfma_f32_16x16x32_bf16 v[60:63], v[148:151], v[164:167], v[60:63]
	v_mfma_f32_16x16x32_bf16 v[56:59], v[156:159], v[164:167], v[56:59]
	v_mfma_f32_16x16x32_bf16 v[44:47], v[148:151], v[172:175], v[44:47]
	v_mfma_f32_16x16x32_bf16 v[40:43], v[156:159], v[172:175], v[40:43]
	v_mfma_f32_16x16x32_bf16 v[28:31], v[148:151], v[180:183], v[28:31]
	v_mfma_f32_16x16x32_bf16 v[24:27], v[156:159], v[180:183], v[24:27]
	v_mfma_f32_16x16x32_bf16 v[12:15], v[148:151], v[188:191], v[12:15]
	v_mfma_f32_16x16x32_bf16 v[8:11], v[156:159], v[188:191], v[8:11]
	s_barrier
	s_add_u32 s48, s48, 0x40080
	s_addc_u32 s49, s49, 0
	s_add_i32 s42, s43, s56
	v_lshl_add_u64 v[144:145], s[48:49], 0, v[96:97]
	s_mov_b32 m0, s42
	s_nop 0
	global_load_lds_dwordx4 v[144:145], off
	v_lshl_add_u64 v[144:145], s[48:49], 0, v[130:131]
	s_add_i32 m0, s42, 0x2000
	s_nop 0
	global_load_lds_dwordx4 v[144:145], off
	s_waitcnt vmcnt(6)
	s_barrier
	v_mfma_f32_16x16x32_bf16 v[52:55], v[192:195], v[160:163], v[52:55]
	v_mfma_f32_16x16x32_bf16 v[48:51], v[200:203], v[160:163], v[48:51]
	v_mfma_f32_16x16x32_bf16 v[36:39], v[192:195], v[168:171], v[36:39]
	v_mfma_f32_16x16x32_bf16 v[32:35], v[200:203], v[168:171], v[32:35]
	v_mfma_f32_16x16x32_bf16 v[20:23], v[192:195], v[176:179], v[20:23]
	v_mfma_f32_16x16x32_bf16 v[16:19], v[200:203], v[176:179], v[16:19]
	v_mfma_f32_16x16x32_bf16 v[4:7], v[192:195], v[184:187], v[4:7]
	v_mfma_f32_16x16x32_bf16 v[0:3], v[200:203], v[184:187], v[0:3]
	v_mfma_f32_16x16x32_bf16 v[52:55], v[196:199], v[164:167], v[52:55]
	v_mfma_f32_16x16x32_bf16 v[48:51], v[208:211], v[164:167], v[48:51]
	v_mfma_f32_16x16x32_bf16 v[36:39], v[196:199], v[172:175], v[36:39]
	v_mfma_f32_16x16x32_bf16 v[32:35], v[208:211], v[172:175], v[32:35]
	v_mfma_f32_16x16x32_bf16 v[20:23], v[196:199], v[180:183], v[20:23]
	v_mfma_f32_16x16x32_bf16 v[16:19], v[208:211], v[180:183], v[16:19]
	v_mfma_f32_16x16x32_bf16 v[4:7], v[196:199], v[188:191], v[4:7]
	v_mfma_f32_16x16x32_bf16 v[0:3], v[208:211], v[188:191], v[0:3]
	s_add_i32 s70, s70, 2
	s_add_u32 s46, s46, 0x100
	s_addc_u32 s47, s47, 0
	s_add_u32 s68, s68, 0x100
	s_addc_u32 s69, s69, 0
	s_cmp_gt_u32 s70, 13
	s_barrier
	s_cbranch_scc0 .LBB0_65
	v_lshl_add_u32 v144, s44, 8, v140
	v_max_f32_e32 v126, v126, v126
	v_max_f32_e32 v122, v122, v122
	v_max_f32_e32 v127, v127, v127
	v_max_f32_e32 v123, v123, v123
	v_max_f32_e32 v128, v128, v128
	v_max_f32_e32 v129, v129, v129
	v_lshl_or_b32 v146, s65, 8, v142
	v_ashrrev_i32_e32 v145, 31, v144
	v_max_f32_e32 v126, 0, v126
	v_max_f32_e32 v122, 0, v122
	v_max_f32_e32 v127, 0, v127
	v_max_f32_e32 v123, 0, v123
	v_max_f32_e32 v128, 0, v128
	v_max_f32_e32 v124, v124, v124
	v_max_f32_e32 v129, 0, v129
	v_max_f32_e32 v125, v125, v125
	v_readlane_b32 s42, v251, 49
	v_ashrrev_i32_e32 v147, 31, v146
	v_lshlrev_b64 v[148:149], 13, v[144:145]
	v_pk_mul_f32 v[126:127], v[126:127], v[126:127]
	v_pk_mul_f32 v[122:123], v[122:123], v[122:123]
	v_max_f32_e32 v124, 0, v124
	v_max_f32_e32 v125, 0, v125
	v_pk_mul_f32 v[128:129], v[128:129], v[128:129]
	v_readlane_b32 s43, v251, 50
	v_pk_mul_f32 v[150:151], v[124:125], v[124:125]
	v_cvt_pk_bf16_f32 v124, v126, v127
	v_cvt_pk_bf16_f32 v125, v128, v129
	v_cvt_pk_bf16_f32 v126, v122, v123
	v_lshl_add_u64 v[122:123], s[42:43], 0, v[148:149]
	v_lshlrev_b64 v[128:129], 1, v[146:147]
	v_max_f32_e32 v114, v114, v114
	v_max_f32_e32 v115, v115, v115
	v_cvt_pk_bf16_f32 v127, v150, v151
	v_lshl_add_u64 v[122:123], v[122:123], 0, v[128:129]
	v_max_f32_e32 v114, 0, v114
	v_max_f32_e32 v115, 0, v115
	global_store_dwordx4 v[122:123], v[124:127], off
	v_max_f32_e32 v118, v118, v118
	v_max_f32_e32 v119, v119, v119
	v_pk_mul_f32 v[124:125], v[114:115], v[114:115]
	v_max_f32_e32 v115, v116, v116
	v_max_f32_e32 v114, v120, v120
	v_max_f32_e32 v116, 0, v115
	v_max_f32_e32 v115, v121, v121
	v_max_f32_e32 v117, v117, v117
	v_max_f32_e32 v118, 0, v118
	v_max_f32_e32 v119, 0, v119
	v_max_f32_e32 v114, 0, v114
	v_max_f32_e32 v115, 0, v115
	v_max_f32_e32 v117, 0, v117
	v_pk_mul_f32 v[118:119], v[118:119], v[118:119]
	v_pk_mul_f32 v[120:121], v[114:115], v[114:115]
	v_pk_mul_f32 v[126:127], v[116:117], v[116:117]
	v_max_f32_e32 v106, v106, v106
	v_max_f32_e32 v107, v107, v107
	v_cvt_pk_bf16_f32 v114, v118, v119
	v_cvt_pk_bf16_f32 v115, v120, v121
	v_cvt_pk_bf16_f32 v116, v124, v125
	v_cvt_pk_bf16_f32 v117, v126, v127
	v_max_f32_e32 v106, 0, v106
	v_max_f32_e32 v107, 0, v107
	global_store_dwordx4 v[122:123], v[114:117], off offset:256
	v_max_f32_e32 v110, v110, v110
	v_max_f32_e32 v111, v111, v111
	v_or_b32_e32 v114, 16, v144
	v_pk_mul_f32 v[116:117], v[106:107], v[106:107]
	v_max_f32_e32 v107, v108, v108
	v_ashrrev_i32_e32 v115, 31, v114
	v_max_f32_e32 v110, 0, v110
	v_max_f32_e32 v111, 0, v111
	v_max_f32_e32 v106, v112, v112
	v_max_f32_e32 v108, 0, v107
	v_max_f32_e32 v107, v113, v113
	v_max_f32_e32 v109, v109, v109
	v_lshlrev_b64 v[114:115], 13, v[114:115]
	v_pk_mul_f32 v[110:111], v[110:111], v[110:111]
	v_max_f32_e32 v106, 0, v106
	v_max_f32_e32 v107, 0, v107
	v_max_f32_e32 v109, 0, v109
	v_pk_mul_f32 v[112:113], v[106:107], v[106:107]
;   DEV void operator()(const f32x4 (&acc)[2][2][4][2], const pg8::Unit& u, int wr, int wc, int fr, int fq) const {
;     ...
; #pragma unroll
;     for (int ai = 0; ai < 2; ++ai)
; #pragma unroll
;       for (int m = 0; m < 4; ++m) {
;         const int row = row0 + ai * 128 + m * 16;
; #pragma unroll
;         for (int bj = 0; bj < 2; ++bj) {
;           float v[8];
; #pragma unroll
;           for (int j = 0; j < 4; ++j) {
;             const float r0 = fmaxf(acc[ai][bj][m][0][j], 0.f), r1 = fmaxf(acc[ai][bj][m][1][j], 0.f);
;             v[j] = r0 * r0; v[4 + j] = r1 * r1;
;           }
;           u32x4 o;
;           o[0] = pk2(v[0], v[1]); o[1] = pk2(v[2], v[3]); o[2] = pk2(v[4], v[5]); o[3] = pk2(v[6], v[7]);
;           *(u32x4*)(HID + (size_t)row * 4096 + col0 + bj * 128) = o;
	v_pk_mul_f32 v[118:119], v[108:109], v[108:109]
	v_cvt_pk_bf16_f32 v106, v110, v111
	v_lshl_add_u64 v[110:111], s[42:43], 0, v[114:115]
	v_max_f32_e32 v98, v98, v98
	v_max_f32_e32 v99, v99, v99
	v_cvt_pk_bf16_f32 v107, v112, v113
	v_cvt_pk_bf16_f32 v108, v116, v117
	v_cvt_pk_bf16_f32 v109, v118, v119
	v_lshl_add_u64 v[110:111], v[110:111], 0, v[128:129]
	v_max_f32_e32 v98, 0, v98
	v_max_f32_e32 v99, 0, v99
	global_store_dwordx4 v[110:111], v[106:109], off
	v_max_f32_e32 v102, v102, v102
	v_max_f32_e32 v103, v103, v103
	v_pk_mul_f32 v[106:107], v[98:99], v[98:99]
	v_max_f32_e32 v99, v100, v100
	v_max_f32_e32 v98, v104, v104
	v_max_f32_e32 v100, 0, v99
	v_max_f32_e32 v99, v105, v105
	v_max_f32_e32 v101, v101, v101
	v_max_f32_e32 v102, 0, v102
	v_max_f32_e32 v103, 0, v103
	v_max_f32_e32 v98, 0, v98
	v_max_f32_e32 v99, 0, v99
	v_max_f32_e32 v101, 0, v101
	v_pk_mul_f32 v[102:103], v[102:103], v[102:103]
	v_pk_mul_f32 v[104:105], v[98:99], v[98:99]
	v_pk_mul_f32 v[108:109], v[100:101], v[100:101]
	v_max_f32_e32 v88, v88, v88
	v_max_f32_e32 v89, v89, v89
	v_cvt_pk_bf16_f32 v98, v102, v103
	v_cvt_pk_bf16_f32 v99, v104, v105
	v_cvt_pk_bf16_f32 v100, v106, v107
	v_cvt_pk_bf16_f32 v101, v108, v109
	v_max_f32_e32 v88, 0, v88
	v_max_f32_e32 v89, 0, v89
	global_store_dwordx4 v[110:111], v[98:101], off offset:256
	v_max_f32_e32 v92, v92, v92
	v_max_f32_e32 v93, v93, v93
	v_or_b32_e32 v98, 32, v144
	v_pk_mul_f32 v[100:101], v[88:89], v[88:89]
	v_max_f32_e32 v89, v90, v90
	v_ashrrev_i32_e32 v99, 31, v98
	v_max_f32_e32 v92, 0, v92
	v_max_f32_e32 v93, 0, v93
	v_max_f32_e32 v88, v94, v94
	v_max_f32_e32 v90, 0, v89
	v_max_f32_e32 v89, v95, v95
	v_max_f32_e32 v91, v91, v91
	v_lshlrev_b64 v[98:99], 13, v[98:99]
	v_pk_mul_f32 v[92:93], v[92:93], v[92:93]
	v_max_f32_e32 v88, 0, v88
	v_max_f32_e32 v89, 0, v89
	v_max_f32_e32 v91, 0, v91
	v_pk_mul_f32 v[94:95], v[88:89], v[88:89]
	v_pk_mul_f32 v[102:103], v[90:91], v[90:91]
	v_cvt_pk_bf16_f32 v88, v92, v93
	v_lshl_add_u64 v[92:93], s[42:43], 0, v[98:99]
	v_max_f32_e32 v80, v80, v80
	v_max_f32_e32 v81, v81, v81
	v_cvt_pk_bf16_f32 v89, v94, v95
	v_cvt_pk_bf16_f32 v90, v100, v101
	v_cvt_pk_bf16_f32 v91, v102, v103
	v_lshl_add_u64 v[92:93], v[92:93], 0, v[128:129]
	v_max_f32_e32 v80, 0, v80
	v_max_f32_e32 v81, 0, v81
	global_store_dwordx4 v[92:93], v[88:91], off
	v_max_f32_e32 v84, v84, v84
	v_max_f32_e32 v85, v85, v85
	v_pk_mul_f32 v[88:89], v[80:81], v[80:81]
	v_max_f32_e32 v81, v82, v82
	v_max_f32_e32 v80, v86, v86
	v_max_f32_e32 v82, 0, v81
	v_max_f32_e32 v81, v87, v87
	v_max_f32_e32 v83, v83, v83
	v_max_f32_e32 v84, 0, v84
	v_max_f32_e32 v85, 0, v85
	v_max_f32_e32 v80, 0, v80
	v_max_f32_e32 v81, 0, v81
	v_max_f32_e32 v83, 0, v83
	v_pk_mul_f32 v[84:85], v[84:85], v[84:85]
	v_pk_mul_f32 v[86:87], v[80:81], v[80:81]
	v_pk_mul_f32 v[90:91], v[82:83], v[82:83]
	v_max_f32_e32 v72, v72, v72
	v_max_f32_e32 v73, v73, v73
	v_cvt_pk_bf16_f32 v80, v84, v85
	v_cvt_pk_bf16_f32 v81, v86, v87
	v_cvt_pk_bf16_f32 v82, v88, v89
	v_cvt_pk_bf16_f32 v83, v90, v91
	v_max_f32_e32 v72, 0, v72
	v_max_f32_e32 v73, 0, v73
	global_store_dwordx4 v[92:93], v[80:83], off offset:256
	v_max_f32_e32 v76, v76, v76
	v_max_f32_e32 v77, v77, v77
	v_or_b32_e32 v80, 48, v144
	v_pk_mul_f32 v[82:83], v[72:73], v[72:73]
	v_max_f32_e32 v73, v74, v74
	v_ashrrev_i32_e32 v81, 31, v80
	v_max_f32_e32 v76, 0, v76
	v_max_f32_e32 v77, 0, v77
	v_max_f32_e32 v72, v78, v78
	v_max_f32_e32 v74, 0, v73
	v_max_f32_e32 v73, v79, v79
	v_max_f32_e32 v75, v75, v75
	v_lshlrev_b64 v[80:81], 13, v[80:81]
	v_pk_mul_f32 v[76:77], v[76:77], v[76:77]
	v_max_f32_e32 v72, 0, v72
	v_max_f32_e32 v73, 0, v73
	v_max_f32_e32 v75, 0, v75
	v_pk_mul_f32 v[78:79], v[72:73], v[72:73]
	v_pk_mul_f32 v[84:85], v[74:75], v[74:75]
	v_cvt_pk_bf16_f32 v72, v76, v77
	v_lshl_add_u64 v[76:77], s[42:43], 0, v[80:81]
	v_max_f32_e32 v64, v64, v64
	v_max_f32_e32 v65, v65, v65
	v_cvt_pk_bf16_f32 v73, v78, v79
	v_cvt_pk_bf16_f32 v74, v82, v83
	v_cvt_pk_bf16_f32 v75, v84, v85
	v_lshl_add_u64 v[76:77], v[76:77], 0, v[128:129]
	v_max_f32_e32 v64, 0, v64
	v_max_f32_e32 v65, 0, v65
	global_store_dwordx4 v[76:77], v[72:75], off
	v_max_f32_e32 v68, v68, v68
	v_max_f32_e32 v69, v69, v69
	v_pk_mul_f32 v[72:73], v[64:65], v[64:65]
	v_max_f32_e32 v65, v66, v66
	v_max_f32_e32 v64, v70, v70
	v_max_f32_e32 v66, 0, v65
	v_max_f32_e32 v65, v71, v71
	v_max_f32_e32 v67, v67, v67
	v_max_f32_e32 v68, 0, v68
	v_max_f32_e32 v69, 0, v69
	v_max_f32_e32 v64, 0, v64
	v_max_f32_e32 v65, 0, v65
	v_max_f32_e32 v67, 0, v67
	v_pk_mul_f32 v[68:69], v[68:69], v[68:69]
	v_pk_mul_f32 v[70:71], v[64:65], v[64:65]
	v_pk_mul_f32 v[74:75], v[66:67], v[66:67]
	v_max_f32_e32 v56, v56, v56
	v_max_f32_e32 v57, v57, v57
	v_cvt_pk_bf16_f32 v64, v68, v69
	v_cvt_pk_bf16_f32 v65, v70, v71
	v_cvt_pk_bf16_f32 v66, v72, v73
	v_cvt_pk_bf16_f32 v67, v74, v75
	v_max_f32_e32 v56, 0, v56
	v_max_f32_e32 v57, 0, v57
	global_store_dwordx4 v[76:77], v[64:67], off offset:256
	v_max_f32_e32 v60, v60, v60
	v_max_f32_e32 v61, v61, v61
	v_pk_mul_f32 v[64:65], v[56:57], v[56:57]
	v_max_f32_e32 v57, v58, v58
	v_max_f32_e32 v56, v62, v62
	v_max_f32_e32 v58, 0, v57
	v_max_f32_e32 v57, v63, v63
	v_max_f32_e32 v56, 0, v56
	v_max_f32_e32 v57, 0, v57
	v_max_f32_e32 v59, v59, v59
	v_max_f32_e32 v60, 0, v60
	v_max_f32_e32 v61, 0, v61
	v_max_f32_e32 v59, 0, v59
	v_pk_mul_f32 v[62:63], v[56:57], v[56:57]
	s_mov_b32 s1, 0x100000
	v_pk_mul_f32 v[60:61], v[60:61], v[60:61]
	v_pk_mul_f32 v[66:67], v[58:59], v[58:59]
	v_cvt_pk_bf16_f32 v57, v62, v63
	v_add_co_u32_e32 v62, vcc, s1, v122
	v_max_f32_e32 v48, v48, v48
	v_max_f32_e32 v49, v49, v49
	v_cvt_pk_bf16_f32 v56, v60, v61
;   DEV void operator()(const f32x4 (&acc)[2][2][4][2], const pg8::Unit& u, int wr, int wc, int fr, int fq) const {
;     ...
; #pragma unroll
;     for (int ai = 0; ai < 2; ++ai)
; #pragma unroll
;       for (int m = 0; m < 4; ++m) {
;         const int row = row0 + ai * 128 + m * 16;
; #pragma unroll
;         for (int bj = 0; bj < 2; ++bj) {
;           float v[8];
; #pragma unroll
;           for (int j = 0; j < 4; ++j) {
;             const float r0 = fmaxf(acc[ai][bj][m][0][j], 0.f), r1 = fmaxf(acc[ai][bj][m][1][j], 0.f);
;             v[j] = r0 * r0; v[4 + j] = r1 * r1;
;           }
;           u32x4 o;
;           o[0] = pk2(v[0], v[1]); o[1] = pk2(v[2], v[3]); o[2] = pk2(v[4], v[5]); o[3] = pk2(v[6], v[7]);
;           *(u32x4*)(HID + (size_t)row * 4096 + col0 + bj * 128) = o;
;         }
;       }
	v_cvt_pk_bf16_f32 v58, v64, v65
	v_cvt_pk_bf16_f32 v59, v66, v67
	v_addc_co_u32_e32 v63, vcc, 0, v123, vcc
	v_max_f32_e32 v48, 0, v48
	v_max_f32_e32 v49, 0, v49
	global_store_dwordx4 v[62:63], v[56:59], off
	v_max_f32_e32 v52, v52, v52
	v_max_f32_e32 v53, v53, v53
	v_pk_mul_f32 v[56:57], v[48:49], v[48:49]
	v_max_f32_e32 v49, v50, v50
	v_max_f32_e32 v48, v54, v54
	v_max_f32_e32 v50, 0, v49
	v_max_f32_e32 v49, v55, v55
	v_max_f32_e32 v51, v51, v51
	v_max_f32_e32 v52, 0, v52
	v_max_f32_e32 v53, 0, v53
	v_max_f32_e32 v48, 0, v48
	v_max_f32_e32 v49, 0, v49
	v_max_f32_e32 v51, 0, v51
	s_mov_b64 s[46:47], 0x100000
	v_pk_mul_f32 v[52:53], v[52:53], v[52:53]
	v_pk_mul_f32 v[54:55], v[48:49], v[48:49]
	v_pk_mul_f32 v[58:59], v[50:51], v[50:51]
	v_max_f32_e32 v40, v40, v40
	v_max_f32_e32 v41, v41, v41
	v_lshl_add_u64 v[60:61], v[122:123], 0, s[46:47]
	v_cvt_pk_bf16_f32 v48, v52, v53
	v_cvt_pk_bf16_f32 v49, v54, v55
	v_cvt_pk_bf16_f32 v50, v56, v57
	v_cvt_pk_bf16_f32 v51, v58, v59
	v_max_f32_e32 v40, 0, v40
	v_max_f32_e32 v41, 0, v41
	global_store_dwordx4 v[60:61], v[48:51], off offset:256
	v_max_f32_e32 v44, v44, v44
	v_max_f32_e32 v45, v45, v45
	v_pk_mul_f32 v[48:49], v[40:41], v[40:41]
	v_max_f32_e32 v41, v42, v42
	v_max_f32_e32 v40, v46, v46
	v_max_f32_e32 v42, 0, v41
	v_max_f32_e32 v41, v47, v47
	v_max_f32_e32 v40, 0, v40
	v_max_f32_e32 v41, 0, v41
	v_max_f32_e32 v43, v43, v43
	v_max_f32_e32 v44, 0, v44
	v_max_f32_e32 v45, 0, v45
	v_max_f32_e32 v43, 0, v43
	v_pk_mul_f32 v[46:47], v[40:41], v[40:41]
	s_mov_b32 s1, 0x120000
	v_pk_mul_f32 v[44:45], v[44:45], v[44:45]
	v_pk_mul_f32 v[50:51], v[42:43], v[42:43]
	v_cvt_pk_bf16_f32 v41, v46, v47
	v_add_co_u32_e32 v46, vcc, s1, v122
	v_max_f32_e32 v32, v32, v32
	v_max_f32_e32 v33, v33, v33
	v_cvt_pk_bf16_f32 v40, v44, v45
	v_cvt_pk_bf16_f32 v42, v48, v49
	v_cvt_pk_bf16_f32 v43, v50, v51
	v_addc_co_u32_e32 v47, vcc, 0, v123, vcc
	v_max_f32_e32 v32, 0, v32
	v_max_f32_e32 v33, 0, v33
	global_store_dwordx4 v[46:47], v[40:43], off
	v_max_f32_e32 v36, v36, v36
	v_max_f32_e32 v37, v37, v37
	v_pk_mul_f32 v[40:41], v[32:33], v[32:33]
	v_max_f32_e32 v33, v34, v34
	v_max_f32_e32 v32, v38, v38
	v_max_f32_e32 v34, 0, v33
	v_max_f32_e32 v33, v39, v39
	v_max_f32_e32 v35, v35, v35
	v_max_f32_e32 v36, 0, v36
	v_max_f32_e32 v37, 0, v37
	v_max_f32_e32 v32, 0, v32
	v_max_f32_e32 v33, 0, v33
	v_max_f32_e32 v35, 0, v35
	s_mov_b64 s[46:47], 0x120000
	v_pk_mul_f32 v[36:37], v[36:37], v[36:37]
	v_pk_mul_f32 v[38:39], v[32:33], v[32:33]
	v_pk_mul_f32 v[42:43], v[34:35], v[34:35]
	v_max_f32_e32 v24, v24, v24
	v_max_f32_e32 v25, v25, v25
	v_lshl_add_u64 v[44:45], v[122:123], 0, s[46:47]
	v_cvt_pk_bf16_f32 v32, v36, v37
	v_cvt_pk_bf16_f32 v33, v38, v39
	v_cvt_pk_bf16_f32 v34, v40, v41
	v_cvt_pk_bf16_f32 v35, v42, v43
	v_max_f32_e32 v24, 0, v24
	v_max_f32_e32 v25, 0, v25
	global_store_dwordx4 v[44:45], v[32:35], off offset:256
	v_max_f32_e32 v28, v28, v28
	v_max_f32_e32 v29, v29, v29
	v_pk_mul_f32 v[32:33], v[24:25], v[24:25]
	v_max_f32_e32 v25, v26, v26
	v_max_f32_e32 v24, v30, v30
	v_max_f32_e32 v26, 0, v25
	v_max_f32_e32 v25, v31, v31
	v_max_f32_e32 v24, 0, v24
	v_max_f32_e32 v25, 0, v25
	v_max_f32_e32 v27, v27, v27
	v_max_f32_e32 v28, 0, v28
	v_max_f32_e32 v29, 0, v29
	v_max_f32_e32 v27, 0, v27
	v_pk_mul_f32 v[30:31], v[24:25], v[24:25]
	s_mov_b32 s1, 0x140000
	v_pk_mul_f32 v[28:29], v[28:29], v[28:29]
	v_pk_mul_f32 v[34:35], v[26:27], v[26:27]
	v_cvt_pk_bf16_f32 v25, v30, v31
	v_add_co_u32_e32 v30, vcc, s1, v122
	v_max_f32_e32 v16, v16, v16
	v_max_f32_e32 v17, v17, v17
	v_cvt_pk_bf16_f32 v24, v28, v29
	v_cvt_pk_bf16_f32 v26, v32, v33
	v_cvt_pk_bf16_f32 v27, v34, v35
	v_addc_co_u32_e32 v31, vcc, 0, v123, vcc
	v_max_f32_e32 v16, 0, v16
	v_max_f32_e32 v17, 0, v17
	global_store_dwordx4 v[30:31], v[24:27], off
	v_max_f32_e32 v20, v20, v20
	v_max_f32_e32 v21, v21, v21
	v_pk_mul_f32 v[24:25], v[16:17], v[16:17]
	v_max_f32_e32 v17, v18, v18
	v_max_f32_e32 v16, v22, v22
	v_max_f32_e32 v18, 0, v17
	v_max_f32_e32 v17, v23, v23
	v_max_f32_e32 v19, v19, v19
	v_max_f32_e32 v20, 0, v20
	v_max_f32_e32 v21, 0, v21
	v_max_f32_e32 v16, 0, v16
	v_max_f32_e32 v17, 0, v17
	v_max_f32_e32 v19, 0, v19
	s_mov_b64 s[46:47], 0x140000
	v_pk_mul_f32 v[20:21], v[20:21], v[20:21]
	v_pk_mul_f32 v[22:23], v[16:17], v[16:17]
	v_pk_mul_f32 v[26:27], v[18:19], v[18:19]
	v_max_f32_e32 v8, v8, v8
	v_max_f32_e32 v9, v9, v9
	v_lshl_add_u64 v[28:29], v[122:123], 0, s[46:47]
	v_cvt_pk_bf16_f32 v16, v20, v21
	v_cvt_pk_bf16_f32 v17, v22, v23
	v_cvt_pk_bf16_f32 v18, v24, v25
	v_cvt_pk_bf16_f32 v19, v26, v27
	v_max_f32_e32 v8, 0, v8
	v_max_f32_e32 v9, 0, v9
	global_store_dwordx4 v[28:29], v[16:19], off offset:256
	v_max_f32_e32 v12, v12, v12
	v_max_f32_e32 v13, v13, v13
	v_pk_mul_f32 v[16:17], v[8:9], v[8:9]
	v_max_f32_e32 v9, v10, v10
	v_max_f32_e32 v8, v14, v14
	v_max_f32_e32 v10, 0, v9
	v_max_f32_e32 v9, v15, v15
	v_max_f32_e32 v8, 0, v8
	v_max_f32_e32 v9, 0, v9
	v_max_f32_e32 v11, v11, v11
	v_max_f32_e32 v12, 0, v12
	v_max_f32_e32 v13, 0, v13
	v_max_f32_e32 v11, 0, v11
	v_pk_mul_f32 v[14:15], v[8:9], v[8:9]
	s_mov_b32 s1, 0x160000
	v_pk_mul_f32 v[12:13], v[12:13], v[12:13]
	v_pk_mul_f32 v[18:19], v[10:11], v[10:11]
	v_cvt_pk_bf16_f32 v9, v14, v15
	v_add_co_u32_e32 v14, vcc, s1, v122
	v_max_f32_e32 v0, v0, v0
	v_max_f32_e32 v1, v1, v1
	v_cvt_pk_bf16_f32 v8, v12, v13
	v_cvt_pk_bf16_f32 v10, v16, v17
	v_cvt_pk_bf16_f32 v11, v18, v19
	v_addc_co_u32_e32 v15, vcc, 0, v123, vcc
	v_max_f32_e32 v0, 0, v0
	v_max_f32_e32 v1, 0, v1
	global_store_dwordx4 v[14:15], v[8:11], off
	v_max_f32_e32 v4, v4, v4
	v_max_f32_e32 v5, v5, v5
	v_pk_mul_f32 v[8:9], v[0:1], v[0:1]
	v_max_f32_e32 v1, v2, v2
	v_max_f32_e32 v0, v6, v6
	v_max_f32_e32 v2, 0, v1
	v_max_f32_e32 v1, v7, v7
	v_max_f32_e32 v3, v3, v3
	v_max_f32_e32 v4, 0, v4
	v_max_f32_e32 v5, 0, v5
	v_max_f32_e32 v0, 0, v0
	v_max_f32_e32 v1, 0, v1
	v_max_f32_e32 v3, 0, v3
	s_mov_b64 s[46:47], 0x160000
	v_pk_mul_f32 v[4:5], v[4:5], v[4:5]
	v_pk_mul_f32 v[6:7], v[0:1], v[0:1]
	v_pk_mul_f32 v[10:11], v[2:3], v[2:3]
	v_lshl_add_u64 v[12:13], v[122:123], 0, s[46:47]
	v_cvt_pk_bf16_f32 v0, v4, v5
	v_cvt_pk_bf16_f32 v1, v6, v7
	v_cvt_pk_bf16_f32 v2, v8, v9
	v_cvt_pk_bf16_f32 v3, v10, v11
	s_and_b64 vcc, exec, s[36:37]
	s_mov_b32 s65, s0
	s_mov_b32 s44, s30
	s_mov_b64 s[48:49], s[40:41]
	s_mov_b64 s[46:47], s[38:39]
	global_store_dwordx4 v[12:13], v[0:3], off offset:256
	s_cbranch_vccz .LBB0_62
	s_waitcnt vmcnt(0)
	v_readlane_b32 s64, v255, 38
	s_cmpk_gt_u32 s52, 0xff
	v_readlane_b32 s65, v255, 39
	s_cbranch_scc1 .LBB0_69
	s_barrier

; #define PG8_STAGE(bufoff, gbase, voff) do { _Pragma("unroll") for (int _i = 0; _i < 2; ++_i) \
;         __builtin_amdgcn_global_load_lds((const unsigned*)((const char*)(gbase) + (voff)[_i]), (PG8_LAS unsigned*)(lds + (bufoff) + ldsw + _i * 8192), 16, 0, 0); } while (0)
; #define PG8_LDA(dst, b, h) do { _Pragma("unroll") for (int m = 0; m < 4; ++m) _Pragma("unroll") for (int k = 0; k < 2; ++k) dst[m][k] = *(const PG8_LAS bf16x8*)(lds + PG8_SA(b, h) + aoff + m * 2048 + k * 1024); } while (0)
; #define PG8_LDB(dst, b, h) do { _Pragma("unroll") for (int n = 0; n < 2; ++n) _Pragma("unroll") for (int k = 0; k < 2; ++k) dst[n][k] = *(const PG8_LAS bf16x8*)(lds + PG8_SB(b, h) + boff + n * 2048 + k * 1024); } while (0)
; #define PG8_MMA(ai, bj, At, Bt) do { __builtin_amdgcn_s_setprio(1); _Pragma("unroll") for (int m = 0; m < 4; ++m) _Pragma("unroll") for (int n = 0; n < 2; ++n) _Pragma("unroll") for (int k = 0; k < 2; ++k) \
;         acc[ai][bj][m][n] = __builtin_amdgcn_mfma_f32_16x16x32_bf16(Bt[n][k], At[m][k], acc[ai][bj][m][n], 0, 0, 0); __builtin_amdgcn_s_setprio(0); } while (0)
; #define PG8_WAIT_L(n) asm volatile("s_waitcnt lgkmcnt(" #n ")" ::: "memory")
; #define PG8_BAR __builtin_amdgcn_s_barrier()
; #define PG8_SCHED __builtin_amdgcn_sched_barrier(0)
; template <class Epi, class Sched>
; __device__ __forceinline__ void gemm_phase(PG8_LAS unsigned char* lds, const Gemm g, const Sched& S, const Epi& E) {
;     ...
;             PG8_LDB(B0, 0, 0); PG8_SCHED; PG8_LDA(At, 0, 0); PG8_STAGE(PG8_SA(1, 1), a1 + hstep, voffA);
;             PG8_WAIT_L(8); PG8_BAR; PG8_WAIT_L(0); PG8_MMA(0, 0, At, B0); PG8_BAR; PG8_SCHED;
;             PG8_LDB(B1, 0, 1); PG8_STAGE(PG8_SB(0, 0), b2, voffB);
;             PG8_BAR; PG8_WAIT_L(0); PG8_MMA(0, 1, At, B1); PG8_BAR;
;             PG8_LDA(At, 0, 1); PG8_STAGE(PG8_SA(0, 0), a2, voffA);
;             PG8_BAR; PG8_WAIT_L(0); PG8_MMA(1, 0, At, B0); PG8_BAR; PG8_SCHED;
.Lgp_4525:
.LBB0_87:
	s_add_u32 s40, s38, 0x100
	s_addc_u32 s41, s39, 0
	s_add_i32 s59, 0, 0x10000
	v_add_u32_e32 v102, s59, v240
	ds_read_b128 v[84:87], v102
	ds_read_b128 v[92:95], v102 offset:1024
	ds_read_b128 v[98:101], v102 offset:2048
	ds_read_b128 v[102:105], v102 offset:3072
	s_cmp_eq_u32 s60, 12
	s_cselect_b32 vcc_hi, s47, s41
	s_cselect_b32 vcc_lo, s94, s40
	s_cselect_b32 s53, s45, s57
	s_cselect_b32 s52, s97, s56
	v_lshl_add_u64 v[178:179], s[38:39], 0, v[210:211]
	s_add_i32 m0, s61, 0xc000
	ds_read_b128 v[146:149], v242
	ds_read_b128 v[150:153], v242 offset:1024
	ds_read_b128 v[154:157], v242 offset:2048
	ds_read_b128 v[158:161], v242 offset:3072
	ds_read_b128 v[162:165], v242 offset:4096
	ds_read_b128 v[166:169], v242 offset:5120
	ds_read_b128 v[170:173], v242 offset:6144
	ds_read_b128 v[174:177], v242 offset:7168
	global_load_lds_dwordx4 v[178:179], off
	v_lshl_add_u64 v[178:179], s[38:39], 0, v[212:213]
	s_add_i32 m0, s61, 0xe000
	s_nop 0
	global_load_lds_dwordx4 v[178:179], off
	s_waitcnt lgkmcnt(8)
	s_barrier
	s_waitcnt lgkmcnt(0)
	v_mfma_f32_16x16x32_bf16 v[142:145], v[84:87], v[146:149], v[142:145]
	v_mfma_f32_16x16x32_bf16 v[138:141], v[98:101], v[146:149], v[138:141]
	v_mfma_f32_16x16x32_bf16 v[130:133], v[84:87], v[154:157], v[130:133]
	v_mfma_f32_16x16x32_bf16 v[122:125], v[98:101], v[154:157], v[122:125]
	v_mfma_f32_16x16x32_bf16 v[114:117], v[84:87], v[162:165], v[114:117]
	v_mfma_f32_16x16x32_bf16 v[106:109], v[98:101], v[162:165], v[106:109]
	v_mfma_f32_16x16x32_bf16 v[80:83], v[84:87], v[170:173], v[80:83]
	v_mfma_f32_16x16x32_bf16 v[72:75], v[98:101], v[170:173], v[72:75]
	v_mfma_f32_16x16x32_bf16 v[142:145], v[92:95], v[150:153], v[142:145]
	v_mfma_f32_16x16x32_bf16 v[138:141], v[102:105], v[150:153], v[138:141]
	v_mfma_f32_16x16x32_bf16 v[130:133], v[92:95], v[158:161], v[130:133]
	v_mfma_f32_16x16x32_bf16 v[122:125], v[102:105], v[158:161], v[122:125]
	v_mfma_f32_16x16x32_bf16 v[114:117], v[92:95], v[166:169], v[114:117]
	v_mfma_f32_16x16x32_bf16 v[106:109], v[102:105], v[166:169], v[106:109]
	v_mfma_f32_16x16x32_bf16 v[80:83], v[92:95], v[174:177], v[80:83]
	v_mfma_f32_16x16x32_bf16 v[72:75], v[102:105], v[174:177], v[72:75]
	s_barrier
	s_add_i32 s42, 0, 0x14000
	s_add_i32 s38, s59, s58
	v_add_u32_e32 v190, s42, v240
	v_lshl_add_u64 v[194:195], s[52:53], 0, v[96:97]
	s_mov_b32 m0, s38
	ds_read_b128 v[178:181], v190
	ds_read_b128 v[182:185], v190 offset:1024
	ds_read_b128 v[186:189], v190 offset:2048
	ds_read_b128 v[190:193], v190 offset:3072
	global_load_lds_dwordx4 v[194:195], off
	v_lshl_add_u64 v[196:197], s[52:53], 0, v[208:209]
	s_add_i32 m0, s38, 0x2000
	s_nop 0
	global_load_lds_dwordx4 v[196:197], off
	s_barrier
	s_waitcnt lgkmcnt(0)
	v_mfma_f32_16x16x32_bf16 v[134:137], v[178:181], v[146:149], v[134:137]
	v_mfma_f32_16x16x32_bf16 v[126:129], v[186:189], v[146:149], v[126:129]
	v_mfma_f32_16x16x32_bf16 v[118:121], v[178:181], v[154:157], v[118:121]
	v_mfma_f32_16x16x32_bf16 v[110:113], v[186:189], v[154:157], v[110:113]
	v_mfma_f32_16x16x32_bf16 v[88:91], v[178:181], v[162:165], v[88:91]
	v_mfma_f32_16x16x32_bf16 v[76:79], v[186:189], v[162:165], v[76:79]
	v_mfma_f32_16x16x32_bf16 v[68:71], v[178:181], v[170:173], v[68:71]
	v_mfma_f32_16x16x32_bf16 v[64:67], v[186:189], v[170:173], v[64:67]
	v_mfma_f32_16x16x32_bf16 v[134:137], v[182:185], v[150:153], v[134:137]
	v_mfma_f32_16x16x32_bf16 v[126:129], v[190:193], v[150:153], v[126:129]
	v_mfma_f32_16x16x32_bf16 v[118:121], v[182:185], v[158:161], v[118:121]
	v_mfma_f32_16x16x32_bf16 v[110:113], v[190:193], v[158:161], v[110:113]
	v_mfma_f32_16x16x32_bf16 v[88:91], v[182:185], v[166:169], v[88:91]
	v_mfma_f32_16x16x32_bf16 v[76:79], v[190:193], v[166:169], v[76:79]
	v_mfma_f32_16x16x32_bf16 v[68:71], v[182:185], v[174:177], v[68:71]
	v_mfma_f32_16x16x32_bf16 v[64:67], v[190:193], v[174:177], v[64:67]
	s_mov_b32 m0, s61
	v_lshl_add_u64 v[198:199], vcc, 0, v[96:97]
	s_barrier
	ds_read_b128 v[146:149], v242 offset:16384
	ds_read_b128 v[150:153], v242 offset:17408
	ds_read_b128 v[154:157], v242 offset:18432
	ds_read_b128 v[158:161], v242 offset:19456
	ds_read_b128 v[162:165], v242 offset:20480
	ds_read_b128 v[166:169], v242 offset:21504
	ds_read_b128 v[170:173], v242 offset:22528
	ds_read_b128 v[174:177], v242 offset:23552
	global_load_lds_dwordx4 v[198:199], off
	v_lshl_add_u64 v[200:201], vcc, 0, v[208:209]
	s_mov_b32 m0, s62
	s_nop 0
	global_load_lds_dwordx4 v[200:201], off
	s_barrier
	s_waitcnt lgkmcnt(0)
	v_mfma_f32_16x16x32_bf16 v[60:63], v[84:87], v[146:149], v[60:63]
	v_mfma_f32_16x16x32_bf16 v[56:59], v[98:101], v[146:149], v[56:59]
	v_mfma_f32_16x16x32_bf16 v[48:51], v[84:87], v[154:157], v[48:51]
	v_mfma_f32_16x16x32_bf16 v[40:43], v[98:101], v[154:157], v[40:43]
	v_mfma_f32_16x16x32_bf16 v[32:35], v[84:87], v[162:165], v[32:35]
	v_mfma_f32_16x16x32_bf16 v[24:27], v[98:101], v[162:165], v[24:27]
	v_mfma_f32_16x16x32_bf16 v[16:19], v[84:87], v[170:173], v[16:19]
	v_mfma_f32_16x16x32_bf16 v[8:11], v[98:101], v[170:173], v[8:11]
	v_mfma_f32_16x16x32_bf16 v[60:63], v[92:95], v[150:153], v[60:63]
	v_mfma_f32_16x16x32_bf16 v[56:59], v[102:105], v[150:153], v[56:59]
	v_mfma_f32_16x16x32_bf16 v[48:51], v[92:95], v[158:161], v[48:51]
	v_mfma_f32_16x16x32_bf16 v[40:43], v[102:105], v[158:161], v[40:43]
	v_mfma_f32_16x16x32_bf16 v[32:35], v[92:95], v[166:169], v[32:35]
	v_mfma_f32_16x16x32_bf16 v[24:27], v[102:105], v[166:169], v[24:27]
	v_mfma_f32_16x16x32_bf16 v[16:19], v[92:95], v[174:177], v[16:19]
	v_mfma_f32_16x16x32_bf16 v[8:11], v[102:105], v[174:177], v[8:11]
	s_barrier
; #define PG8_STAGE(bufoff, gbase, voff) do { _Pragma("unroll") for (int _i = 0; _i < 2; ++_i) \
;         __builtin_amdgcn_global_load_lds((const unsigned*)((const char*)(gbase) + (voff)[_i]), (PG8_LAS unsigned*)(lds + (bufoff) + ldsw + _i * 8192), 16, 0, 0); } while (0)
; #define PG8_LDA(dst, b, h) do { _Pragma("unroll") for (int m = 0; m < 4; ++m) _Pragma("unroll") for (int k = 0; k < 2; ++k) dst[m][k] = *(const PG8_LAS bf16x8*)(lds + PG8_SA(b, h) + aoff + m * 2048 + k * 1024); } while (0)
; #define PG8_LDB(dst, b, h) do { _Pragma("unroll") for (int n = 0; n < 2; ++n) _Pragma("unroll") for (int k = 0; k < 2; ++k) dst[n][k] = *(const PG8_LAS bf16x8*)(lds + PG8_SB(b, h) + boff + n * 2048 + k * 1024); } while (0)
; #define PG8_MMA(ai, bj, At, Bt) do { __builtin_amdgcn_s_setprio(1); _Pragma("unroll") for (int m = 0; m < 4; ++m) _Pragma("unroll") for (int n = 0; n < 2; ++n) _Pragma("unroll") for (int k = 0; k < 2; ++k) \
;         acc[ai][bj][m][n] = __builtin_amdgcn_mfma_f32_16x16x32_bf16(Bt[n][k], At[m][k], acc[ai][bj][m][n], 0, 0, 0); __builtin_amdgcn_s_setprio(0); } while (0)
; #define PG8_WAIT_V(n) asm volatile("s_waitcnt vmcnt(" #n ")" ::: "memory")
; #define PG8_WAIT_L(n) asm volatile("s_waitcnt lgkmcnt(" #n ")" ::: "memory")
; #define PG8_BAR __builtin_amdgcn_s_barrier()
; #define PG8_SCHED __builtin_amdgcn_sched_barrier(0)
; template <class Epi, class Sched>
; __device__ __forceinline__ void gemm_phase(PG8_LAS unsigned char* lds, const Gemm g, const Sched& S, const Epi& E) {
;     ...
;             PG8_STAGE(PG8_SB(0, 1), b2 + hstep, voffB);
;             PG8_WAIT_V(6); PG8_BAR; PG8_MMA(1, 1, At, B1); PG8_BAR;
;             PG8_LDB(B0, 1, 0); PG8_SCHED; PG8_LDA(At, 1, 0); PG8_STAGE(PG8_SA(0, 1), a2 + hstep, voffA);
;             PG8_WAIT_L(8); PG8_BAR; PG8_WAIT_L(0); PG8_MMA(0, 0, At, B0); PG8_BAR; PG8_SCHED;
;             PG8_LDB(B1, 1, 1); PG8_STAGE(PG8_SB(1, 0), b3, voffB);
;             PG8_BAR; PG8_WAIT_L(0); PG8_MMA(0, 1, At, B1); PG8_BAR;
	s_add_u32 s38, s52, 0x40000
	s_addc_u32 s39, s53, 0
	s_add_i32 s42, s42, s58
	v_lshl_add_u64 v[84:85], s[38:39], 0, v[96:97]
	s_mov_b32 m0, s42
	s_nop 0
	global_load_lds_dwordx4 v[84:85], off
	v_lshl_add_u64 v[84:85], s[38:39], 0, v[208:209]
	s_add_i32 m0, s42, 0x2000
	s_nop 0
	global_load_lds_dwordx4 v[84:85], off
	s_waitcnt vmcnt(6)
	s_barrier
	v_mfma_f32_16x16x32_bf16 v[52:55], v[178:181], v[146:149], v[52:55]
	v_mfma_f32_16x16x32_bf16 v[44:47], v[186:189], v[146:149], v[44:47]
	v_mfma_f32_16x16x32_bf16 v[36:39], v[178:181], v[154:157], v[36:39]
	v_mfma_f32_16x16x32_bf16 v[28:31], v[186:189], v[154:157], v[28:31]
	v_mfma_f32_16x16x32_bf16 v[20:23], v[178:181], v[162:165], v[20:23]
	v_mfma_f32_16x16x32_bf16 v[12:15], v[186:189], v[162:165], v[12:15]
	v_mfma_f32_16x16x32_bf16 v[4:7], v[178:181], v[170:173], v[4:7]
	v_mfma_f32_16x16x32_bf16 v[0:3], v[186:189], v[170:173], v[0:3]
	v_mfma_f32_16x16x32_bf16 v[52:55], v[182:185], v[150:153], v[52:55]
	v_mfma_f32_16x16x32_bf16 v[44:47], v[190:193], v[150:153], v[44:47]
	v_mfma_f32_16x16x32_bf16 v[36:39], v[182:185], v[158:161], v[36:39]
	v_mfma_f32_16x16x32_bf16 v[28:31], v[190:193], v[158:161], v[28:31]
	v_mfma_f32_16x16x32_bf16 v[20:23], v[182:185], v[166:169], v[20:23]
	v_mfma_f32_16x16x32_bf16 v[12:15], v[190:193], v[166:169], v[12:15]
	v_mfma_f32_16x16x32_bf16 v[4:7], v[182:185], v[174:177], v[4:7]
	v_mfma_f32_16x16x32_bf16 v[0:3], v[190:193], v[174:177], v[0:3]
	s_add_i32 s42, 0, 0x18000
	v_add_u32_e32 v102, s42, v240
	s_barrier
	ds_read_b128 v[84:87], v102
	ds_read_b128 v[92:95], v102 offset:1024
	ds_read_b128 v[98:101], v102 offset:2048
	ds_read_b128 v[102:105], v102 offset:3072
	s_add_u32 s38, vcc_lo, 0x40000
	s_addc_u32 s39, vcc_hi, 0
	s_mov_b32 m0, s63
	v_lshl_add_u64 v[178:179], s[38:39], 0, v[96:97]
	ds_read_b128 v[146:149], v242 offset:32768
	ds_read_b128 v[150:153], v242 offset:33792
	ds_read_b128 v[154:157], v242 offset:34816
	ds_read_b128 v[158:161], v242 offset:35840
	ds_read_b128 v[162:165], v242 offset:36864
	ds_read_b128 v[166:169], v242 offset:37888
	ds_read_b128 v[170:173], v242 offset:38912
	ds_read_b128 v[174:177], v242 offset:39936
	global_load_lds_dwordx4 v[178:179], off
	v_lshl_add_u64 v[178:179], s[38:39], 0, v[208:209]
	s_mov_b32 m0, s64
	s_nop 0
	global_load_lds_dwordx4 v[178:179], off
	s_waitcnt lgkmcnt(8)
	s_barrier
	s_waitcnt lgkmcnt(0)
	v_mfma_f32_16x16x32_bf16 v[142:145], v[84:87], v[146:149], v[142:145]
	v_mfma_f32_16x16x32_bf16 v[138:141], v[98:101], v[146:149], v[138:141]
	v_mfma_f32_16x16x32_bf16 v[130:133], v[84:87], v[154:157], v[130:133]
	v_mfma_f32_16x16x32_bf16 v[122:125], v[98:101], v[154:157], v[122:125]
	v_mfma_f32_16x16x32_bf16 v[114:117], v[84:87], v[162:165], v[114:117]
	v_mfma_f32_16x16x32_bf16 v[106:109], v[98:101], v[162:165], v[106:109]
	v_mfma_f32_16x16x32_bf16 v[80:83], v[84:87], v[170:173], v[80:83]
	v_mfma_f32_16x16x32_bf16 v[72:75], v[98:101], v[170:173], v[72:75]
	v_mfma_f32_16x16x32_bf16 v[142:145], v[92:95], v[150:153], v[142:145]
	v_mfma_f32_16x16x32_bf16 v[138:141], v[102:105], v[150:153], v[138:141]
	v_mfma_f32_16x16x32_bf16 v[130:133], v[92:95], v[158:161], v[130:133]
	v_mfma_f32_16x16x32_bf16 v[122:125], v[102:105], v[158:161], v[122:125]
	v_mfma_f32_16x16x32_bf16 v[114:117], v[92:95], v[166:169], v[114:117]
	v_mfma_f32_16x16x32_bf16 v[106:109], v[102:105], v[166:169], v[106:109]
	v_mfma_f32_16x16x32_bf16 v[80:83], v[92:95], v[174:177], v[80:83]
	v_mfma_f32_16x16x32_bf16 v[72:75], v[102:105], v[174:177], v[72:75]
	s_barrier
	s_add_i32 s43, 0, 0x1c000
	s_add_i32 s38, s42, s58
	v_add_u32_e32 v190, s43, v240
	v_lshl_add_u64 v[194:195], v[194:195], 0, s[2:3]
	s_mov_b32 m0, s38
	ds_read_b128 v[178:181], v190
	ds_read_b128 v[182:185], v190 offset:1024
	ds_read_b128 v[186:189], v190 offset:2048
	ds_read_b128 v[190:193], v190 offset:3072
	global_load_lds_dwordx4 v[194:195], off
	v_lshl_add_u64 v[194:195], v[196:197], 0, s[2:3]
	s_add_i32 m0, s38, 0x2000
	s_nop 0
	global_load_lds_dwordx4 v[194:195], off
	s_barrier
	s_waitcnt lgkmcnt(0)
	v_mfma_f32_16x16x32_bf16 v[134:137], v[178:181], v[146:149], v[134:137]
	v_mfma_f32_16x16x32_bf16 v[126:129], v[186:189], v[146:149], v[126:129]
	v_mfma_f32_16x16x32_bf16 v[118:121], v[178:181], v[154:157], v[118:121]
	v_mfma_f32_16x16x32_bf16 v[110:113], v[186:189], v[154:157], v[110:113]
	v_mfma_f32_16x16x32_bf16 v[88:91], v[178:181], v[162:165], v[88:91]
	v_mfma_f32_16x16x32_bf16 v[76:79], v[186:189], v[162:165], v[76:79]
	v_mfma_f32_16x16x32_bf16 v[68:71], v[178:181], v[170:173], v[68:71]
	v_mfma_f32_16x16x32_bf16 v[64:67], v[186:189], v[170:173], v[64:67]
	v_mfma_f32_16x16x32_bf16 v[134:137], v[182:185], v[150:153], v[134:137]
	v_mfma_f32_16x16x32_bf16 v[126:129], v[190:193], v[150:153], v[126:129]
	v_mfma_f32_16x16x32_bf16 v[118:121], v[182:185], v[158:161], v[118:121]
	v_mfma_f32_16x16x32_bf16 v[110:113], v[190:193], v[158:161], v[110:113]
	v_mfma_f32_16x16x32_bf16 v[88:91], v[182:185], v[166:169], v[88:91]
	v_mfma_f32_16x16x32_bf16 v[76:79], v[190:193], v[166:169], v[76:79]
	v_mfma_f32_16x16x32_bf16 v[68:71], v[182:185], v[174:177], v[68:71]
	v_mfma_f32_16x16x32_bf16 v[64:67], v[190:193], v[174:177], v[64:67]
	s_mov_b32 m0, s69
	v_lshl_add_u64 v[194:195], v[198:199], 0, s[2:3]
	s_barrier
	ds_read_b128 v[146:149], v242 offset:49152
	ds_read_b128 v[150:153], v242 offset:50176
	ds_read_b128 v[154:157], v242 offset:51200
	ds_read_b128 v[158:161], v242 offset:52224
	ds_read_b128 v[162:165], v242 offset:53248
	ds_read_b128 v[166:169], v242 offset:54272
	ds_read_b128 v[170:173], v242 offset:55296
	ds_read_b128 v[174:177], v242 offset:56320
	global_load_lds_dwordx4 v[194:195], off
	v_lshl_add_u64 v[194:195], v[200:201], 0, s[2:3]
	s_mov_b32 m0, s70
	s_nop 0
	global_load_lds_dwordx4 v[194:195], off
	s_barrier
; #define PG8_STAGE(bufoff, gbase, voff) do { _Pragma("unroll") for (int _i = 0; _i < 2; ++_i) \
;         __builtin_amdgcn_global_load_lds((const unsigned*)((const char*)(gbase) + (voff)[_i]), (PG8_LAS unsigned*)(lds + (bufoff) + ldsw + _i * 8192), 16, 0, 0); } while (0)
; #define PG8_LDA(dst, b, h) do { _Pragma("unroll") for (int m = 0; m < 4; ++m) _Pragma("unroll") for (int k = 0; k < 2; ++k) dst[m][k] = *(const PG8_LAS bf16x8*)(lds + PG8_SA(b, h) + aoff + m * 2048 + k * 1024); } while (0)
; #define PG8_MMA(ai, bj, At, Bt) do { __builtin_amdgcn_s_setprio(1); _Pragma("unroll") for (int m = 0; m < 4; ++m) _Pragma("unroll") for (int n = 0; n < 2; ++n) _Pragma("unroll") for (int k = 0; k < 2; ++k) \
;         acc[ai][bj][m][n] = __builtin_amdgcn_mfma_f32_16x16x32_bf16(Bt[n][k], At[m][k], acc[ai][bj][m][n], 0, 0, 0); __builtin_amdgcn_s_setprio(0); } while (0)
; #define PG8_WAIT_V(n) asm volatile("s_waitcnt vmcnt(" #n ")" ::: "memory")
; #define PG8_BAR __builtin_amdgcn_s_barrier()
; template <class Epi, class Sched>
; __device__ __forceinline__ void gemm_phase(PG8_LAS unsigned char* lds, const Gemm g, const Sched& S, const Epi& E) {
;     ...
;             PG8_LDA(At, 1, 1); PG8_STAGE(PG8_SA(1, 0), a3, voffA);
;             PG8_BAR; PG8_WAIT_L(0); PG8_MMA(1, 0, At, B0); PG8_BAR; PG8_SCHED;
;             PG8_STAGE(PG8_SB(1, 1), b3 + hstep, voffB);
;             PG8_WAIT_V(6); PG8_BAR; PG8_MMA(1, 1, At, B1); PG8_BAR;
;         }
;   DEV void operator()(const f32x4 (&acc)[2][2][4][2], const pg8::Unit& u, int wr, int wc, int fr, int fq) const {
;     const int row0 = u.pm * 256 + wr * 64 + fr, col0 = u.pn * 256 + wc * 32 + 4 * fq;
;     const float* gt = mod + (size_t)modrow(row0) * 6144;
;     f32x4 g4[2][2];
; #pragma unroll
;     for (int bj = 0; bj < 2; ++bj)
; #pragma unroll
;       for (int n = 0; n < 2; ++n) g4[bj][n] = *(const f32x4*)(gt + col0 + bj * 128 + n * 16);
; #pragma unroll
;     for (int ai = 0; ai < 2; ++ai) {
;       f32x4 xv[4][2][2];
; #pragma unroll
;       for (int m = 0; m < 4; ++m) {
;         const int row = row0 + ai * 128 + m * 16;
;         const float* xi = row < T_LAT ? rin_lat + (size_t)row * DM : rin_ctx + (size_t)(row - T_LAT) * DM;
; #pragma unroll
;         for (int bj = 0; bj < 2; ++bj)
; #pragma unroll
;           for (int n = 0; n < 2; ++n) xv[m][bj][n] = *(const f32x4*)(xi + col0 + bj * 128 + n * 16);
;       }
	s_waitcnt lgkmcnt(0)
	v_mfma_f32_16x16x32_bf16 v[60:63], v[84:87], v[146:149], v[60:63]
	v_mfma_f32_16x16x32_bf16 v[56:59], v[98:101], v[146:149], v[56:59]
	v_mfma_f32_16x16x32_bf16 v[48:51], v[84:87], v[154:157], v[48:51]
	v_mfma_f32_16x16x32_bf16 v[40:43], v[98:101], v[154:157], v[40:43]
	v_mfma_f32_16x16x32_bf16 v[32:35], v[84:87], v[162:165], v[32:35]
	v_mfma_f32_16x16x32_bf16 v[24:27], v[98:101], v[162:165], v[24:27]
	v_mfma_f32_16x16x32_bf16 v[16:19], v[84:87], v[170:173], v[16:19]
	v_mfma_f32_16x16x32_bf16 v[8:11], v[98:101], v[170:173], v[8:11]
	v_mfma_f32_16x16x32_bf16 v[60:63], v[92:95], v[150:153], v[60:63]
	v_mfma_f32_16x16x32_bf16 v[56:59], v[102:105], v[150:153], v[56:59]
	v_mfma_f32_16x16x32_bf16 v[48:51], v[92:95], v[158:161], v[48:51]
	v_mfma_f32_16x16x32_bf16 v[40:43], v[102:105], v[158:161], v[40:43]
	v_mfma_f32_16x16x32_bf16 v[32:35], v[92:95], v[166:169], v[32:35]
	v_mfma_f32_16x16x32_bf16 v[24:27], v[102:105], v[166:169], v[24:27]
	v_mfma_f32_16x16x32_bf16 v[16:19], v[92:95], v[174:177], v[16:19]
	v_mfma_f32_16x16x32_bf16 v[8:11], v[102:105], v[174:177], v[8:11]
	s_barrier
	s_add_u32 s38, s52, 0x40080
	s_addc_u32 s39, s53, 0
	s_add_i32 s42, s43, s58
	v_lshl_add_u64 v[84:85], s[38:39], 0, v[96:97]
	s_mov_b32 m0, s42
	s_nop 0
	global_load_lds_dwordx4 v[84:85], off
	v_lshl_add_u64 v[84:85], s[38:39], 0, v[208:209]
	s_add_i32 m0, s42, 0x2000
	s_nop 0
	global_load_lds_dwordx4 v[84:85], off
	s_waitcnt vmcnt(6)
	s_barrier
	v_mfma_f32_16x16x32_bf16 v[52:55], v[178:181], v[146:149], v[52:55]
	v_mfma_f32_16x16x32_bf16 v[44:47], v[186:189], v[146:149], v[44:47]
	v_mfma_f32_16x16x32_bf16 v[36:39], v[178:181], v[154:157], v[36:39]
	v_mfma_f32_16x16x32_bf16 v[28:31], v[186:189], v[154:157], v[28:31]
	v_mfma_f32_16x16x32_bf16 v[20:23], v[178:181], v[162:165], v[20:23]
	v_mfma_f32_16x16x32_bf16 v[12:15], v[186:189], v[162:165], v[12:15]
	v_mfma_f32_16x16x32_bf16 v[4:7], v[178:181], v[170:173], v[4:7]
	v_mfma_f32_16x16x32_bf16 v[0:3], v[186:189], v[170:173], v[0:3]
	v_mfma_f32_16x16x32_bf16 v[52:55], v[182:185], v[150:153], v[52:55]
	v_mfma_f32_16x16x32_bf16 v[44:47], v[190:193], v[150:153], v[44:47]
	v_mfma_f32_16x16x32_bf16 v[36:39], v[182:185], v[158:161], v[36:39]
	v_mfma_f32_16x16x32_bf16 v[28:31], v[190:193], v[158:161], v[28:31]
	v_mfma_f32_16x16x32_bf16 v[20:23], v[182:185], v[166:169], v[20:23]
	v_mfma_f32_16x16x32_bf16 v[12:15], v[190:193], v[166:169], v[12:15]
	v_mfma_f32_16x16x32_bf16 v[4:7], v[182:185], v[174:177], v[4:7]
	v_mfma_f32_16x16x32_bf16 v[0:3], v[190:193], v[174:177], v[0:3]
	s_add_i32 s60, s60, 2
	s_add_u32 s56, s56, 0x100
	s_addc_u32 s57, s57, 0
	s_cmp_gt_u32 s60, 13
	s_mov_b64 s[38:39], s[40:41]
	s_barrier
	s_cbranch_scc0 .LBB0_87
	v_lshl_add_u32 v247, s0, 8, v239
	s_mov_b32 s42, 0x8000
	v_min_i32_e32 v85, 0x8000, v247
	v_cmp_gt_i32_e64 s[40:41], s42, v247
	v_add_u32_e32 v146, 0xffff8000, v247
	v_ashrrev_i32_e32 v147, 31, v247
	v_lshl_or_b32 v84, s1, 8, v241
	v_ashrrev_i32_e32 v85, 12, v85
	v_cndmask_b32_e64 v147, 0, v147, s[40:41]
	v_cndmask_b32_e64 v146, v146, v247, s[40:41]
	v_mov_b32_e32 v248, s67
	v_mov_b32_e32 v249, s65
	v_mov_b32_e32 v250, s68
	v_mov_b32_e32 v238, s66
	v_mul_hi_i32_i24_e32 v87, 0x6000, v85
	v_mul_i32_i24_e32 v86, 0x6000, v85
	v_ashrrev_i32_e32 v85, 31, v84
	v_cndmask_b32_e64 v149, v248, v249, s[40:41]
	v_cndmask_b32_e64 v148, v250, v238, s[40:41]
	v_lshlrev_b64 v[222:223], 12, v[146:147]
	v_lshlrev_b64 v[214:215], 2, v[84:85]
	v_lshl_add_u64 v[146:147], v[148:149], 0, v[222:223]
	v_lshl_add_u64 v[224:225], v[146:147], 0, v[214:215]
	v_or_b32_e32 v146, 16, v247
	v_cmp_gt_i32_e64 s[38:39], s42, v146
	v_ashrrev_i32_e32 v147, 31, v146
	v_add_u32_e32 v148, 0xffff8010, v247
	v_cndmask_b32_e64 v147, 0, v147, s[38:39]
	v_cndmask_b32_e64 v146, v148, v146, s[38:39]
	v_cndmask_b32_e64 v149, v248, v249, s[38:39]
	v_cndmask_b32_e64 v148, v250, v238, s[38:39]
	v_lshlrev_b64 v[220:221], 12, v[146:147]
	v_lshl_add_u64 v[86:87], s[30:31], 0, v[86:87]
	v_lshl_add_u64 v[146:147], v[148:149], 0, v[220:221]
	v_lshl_add_u64 v[84:85], v[86:87], 0, v[214:215]
	v_lshl_add_u64 v[146:147], v[146:147], 0, v[214:215]
	global_load_dwordx4 v[102:105], v[84:85], off
	global_load_dwordx4 v[98:101], v[84:85], off offset:64
	global_load_dwordx4 v[92:95], v[84:85], off offset:512
	s_nop 0
	global_load_dwordx4 v[84:87], v[84:85], off offset:576
	s_nop 0
	global_load_dwordx4 v[202:205], v[224:225], off offset:64
	global_load_dwordx4 v[198:201], v[224:225], off offset:512
	global_load_dwordx4 v[194:197], v[224:225], off offset:576
	global_load_dwordx4 v[190:193], v[146:147], off
	global_load_dwordx4 v[186:189], v[146:147], off offset:64
	global_load_dwordx4 v[182:185], v[146:147], off offset:512
	global_load_dwordx4 v[178:181], v[146:147], off offset:576
	v_or_b32_e32 v146, 32, v247
	v_cmp_gt_i32_e64 s[0:1], s42, v146
	v_ashrrev_i32_e32 v147, 31, v146
	v_add_u32_e32 v148, 0xffff8020, v247
	v_cndmask_b32_e64 v147, 0, v147, s[0:1]
	v_cndmask_b32_e64 v146, v148, v146, s[0:1]
	v_cndmask_b32_e64 v149, v248, v249, s[0:1]
	v_cndmask_b32_e64 v148, v250, v238, s[0:1]
	v_lshlrev_b64 v[218:219], 12, v[146:147]
	v_lshl_add_u64 v[146:147], v[148:149], 0, v[218:219]
	v_lshl_add_u64 v[146:147], v[146:147], 0, v[214:215]
	global_load_dwordx4 v[174:177], v[146:147], off
	global_load_dwordx4 v[170:173], v[146:147], off offset:64
	global_load_dwordx4 v[166:169], v[146:147], off offset:512
	global_load_dwordx4 v[162:165], v[146:147], off offset:576
	v_or_b32_e32 v146, 48, v247
	v_cmp_gt_i32_e32 vcc, s42, v146
	v_ashrrev_i32_e32 v147, 31, v146
	v_add_u32_e32 v148, 0xffff8030, v247
	v_cndmask_b32_e32 v147, 0, v147, vcc
	v_cndmask_b32_e32 v146, v148, v146, vcc
	v_readlane_b32 s42, v251, 52
	v_cndmask_b32_e32 v149, v248, v249, vcc
	v_cndmask_b32_e32 v148, v250, v238, vcc
	v_lshlrev_b64 v[216:217], 12, v[146:147]
	v_mov_b32_e32 v243, s42
	v_readlane_b32 s42, v251, 51
	v_lshl_add_u64 v[146:147], v[148:149], 0, v[216:217]
	v_mov_b32_e32 v244, s73
	v_mov_b32_e32 v245, s42
	v_mov_b32_e32 v246, s72
	v_lshl_add_u64 v[146:147], v[146:147], 0, v[214:215]
	v_cndmask_b32_e64 v229, v243, v244, s[40:41]
	v_cndmask_b32_e64 v228, v245, v246, s[40:41]
	global_load_dwordx4 v[158:161], v[146:147], off
	global_load_dwordx4 v[154:157], v[146:147], off offset:64
	global_load_dwordx4 v[150:153], v[146:147], off offset:512
	s_nop 0
	global_load_dwordx4 v[146:149], v[146:147], off offset:576
	v_lshl_add_u64 v[222:223], v[228:229], 0, v[222:223]
	global_load_dwordx4 v[228:231], v[224:225], off
	v_lshl_add_u64 v[222:223], v[222:223], 0, v[214:215]
	s_movk_i32 s42, 0x7f50
	s_waitcnt vmcnt(0)
;   DEV void operator()(const f32x4 (&acc)[2][2][4][2], const pg8::Unit& u, int wr, int wc, int fr, int fq) const {
;     ...
;     for (int ai = 0; ai < 2; ++ai) {
;       f32x4 xv[4][2][2];
; #pragma unroll
;       for (int m = 0; m < 4; ++m) {
;         const int row = row0 + ai * 128 + m * 16;
;         const float* xi = row < T_LAT ? rin_lat + (size_t)row * DM : rin_ctx + (size_t)(row - T_LAT) * DM;
; #pragma unroll
;         for (int bj = 0; bj < 2; ++bj)
; #pragma unroll
;           for (int n = 0; n < 2; ++n) xv[m][bj][n] = *(const f32x4*)(xi + col0 + bj * 128 + n * 16);
;       }
; #pragma unroll
;       for (int m = 0; m < 4; ++m) {
;         const int row = row0 + ai * 128 + m * 16;
;         float* xr = row < T_LAT ? out + (size_t)row * DM : xc + (size_t)(row - T_LAT) * DM;
; #pragma unroll
;         for (int bj = 0; bj < 2; ++bj)
; #pragma unroll
;           for (int n = 0; n < 2; ++n) {
;             const f32x4 r = xv[m][bj][n] + g4[bj][n] * acc[ai][bj][m][n];
;             if (store) *(f32x4*)(xr + col0 + bj * 128 + n * 16) = r;
;           }
;       }
	v_pk_fma_f32 v[140:141], v[140:141], v[100:101], v[204:205]
	v_pk_fma_f32 v[136:137], v[136:137], v[94:95], v[200:201]
	v_pk_fma_f32 v[128:129], v[128:129], v[86:87], v[196:197]
	v_pk_fma_f32 v[126:127], v[126:127], v[84:85], v[194:195]
	global_store_dwordx4 v[222:223], v[126:129], off offset:576
	v_pk_fma_f32 v[134:135], v[134:135], v[92:93], v[198:199]
	v_pk_fma_f32 v[138:139], v[138:139], v[98:99], v[202:203]
	v_cndmask_b32_e64 v127, v243, v244, s[38:39]
	v_cndmask_b32_e64 v126, v245, v246, s[38:39]
	v_lshl_add_u64 v[126:127], v[126:127], 0, v[220:221]
	global_store_dwordx4 v[222:223], v[134:137], off offset:512
	v_pk_fma_f32 v[112:113], v[112:113], v[86:87], v[180:181]
	v_pk_fma_f32 v[110:111], v[110:111], v[84:85], v[178:179]
	v_lshl_add_u64 v[134:135], v[126:127], 0, v[214:215]
	global_store_dwordx4 v[222:223], v[138:141], off offset:64
	v_pk_fma_f32 v[120:121], v[120:121], v[94:95], v[184:185]
	v_pk_fma_f32 v[118:119], v[118:119], v[92:93], v[182:183]
	v_pk_fma_f32 v[128:129], v[132:133], v[104:105], v[192:193]
	v_pk_fma_f32 v[126:127], v[130:131], v[102:103], v[190:191]
	v_pk_fma_f32 v[124:125], v[124:125], v[100:101], v[188:189]
	v_pk_fma_f32 v[122:123], v[122:123], v[98:99], v[186:187]
	v_pk_fma_f32 v[78:79], v[78:79], v[86:87], v[164:165]
	v_pk_fma_f32 v[76:77], v[76:77], v[84:85], v[162:163]
	v_pk_fma_f32 v[90:91], v[90:91], v[94:95], v[168:169]
	v_pk_fma_f32 v[88:89], v[88:89], v[92:93], v[166:167]
	v_pk_fma_f32 v[108:109], v[108:109], v[100:101], v[172:173]
	v_pk_fma_f32 v[106:107], v[106:107], v[98:99], v[170:171]
	v_pk_fma_f32 v[74:75], v[74:75], v[100:101], v[156:157]
	v_pk_fma_f32 v[68:69], v[68:69], v[92:93], v[150:151]
	v_pk_fma_f32 v[66:67], v[66:67], v[86:87], v[148:149]
	v_pk_fma_f32 v[64:65], v[64:65], v[84:85], v[146:147]
	v_pk_fma_f32 v[144:145], v[144:145], v[104:105], v[230:231]
	v_pk_fma_f32 v[142:143], v[142:143], v[102:103], v[228:229]
	global_store_dwordx4 v[222:223], v[142:145], off
	global_store_dwordx4 v[134:135], v[110:113], off offset:576
	global_store_dwordx4 v[134:135], v[118:121], off offset:512
	global_store_dwordx4 v[134:135], v[126:129], off
	v_cndmask_b32_e64 v111, v243, v244, s[0:1]
	v_cndmask_b32_e64 v110, v245, v246, s[0:1]
	v_lshl_add_u64 v[110:111], v[110:111], 0, v[218:219]
	v_lshl_add_u64 v[118:119], v[110:111], 0, v[214:215]
	global_store_dwordx4 v[134:135], v[122:125], off offset:64
	global_store_dwordx4 v[118:119], v[76:79], off offset:576
	v_pk_fma_f32 v[112:113], v[116:117], v[104:105], v[176:177]
	v_pk_fma_f32 v[110:111], v[114:115], v[102:103], v[174:175]
	v_cndmask_b32_e32 v77, v243, v244, vcc
	v_cndmask_b32_e32 v76, v245, v246, vcc
	v_lshl_add_u64 v[76:77], v[76:77], 0, v[216:217]
	global_store_dwordx4 v[118:119], v[88:91], off offset:512
	global_store_dwordx4 v[118:119], v[110:113], off
	global_store_dwordx4 v[118:119], v[106:109], off offset:64
	v_lshl_add_u64 v[88:89], v[76:77], 0, v[214:215]
	global_store_dwordx4 v[88:89], v[64:67], off offset:576
	s_movk_i32 s0, 0x7f80
	v_cmp_gt_i32_e64 s[40:41], s0, v247
	v_add_u32_e32 v64, 0x80, v247
	v_ashrrev_i32_e32 v65, 31, v64
	v_add_u32_e32 v66, 0xffff8080, v247
	v_cndmask_b32_e64 v65, 0, v65, s[40:41]
	v_cndmask_b32_e64 v64, v66, v64, s[40:41]
	v_cndmask_b32_e64 v67, v248, v249, s[40:41]
	v_cndmask_b32_e64 v66, v250, v238, s[40:41]
	v_lshlrev_b64 v[148:149], 12, v[64:65]
	v_lshl_add_u64 v[64:65], v[66:67], 0, v[148:149]
	v_lshl_add_u64 v[150:151], v[64:65], 0, v[214:215]
	v_add_u32_e32 v64, 0x90, v247
	s_movk_i32 s0, 0x7f70
	v_cmp_gt_i32_e64 s[38:39], s0, v247
	v_ashrrev_i32_e32 v65, 31, v64
	v_add_u32_e32 v66, 0xffff8090, v247
	v_cndmask_b32_e64 v65, 0, v65, s[38:39]
	v_cndmask_b32_e64 v64, v66, v64, s[38:39]
	v_cndmask_b32_e64 v67, v248, v249, s[38:39]
	v_cndmask_b32_e64 v66, v250, v238, s[38:39]
	v_lshlrev_b64 v[146:147], 12, v[64:65]
	v_pk_fma_f32 v[78:79], v[82:83], v[104:105], v[160:161]
	v_pk_fma_f32 v[76:77], v[80:81], v[102:103], v[158:159]
	v_pk_fma_f32 v[72:73], v[72:73], v[98:99], v[154:155]
	v_pk_fma_f32 v[70:71], v[70:71], v[94:95], v[152:153]
	v_lshl_add_u64 v[64:65], v[66:67], 0, v[146:147]
	global_store_dwordx4 v[88:89], v[76:79], off
	global_store_dwordx4 v[88:89], v[72:75], off offset:64
	global_store_dwordx4 v[88:89], v[68:71], off offset:512
	v_lshl_add_u64 v[64:65], v[64:65], 0, v[214:215]
	global_load_dwordx4 v[138:141], v[150:151], off offset:64
	global_load_dwordx4 v[134:137], v[150:151], off offset:512
	global_load_dwordx4 v[130:133], v[150:151], off offset:576
	global_load_dwordx4 v[126:129], v[64:65], off
	global_load_dwordx4 v[122:125], v[64:65], off offset:64
	global_load_dwordx4 v[118:121], v[64:65], off offset:512
	global_load_dwordx4 v[114:117], v[64:65], off offset:576
	v_add_u32_e32 v64, 0xa0, v247
	s_movk_i32 s0, 0x7f60
	v_cmp_gt_i32_e64 s[0:1], s0, v247
	v_ashrrev_i32_e32 v65, 31, v64
	v_add_u32_e32 v66, 0xffff80a0, v247
	v_cndmask_b32_e64 v65, 0, v65, s[0:1]
	v_cndmask_b32_e64 v64, v66, v64, s[0:1]
	v_cndmask_b32_e64 v67, v248, v249, s[0:1]
	v_cndmask_b32_e64 v66, v250, v238, s[0:1]
	v_lshlrev_b64 v[144:145], 12, v[64:65]
	v_lshl_add_u64 v[64:65], v[66:67], 0, v[144:145]
	v_lshl_add_u64 v[64:65], v[64:65], 0, v[214:215]
	global_load_dwordx4 v[110:113], v[64:65], off
	global_load_dwordx4 v[106:109], v[64:65], off offset:64
	global_load_dwordx4 v[88:91], v[64:65], off offset:512
	global_load_dwordx4 v[80:83], v[64:65], off offset:576
	v_add_u32_e32 v64, 0xb0, v247
	v_cmp_gt_i32_e32 vcc, s42, v247
	v_ashrrev_i32_e32 v65, 31, v64
	v_add_u32_e32 v66, 0xffff80b0, v247
	v_cndmask_b32_e32 v65, 0, v65, vcc
	v_cndmask_b32_e32 v64, v66, v64, vcc
	v_cndmask_b32_e32 v67, v248, v249, vcc
	v_cndmask_b32_e32 v66, v250, v238, vcc
	v_lshlrev_b64 v[142:143], 12, v[64:65]
	v_lshl_add_u64 v[64:65], v[66:67], 0, v[142:143]
	v_lshl_add_u64 v[64:65], v[64:65], 0, v[214:215]
	v_cndmask_b32_e64 v153, v243, v244, s[40:41]
	v_cndmask_b32_e64 v152, v245, v246, s[40:41]
	global_load_dwordx4 v[76:79], v[64:65], off
	global_load_dwordx4 v[72:75], v[64:65], off offset:64
	global_load_dwordx4 v[68:71], v[64:65], off offset:512
	s_nop 0
	global_load_dwordx4 v[64:67], v[64:65], off offset:576
	v_lshl_add_u64 v[148:149], v[152:153], 0, v[148:149]
	global_load_dwordx4 v[150:153], v[150:151], off
	v_lshl_add_u64 v[148:149], v[148:149], 0, v[214:215]
	s_mov_b64 s[40:41], s[50:51]
	s_waitcnt vmcnt(0)
; #define PG8_WAIT_V(n) asm volatile("s_waitcnt vmcnt(" #n ")" ::: "memory")
; #define PG8_BAR __builtin_amdgcn_s_barrier()
; template <class Epi, class Sched>
; __device__ __forceinline__ void gemm_phase(PG8_LAS unsigned char* lds, const Gemm g, const Sched& S, const Epi& E) {
;     ...
;         if (!has_next) break;
; #pragma unroll
;         for (int a = 0; a < 2; ++a)
; #pragma unroll
;             for (int b = 0; b < 2; ++b)
; #pragma unroll
;                 for (int m = 0; m < 4; ++m)
; #pragma unroll
;                     for (int n = 0; n < 2; ++n) acc[a][b][m][n] = (f32x4){0.f, 0.f, 0.f, 0.f};
;         cur = nxt; cA = nA; cB = nB; ++ui;
;     }
;     PG8_WAIT_V(0);
;     if (wr == 0) PG8_BAR;
;     PG8_BAR;
;   DEV void operator()(const f32x4 (&acc)[2][2][4][2], const pg8::Unit& u, int wr, int wc, int fr, int fq) const {
;     ...
;       for (int m = 0; m < 4; ++m) {
;         const int row = row0 + ai * 128 + m * 16;
;         float* xr = row < T_LAT ? out + (size_t)row * DM : xc + (size_t)(row - T_LAT) * DM;
; #pragma unroll
;         for (int bj = 0; bj < 2; ++bj)
; #pragma unroll
;           for (int n = 0; n < 2; ++n) {
;             const f32x4 r = xv[m][bj][n] + g4[bj][n] * acc[ai][bj][m][n];
;             if (store) *(f32x4*)(xr + col0 + bj * 128 + n * 16) = r;
;           }
;       }
	v_pk_fma_f32 v[58:59], v[58:59], v[100:101], v[140:141]
	v_pk_fma_f32 v[54:55], v[54:55], v[94:95], v[136:137]
	v_pk_fma_f32 v[46:47], v[46:47], v[86:87], v[132:133]
	v_pk_fma_f32 v[44:45], v[44:45], v[84:85], v[130:131]
	global_store_dwordx4 v[148:149], v[44:47], off offset:576
	v_pk_fma_f32 v[52:53], v[52:53], v[92:93], v[134:135]
	v_pk_fma_f32 v[56:57], v[56:57], v[98:99], v[138:139]
	v_cndmask_b32_e64 v45, v243, v244, s[38:39]
	v_cndmask_b32_e64 v44, v245, v246, s[38:39]
	v_lshl_add_u64 v[44:45], v[44:45], 0, v[146:147]
	global_store_dwordx4 v[148:149], v[52:55], off offset:512
	v_pk_fma_f32 v[30:31], v[30:31], v[86:87], v[116:117]
	v_pk_fma_f32 v[28:29], v[28:29], v[84:85], v[114:115]
	v_lshl_add_u64 v[52:53], v[44:45], 0, v[214:215]
	global_store_dwordx4 v[148:149], v[56:59], off offset:64
	v_pk_fma_f32 v[38:39], v[38:39], v[94:95], v[120:121]
	v_pk_fma_f32 v[36:37], v[36:37], v[92:93], v[118:119]
	v_pk_fma_f32 v[46:47], v[50:51], v[104:105], v[128:129]
	v_pk_fma_f32 v[44:45], v[48:49], v[102:103], v[126:127]
	v_pk_fma_f32 v[42:43], v[42:43], v[100:101], v[124:125]
	v_pk_fma_f32 v[40:41], v[40:41], v[98:99], v[122:123]
	v_pk_fma_f32 v[14:15], v[14:15], v[86:87], v[82:83]
	v_pk_fma_f32 v[12:13], v[12:13], v[84:85], v[80:81]
	v_pk_fma_f32 v[22:23], v[22:23], v[94:95], v[90:91]
	v_pk_fma_f32 v[20:21], v[20:21], v[92:93], v[88:89]
	v_pk_fma_f32 v[26:27], v[26:27], v[100:101], v[108:109]
	v_pk_fma_f32 v[24:25], v[24:25], v[98:99], v[106:107]
	s_mov_b64 s[38:39], s[48:49]
	v_pk_fma_f32 v[10:11], v[10:11], v[100:101], v[74:75]
	v_pk_fma_f32 v[8:9], v[8:9], v[98:99], v[72:73]
	v_pk_fma_f32 v[6:7], v[6:7], v[94:95], v[70:71]
	v_pk_fma_f32 v[4:5], v[4:5], v[92:93], v[68:69]
	v_pk_fma_f32 v[62:63], v[62:63], v[104:105], v[152:153]
	v_pk_fma_f32 v[60:61], v[60:61], v[102:103], v[150:151]
	global_store_dwordx4 v[148:149], v[60:63], off
	global_store_dwordx4 v[52:53], v[28:31], off offset:576
	global_store_dwordx4 v[52:53], v[36:39], off offset:512
	global_store_dwordx4 v[52:53], v[44:47], off
	v_cndmask_b32_e64 v29, v243, v244, s[0:1]
	v_cndmask_b32_e64 v28, v245, v246, s[0:1]
	v_lshl_add_u64 v[28:29], v[28:29], 0, v[144:145]
	v_lshl_add_u64 v[36:37], v[28:29], 0, v[214:215]
	global_store_dwordx4 v[52:53], v[40:43], off offset:64
	global_store_dwordx4 v[36:37], v[12:15], off offset:576
	v_pk_fma_f32 v[30:31], v[34:35], v[104:105], v[112:113]
	v_pk_fma_f32 v[28:29], v[32:33], v[102:103], v[110:111]
	v_cndmask_b32_e32 v13, v243, v244, vcc
	v_cndmask_b32_e32 v12, v245, v246, vcc
	v_lshl_add_u64 v[12:13], v[12:13], 0, v[142:143]
	global_store_dwordx4 v[36:37], v[20:23], off offset:512
	v_pk_fma_f32 v[14:15], v[18:19], v[104:105], v[78:79]
	v_pk_fma_f32 v[2:3], v[2:3], v[86:87], v[66:67]
	v_lshl_add_u64 v[20:21], v[12:13], 0, v[214:215]
	v_pk_fma_f32 v[12:13], v[16:17], v[102:103], v[76:77]
	v_pk_fma_f32 v[0:1], v[0:1], v[84:85], v[64:65]
	s_and_b64 vcc, exec, s[36:37]
	s_mov_b32 s1, s44
	s_mov_b32 s0, s46
	global_store_dwordx4 v[36:37], v[28:31], off
	global_store_dwordx4 v[36:37], v[24:27], off offset:64
	global_store_dwordx4 v[20:21], v[12:15], off
	global_store_dwordx4 v[20:21], v[8:11], off offset:64
	global_store_dwordx4 v[20:21], v[4:7], off offset:512
	global_store_dwordx4 v[20:21], v[0:3], off offset:576
	s_cbranch_vccz .LBB0_84
	s_waitcnt vmcnt(0)
	v_readlane_b32 s0, v255, 48
	v_readlane_b32 s66, v255, 34
	v_readlane_b32 s68, v255, 36
	s_cmpk_gt_u32 s0, 0xff
	v_readlane_b32 s67, v255, 35
	v_readlane_b32 s69, v255, 37
	v_readlane_b32 s70, v255, 41
	s_mov_b64 s[78:79], 0
	s_cbranch_scc1 .LBB0_91
	s_barrier

; #define PG8_STAGE(bufoff, gbase, voff) do { _Pragma("unroll") for (int _i = 0; _i < 2; ++_i) \
;         __builtin_amdgcn_global_load_lds((const unsigned*)((const char*)(gbase) + (voff)[_i]), (PG8_LAS unsigned*)(lds + (bufoff) + ldsw + _i * 8192), 16, 0, 0); } while (0)
; #define PG8_LDA(dst, b, h) do { _Pragma("unroll") for (int m = 0; m < 4; ++m) _Pragma("unroll") for (int k = 0; k < 2; ++k) dst[m][k] = *(const PG8_LAS bf16x8*)(lds + PG8_SA(b, h) + aoff + m * 2048 + k * 1024); } while (0)
; #define PG8_WAIT_V(n) asm volatile("s_waitcnt vmcnt(" #n ")" ::: "memory")
; template <class Epi, class Sched>
; __device__ __forceinline__ void gemm_phase(PG8_LAS unsigned char* lds, const Gemm g, const Sched& S, const Epi& E) {
;     ...
;         for (int t = 0; t < nt; t += 2) {
;             const bool last = (t == nt - 2);
;             const char* a1 = cA + (size_t)(t + 1) * kstep;
;             const char* a2 = last ? nA : cA + (size_t)(t + 2) * kstep; const char* b2 = last ? nB : cB + (size_t)(t + 2) * kstep;
;             const char* a3 = a2 + kstep; const char* b3 = b2 + kstep;
;             if (last && has_next) S.a_ready(nxt);
;             PG8_LDB(B0, 0, 0); PG8_SCHED; PG8_LDA(At, 0, 0); PG8_STAGE(PG8_SA(1, 1), a1 + hstep, voffA);
;             PG8_WAIT_L(8); PG8_BAR; PG8_WAIT_L(0); PG8_MMA(0, 0, At, B0); PG8_BAR; PG8_SCHED;
;             PG8_LDB(B1, 0, 1); PG8_STAGE(PG8_SB(0, 0), b2, voffB);
;             PG8_BAR; PG8_WAIT_L(0); PG8_MMA(0, 1, At, B1); PG8_BAR;
;             PG8_LDA(At, 0, 1); PG8_STAGE(PG8_SA(0, 0), a2, voffA);
;             PG8_BAR; PG8_WAIT_L(0); PG8_MMA(1, 0, At, B0); PG8_BAR; PG8_SCHED;
;             PG8_STAGE(PG8_SB(0, 1), b2 + hstep, voffB);
;             PG8_WAIT_V(6); PG8_BAR; PG8_MMA(1, 1, At, B1); PG8_BAR;
;             PG8_LDB(B0, 1, 0); PG8_SCHED; PG8_LDA(At, 1, 0); PG8_STAGE(PG8_SA(0, 1), a2 + hstep, voffA);
;             PG8_WAIT_L(8); PG8_BAR; PG8_WAIT_L(0); PG8_MMA(0, 0, At, B0); PG8_BAR; PG8_SCHED;
;             PG8_LDB(B1, 1, 1); PG8_STAGE(PG8_SB(1, 0), b3, voffB);
;             PG8_BAR; PG8_WAIT_L(0); PG8_MMA(0, 1, At, B1); PG8_BAR;
;             PG8_LDA(At, 1, 1); PG8_STAGE(PG8_SA(1, 0), a3, voffA);
;             PG8_BAR; PG8_WAIT_L(0); PG8_MMA(1, 0, At, B0); PG8_BAR; PG8_SCHED;
;             PG8_STAGE(PG8_SB(1, 1), b3 + hstep, voffB);
;             PG8_WAIT_V(6); PG8_BAR; PG8_MMA(1, 1, At, B1); PG8_BAR;
.Lgp_5880:
.LBB0_105:
	s_add_u32 s50, s48, 0xfffe0080
	s_addc_u32 s51, s49, -1
	s_add_i32 s70, 0, 0x10000
	v_add_u32_e32 v96, s70, v221
	ds_read_b128 v[130:133], v96
	ds_read_b128 v[134:137], v96 offset:1024
	ds_read_b128 v[138:141], v96 offset:2048
	ds_read_b128 v[142:145], v96 offset:3072
	s_cmp_eq_u32 s69, 4
	s_cselect_b32 s53, s1, s51
	s_cselect_b32 s52, s39, s50
	s_cselect_b32 s51, s31, s68
	s_cselect_b32 s50, s47, s67
	v_lshl_add_u64 v[178:179], s[48:49], 0, v[204:205]
	s_add_i32 m0, s59, 0xc000
	ds_read_b128 v[146:149], v223
	ds_read_b128 v[150:153], v223 offset:1024
	ds_read_b128 v[154:157], v223 offset:2048
	ds_read_b128 v[158:161], v223 offset:3072
	ds_read_b128 v[162:165], v223 offset:4096
	ds_read_b128 v[166:169], v223 offset:5120
	ds_read_b128 v[170:173], v223 offset:6144
	ds_read_b128 v[174:177], v223 offset:7168
	global_load_lds_dwordx4 v[178:179], off
	v_lshl_add_u64 v[178:179], s[48:49], 0, v[208:209]
	s_add_i32 m0, s59, 0xe000
	s_nop 0
	global_load_lds_dwordx4 v[178:179], off
	s_waitcnt lgkmcnt(8)
	s_barrier
	s_waitcnt lgkmcnt(0)
	v_mfma_f32_16x16x32_bf16 v[126:129], v[130:133], v[146:149], v[126:129]
	v_mfma_f32_16x16x32_bf16 v[122:125], v[138:141], v[146:149], v[122:125]
	v_mfma_f32_16x16x32_bf16 v[110:113], v[130:133], v[154:157], v[110:113]
	v_mfma_f32_16x16x32_bf16 v[106:109], v[138:141], v[154:157], v[106:109]
	v_mfma_f32_16x16x32_bf16 v[92:95], v[130:133], v[162:165], v[92:95]
	v_mfma_f32_16x16x32_bf16 v[88:91], v[138:141], v[162:165], v[88:91]
	v_mfma_f32_16x16x32_bf16 v[76:79], v[130:133], v[170:173], v[76:79]
	v_mfma_f32_16x16x32_bf16 v[72:75], v[138:141], v[170:173], v[72:75]
	v_mfma_f32_16x16x32_bf16 v[126:129], v[134:137], v[150:153], v[126:129]
	v_mfma_f32_16x16x32_bf16 v[122:125], v[142:145], v[150:153], v[122:125]
	v_mfma_f32_16x16x32_bf16 v[110:113], v[134:137], v[158:161], v[110:113]
	v_mfma_f32_16x16x32_bf16 v[106:109], v[142:145], v[158:161], v[106:109]
	v_mfma_f32_16x16x32_bf16 v[92:95], v[134:137], v[166:169], v[92:95]
	v_mfma_f32_16x16x32_bf16 v[88:91], v[142:145], v[166:169], v[88:91]
	v_mfma_f32_16x16x32_bf16 v[76:79], v[134:137], v[174:177], v[76:79]
	v_mfma_f32_16x16x32_bf16 v[72:75], v[142:145], v[174:177], v[72:75]
	s_barrier
	s_add_i32 s94, 0, 0x14000
	s_add_i32 s70, s70, s58
	v_add_u32_e32 v96, s94, v221
	v_lshl_add_u64 v[194:195], s[50:51], 0, v[198:199]
	s_mov_b32 m0, s70
	ds_read_b128 v[178:181], v96
	ds_read_b128 v[182:185], v96 offset:1024
	ds_read_b128 v[186:189], v96 offset:2048
	ds_read_b128 v[190:193], v96 offset:3072
	global_load_lds_dwordx4 v[194:195], off
	v_lshl_add_u64 v[210:211], s[50:51], 0, v[202:203]
	s_add_i32 m0, s70, 0x2000
	s_nop 0
	global_load_lds_dwordx4 v[210:211], off
	s_barrier
	s_waitcnt lgkmcnt(0)
	v_mfma_f32_16x16x32_bf16 v[118:121], v[178:181], v[146:149], v[118:121]
	v_mfma_f32_16x16x32_bf16 v[114:117], v[186:189], v[146:149], v[114:117]
	v_mfma_f32_16x16x32_bf16 v[102:105], v[178:181], v[154:157], v[102:105]
	v_mfma_f32_16x16x32_bf16 v[98:101], v[186:189], v[154:157], v[98:101]
	v_mfma_f32_16x16x32_bf16 v[84:87], v[178:181], v[162:165], v[84:87]
	v_mfma_f32_16x16x32_bf16 v[80:83], v[186:189], v[162:165], v[80:83]
	v_mfma_f32_16x16x32_bf16 v[68:71], v[178:181], v[170:173], v[68:71]
	v_mfma_f32_16x16x32_bf16 v[64:67], v[186:189], v[170:173], v[64:67]
	v_mfma_f32_16x16x32_bf16 v[118:121], v[182:185], v[150:153], v[118:121]
	v_mfma_f32_16x16x32_bf16 v[114:117], v[190:193], v[150:153], v[114:117]
	v_mfma_f32_16x16x32_bf16 v[102:105], v[182:185], v[158:161], v[102:105]
	v_mfma_f32_16x16x32_bf16 v[98:101], v[190:193], v[158:161], v[98:101]
	v_mfma_f32_16x16x32_bf16 v[84:87], v[182:185], v[166:169], v[84:87]
	v_mfma_f32_16x16x32_bf16 v[80:83], v[190:193], v[166:169], v[80:83]
	v_mfma_f32_16x16x32_bf16 v[68:71], v[182:185], v[174:177], v[68:71]
	v_mfma_f32_16x16x32_bf16 v[64:67], v[190:193], v[174:177], v[64:67]
	s_mov_b32 m0, s59
	v_lshl_add_u64 v[212:213], s[52:53], 0, v[196:197]
	s_barrier
	ds_read_b128 v[146:149], v223 offset:16384
	ds_read_b128 v[150:153], v223 offset:17408
	ds_read_b128 v[154:157], v223 offset:18432
	ds_read_b128 v[158:161], v223 offset:19456
	ds_read_b128 v[162:165], v223 offset:20480
	ds_read_b128 v[166:169], v223 offset:21504
	ds_read_b128 v[170:173], v223 offset:22528
	ds_read_b128 v[174:177], v223 offset:23552
	global_load_lds_dwordx4 v[212:213], off
	v_lshl_add_u64 v[214:215], s[52:53], 0, v[200:201]
	s_mov_b32 m0, s60
	s_nop 0
	global_load_lds_dwordx4 v[214:215], off
	s_barrier
	s_waitcnt lgkmcnt(0)
	v_mfma_f32_16x16x32_bf16 v[60:63], v[130:133], v[146:149], v[60:63]
	v_mfma_f32_16x16x32_bf16 v[56:59], v[138:141], v[146:149], v[56:59]
	v_mfma_f32_16x16x32_bf16 v[44:47], v[130:133], v[154:157], v[44:47]
	v_mfma_f32_16x16x32_bf16 v[40:43], v[138:141], v[154:157], v[40:43]
	v_mfma_f32_16x16x32_bf16 v[28:31], v[130:133], v[162:165], v[28:31]
	v_mfma_f32_16x16x32_bf16 v[24:27], v[138:141], v[162:165], v[24:27]
	v_mfma_f32_16x16x32_bf16 v[12:15], v[130:133], v[170:173], v[12:15]
	v_mfma_f32_16x16x32_bf16 v[8:11], v[138:141], v[170:173], v[8:11]
	v_mfma_f32_16x16x32_bf16 v[60:63], v[134:137], v[150:153], v[60:63]
	v_mfma_f32_16x16x32_bf16 v[56:59], v[142:145], v[150:153], v[56:59]
	v_mfma_f32_16x16x32_bf16 v[44:47], v[134:137], v[158:161], v[44:47]
	v_mfma_f32_16x16x32_bf16 v[40:43], v[142:145], v[158:161], v[40:43]
	v_mfma_f32_16x16x32_bf16 v[28:31], v[134:137], v[166:169], v[28:31]
	v_mfma_f32_16x16x32_bf16 v[24:27], v[142:145], v[166:169], v[24:27]
	v_mfma_f32_16x16x32_bf16 v[12:15], v[134:137], v[174:177], v[12:15]
	v_mfma_f32_16x16x32_bf16 v[8:11], v[142:145], v[174:177], v[8:11]
	s_barrier
; #define PG8_STAGE(bufoff, gbase, voff) do { _Pragma("unroll") for (int _i = 0; _i < 2; ++_i) \
;         __builtin_amdgcn_global_load_lds((const unsigned*)((const char*)(gbase) + (voff)[_i]), (PG8_LAS unsigned*)(lds + (bufoff) + ldsw + _i * 8192), 16, 0, 0); } while (0)
; #define PG8_LDA(dst, b, h) do { _Pragma("unroll") for (int m = 0; m < 4; ++m) _Pragma("unroll") for (int k = 0; k < 2; ++k) dst[m][k] = *(const PG8_LAS bf16x8*)(lds + PG8_SA(b, h) + aoff + m * 2048 + k * 1024); } while (0)
; #define PG8_WAIT_V(n) asm volatile("s_waitcnt vmcnt(" #n ")" ::: "memory")
; template <class Epi, class Sched>
; __device__ __forceinline__ void gemm_phase(PG8_LAS unsigned char* lds, const Gemm g, const Sched& S, const Epi& E) {
;     ...
;         for (int t = 0; t < nt; t += 2) {
;             const bool last = (t == nt - 2);
;             const char* a1 = cA + (size_t)(t + 1) * kstep;
;             const char* a2 = last ? nA : cA + (size_t)(t + 2) * kstep; const char* b2 = last ? nB : cB + (size_t)(t + 2) * kstep;
;             const char* a3 = a2 + kstep; const char* b3 = b2 + kstep;
;             if (last && has_next) S.a_ready(nxt);
;             PG8_LDB(B0, 0, 0); PG8_SCHED; PG8_LDA(At, 0, 0); PG8_STAGE(PG8_SA(1, 1), a1 + hstep, voffA);
;             PG8_WAIT_L(8); PG8_BAR; PG8_WAIT_L(0); PG8_MMA(0, 0, At, B0); PG8_BAR; PG8_SCHED;
;             PG8_LDB(B1, 0, 1); PG8_STAGE(PG8_SB(0, 0), b2, voffB);
;             PG8_BAR; PG8_WAIT_L(0); PG8_MMA(0, 1, At, B1); PG8_BAR;
;             PG8_LDA(At, 0, 1); PG8_STAGE(PG8_SA(0, 0), a2, voffA);
;             PG8_BAR; PG8_WAIT_L(0); PG8_MMA(1, 0, At, B0); PG8_BAR; PG8_SCHED;
;             PG8_STAGE(PG8_SB(0, 1), b2 + hstep, voffB);
;             PG8_WAIT_V(6); PG8_BAR; PG8_MMA(1, 1, At, B1); PG8_BAR;
;             PG8_LDB(B0, 1, 0); PG8_SCHED; PG8_LDA(At, 1, 0); PG8_STAGE(PG8_SA(0, 1), a2 + hstep, voffA);
;             PG8_WAIT_L(8); PG8_BAR; PG8_WAIT_L(0); PG8_MMA(0, 0, At, B0); PG8_BAR; PG8_SCHED;
;             PG8_LDB(B1, 1, 1); PG8_STAGE(PG8_SB(1, 0), b3, voffB);
;             PG8_BAR; PG8_WAIT_L(0); PG8_MMA(0, 1, At, B1); PG8_BAR;
;             PG8_LDA(At, 1, 1); PG8_STAGE(PG8_SA(1, 0), a3, voffA);
;             PG8_BAR; PG8_WAIT_L(0); PG8_MMA(1, 0, At, B0); PG8_BAR; PG8_SCHED;
;             PG8_STAGE(PG8_SB(1, 1), b3 + hstep, voffB);
;             PG8_WAIT_V(6); PG8_BAR; PG8_MMA(1, 1, At, B1); PG8_BAR;
	s_add_u32 s70, s50, 0x20000
	s_addc_u32 s71, s51, 0
	s_add_i32 s94, s94, s58
	v_lshl_add_u64 v[130:131], s[70:71], 0, v[198:199]
	s_mov_b32 m0, s94
	s_nop 0
	global_load_lds_dwordx4 v[130:131], off
	v_lshl_add_u64 v[130:131], s[70:71], 0, v[202:203]
	s_add_i32 m0, s94, 0x2000
	s_nop 0
	global_load_lds_dwordx4 v[130:131], off
	s_waitcnt vmcnt(6)
	s_barrier
	v_mfma_f32_16x16x32_bf16 v[52:55], v[178:181], v[146:149], v[52:55]
	v_mfma_f32_16x16x32_bf16 v[48:51], v[186:189], v[146:149], v[48:51]
	v_mfma_f32_16x16x32_bf16 v[36:39], v[178:181], v[154:157], v[36:39]
	v_mfma_f32_16x16x32_bf16 v[32:35], v[186:189], v[154:157], v[32:35]
	v_mfma_f32_16x16x32_bf16 v[20:23], v[178:181], v[162:165], v[20:23]
	v_mfma_f32_16x16x32_bf16 v[16:19], v[186:189], v[162:165], v[16:19]
	v_mfma_f32_16x16x32_bf16 v[4:7], v[178:181], v[170:173], v[4:7]
	v_mfma_f32_16x16x32_bf16 v[0:3], v[186:189], v[170:173], v[0:3]
	v_mfma_f32_16x16x32_bf16 v[52:55], v[182:185], v[150:153], v[52:55]
	v_mfma_f32_16x16x32_bf16 v[48:51], v[190:193], v[150:153], v[48:51]
	v_mfma_f32_16x16x32_bf16 v[36:39], v[182:185], v[158:161], v[36:39]
	v_mfma_f32_16x16x32_bf16 v[32:35], v[190:193], v[158:161], v[32:35]
	v_mfma_f32_16x16x32_bf16 v[20:23], v[182:185], v[166:169], v[20:23]
	v_mfma_f32_16x16x32_bf16 v[16:19], v[190:193], v[166:169], v[16:19]
	v_mfma_f32_16x16x32_bf16 v[4:7], v[182:185], v[174:177], v[4:7]
	v_mfma_f32_16x16x32_bf16 v[0:3], v[190:193], v[174:177], v[0:3]
	s_add_i32 s70, 0, 0x18000
	v_add_u32_e32 v96, s70, v221
	s_barrier
	ds_read_b128 v[130:133], v96
	ds_read_b128 v[134:137], v96 offset:1024
	ds_read_b128 v[138:141], v96 offset:2048
	ds_read_b128 v[142:145], v96 offset:3072
	s_add_u32 s52, s52, 0x20000
	s_addc_u32 s53, s53, 0
	s_mov_b32 m0, s61
	v_lshl_add_u64 v[178:179], s[52:53], 0, v[196:197]
	ds_read_b128 v[146:149], v223 offset:32768
	ds_read_b128 v[150:153], v223 offset:33792
	ds_read_b128 v[154:157], v223 offset:34816
	ds_read_b128 v[158:161], v223 offset:35840
	ds_read_b128 v[162:165], v223 offset:36864
	ds_read_b128 v[166:169], v223 offset:37888
	ds_read_b128 v[170:173], v223 offset:38912
	ds_read_b128 v[174:177], v223 offset:39936
	global_load_lds_dwordx4 v[178:179], off
	v_lshl_add_u64 v[178:179], s[52:53], 0, v[200:201]
	s_mov_b32 m0, s62
	s_nop 0
	global_load_lds_dwordx4 v[178:179], off
	s_waitcnt lgkmcnt(8)
	s_barrier
	s_waitcnt lgkmcnt(0)
	v_mfma_f32_16x16x32_bf16 v[126:129], v[130:133], v[146:149], v[126:129]
	v_mfma_f32_16x16x32_bf16 v[122:125], v[138:141], v[146:149], v[122:125]
	v_mfma_f32_16x16x32_bf16 v[110:113], v[130:133], v[154:157], v[110:113]
	v_mfma_f32_16x16x32_bf16 v[106:109], v[138:141], v[154:157], v[106:109]
	v_mfma_f32_16x16x32_bf16 v[92:95], v[130:133], v[162:165], v[92:95]
	v_mfma_f32_16x16x32_bf16 v[88:91], v[138:141], v[162:165], v[88:91]
	v_mfma_f32_16x16x32_bf16 v[76:79], v[130:133], v[170:173], v[76:79]
	v_mfma_f32_16x16x32_bf16 v[72:75], v[138:141], v[170:173], v[72:75]
	v_mfma_f32_16x16x32_bf16 v[126:129], v[134:137], v[150:153], v[126:129]
	v_mfma_f32_16x16x32_bf16 v[122:125], v[142:145], v[150:153], v[122:125]
	v_mfma_f32_16x16x32_bf16 v[110:113], v[134:137], v[158:161], v[110:113]
	v_mfma_f32_16x16x32_bf16 v[106:109], v[142:145], v[158:161], v[106:109]
	v_mfma_f32_16x16x32_bf16 v[92:95], v[134:137], v[166:169], v[92:95]
	v_mfma_f32_16x16x32_bf16 v[88:91], v[142:145], v[166:169], v[88:91]
	v_mfma_f32_16x16x32_bf16 v[76:79], v[134:137], v[174:177], v[76:79]
	v_mfma_f32_16x16x32_bf16 v[72:75], v[142:145], v[174:177], v[72:75]
	s_barrier
	s_add_i32 s52, 0, 0x1c000
	s_add_i32 s53, s70, s58
	v_add_u32_e32 v96, s52, v221
	v_lshl_add_u64 v[194:195], v[194:195], 0, s[2:3]
	s_mov_b32 m0, s53
	ds_read_b128 v[178:181], v96
	ds_read_b128 v[182:185], v96 offset:1024
	ds_read_b128 v[186:189], v96 offset:2048
	ds_read_b128 v[190:193], v96 offset:3072
	global_load_lds_dwordx4 v[194:195], off
	v_lshl_add_u64 v[194:195], v[210:211], 0, s[2:3]
	s_add_i32 m0, s53, 0x2000
	s_nop 0
	global_load_lds_dwordx4 v[194:195], off
	s_barrier
	s_waitcnt lgkmcnt(0)
	v_mfma_f32_16x16x32_bf16 v[118:121], v[178:181], v[146:149], v[118:121]
	v_mfma_f32_16x16x32_bf16 v[114:117], v[186:189], v[146:149], v[114:117]
	v_mfma_f32_16x16x32_bf16 v[102:105], v[178:181], v[154:157], v[102:105]
	v_mfma_f32_16x16x32_bf16 v[98:101], v[186:189], v[154:157], v[98:101]
	v_mfma_f32_16x16x32_bf16 v[84:87], v[178:181], v[162:165], v[84:87]
	v_mfma_f32_16x16x32_bf16 v[80:83], v[186:189], v[162:165], v[80:83]
	v_mfma_f32_16x16x32_bf16 v[68:71], v[178:181], v[170:173], v[68:71]
	v_mfma_f32_16x16x32_bf16 v[64:67], v[186:189], v[170:173], v[64:67]
	v_mfma_f32_16x16x32_bf16 v[118:121], v[182:185], v[150:153], v[118:121]
	v_mfma_f32_16x16x32_bf16 v[114:117], v[190:193], v[150:153], v[114:117]
	v_mfma_f32_16x16x32_bf16 v[102:105], v[182:185], v[158:161], v[102:105]
	v_mfma_f32_16x16x32_bf16 v[98:101], v[190:193], v[158:161], v[98:101]
	v_mfma_f32_16x16x32_bf16 v[84:87], v[182:185], v[166:169], v[84:87]
	v_mfma_f32_16x16x32_bf16 v[80:83], v[190:193], v[166:169], v[80:83]
	v_mfma_f32_16x16x32_bf16 v[68:71], v[182:185], v[174:177], v[68:71]
	v_mfma_f32_16x16x32_bf16 v[64:67], v[190:193], v[174:177], v[64:67]
	s_mov_b32 m0, s63
	v_lshl_add_u64 v[194:195], v[212:213], 0, s[2:3]
	s_barrier
; #define PG8_STAGE(bufoff, gbase, voff) do { _Pragma("unroll") for (int _i = 0; _i < 2; ++_i) \
;         __builtin_amdgcn_global_load_lds((const unsigned*)((const char*)(gbase) + (voff)[_i]), (PG8_LAS unsigned*)(lds + (bufoff) + ldsw + _i * 8192), 16, 0, 0); } while (0)
; #define PG8_LDA(dst, b, h) do { _Pragma("unroll") for (int m = 0; m < 4; ++m) _Pragma("unroll") for (int k = 0; k < 2; ++k) dst[m][k] = *(const PG8_LAS bf16x8*)(lds + PG8_SA(b, h) + aoff + m * 2048 + k * 1024); } while (0)
; #define PG8_WAIT_V(n) asm volatile("s_waitcnt vmcnt(" #n ")" ::: "memory")
; #define PG8_WAIT_L(n) asm volatile("s_waitcnt lgkmcnt(" #n ")" ::: "memory")
; template <class Epi, class Sched>
; __device__ __forceinline__ void gemm_phase(PG8_LAS unsigned char* lds, const Gemm g, const Sched& S, const Epi& E) {
;     ...
;             PG8_WAIT_V(6); PG8_BAR; PG8_MMA(1, 1, At, B1); PG8_BAR;
;             PG8_LDB(B0, 1, 0); PG8_SCHED; PG8_LDA(At, 1, 0); PG8_STAGE(PG8_SA(0, 1), a2 + hstep, voffA);
;             PG8_WAIT_L(8); PG8_BAR; PG8_WAIT_L(0); PG8_MMA(0, 0, At, B0); PG8_BAR; PG8_SCHED;
;             PG8_LDB(B1, 1, 1); PG8_STAGE(PG8_SB(1, 0), b3, voffB);
;             PG8_BAR; PG8_WAIT_L(0); PG8_MMA(0, 1, At, B1); PG8_BAR;
;             PG8_LDA(At, 1, 1); PG8_STAGE(PG8_SA(1, 0), a3, voffA);
;             PG8_BAR; PG8_WAIT_L(0); PG8_MMA(1, 0, At, B0); PG8_BAR; PG8_SCHED;
;             PG8_STAGE(PG8_SB(1, 1), b3 + hstep, voffB);
;             PG8_WAIT_V(6); PG8_BAR; PG8_MMA(1, 1, At, B1); PG8_BAR;
;   DEV void operator()(const f32x4 (&acc)[2][2][4][2], const pg8::Unit& u, int wr, int wc, int fr, int fq) const {
;     const int b = u.pn >> 2, pn = u.pn & 3, pm = u.pm - 136 * (b == 0 ? 11 : (b == 1 ? 12 : 6));
;     const bf16_t* G = (const bf16_t*)(ws + (b == 0 ? O_G1 : (b == 1 ? O_G2 : O_G3)));
;     bf16_t* M = (bf16_t*)(ws + O_M);
;     const int row0 = pm * 256 + wr * 64 + fr, col0 = pn * 256 + wc * 32 + 8 * fq;
; #pragma unroll
;     for (int ai = 0; ai < 2; ++ai) {
;       u32x4 gv[4][2], mv[4][2];
; #pragma unroll
;       for (int m = 0; m < 4; ++m)
; #pragma unroll
;         for (int bj = 0; bj < 2; ++bj) {
;           const size_t off = (size_t)(row0 + ai * 128 + m * 16) * DM + col0 + bj * 128;
;           gv[m][bj] = *(const u32x4*)(G + off);
;           mv[m][bj] = (u32x4){0u, 0u, 0u, 0u};
;           if (b > 0) mv[m][bj] = *(const u32x4*)(M + off);
	ds_read_b128 v[146:149], v223 offset:49152
	ds_read_b128 v[150:153], v223 offset:50176
	ds_read_b128 v[154:157], v223 offset:51200
	ds_read_b128 v[158:161], v223 offset:52224
	ds_read_b128 v[162:165], v223 offset:53248
	ds_read_b128 v[166:169], v223 offset:54272
	ds_read_b128 v[170:173], v223 offset:55296
	ds_read_b128 v[174:177], v223 offset:56320
	global_load_lds_dwordx4 v[194:195], off
	v_lshl_add_u64 v[194:195], v[214:215], 0, s[2:3]
	s_mov_b32 m0, s64
	s_nop 0
	global_load_lds_dwordx4 v[194:195], off
	s_barrier
	s_waitcnt lgkmcnt(0)
	v_mfma_f32_16x16x32_bf16 v[60:63], v[130:133], v[146:149], v[60:63]
	v_mfma_f32_16x16x32_bf16 v[56:59], v[138:141], v[146:149], v[56:59]
	v_mfma_f32_16x16x32_bf16 v[44:47], v[130:133], v[154:157], v[44:47]
	v_mfma_f32_16x16x32_bf16 v[40:43], v[138:141], v[154:157], v[40:43]
	v_mfma_f32_16x16x32_bf16 v[28:31], v[130:133], v[162:165], v[28:31]
	v_mfma_f32_16x16x32_bf16 v[24:27], v[138:141], v[162:165], v[24:27]
	v_mfma_f32_16x16x32_bf16 v[12:15], v[130:133], v[170:173], v[12:15]
	v_mfma_f32_16x16x32_bf16 v[8:11], v[138:141], v[170:173], v[8:11]
	v_mfma_f32_16x16x32_bf16 v[60:63], v[134:137], v[150:153], v[60:63]
	v_mfma_f32_16x16x32_bf16 v[56:59], v[142:145], v[150:153], v[56:59]
	v_mfma_f32_16x16x32_bf16 v[44:47], v[134:137], v[158:161], v[44:47]
	v_mfma_f32_16x16x32_bf16 v[40:43], v[142:145], v[158:161], v[40:43]
	v_mfma_f32_16x16x32_bf16 v[28:31], v[134:137], v[166:169], v[28:31]
	v_mfma_f32_16x16x32_bf16 v[24:27], v[142:145], v[166:169], v[24:27]
	v_mfma_f32_16x16x32_bf16 v[12:15], v[134:137], v[174:177], v[12:15]
	v_mfma_f32_16x16x32_bf16 v[8:11], v[142:145], v[174:177], v[8:11]
	s_barrier
	s_add_u32 s50, s50, 0x20080
	s_addc_u32 s51, s51, 0
	s_add_i32 s52, s52, s58
	v_lshl_add_u64 v[130:131], s[50:51], 0, v[198:199]
	s_mov_b32 m0, s52
	s_nop 0
	global_load_lds_dwordx4 v[130:131], off
	v_lshl_add_u64 v[130:131], s[50:51], 0, v[202:203]
	s_add_i32 m0, s52, 0x2000
	s_nop 0
	global_load_lds_dwordx4 v[130:131], off
	s_waitcnt vmcnt(6)
	s_barrier
	v_mfma_f32_16x16x32_bf16 v[52:55], v[178:181], v[146:149], v[52:55]
	v_mfma_f32_16x16x32_bf16 v[48:51], v[186:189], v[146:149], v[48:51]
	v_mfma_f32_16x16x32_bf16 v[36:39], v[178:181], v[154:157], v[36:39]
	v_mfma_f32_16x16x32_bf16 v[32:35], v[186:189], v[154:157], v[32:35]
	v_mfma_f32_16x16x32_bf16 v[20:23], v[178:181], v[162:165], v[20:23]
	v_mfma_f32_16x16x32_bf16 v[16:19], v[186:189], v[162:165], v[16:19]
	v_mfma_f32_16x16x32_bf16 v[4:7], v[178:181], v[170:173], v[4:7]
	v_mfma_f32_16x16x32_bf16 v[0:3], v[186:189], v[170:173], v[0:3]
	v_mfma_f32_16x16x32_bf16 v[52:55], v[182:185], v[150:153], v[52:55]
	v_mfma_f32_16x16x32_bf16 v[48:51], v[190:193], v[150:153], v[48:51]
	v_mfma_f32_16x16x32_bf16 v[36:39], v[182:185], v[158:161], v[36:39]
	v_mfma_f32_16x16x32_bf16 v[32:35], v[190:193], v[158:161], v[32:35]
	v_mfma_f32_16x16x32_bf16 v[20:23], v[182:185], v[166:169], v[20:23]
	v_mfma_f32_16x16x32_bf16 v[16:19], v[190:193], v[166:169], v[16:19]
	v_mfma_f32_16x16x32_bf16 v[4:7], v[182:185], v[174:177], v[4:7]
	v_mfma_f32_16x16x32_bf16 v[0:3], v[190:193], v[174:177], v[0:3]
	s_add_i32 s69, s69, 2
	s_add_u32 s48, s48, 0x100
	s_addc_u32 s49, s49, 0
	s_add_u32 s67, s67, 0x100
	s_addc_u32 s68, s68, 0
	s_cmp_gt_u32 s69, 5
	s_barrier
	s_cbranch_scc0 .LBB0_105
	s_ashr_i32 s1, s0, 2
	s_cmp_eq_u32 s1, 1
	s_movk_i32 s31, 0xf9a0
	s_mov_b32 s39, 0xee00000
	s_cselect_b32 s31, s31, 0xfffffcd0
	s_cselect_b32 s39, s39, 0x13200000
	s_cmp_lt_u32 s0, 4
	s_cselect_b32 s31, 0xfffffa28, s31
	s_cselect_b32 s39, 0x6600000, s39
	s_add_i32 s31, s31, s46
	s_add_u32 s46, s74, s39
	s_addc_u32 s47, s75, 0
	v_lshl_add_u32 v212, s31, 8, v220
	s_lshl_b32 s0, s0, 8
	s_and_b32 s0, s0, 0x300
	v_ashrrev_i32_e32 v213, 31, v212
	v_or_b32_e32 v224, s0, v222
	v_lshlrev_b64 v[130:131], 10, v[212:213]
	v_or_b32_e32 v130, v130, v224
	v_lshl_add_u64 v[132:133], v[130:131], 1, s[46:47]
	global_load_dwordx4 v[188:191], v[132:133], off
	s_cmp_gt_i32 s1, 0
	s_cselect_b64 s[48:49], -1, 0
	s_cmp_lt_i32 s1, 1
	v_lshl_add_u64 v[130:131], v[130:131], 1, s[74:75]
	s_cbranch_scc1 .LBB0_108
	global_load_dwordx4 v[192:195], v[130:131], off
	s_branch .LBB0_109

; #define PG8_STAGE(bufoff, gbase, voff) do { _Pragma("unroll") for (int _i = 0; _i < 2; ++_i) \
;         __builtin_amdgcn_global_load_lds((const unsigned*)((const char*)(gbase) + (voff)[_i]), (PG8_LAS unsigned*)(lds + (bufoff) + ldsw + _i * 8192), 16, 0, 0); } while (0)
; #define PG8_LDA(dst, b, h) do { _Pragma("unroll") for (int m = 0; m < 4; ++m) _Pragma("unroll") for (int k = 0; k < 2; ++k) dst[m][k] = *(const PG8_LAS bf16x8*)(lds + PG8_SA(b, h) + aoff + m * 2048 + k * 1024); } while (0)
; #define PG8_WAIT_V(n) asm volatile("s_waitcnt vmcnt(" #n ")" ::: "memory")
; template <class Epi, class Sched>
; __device__ __forceinline__ void gemm_phase(PG8_LAS unsigned char* lds, const Gemm g, const Sched& S, const Epi& E) {
;     ...
;         for (int t = 0; t < nt; t += 2) {
;             const bool last = (t == nt - 2);
;             const char* a1 = cA + (size_t)(t + 1) * kstep;
;             const char* a2 = last ? nA : cA + (size_t)(t + 2) * kstep; const char* b2 = last ? nB : cB + (size_t)(t + 2) * kstep;
;             const char* a3 = a2 + kstep; const char* b3 = b2 + kstep;
;             if (last && has_next) S.a_ready(nxt);
;             PG8_LDB(B0, 0, 0); PG8_SCHED; PG8_LDA(At, 0, 0); PG8_STAGE(PG8_SA(1, 1), a1 + hstep, voffA);
;             PG8_WAIT_L(8); PG8_BAR; PG8_WAIT_L(0); PG8_MMA(0, 0, At, B0); PG8_BAR; PG8_SCHED;
;             PG8_LDB(B1, 0, 1); PG8_STAGE(PG8_SB(0, 0), b2, voffB);
;             PG8_BAR; PG8_WAIT_L(0); PG8_MMA(0, 1, At, B1); PG8_BAR;
;             PG8_LDA(At, 0, 1); PG8_STAGE(PG8_SA(0, 0), a2, voffA);
;             PG8_BAR; PG8_WAIT_L(0); PG8_MMA(1, 0, At, B0); PG8_BAR; PG8_SCHED;
;             PG8_STAGE(PG8_SB(0, 1), b2 + hstep, voffB);
;             PG8_WAIT_V(6); PG8_BAR; PG8_MMA(1, 1, At, B1); PG8_BAR;
;             PG8_LDB(B0, 1, 0); PG8_SCHED; PG8_LDA(At, 1, 0); PG8_STAGE(PG8_SA(0, 1), a2 + hstep, voffA);
;             PG8_WAIT_L(8); PG8_BAR; PG8_WAIT_L(0); PG8_MMA(0, 0, At, B0); PG8_BAR; PG8_SCHED;
;             PG8_LDB(B1, 1, 1); PG8_STAGE(PG8_SB(1, 0), b3, voffB);
;             PG8_BAR; PG8_WAIT_L(0); PG8_MMA(0, 1, At, B1); PG8_BAR;
;             PG8_LDA(At, 1, 1); PG8_STAGE(PG8_SA(1, 0), a3, voffA);
;             PG8_BAR; PG8_WAIT_L(0); PG8_MMA(1, 0, At, B0); PG8_BAR; PG8_SCHED;
;             PG8_STAGE(PG8_SB(1, 1), b3 + hstep, voffB);
;             PG8_WAIT_V(6); PG8_BAR; PG8_MMA(1, 1, At, B1); PG8_BAR;
.Lgp_7151:
.LBB0_152:
	s_add_u32 s48, s46, 0xfffc0080
	s_addc_u32 s49, s47, -1
	s_add_i32 s71, 0, 0x10000
	v_add_u32_e32 v96, s71, v147
	ds_read_b128 v[142:145], v96
	ds_read_b128 v[150:153], v96 offset:1024
	ds_read_b128 v[154:157], v96 offset:2048
	ds_read_b128 v[158:161], v96 offset:3072
	s_cmp_eq_u32 s70, 12
	s_cselect_b32 s51, s31, s49
	s_cselect_b32 s50, s66, s48
	s_cselect_b32 s49, s1, s69
	s_cselect_b32 s48, s67, s68
	v_lshl_add_u64 v[194:195], s[46:47], 0, v[138:139]
	s_add_i32 m0, s45, 0xc000
	ds_read_b128 v[162:165], v149
	ds_read_b128 v[166:169], v149 offset:1024
	ds_read_b128 v[170:173], v149 offset:2048
	ds_read_b128 v[174:177], v149 offset:3072
	ds_read_b128 v[178:181], v149 offset:4096
	ds_read_b128 v[182:185], v149 offset:5120
	ds_read_b128 v[186:189], v149 offset:6144
	ds_read_b128 v[190:193], v149 offset:7168
	global_load_lds_dwordx4 v[194:195], off
	v_lshl_add_u64 v[194:195], s[46:47], 0, v[140:141]
	s_add_i32 m0, s45, 0xe000
	s_nop 0
	global_load_lds_dwordx4 v[194:195], off
	s_waitcnt lgkmcnt(8)
	s_barrier
	s_waitcnt lgkmcnt(0)
	v_mfma_f32_16x16x32_bf16 v[126:129], v[142:145], v[162:165], v[126:129]
	v_mfma_f32_16x16x32_bf16 v[122:125], v[154:157], v[162:165], v[122:125]
	v_mfma_f32_16x16x32_bf16 v[110:113], v[142:145], v[170:173], v[110:113]
	v_mfma_f32_16x16x32_bf16 v[106:109], v[154:157], v[170:173], v[106:109]
	v_mfma_f32_16x16x32_bf16 v[92:95], v[142:145], v[178:181], v[92:95]
	v_mfma_f32_16x16x32_bf16 v[88:91], v[154:157], v[178:181], v[88:91]
	v_mfma_f32_16x16x32_bf16 v[76:79], v[142:145], v[186:189], v[76:79]
	v_mfma_f32_16x16x32_bf16 v[72:75], v[154:157], v[186:189], v[72:75]
	v_mfma_f32_16x16x32_bf16 v[126:129], v[150:153], v[166:169], v[126:129]
	v_mfma_f32_16x16x32_bf16 v[122:125], v[158:161], v[166:169], v[122:125]
	v_mfma_f32_16x16x32_bf16 v[110:113], v[150:153], v[174:177], v[110:113]
	v_mfma_f32_16x16x32_bf16 v[106:109], v[158:161], v[174:177], v[106:109]
	v_mfma_f32_16x16x32_bf16 v[92:95], v[150:153], v[182:185], v[92:95]
	v_mfma_f32_16x16x32_bf16 v[88:91], v[158:161], v[182:185], v[88:91]
	v_mfma_f32_16x16x32_bf16 v[76:79], v[150:153], v[190:193], v[76:79]
	v_mfma_f32_16x16x32_bf16 v[72:75], v[158:161], v[190:193], v[72:75]
	s_barrier
	s_add_i32 s94, 0, 0x14000
	s_add_i32 s71, s71, s56
	v_add_u32_e32 v96, s94, v147
	v_lshl_add_u64 v[212:213], s[48:49], 0, v[134:135]
	s_mov_b32 m0, s71
	ds_read_b128 v[194:197], v96
	ds_read_b128 v[198:201], v96 offset:1024
	ds_read_b128 v[202:205], v96 offset:2048
	ds_read_b128 v[208:211], v96 offset:3072
	global_load_lds_dwordx4 v[212:213], off
	v_lshl_add_u64 v[214:215], s[48:49], 0, v[130:131]
	s_add_i32 m0, s71, 0x2000
	s_nop 0
	global_load_lds_dwordx4 v[214:215], off
	s_barrier
	s_waitcnt lgkmcnt(0)
	v_mfma_f32_16x16x32_bf16 v[118:121], v[194:197], v[162:165], v[118:121]
	v_mfma_f32_16x16x32_bf16 v[114:117], v[202:205], v[162:165], v[114:117]
	v_mfma_f32_16x16x32_bf16 v[102:105], v[194:197], v[170:173], v[102:105]
	v_mfma_f32_16x16x32_bf16 v[98:101], v[202:205], v[170:173], v[98:101]
	v_mfma_f32_16x16x32_bf16 v[84:87], v[194:197], v[178:181], v[84:87]
	v_mfma_f32_16x16x32_bf16 v[80:83], v[202:205], v[178:181], v[80:83]
	v_mfma_f32_16x16x32_bf16 v[68:71], v[194:197], v[186:189], v[68:71]
	v_mfma_f32_16x16x32_bf16 v[64:67], v[202:205], v[186:189], v[64:67]
	v_mfma_f32_16x16x32_bf16 v[118:121], v[198:201], v[166:169], v[118:121]
	v_mfma_f32_16x16x32_bf16 v[114:117], v[208:211], v[166:169], v[114:117]
	v_mfma_f32_16x16x32_bf16 v[102:105], v[198:201], v[174:177], v[102:105]
	v_mfma_f32_16x16x32_bf16 v[98:101], v[208:211], v[174:177], v[98:101]
	v_mfma_f32_16x16x32_bf16 v[84:87], v[198:201], v[182:185], v[84:87]
	v_mfma_f32_16x16x32_bf16 v[80:83], v[208:211], v[182:185], v[80:83]
	v_mfma_f32_16x16x32_bf16 v[68:71], v[198:201], v[190:193], v[68:71]
	v_mfma_f32_16x16x32_bf16 v[64:67], v[208:211], v[190:193], v[64:67]
	s_mov_b32 m0, s45
	v_lshl_add_u64 v[216:217], s[50:51], 0, v[136:137]
	s_barrier
	ds_read_b128 v[162:165], v149 offset:16384
	ds_read_b128 v[166:169], v149 offset:17408
	ds_read_b128 v[170:173], v149 offset:18432
	ds_read_b128 v[174:177], v149 offset:19456
	ds_read_b128 v[178:181], v149 offset:20480
	ds_read_b128 v[182:185], v149 offset:21504
	ds_read_b128 v[186:189], v149 offset:22528
	ds_read_b128 v[190:193], v149 offset:23552
	global_load_lds_dwordx4 v[216:217], off
	v_lshl_add_u64 v[218:219], s[50:51], 0, v[132:133]
	s_mov_b32 m0, s59
	s_nop 0
	global_load_lds_dwordx4 v[218:219], off
	s_barrier
	s_waitcnt lgkmcnt(0)
	v_mfma_f32_16x16x32_bf16 v[60:63], v[142:145], v[162:165], v[60:63]
	v_mfma_f32_16x16x32_bf16 v[56:59], v[154:157], v[162:165], v[56:59]
	v_mfma_f32_16x16x32_bf16 v[44:47], v[142:145], v[170:173], v[44:47]
	v_mfma_f32_16x16x32_bf16 v[40:43], v[154:157], v[170:173], v[40:43]
	v_mfma_f32_16x16x32_bf16 v[28:31], v[142:145], v[178:181], v[28:31]
	v_mfma_f32_16x16x32_bf16 v[24:27], v[154:157], v[178:181], v[24:27]
	v_mfma_f32_16x16x32_bf16 v[12:15], v[142:145], v[186:189], v[12:15]
	v_mfma_f32_16x16x32_bf16 v[8:11], v[154:157], v[186:189], v[8:11]
	v_mfma_f32_16x16x32_bf16 v[60:63], v[150:153], v[166:169], v[60:63]
	v_mfma_f32_16x16x32_bf16 v[56:59], v[158:161], v[166:169], v[56:59]
	v_mfma_f32_16x16x32_bf16 v[44:47], v[150:153], v[174:177], v[44:47]
	v_mfma_f32_16x16x32_bf16 v[40:43], v[158:161], v[174:177], v[40:43]
	v_mfma_f32_16x16x32_bf16 v[28:31], v[150:153], v[182:185], v[28:31]
	v_mfma_f32_16x16x32_bf16 v[24:27], v[158:161], v[182:185], v[24:27]
	v_mfma_f32_16x16x32_bf16 v[12:15], v[150:153], v[190:193], v[12:15]
	v_mfma_f32_16x16x32_bf16 v[8:11], v[158:161], v[190:193], v[8:11]
	s_barrier
; #define PG8_STAGE(bufoff, gbase, voff) do { _Pragma("unroll") for (int _i = 0; _i < 2; ++_i) \
;         __builtin_amdgcn_global_load_lds((const unsigned*)((const char*)(gbase) + (voff)[_i]), (PG8_LAS unsigned*)(lds + (bufoff) + ldsw + _i * 8192), 16, 0, 0); } while (0)
; #define PG8_LDA(dst, b, h) do { _Pragma("unroll") for (int m = 0; m < 4; ++m) _Pragma("unroll") for (int k = 0; k < 2; ++k) dst[m][k] = *(const PG8_LAS bf16x8*)(lds + PG8_SA(b, h) + aoff + m * 2048 + k * 1024); } while (0)
; #define PG8_WAIT_V(n) asm volatile("s_waitcnt vmcnt(" #n ")" ::: "memory")
; template <class Epi, class Sched>
; __device__ __forceinline__ void gemm_phase(PG8_LAS unsigned char* lds, const Gemm g, const Sched& S, const Epi& E) {
;     ...
;         for (int t = 0; t < nt; t += 2) {
;             const bool last = (t == nt - 2);
;             const char* a1 = cA + (size_t)(t + 1) * kstep;
;             const char* a2 = last ? nA : cA + (size_t)(t + 2) * kstep; const char* b2 = last ? nB : cB + (size_t)(t + 2) * kstep;
;             const char* a3 = a2 + kstep; const char* b3 = b2 + kstep;
;             if (last && has_next) S.a_ready(nxt);
;             PG8_LDB(B0, 0, 0); PG8_SCHED; PG8_LDA(At, 0, 0); PG8_STAGE(PG8_SA(1, 1), a1 + hstep, voffA);
;             PG8_WAIT_L(8); PG8_BAR; PG8_WAIT_L(0); PG8_MMA(0, 0, At, B0); PG8_BAR; PG8_SCHED;
;             PG8_LDB(B1, 0, 1); PG8_STAGE(PG8_SB(0, 0), b2, voffB);
;             PG8_BAR; PG8_WAIT_L(0); PG8_MMA(0, 1, At, B1); PG8_BAR;
;             PG8_LDA(At, 0, 1); PG8_STAGE(PG8_SA(0, 0), a2, voffA);
;             PG8_BAR; PG8_WAIT_L(0); PG8_MMA(1, 0, At, B0); PG8_BAR; PG8_SCHED;
;             PG8_STAGE(PG8_SB(0, 1), b2 + hstep, voffB);
;             PG8_WAIT_V(6); PG8_BAR; PG8_MMA(1, 1, At, B1); PG8_BAR;
;             PG8_LDB(B0, 1, 0); PG8_SCHED; PG8_LDA(At, 1, 0); PG8_STAGE(PG8_SA(0, 1), a2 + hstep, voffA);
;             PG8_WAIT_L(8); PG8_BAR; PG8_WAIT_L(0); PG8_MMA(0, 0, At, B0); PG8_BAR; PG8_SCHED;
;             PG8_LDB(B1, 1, 1); PG8_STAGE(PG8_SB(1, 0), b3, voffB);
;             PG8_BAR; PG8_WAIT_L(0); PG8_MMA(0, 1, At, B1); PG8_BAR;
;             PG8_LDA(At, 1, 1); PG8_STAGE(PG8_SA(1, 0), a3, voffA);
;             PG8_BAR; PG8_WAIT_L(0); PG8_MMA(1, 0, At, B0); PG8_BAR; PG8_SCHED;
;             PG8_STAGE(PG8_SB(1, 1), b3 + hstep, voffB);
;             PG8_WAIT_V(6); PG8_BAR; PG8_MMA(1, 1, At, B1); PG8_BAR;
	s_add_u32 vcc_lo, s48, 0x40000
	s_addc_u32 vcc_hi, s49, 0
	s_add_i32 s71, s94, s56
	v_lshl_add_u64 v[142:143], vcc, 0, v[134:135]
	s_mov_b32 m0, s71
	s_nop 0
	global_load_lds_dwordx4 v[142:143], off
	v_lshl_add_u64 v[142:143], vcc, 0, v[130:131]
	s_add_i32 m0, s71, 0x2000
	s_nop 0
	global_load_lds_dwordx4 v[142:143], off
	s_waitcnt vmcnt(6)
	s_barrier
	v_mfma_f32_16x16x32_bf16 v[52:55], v[194:197], v[162:165], v[52:55]
	v_mfma_f32_16x16x32_bf16 v[48:51], v[202:205], v[162:165], v[48:51]
	v_mfma_f32_16x16x32_bf16 v[36:39], v[194:197], v[170:173], v[36:39]
	v_mfma_f32_16x16x32_bf16 v[32:35], v[202:205], v[170:173], v[32:35]
	v_mfma_f32_16x16x32_bf16 v[20:23], v[194:197], v[178:181], v[20:23]
	v_mfma_f32_16x16x32_bf16 v[16:19], v[202:205], v[178:181], v[16:19]
	v_mfma_f32_16x16x32_bf16 v[4:7], v[194:197], v[186:189], v[4:7]
	v_mfma_f32_16x16x32_bf16 v[0:3], v[202:205], v[186:189], v[0:3]
	v_mfma_f32_16x16x32_bf16 v[52:55], v[198:201], v[166:169], v[52:55]
	v_mfma_f32_16x16x32_bf16 v[48:51], v[208:211], v[166:169], v[48:51]
	v_mfma_f32_16x16x32_bf16 v[36:39], v[198:201], v[174:177], v[36:39]
	v_mfma_f32_16x16x32_bf16 v[32:35], v[208:211], v[174:177], v[32:35]
	v_mfma_f32_16x16x32_bf16 v[20:23], v[198:201], v[182:185], v[20:23]
	v_mfma_f32_16x16x32_bf16 v[16:19], v[208:211], v[182:185], v[16:19]
	v_mfma_f32_16x16x32_bf16 v[4:7], v[198:201], v[190:193], v[4:7]
	v_mfma_f32_16x16x32_bf16 v[0:3], v[208:211], v[190:193], v[0:3]
	s_add_i32 s71, 0, 0x18000
	v_add_u32_e32 v96, s71, v147
	s_barrier
	ds_read_b128 v[142:145], v96
	ds_read_b128 v[150:153], v96 offset:1024
	ds_read_b128 v[154:157], v96 offset:2048
	ds_read_b128 v[158:161], v96 offset:3072
	s_add_u32 s50, s50, 0x40000
	s_addc_u32 s51, s51, 0
	s_mov_b32 m0, s60
	v_lshl_add_u64 v[194:195], s[50:51], 0, v[136:137]
	ds_read_b128 v[162:165], v149 offset:32768
	ds_read_b128 v[166:169], v149 offset:33792
	ds_read_b128 v[170:173], v149 offset:34816
	ds_read_b128 v[174:177], v149 offset:35840
	ds_read_b128 v[178:181], v149 offset:36864
	ds_read_b128 v[182:185], v149 offset:37888
	ds_read_b128 v[186:189], v149 offset:38912
	ds_read_b128 v[190:193], v149 offset:39936
	global_load_lds_dwordx4 v[194:195], off
	v_lshl_add_u64 v[194:195], s[50:51], 0, v[132:133]
	s_mov_b32 m0, s61
	s_nop 0
	global_load_lds_dwordx4 v[194:195], off
	s_waitcnt lgkmcnt(8)
	s_barrier
	s_waitcnt lgkmcnt(0)
	v_mfma_f32_16x16x32_bf16 v[126:129], v[142:145], v[162:165], v[126:129]
	v_mfma_f32_16x16x32_bf16 v[122:125], v[154:157], v[162:165], v[122:125]
	v_mfma_f32_16x16x32_bf16 v[110:113], v[142:145], v[170:173], v[110:113]
	v_mfma_f32_16x16x32_bf16 v[106:109], v[154:157], v[170:173], v[106:109]
	v_mfma_f32_16x16x32_bf16 v[92:95], v[142:145], v[178:181], v[92:95]
	v_mfma_f32_16x16x32_bf16 v[88:91], v[154:157], v[178:181], v[88:91]
	v_mfma_f32_16x16x32_bf16 v[76:79], v[142:145], v[186:189], v[76:79]
	v_mfma_f32_16x16x32_bf16 v[72:75], v[154:157], v[186:189], v[72:75]
	v_mfma_f32_16x16x32_bf16 v[126:129], v[150:153], v[166:169], v[126:129]
	v_mfma_f32_16x16x32_bf16 v[122:125], v[158:161], v[166:169], v[122:125]
	v_mfma_f32_16x16x32_bf16 v[110:113], v[150:153], v[174:177], v[110:113]
	v_mfma_f32_16x16x32_bf16 v[106:109], v[158:161], v[174:177], v[106:109]
	v_mfma_f32_16x16x32_bf16 v[92:95], v[150:153], v[182:185], v[92:95]
	v_mfma_f32_16x16x32_bf16 v[88:91], v[158:161], v[182:185], v[88:91]
	v_mfma_f32_16x16x32_bf16 v[76:79], v[150:153], v[190:193], v[76:79]
	v_mfma_f32_16x16x32_bf16 v[72:75], v[158:161], v[190:193], v[72:75]
	s_barrier
	s_add_i32 s50, 0, 0x1c000
	s_add_i32 s51, s71, s56
	v_add_u32_e32 v96, s50, v147
	v_lshl_add_u64 v[212:213], v[212:213], 0, s[2:3]
	s_mov_b32 m0, s51
	ds_read_b128 v[194:197], v96
	ds_read_b128 v[198:201], v96 offset:1024
	ds_read_b128 v[202:205], v96 offset:2048
	ds_read_b128 v[208:211], v96 offset:3072
	global_load_lds_dwordx4 v[212:213], off
	v_lshl_add_u64 v[212:213], v[214:215], 0, s[2:3]
	s_add_i32 m0, s51, 0x2000
	s_nop 0
	global_load_lds_dwordx4 v[212:213], off
	s_barrier
	s_waitcnt lgkmcnt(0)
	v_mfma_f32_16x16x32_bf16 v[118:121], v[194:197], v[162:165], v[118:121]
	v_mfma_f32_16x16x32_bf16 v[114:117], v[202:205], v[162:165], v[114:117]
	v_mfma_f32_16x16x32_bf16 v[102:105], v[194:197], v[170:173], v[102:105]
	v_mfma_f32_16x16x32_bf16 v[98:101], v[202:205], v[170:173], v[98:101]
	v_mfma_f32_16x16x32_bf16 v[84:87], v[194:197], v[178:181], v[84:87]
	v_mfma_f32_16x16x32_bf16 v[80:83], v[202:205], v[178:181], v[80:83]
	v_mfma_f32_16x16x32_bf16 v[68:71], v[194:197], v[186:189], v[68:71]
	v_mfma_f32_16x16x32_bf16 v[64:67], v[202:205], v[186:189], v[64:67]
	v_mfma_f32_16x16x32_bf16 v[118:121], v[198:201], v[166:169], v[118:121]
	v_mfma_f32_16x16x32_bf16 v[114:117], v[208:211], v[166:169], v[114:117]
	v_mfma_f32_16x16x32_bf16 v[102:105], v[198:201], v[174:177], v[102:105]
	v_mfma_f32_16x16x32_bf16 v[98:101], v[208:211], v[174:177], v[98:101]
	v_mfma_f32_16x16x32_bf16 v[84:87], v[198:201], v[182:185], v[84:87]
	v_mfma_f32_16x16x32_bf16 v[80:83], v[208:211], v[182:185], v[80:83]
	v_mfma_f32_16x16x32_bf16 v[68:71], v[198:201], v[190:193], v[68:71]
	v_mfma_f32_16x16x32_bf16 v[64:67], v[208:211], v[190:193], v[64:67]
	s_mov_b32 m0, s62
	v_lshl_add_u64 v[212:213], v[216:217], 0, s[2:3]
	s_barrier
	ds_read_b128 v[162:165], v149 offset:49152
	ds_read_b128 v[166:169], v149 offset:50176
	ds_read_b128 v[170:173], v149 offset:51200
	ds_read_b128 v[174:177], v149 offset:52224
	ds_read_b128 v[178:181], v149 offset:53248
	ds_read_b128 v[182:185], v149 offset:54272
	ds_read_b128 v[186:189], v149 offset:55296
	ds_read_b128 v[190:193], v149 offset:56320
	global_load_lds_dwordx4 v[212:213], off
	v_lshl_add_u64 v[212:213], v[218:219], 0, s[2:3]
	s_mov_b32 m0, s63
	s_nop 0
	global_load_lds_dwordx4 v[212:213], off
	s_barrier
; DEV float sigmoidf_(float x) { return __builtin_amdgcn_rcpf(1.f + __expf(-x)); }
; #define PG8_MMA(ai, bj, At, Bt) do { __builtin_amdgcn_s_setprio(1); _Pragma("unroll") for (int m = 0; m < 4; ++m) _Pragma("unroll") for (int n = 0; n < 2; ++n) _Pragma("unroll") for (int k = 0; k < 2; ++k) \
;         acc[ai][bj][m][n] = __builtin_amdgcn_mfma_f32_16x16x32_bf16(Bt[n][k], At[m][k], acc[ai][bj][m][n], 0, 0, 0); __builtin_amdgcn_s_setprio(0); } while (0)
; #define PG8_WAIT_V(n) asm volatile("s_waitcnt vmcnt(" #n ")" ::: "memory")
; #define PG8_BAR __builtin_amdgcn_s_barrier()
; template <class Epi, class Sched>
; __device__ __forceinline__ void gemm_phase(PG8_LAS unsigned char* lds, const Gemm g, const Sched& S, const Epi& E) {
;     ...
;             PG8_WAIT_V(6); PG8_BAR; PG8_MMA(1, 1, At, B1); PG8_BAR;
;   DEV void operator()(const f32x4 (&acc)[2][2][4][2], const pg8::Unit& u, int wr, int wc, int fr, int fq) const {
;     const int b = u.pn >> 2, pn = u.pn & 3;
;     bf16_t* G = (bf16_t*)(ws + (b == 0 ? O_G1 : (b == 1 ? O_G2 : O_G3)));
;     const int row0 = u.pm * 256 + wr * 64 + fr, col0 = pn * 256 + wc * 32 + 8 * fq;
; #pragma unroll
;     for (int ai = 0; ai < 2; ++ai)
; #pragma unroll
;       for (int m = 0; m < 4; ++m) {
;         const int row = row0 + ai * 128 + m * 16;
; #pragma unroll
;         for (int bj = 0; bj < 2; ++bj) {
;           const f32x4 a0 = acc[ai][bj][m][0], a1 = acc[ai][bj][m][1];
;           u32x4 o;
;           o[0] = pk2(sigmoidf_(a0[0]), sigmoidf_(a0[1])); o[1] = pk2(sigmoidf_(a0[2]), sigmoidf_(a0[3]));
;           o[2] = pk2(sigmoidf_(a1[0]), sigmoidf_(a1[1])); o[3] = pk2(sigmoidf_(a1[2]), sigmoidf_(a1[3]));
;           *(u32x4*)(G + (size_t)row * DM + col0 + bj * 128) = o;
	s_waitcnt lgkmcnt(0)
	v_mfma_f32_16x16x32_bf16 v[60:63], v[142:145], v[162:165], v[60:63]
	v_mfma_f32_16x16x32_bf16 v[56:59], v[154:157], v[162:165], v[56:59]
	v_mfma_f32_16x16x32_bf16 v[44:47], v[142:145], v[170:173], v[44:47]
	v_mfma_f32_16x16x32_bf16 v[40:43], v[154:157], v[170:173], v[40:43]
	v_mfma_f32_16x16x32_bf16 v[28:31], v[142:145], v[178:181], v[28:31]
	v_mfma_f32_16x16x32_bf16 v[24:27], v[154:157], v[178:181], v[24:27]
	v_mfma_f32_16x16x32_bf16 v[12:15], v[142:145], v[186:189], v[12:15]
	v_mfma_f32_16x16x32_bf16 v[8:11], v[154:157], v[186:189], v[8:11]
	v_mfma_f32_16x16x32_bf16 v[60:63], v[150:153], v[166:169], v[60:63]
	v_mfma_f32_16x16x32_bf16 v[56:59], v[158:161], v[166:169], v[56:59]
	v_mfma_f32_16x16x32_bf16 v[44:47], v[150:153], v[174:177], v[44:47]
	v_mfma_f32_16x16x32_bf16 v[40:43], v[158:161], v[174:177], v[40:43]
	v_mfma_f32_16x16x32_bf16 v[28:31], v[150:153], v[182:185], v[28:31]
	v_mfma_f32_16x16x32_bf16 v[24:27], v[158:161], v[182:185], v[24:27]
	v_mfma_f32_16x16x32_bf16 v[12:15], v[150:153], v[190:193], v[12:15]
	v_mfma_f32_16x16x32_bf16 v[8:11], v[158:161], v[190:193], v[8:11]
	s_barrier
	s_add_u32 s48, s48, 0x40080
	s_addc_u32 s49, s49, 0
	s_add_i32 s50, s50, s56
	v_lshl_add_u64 v[142:143], s[48:49], 0, v[134:135]
	s_mov_b32 m0, s50
	s_nop 0
	global_load_lds_dwordx4 v[142:143], off
	v_lshl_add_u64 v[142:143], s[48:49], 0, v[130:131]
	s_add_i32 m0, s50, 0x2000
	s_nop 0
	global_load_lds_dwordx4 v[142:143], off
	s_waitcnt vmcnt(6)
	s_barrier
	v_mfma_f32_16x16x32_bf16 v[52:55], v[194:197], v[162:165], v[52:55]
	v_mfma_f32_16x16x32_bf16 v[48:51], v[202:205], v[162:165], v[48:51]
	v_mfma_f32_16x16x32_bf16 v[36:39], v[194:197], v[170:173], v[36:39]
	v_mfma_f32_16x16x32_bf16 v[32:35], v[202:205], v[170:173], v[32:35]
	v_mfma_f32_16x16x32_bf16 v[20:23], v[194:197], v[178:181], v[20:23]
	v_mfma_f32_16x16x32_bf16 v[16:19], v[202:205], v[178:181], v[16:19]
	v_mfma_f32_16x16x32_bf16 v[4:7], v[194:197], v[186:189], v[4:7]
	v_mfma_f32_16x16x32_bf16 v[0:3], v[202:205], v[186:189], v[0:3]
	v_mfma_f32_16x16x32_bf16 v[52:55], v[198:201], v[166:169], v[52:55]
	v_mfma_f32_16x16x32_bf16 v[48:51], v[208:211], v[166:169], v[48:51]
	v_mfma_f32_16x16x32_bf16 v[36:39], v[198:201], v[174:177], v[36:39]
	v_mfma_f32_16x16x32_bf16 v[32:35], v[208:211], v[174:177], v[32:35]
	v_mfma_f32_16x16x32_bf16 v[20:23], v[198:201], v[182:185], v[20:23]
	v_mfma_f32_16x16x32_bf16 v[16:19], v[208:211], v[182:185], v[16:19]
	v_mfma_f32_16x16x32_bf16 v[4:7], v[198:201], v[190:193], v[4:7]
	v_mfma_f32_16x16x32_bf16 v[0:3], v[208:211], v[190:193], v[0:3]
	s_add_i32 s70, s70, 2
	s_add_u32 s46, s46, 0x100
	s_addc_u32 s47, s47, 0
	s_add_u32 s68, s68, 0x100
	s_addc_u32 s69, s69, 0
	s_cmp_gt_u32 s70, 13
	s_barrier
	s_cbranch_scc0 .LBB0_152
	s_and_b32 s1, s65, -4
	s_cmp_eq_u32 s1, 4
	s_mov_b32 s1, 0xee00000
	s_cselect_b32 s1, s1, 0x13200000
	s_cmp_gt_u32 s65, 3
	s_cselect_b32 s1, s1, 0x6600000
	s_add_u32 s46, s74, s1
	s_addc_u32 s47, s75, 0
	s_lshl_b32 s1, s65, 8
	s_and_b32 s1, s1, 0x300
	v_mul_f32_e32 v122, 0xbfb8aa3b, v122
	v_or_b32_e32 v96, s1, v148
	v_exp_f32_e32 v122, v122
	v_mul_f32_e32 v123, 0xbfb8aa3b, v123
	v_lshl_add_u32 v144, s44, 8, v146
	v_lshlrev_b32_e32 v96, 1, v96
	v_exp_f32_e32 v123, v123
	v_lshl_add_u64 v[142:143], s[46:47], 0, v[96:97]
	v_ashrrev_i32_e32 v145, 31, v144
	v_mul_f32_e32 v96, 0xbfb8aa3b, v126
	v_mul_f32_e32 v126, 0xbfb8aa3b, v127
	v_lshlrev_b64 v[150:151], 11, v[144:145]
	v_exp_f32_e32 v96, v96
	v_exp_f32_e32 v145, v126
	v_add_f32_e32 v122, 1.0, v122
	v_lshl_add_u64 v[126:127], v[142:143], 0, v[150:151]
	v_rcp_f32_e32 v150, v122
	v_add_f32_e32 v122, 1.0, v123
	v_mul_f32_e32 v123, 0xbfb8aa3b, v124
	v_exp_f32_e32 v123, v123
	v_mul_f32_e32 v124, 0xbfb8aa3b, v125
	v_mul_f32_e32 v114, 0xbfb8aa3b, v114
	v_add_f32_e32 v96, 1.0, v96
	v_add_f32_e32 v145, 1.0, v145
	v_mul_f32_e32 v128, 0xbfb8aa3b, v128
	v_mul_f32_e32 v129, 0xbfb8aa3b, v129
	v_exp_f32_e32 v124, v124
	v_exp_f32_e32 v114, v114
	v_mul_f32_e32 v115, 0xbfb8aa3b, v115
	v_rcp_f32_e32 v96, v96
	v_exp_f32_e32 v128, v128
	v_exp_f32_e32 v129, v129
	v_rcp_f32_e32 v145, v145
	v_exp_f32_e32 v115, v115
	v_rcp_f32_e32 v125, v122
	v_add_f32_e32 v122, 1.0, v123
	v_rcp_f32_e32 v151, v122
	v_add_f32_e32 v122, 1.0, v124
	v_add_f32_e32 v114, 1.0, v114
	v_add_f32_e32 v128, 1.0, v128
	v_add_f32_e32 v129, 1.0, v129
	v_rcp_f32_e32 v152, v122
	v_cvt_pk_bf16_f32 v122, v96, v145
	v_mul_f32_e32 v96, 0xbfb8aa3b, v118
	v_mul_f32_e32 v118, 0xbfb8aa3b, v119
	v_mul_f32_e32 v119, 0xbfb8aa3b, v120
	v_mul_f32_e32 v120, 0xbfb8aa3b, v121
	v_rcp_f32_e32 v121, v114
	v_add_f32_e32 v114, 1.0, v115
	v_mul_f32_e32 v115, 0xbfb8aa3b, v116
	v_rcp_f32_e32 v128, v128
	v_rcp_f32_e32 v129, v129
	v_exp_f32_e32 v115, v115
	v_mul_f32_e32 v116, 0xbfb8aa3b, v117
	v_exp_f32_e32 v96, v96
	v_exp_f32_e32 v118, v118
	v_exp_f32_e32 v119, v119
	v_exp_f32_e32 v120, v120
	v_exp_f32_e32 v116, v116
	v_cvt_pk_bf16_f32 v123, v128, v129
	v_cvt_pk_bf16_f32 v124, v150, v125
	v_cvt_pk_bf16_f32 v125, v151, v152
	v_rcp_f32_e32 v117, v114
	v_add_f32_e32 v114, 1.0, v115
	global_store_dwordx4 v[126:127], v[122:125], off
	v_add_f32_e32 v96, 1.0, v96
	v_add_f32_e32 v118, 1.0, v118
	v_add_f32_e32 v119, 1.0, v119
	v_add_f32_e32 v120, 1.0, v120
	v_rcp_f32_e32 v122, v114
	v_add_f32_e32 v114, 1.0, v116
	v_rcp_f32_e32 v96, v96
	v_rcp_f32_e32 v118, v118
	v_rcp_f32_e32 v119, v119
	v_rcp_f32_e32 v120, v120
	v_rcp_f32_e32 v123, v114
	v_mul_f32_e32 v106, 0xbfb8aa3b, v106
	v_exp_f32_e32 v106, v106
	v_mul_f32_e32 v107, 0xbfb8aa3b, v107
	v_cvt_pk_bf16_f32 v114, v96, v118
	v_cvt_pk_bf16_f32 v115, v119, v120
	v_cvt_pk_bf16_f32 v116, v121, v117
	v_cvt_pk_bf16_f32 v117, v122, v123
; DEV float sigmoidf_(float x) { return __builtin_amdgcn_rcpf(1.f + __expf(-x)); }
;   DEV void operator()(const f32x4 (&acc)[2][2][4][2], const pg8::Unit& u, int wr, int wc, int fr, int fq) const {
;     ...
;     for (int ai = 0; ai < 2; ++ai)
; #pragma unroll
;       for (int m = 0; m < 4; ++m) {
;         const int row = row0 + ai * 128 + m * 16;
; #pragma unroll
;         for (int bj = 0; bj < 2; ++bj) {
;           const f32x4 a0 = acc[ai][bj][m][0], a1 = acc[ai][bj][m][1];
;           u32x4 o;
;           o[0] = pk2(sigmoidf_(a0[0]), sigmoidf_(a0[1])); o[1] = pk2(sigmoidf_(a0[2]), sigmoidf_(a0[3]));
;           o[2] = pk2(sigmoidf_(a1[0]), sigmoidf_(a1[1])); o[3] = pk2(sigmoidf_(a1[2]), sigmoidf_(a1[3]));
;           *(u32x4*)(G + (size_t)row * DM + col0 + bj * 128) = o;
	v_exp_f32_e32 v107, v107
	global_store_dwordx4 v[126:127], v[114:117], off offset:256
	v_mul_f32_e32 v96, 0xbfb8aa3b, v110
	v_mul_f32_e32 v110, 0xbfb8aa3b, v111
	v_or_b32_e32 v114, 16, v144
	v_ashrrev_i32_e32 v115, 31, v114
	v_exp_f32_e32 v96, v96
	v_exp_f32_e32 v116, v110
	v_lshlrev_b64 v[114:115], 11, v[114:115]
	v_add_f32_e32 v106, 1.0, v106
	v_lshl_add_u64 v[110:111], v[142:143], 0, v[114:115]
	v_rcp_f32_e32 v115, v106
	v_add_f32_e32 v106, 1.0, v107
	v_mul_f32_e32 v107, 0xbfb8aa3b, v108
	v_exp_f32_e32 v107, v107
	v_mul_f32_e32 v108, 0xbfb8aa3b, v109
	v_mul_f32_e32 v98, 0xbfb8aa3b, v98
	v_add_f32_e32 v96, 1.0, v96
	v_add_f32_e32 v114, 1.0, v116
	v_mul_f32_e32 v112, 0xbfb8aa3b, v112
	v_mul_f32_e32 v113, 0xbfb8aa3b, v113
	v_exp_f32_e32 v108, v108
	v_exp_f32_e32 v98, v98
	v_mul_f32_e32 v99, 0xbfb8aa3b, v99
	v_rcp_f32_e32 v96, v96
	v_exp_f32_e32 v112, v112
	v_exp_f32_e32 v113, v113
	v_rcp_f32_e32 v114, v114
	v_exp_f32_e32 v99, v99
	v_rcp_f32_e32 v109, v106
	v_add_f32_e32 v106, 1.0, v107
	v_rcp_f32_e32 v116, v106
	v_add_f32_e32 v106, 1.0, v108
	v_add_f32_e32 v98, 1.0, v98
	v_add_f32_e32 v112, 1.0, v112
	v_add_f32_e32 v113, 1.0, v113
	v_rcp_f32_e32 v117, v106
	v_cvt_pk_bf16_f32 v106, v96, v114
	v_mul_f32_e32 v96, 0xbfb8aa3b, v102
	v_mul_f32_e32 v102, 0xbfb8aa3b, v103
	v_mul_f32_e32 v103, 0xbfb8aa3b, v104
	v_mul_f32_e32 v104, 0xbfb8aa3b, v105
	v_rcp_f32_e32 v105, v98
	v_add_f32_e32 v98, 1.0, v99
	v_mul_f32_e32 v99, 0xbfb8aa3b, v100
	v_rcp_f32_e32 v112, v112
	v_rcp_f32_e32 v113, v113
	v_exp_f32_e32 v99, v99
	v_mul_f32_e32 v100, 0xbfb8aa3b, v101
	v_exp_f32_e32 v96, v96
	v_exp_f32_e32 v102, v102
	v_exp_f32_e32 v103, v103
	v_exp_f32_e32 v104, v104
	v_exp_f32_e32 v100, v100
	v_cvt_pk_bf16_f32 v107, v112, v113
	v_cvt_pk_bf16_f32 v108, v115, v109
	v_cvt_pk_bf16_f32 v109, v116, v117
	v_rcp_f32_e32 v101, v98
	v_add_f32_e32 v98, 1.0, v99
	global_store_dwordx4 v[110:111], v[106:109], off
	v_add_f32_e32 v96, 1.0, v96
	v_add_f32_e32 v102, 1.0, v102
	v_add_f32_e32 v103, 1.0, v103
	v_add_f32_e32 v104, 1.0, v104
	v_rcp_f32_e32 v106, v98
	v_add_f32_e32 v98, 1.0, v100
	v_rcp_f32_e32 v96, v96
	v_rcp_f32_e32 v102, v102
	v_rcp_f32_e32 v103, v103
	v_rcp_f32_e32 v104, v104
	v_rcp_f32_e32 v107, v98
	v_mul_f32_e32 v88, 0xbfb8aa3b, v88
	v_exp_f32_e32 v88, v88
	v_mul_f32_e32 v89, 0xbfb8aa3b, v89
	v_cvt_pk_bf16_f32 v98, v96, v102
	v_cvt_pk_bf16_f32 v99, v103, v104
	v_cvt_pk_bf16_f32 v100, v105, v101
	v_cvt_pk_bf16_f32 v101, v106, v107
	v_exp_f32_e32 v89, v89
	global_store_dwordx4 v[110:111], v[98:101], off offset:256
	v_mul_f32_e32 v92, 0xbfb8aa3b, v92
	v_exp_f32_e32 v96, v92
	v_or_b32_e32 v98, 32, v144
	v_ashrrev_i32_e32 v99, 31, v98
	v_lshlrev_b64 v[98:99], 11, v[98:99]
	v_mul_f32_e32 v92, 0xbfb8aa3b, v93
	v_add_f32_e32 v88, 1.0, v88
	v_exp_f32_e32 v100, v92
	v_lshl_add_u64 v[92:93], v[142:143], 0, v[98:99]
	v_rcp_f32_e32 v99, v88
	v_add_f32_e32 v88, 1.0, v89
	v_mul_f32_e32 v89, 0xbfb8aa3b, v90
	v_mul_f32_e32 v94, 0xbfb8aa3b, v94
	v_mul_f32_e32 v95, 0xbfb8aa3b, v95
	v_exp_f32_e32 v89, v89
	v_mul_f32_e32 v90, 0xbfb8aa3b, v91
	v_exp_f32_e32 v94, v94
	v_exp_f32_e32 v95, v95
	v_exp_f32_e32 v90, v90
	v_rcp_f32_e32 v91, v88
	v_add_f32_e32 v88, 1.0, v89
	v_add_f32_e32 v96, 1.0, v96
	v_add_f32_e32 v98, 1.0, v100
	v_add_f32_e32 v94, 1.0, v94
	v_add_f32_e32 v95, 1.0, v95
	v_rcp_f32_e32 v100, v88
	v_add_f32_e32 v88, 1.0, v90
	v_mul_f32_e32 v80, 0xbfb8aa3b, v80
	v_rcp_f32_e32 v96, v96
	v_rcp_f32_e32 v98, v98
	v_rcp_f32_e32 v94, v94
	v_rcp_f32_e32 v95, v95
	v_rcp_f32_e32 v101, v88
	v_exp_f32_e32 v80, v80
	v_mul_f32_e32 v81, 0xbfb8aa3b, v81
	v_exp_f32_e32 v81, v81
	v_cvt_pk_bf16_f32 v88, v96, v98
	v_cvt_pk_bf16_f32 v89, v94, v95
	v_cvt_pk_bf16_f32 v90, v99, v91
	v_cvt_pk_bf16_f32 v91, v100, v101
	v_add_f32_e32 v80, 1.0, v80
	global_store_dwordx4 v[92:93], v[88:91], off
	v_mul_f32_e32 v84, 0xbfb8aa3b, v84
	v_mul_f32_e32 v85, 0xbfb8aa3b, v85
	v_rcp_f32_e32 v88, v80
	v_add_f32_e32 v80, 1.0, v81
	v_mul_f32_e32 v81, 0xbfb8aa3b, v82
	v_mul_f32_e32 v86, 0xbfb8aa3b, v86
	v_mul_f32_e32 v87, 0xbfb8aa3b, v87
	v_exp_f32_e32 v81, v81
	v_mul_f32_e32 v82, 0xbfb8aa3b, v83
	v_exp_f32_e32 v84, v84
	v_exp_f32_e32 v85, v85
	v_exp_f32_e32 v86, v86
	v_exp_f32_e32 v87, v87
	v_exp_f32_e32 v82, v82
	v_rcp_f32_e32 v83, v80
	v_add_f32_e32 v80, 1.0, v81
	v_add_f32_e32 v84, 1.0, v84
	v_add_f32_e32 v85, 1.0, v85
	v_add_f32_e32 v86, 1.0, v86
	v_add_f32_e32 v87, 1.0, v87
	v_rcp_f32_e32 v89, v80
	v_add_f32_e32 v80, 1.0, v82
	v_rcp_f32_e32 v84, v84
	v_rcp_f32_e32 v85, v85
	v_rcp_f32_e32 v86, v86
	v_rcp_f32_e32 v87, v87
	v_rcp_f32_e32 v90, v80
	v_mul_f32_e32 v72, 0xbfb8aa3b, v72
	v_cvt_pk_bf16_f32 v80, v84, v85
	v_cvt_pk_bf16_f32 v81, v86, v87
	v_cvt_pk_bf16_f32 v82, v88, v83
	v_cvt_pk_bf16_f32 v83, v89, v90
	v_mul_f32_e32 v76, 0xbfb8aa3b, v76
	v_exp_f32_e32 v72, v72
	v_mul_f32_e32 v73, 0xbfb8aa3b, v73
	global_store_dwordx4 v[92:93], v[80:83], off offset:256
	v_exp_f32_e32 v73, v73
	v_add_f32_e32 v72, 1.0, v72
	v_exp_f32_e32 v82, v76
	v_or_b32_e32 v80, 48, v144
	v_ashrrev_i32_e32 v81, 31, v80
	v_lshlrev_b64 v[80:81], 11, v[80:81]
	v_mul_f32_e32 v76, 0xbfb8aa3b, v77
	v_exp_f32_e32 v83, v76
	v_lshl_add_u64 v[76:77], v[142:143], 0, v[80:81]
	v_add_f32_e32 v80, 1.0, v82
	v_rcp_f32_e32 v82, v72
	v_add_f32_e32 v72, 1.0, v73
	v_mul_f32_e32 v73, 0xbfb8aa3b, v74
	v_mul_f32_e32 v78, 0xbfb8aa3b, v78
	v_mul_f32_e32 v79, 0xbfb8aa3b, v79
	v_exp_f32_e32 v73, v73
	v_mul_f32_e32 v74, 0xbfb8aa3b, v75
	v_exp_f32_e32 v78, v78
	v_exp_f32_e32 v79, v79
	v_exp_f32_e32 v74, v74
	v_rcp_f32_e32 v75, v72
	v_add_f32_e32 v72, 1.0, v73
	v_add_f32_e32 v81, 1.0, v83
	v_add_f32_e32 v78, 1.0, v78
	v_add_f32_e32 v79, 1.0, v79
	v_rcp_f32_e32 v83, v72
; DEV float sigmoidf_(float x) { return __builtin_amdgcn_rcpf(1.f + __expf(-x)); }
;   DEV void operator()(const f32x4 (&acc)[2][2][4][2], const pg8::Unit& u, int wr, int wc, int fr, int fq) const {
;     ...
;     for (int ai = 0; ai < 2; ++ai)
; #pragma unroll
;       for (int m = 0; m < 4; ++m) {
;         const int row = row0 + ai * 128 + m * 16;
; #pragma unroll
;         for (int bj = 0; bj < 2; ++bj) {
;           const f32x4 a0 = acc[ai][bj][m][0], a1 = acc[ai][bj][m][1];
;           u32x4 o;
;           o[0] = pk2(sigmoidf_(a0[0]), sigmoidf_(a0[1])); o[1] = pk2(sigmoidf_(a0[2]), sigmoidf_(a0[3]));
;           o[2] = pk2(sigmoidf_(a1[0]), sigmoidf_(a1[1])); o[3] = pk2(sigmoidf_(a1[2]), sigmoidf_(a1[3]));
;           *(u32x4*)(G + (size_t)row * DM + col0 + bj * 128) = o;
	v_add_f32_e32 v72, 1.0, v74
	v_mul_f32_e32 v64, 0xbfb8aa3b, v64
	v_rcp_f32_e32 v80, v80
	v_rcp_f32_e32 v81, v81
	v_rcp_f32_e32 v78, v78
	v_rcp_f32_e32 v79, v79
	v_rcp_f32_e32 v84, v72
	v_exp_f32_e32 v64, v64
	v_mul_f32_e32 v65, 0xbfb8aa3b, v65
	v_exp_f32_e32 v65, v65
	v_cvt_pk_bf16_f32 v72, v80, v81
	v_cvt_pk_bf16_f32 v73, v78, v79
	v_cvt_pk_bf16_f32 v74, v82, v75
	v_cvt_pk_bf16_f32 v75, v83, v84
	v_add_f32_e32 v64, 1.0, v64
	global_store_dwordx4 v[76:77], v[72:75], off
	v_mul_f32_e32 v68, 0xbfb8aa3b, v68
	v_mul_f32_e32 v69, 0xbfb8aa3b, v69
	v_rcp_f32_e32 v72, v64
	v_add_f32_e32 v64, 1.0, v65
	v_mul_f32_e32 v65, 0xbfb8aa3b, v66
	v_mul_f32_e32 v70, 0xbfb8aa3b, v70
	v_mul_f32_e32 v71, 0xbfb8aa3b, v71
	v_exp_f32_e32 v65, v65
	v_mul_f32_e32 v66, 0xbfb8aa3b, v67
	v_exp_f32_e32 v68, v68
	v_exp_f32_e32 v69, v69
	v_exp_f32_e32 v70, v70
	v_exp_f32_e32 v71, v71
	v_exp_f32_e32 v66, v66
	v_rcp_f32_e32 v67, v64
	v_add_f32_e32 v64, 1.0, v65
	v_add_f32_e32 v68, 1.0, v68
	v_add_f32_e32 v69, 1.0, v69
	v_add_f32_e32 v70, 1.0, v70
	v_add_f32_e32 v71, 1.0, v71
	v_rcp_f32_e32 v73, v64
	v_add_f32_e32 v64, 1.0, v66
	v_mul_f32_e32 v56, 0xbfb8aa3b, v56
	v_rcp_f32_e32 v68, v68
	v_rcp_f32_e32 v69, v69
	v_rcp_f32_e32 v70, v70
	v_rcp_f32_e32 v71, v71
	v_rcp_f32_e32 v74, v64
	v_exp_f32_e32 v56, v56
	v_mul_f32_e32 v57, 0xbfb8aa3b, v57
	v_exp_f32_e32 v57, v57
	v_cvt_pk_bf16_f32 v64, v68, v69
	v_cvt_pk_bf16_f32 v65, v70, v71
	v_cvt_pk_bf16_f32 v66, v72, v67
	v_cvt_pk_bf16_f32 v67, v73, v74
	v_add_f32_e32 v56, 1.0, v56
	global_store_dwordx4 v[76:77], v[64:67], off offset:256
	v_mul_f32_e32 v60, 0xbfb8aa3b, v60
	v_mul_f32_e32 v62, 0xbfb8aa3b, v62
	v_mul_f32_e32 v63, 0xbfb8aa3b, v63
	v_rcp_f32_e32 v66, v56
	v_add_f32_e32 v56, 1.0, v57
	v_mul_f32_e32 v57, 0xbfb8aa3b, v58
	v_exp_f32_e32 v64, v60
	v_mul_f32_e32 v60, 0xbfb8aa3b, v61
	v_exp_f32_e32 v62, v62
	v_exp_f32_e32 v63, v63
	v_exp_f32_e32 v57, v57
	v_mul_f32_e32 v58, 0xbfb8aa3b, v59
	v_exp_f32_e32 v65, v60
	v_exp_f32_e32 v58, v58
	v_add_f32_e32 v62, 1.0, v62
	v_add_f32_e32 v63, 1.0, v63
	v_rcp_f32_e32 v59, v56
	v_add_f32_e32 v56, 1.0, v57
	v_add_f32_e32 v64, 1.0, v64
	v_add_f32_e32 v65, 1.0, v65
	v_rcp_f32_e32 v62, v62
	v_rcp_f32_e32 v63, v63
	v_rcp_f32_e32 v67, v56
	v_add_f32_e32 v56, 1.0, v58
	v_mul_f32_e32 v48, 0xbfb8aa3b, v48
	v_rcp_f32_e32 v64, v64
	v_rcp_f32_e32 v65, v65
	v_rcp_f32_e32 v68, v56
	v_exp_f32_e32 v48, v48
	v_mul_f32_e32 v49, 0xbfb8aa3b, v49
	v_exp_f32_e32 v49, v49
	s_mov_b32 s1, 0x40000
	v_cvt_pk_bf16_f32 v57, v62, v63
	v_add_co_u32_e32 v62, vcc, s1, v126
	v_cvt_pk_bf16_f32 v56, v64, v65
	v_cvt_pk_bf16_f32 v58, v66, v59
	v_cvt_pk_bf16_f32 v59, v67, v68
	v_addc_co_u32_e32 v63, vcc, 0, v127, vcc
	v_add_f32_e32 v48, 1.0, v48
	global_store_dwordx4 v[62:63], v[56:59], off
	v_mul_f32_e32 v52, 0xbfb8aa3b, v52
	v_mul_f32_e32 v53, 0xbfb8aa3b, v53
	v_rcp_f32_e32 v56, v48
	v_add_f32_e32 v48, 1.0, v49
	v_mul_f32_e32 v49, 0xbfb8aa3b, v50
	v_mul_f32_e32 v54, 0xbfb8aa3b, v54
	v_mul_f32_e32 v55, 0xbfb8aa3b, v55
	v_exp_f32_e32 v49, v49
	v_mul_f32_e32 v50, 0xbfb8aa3b, v51
	v_exp_f32_e32 v52, v52
	v_exp_f32_e32 v53, v53
	v_exp_f32_e32 v54, v54
	v_exp_f32_e32 v55, v55
	v_exp_f32_e32 v50, v50
	v_rcp_f32_e32 v51, v48
	v_add_f32_e32 v48, 1.0, v49
	v_add_f32_e32 v52, 1.0, v52
	v_add_f32_e32 v53, 1.0, v53
	v_add_f32_e32 v54, 1.0, v54
	v_add_f32_e32 v55, 1.0, v55
	v_rcp_f32_e32 v57, v48
	v_add_f32_e32 v48, 1.0, v50
	v_mul_f32_e32 v40, 0xbfb8aa3b, v40
	v_rcp_f32_e32 v52, v52
	v_rcp_f32_e32 v53, v53
	v_rcp_f32_e32 v54, v54
	v_rcp_f32_e32 v55, v55
	v_rcp_f32_e32 v58, v48
	v_exp_f32_e32 v40, v40
	v_mul_f32_e32 v41, 0xbfb8aa3b, v41
	v_exp_f32_e32 v41, v41
	s_mov_b64 s[46:47], 0x40000
	v_lshl_add_u64 v[60:61], v[126:127], 0, s[46:47]
	v_cvt_pk_bf16_f32 v48, v52, v53
	v_cvt_pk_bf16_f32 v49, v54, v55
	v_cvt_pk_bf16_f32 v50, v56, v51
	v_cvt_pk_bf16_f32 v51, v57, v58
	v_add_f32_e32 v40, 1.0, v40
	global_store_dwordx4 v[60:61], v[48:51], off offset:256
	v_mul_f32_e32 v44, 0xbfb8aa3b, v44
	v_mul_f32_e32 v46, 0xbfb8aa3b, v46
	v_mul_f32_e32 v47, 0xbfb8aa3b, v47
	v_rcp_f32_e32 v50, v40
	v_add_f32_e32 v40, 1.0, v41
	v_mul_f32_e32 v41, 0xbfb8aa3b, v42
	v_exp_f32_e32 v48, v44
	v_mul_f32_e32 v44, 0xbfb8aa3b, v45
	v_exp_f32_e32 v46, v46
	v_exp_f32_e32 v47, v47
	v_exp_f32_e32 v41, v41
	v_mul_f32_e32 v42, 0xbfb8aa3b, v43
	v_exp_f32_e32 v49, v44
	v_exp_f32_e32 v42, v42
	v_add_f32_e32 v46, 1.0, v46
	v_add_f32_e32 v47, 1.0, v47
	v_rcp_f32_e32 v43, v40
	v_add_f32_e32 v40, 1.0, v41
	v_add_f32_e32 v48, 1.0, v48
	v_add_f32_e32 v49, 1.0, v49
	v_rcp_f32_e32 v46, v46
	v_rcp_f32_e32 v47, v47
	v_rcp_f32_e32 v51, v40
	v_add_f32_e32 v40, 1.0, v42
	v_mul_f32_e32 v32, 0xbfb8aa3b, v32
	v_rcp_f32_e32 v48, v48
	v_rcp_f32_e32 v49, v49
	v_rcp_f32_e32 v52, v40
	v_exp_f32_e32 v32, v32
	v_mul_f32_e32 v33, 0xbfb8aa3b, v33
	v_exp_f32_e32 v33, v33
	s_mov_b32 s1, 0x48000
	v_cvt_pk_bf16_f32 v41, v46, v47
	v_add_co_u32_e32 v46, vcc, s1, v126
	v_cvt_pk_bf16_f32 v40, v48, v49
	v_cvt_pk_bf16_f32 v42, v50, v43
	v_cvt_pk_bf16_f32 v43, v51, v52
	v_addc_co_u32_e32 v47, vcc, 0, v127, vcc
	v_add_f32_e32 v32, 1.0, v32
	global_store_dwordx4 v[46:47], v[40:43], off
	v_mul_f32_e32 v36, 0xbfb8aa3b, v36
	v_mul_f32_e32 v37, 0xbfb8aa3b, v37
	v_rcp_f32_e32 v40, v32
	v_add_f32_e32 v32, 1.0, v33
	v_mul_f32_e32 v33, 0xbfb8aa3b, v34
	v_mul_f32_e32 v38, 0xbfb8aa3b, v38
	v_mul_f32_e32 v39, 0xbfb8aa3b, v39
	v_exp_f32_e32 v33, v33
	v_mul_f32_e32 v34, 0xbfb8aa3b, v35
	v_exp_f32_e32 v36, v36
	v_exp_f32_e32 v37, v37
	v_exp_f32_e32 v38, v38
	v_exp_f32_e32 v39, v39
	v_exp_f32_e32 v34, v34
; DEV float sigmoidf_(float x) { return __builtin_amdgcn_rcpf(1.f + __expf(-x)); }
; #define PG8_WAIT_V(n) asm volatile("s_waitcnt vmcnt(" #n ")" ::: "memory")
; #define PG8_BAR __builtin_amdgcn_s_barrier()
; template <class Epi, class Sched>
; __device__ __forceinline__ void gemm_phase(PG8_LAS unsigned char* lds, const Gemm g, const Sched& S, const Epi& E) {
;     ...
;         if (!has_next) break;
; #pragma unroll
;         for (int a = 0; a < 2; ++a)
; #pragma unroll
;             for (int b = 0; b < 2; ++b)
; #pragma unroll
;                 for (int m = 0; m < 4; ++m)
; #pragma unroll
;                     for (int n = 0; n < 2; ++n) acc[a][b][m][n] = (f32x4){0.f, 0.f, 0.f, 0.f};
;         cur = nxt; cA = nA; cB = nB; ++ui;
;     }
;     PG8_WAIT_V(0);
;     if (wr == 0) PG8_BAR;
;     PG8_BAR;
;   DEV void operator()(const f32x4 (&acc)[2][2][4][2], const pg8::Unit& u, int wr, int wc, int fr, int fq) const {
;     ...
;     for (int ai = 0; ai < 2; ++ai)
; #pragma unroll
;       for (int m = 0; m < 4; ++m) {
;         const int row = row0 + ai * 128 + m * 16;
; #pragma unroll
;         for (int bj = 0; bj < 2; ++bj) {
;           const f32x4 a0 = acc[ai][bj][m][0], a1 = acc[ai][bj][m][1];
;           u32x4 o;
;           o[0] = pk2(sigmoidf_(a0[0]), sigmoidf_(a0[1])); o[1] = pk2(sigmoidf_(a0[2]), sigmoidf_(a0[3]));
;           o[2] = pk2(sigmoidf_(a1[0]), sigmoidf_(a1[1])); o[3] = pk2(sigmoidf_(a1[2]), sigmoidf_(a1[3]));
;           *(u32x4*)(G + (size_t)row * DM + col0 + bj * 128) = o;
	v_rcp_f32_e32 v35, v32
	v_add_f32_e32 v32, 1.0, v33
	v_add_f32_e32 v36, 1.0, v36
	v_add_f32_e32 v37, 1.0, v37
	v_add_f32_e32 v38, 1.0, v38
	v_add_f32_e32 v39, 1.0, v39
	v_rcp_f32_e32 v41, v32
	v_add_f32_e32 v32, 1.0, v34
	v_mul_f32_e32 v24, 0xbfb8aa3b, v24
	v_rcp_f32_e32 v36, v36
	v_rcp_f32_e32 v37, v37
	v_rcp_f32_e32 v38, v38
	v_rcp_f32_e32 v39, v39
	v_rcp_f32_e32 v42, v32
	v_exp_f32_e32 v24, v24
	v_mul_f32_e32 v25, 0xbfb8aa3b, v25
	v_exp_f32_e32 v25, v25
	s_mov_b64 s[46:47], 0x48000
	v_lshl_add_u64 v[44:45], v[126:127], 0, s[46:47]
	v_cvt_pk_bf16_f32 v32, v36, v37
	v_cvt_pk_bf16_f32 v33, v38, v39
	v_cvt_pk_bf16_f32 v34, v40, v35
	v_cvt_pk_bf16_f32 v35, v41, v42
	v_add_f32_e32 v24, 1.0, v24
	global_store_dwordx4 v[44:45], v[32:35], off offset:256
	v_mul_f32_e32 v28, 0xbfb8aa3b, v28
	v_mul_f32_e32 v30, 0xbfb8aa3b, v30
	v_mul_f32_e32 v31, 0xbfb8aa3b, v31
	v_rcp_f32_e32 v34, v24
	v_add_f32_e32 v24, 1.0, v25
	v_mul_f32_e32 v25, 0xbfb8aa3b, v26
	v_exp_f32_e32 v32, v28
	v_mul_f32_e32 v28, 0xbfb8aa3b, v29
	v_exp_f32_e32 v30, v30
	v_exp_f32_e32 v31, v31
	v_exp_f32_e32 v25, v25
	v_mul_f32_e32 v26, 0xbfb8aa3b, v27
	v_exp_f32_e32 v33, v28
	v_exp_f32_e32 v26, v26
	v_add_f32_e32 v30, 1.0, v30
	v_add_f32_e32 v31, 1.0, v31
	v_rcp_f32_e32 v27, v24
	v_add_f32_e32 v24, 1.0, v25
	v_add_f32_e32 v32, 1.0, v32
	v_add_f32_e32 v33, 1.0, v33
	v_rcp_f32_e32 v30, v30
	v_rcp_f32_e32 v31, v31
	v_rcp_f32_e32 v35, v24
	v_add_f32_e32 v24, 1.0, v26
	v_mul_f32_e32 v16, 0xbfb8aa3b, v16
	v_rcp_f32_e32 v32, v32
	v_rcp_f32_e32 v33, v33
	v_rcp_f32_e32 v36, v24
	v_exp_f32_e32 v16, v16
	v_mul_f32_e32 v17, 0xbfb8aa3b, v17
	v_exp_f32_e32 v17, v17
	s_mov_b32 s1, 0x50000
	v_cvt_pk_bf16_f32 v25, v30, v31
	v_add_co_u32_e32 v30, vcc, s1, v126
	v_cvt_pk_bf16_f32 v24, v32, v33
	v_cvt_pk_bf16_f32 v26, v34, v27
	v_cvt_pk_bf16_f32 v27, v35, v36
	v_addc_co_u32_e32 v31, vcc, 0, v127, vcc
	v_add_f32_e32 v16, 1.0, v16
	global_store_dwordx4 v[30:31], v[24:27], off
	v_mul_f32_e32 v20, 0xbfb8aa3b, v20
	v_mul_f32_e32 v21, 0xbfb8aa3b, v21
	v_rcp_f32_e32 v24, v16
	v_add_f32_e32 v16, 1.0, v17
	v_mul_f32_e32 v17, 0xbfb8aa3b, v18
	v_mul_f32_e32 v22, 0xbfb8aa3b, v22
	v_mul_f32_e32 v23, 0xbfb8aa3b, v23
	v_exp_f32_e32 v17, v17
	v_mul_f32_e32 v18, 0xbfb8aa3b, v19
	v_exp_f32_e32 v20, v20
	v_exp_f32_e32 v21, v21
	v_exp_f32_e32 v22, v22
	v_exp_f32_e32 v23, v23
	v_exp_f32_e32 v18, v18
	v_rcp_f32_e32 v19, v16
	v_add_f32_e32 v16, 1.0, v17
	v_add_f32_e32 v20, 1.0, v20
	v_add_f32_e32 v21, 1.0, v21
	v_add_f32_e32 v22, 1.0, v22
	v_add_f32_e32 v23, 1.0, v23
	v_rcp_f32_e32 v25, v16
	v_add_f32_e32 v16, 1.0, v18
	v_mul_f32_e32 v8, 0xbfb8aa3b, v8
	v_rcp_f32_e32 v20, v20
	v_rcp_f32_e32 v21, v21
	v_rcp_f32_e32 v22, v22
	v_rcp_f32_e32 v23, v23
	v_rcp_f32_e32 v26, v16
	v_exp_f32_e32 v8, v8
	v_mul_f32_e32 v9, 0xbfb8aa3b, v9
	v_exp_f32_e32 v9, v9
	s_mov_b64 s[46:47], 0x50000
	v_lshl_add_u64 v[28:29], v[126:127], 0, s[46:47]
	v_cvt_pk_bf16_f32 v16, v20, v21
	v_cvt_pk_bf16_f32 v17, v22, v23
	v_cvt_pk_bf16_f32 v18, v24, v19
	v_cvt_pk_bf16_f32 v19, v25, v26
	v_add_f32_e32 v8, 1.0, v8
	global_store_dwordx4 v[28:29], v[16:19], off offset:256
	v_mul_f32_e32 v12, 0xbfb8aa3b, v12
	v_mul_f32_e32 v14, 0xbfb8aa3b, v14
	v_mul_f32_e32 v15, 0xbfb8aa3b, v15
	v_rcp_f32_e32 v18, v8
	v_add_f32_e32 v8, 1.0, v9
	v_mul_f32_e32 v9, 0xbfb8aa3b, v10
	v_exp_f32_e32 v16, v12
	v_mul_f32_e32 v12, 0xbfb8aa3b, v13
	v_exp_f32_e32 v14, v14
	v_exp_f32_e32 v15, v15
	v_exp_f32_e32 v9, v9
	v_mul_f32_e32 v10, 0xbfb8aa3b, v11
	v_exp_f32_e32 v17, v12
	v_exp_f32_e32 v10, v10
	v_add_f32_e32 v14, 1.0, v14
	v_add_f32_e32 v15, 1.0, v15
	v_rcp_f32_e32 v11, v8
	v_add_f32_e32 v8, 1.0, v9
	v_add_f32_e32 v16, 1.0, v16
	v_add_f32_e32 v17, 1.0, v17
	v_rcp_f32_e32 v14, v14
	v_rcp_f32_e32 v15, v15
	v_rcp_f32_e32 v19, v8
	v_add_f32_e32 v8, 1.0, v10
	v_mul_f32_e32 v0, 0xbfb8aa3b, v0
	v_rcp_f32_e32 v16, v16
	v_rcp_f32_e32 v17, v17
	v_rcp_f32_e32 v20, v8
	v_exp_f32_e32 v0, v0
	v_mul_f32_e32 v1, 0xbfb8aa3b, v1
	v_exp_f32_e32 v1, v1
	s_mov_b32 s1, 0x58000
	v_cvt_pk_bf16_f32 v9, v14, v15
	v_add_co_u32_e32 v14, vcc, s1, v126
	v_cvt_pk_bf16_f32 v8, v16, v17
	v_cvt_pk_bf16_f32 v10, v18, v11
	v_cvt_pk_bf16_f32 v11, v19, v20
	v_addc_co_u32_e32 v15, vcc, 0, v127, vcc
	v_add_f32_e32 v0, 1.0, v0
	global_store_dwordx4 v[14:15], v[8:11], off
	v_mul_f32_e32 v4, 0xbfb8aa3b, v4
	v_mul_f32_e32 v5, 0xbfb8aa3b, v5
	v_rcp_f32_e32 v8, v0
	v_add_f32_e32 v0, 1.0, v1
	v_mul_f32_e32 v1, 0xbfb8aa3b, v2
	v_mul_f32_e32 v6, 0xbfb8aa3b, v6
	v_mul_f32_e32 v7, 0xbfb8aa3b, v7
	v_exp_f32_e32 v1, v1
	v_mul_f32_e32 v2, 0xbfb8aa3b, v3
	v_exp_f32_e32 v4, v4
	v_exp_f32_e32 v5, v5
	v_exp_f32_e32 v6, v6
	v_exp_f32_e32 v7, v7
	v_exp_f32_e32 v2, v2
	v_rcp_f32_e32 v3, v0
	v_add_f32_e32 v0, 1.0, v1
	v_add_f32_e32 v4, 1.0, v4
	v_add_f32_e32 v5, 1.0, v5
	v_add_f32_e32 v6, 1.0, v6
	v_add_f32_e32 v7, 1.0, v7
	v_rcp_f32_e32 v9, v0
	v_add_f32_e32 v0, 1.0, v2
	v_rcp_f32_e32 v4, v4
	v_rcp_f32_e32 v5, v5
	v_rcp_f32_e32 v6, v6
	v_rcp_f32_e32 v7, v7
	v_rcp_f32_e32 v10, v0
	s_mov_b64 s[46:47], 0x58000
	v_lshl_add_u64 v[12:13], v[126:127], 0, s[46:47]
	v_cvt_pk_bf16_f32 v0, v4, v5
	v_cvt_pk_bf16_f32 v1, v6, v7
	v_cvt_pk_bf16_f32 v2, v8, v3
	v_cvt_pk_bf16_f32 v3, v9, v10
	s_and_b64 vcc, exec, s[36:37]
	s_mov_b32 s65, s0
	s_mov_b32 s44, s30
	s_mov_b64 s[48:49], s[40:41]
	s_mov_b64 s[46:47], s[38:39]
	global_store_dwordx4 v[12:13], v[0:3], off offset:256
	s_cbranch_vccz .LBB0_149
	s_waitcnt vmcnt(0)
	v_readlane_b32 s64, v255, 38
	s_cmpk_gt_u32 s53, 0xff
	v_readlane_b32 s65, v255, 39
	s_cbranch_scc1 .LBB0_156
	s_barrier

; DEV int ltid() { int t = threadIdx.x; asm volatile("" : "+v"(t)); return t; }
; DEV void shift_tile(const Params& p, int l, int tile) {
;     ...
;   const int tid = ltid();
;   if (tid >= 480) return;
;   const int half = tid >= 240 ? 1 : 0, ch = tid - half * 240, col = ch * 8;
;   const int rb = r0 + half * 16;
;   u32x4 rows[18];
; #pragma unroll
;   for (int i = 0; i < 18; ++i) {
;     const int rr = rb - 1 + i;
;     rows[i] = (u32x4){0u, 0u, 0u, 0u};
;     if (rr >= s_lo && rr < s_hi) rows[i] = *(const u32x4*)(ZRW + (size_t)rr * 1920 + col);
;   }
;   const float* sw = p.rwkv_shift + (size_t)l * 3 * 1920 + col;
;   float w0[8], w1[8], w2[8];
; #pragma unroll
;   for (int j = 0; j < 8; ++j) { w0[j] = sw[j]; w1[j] = sw[1920 + j]; w2[j] = sw[3840 + j]; }
;   const int act = (col >= 1536 && col < 1664) ? 1 : (col >= 1792 ? 2 : 0);
.LBB0_306:
	s_cmpk_gt_i32 s40, 0x43f
	s_mov_b64 s[0:1], -1
	s_cbranch_scc0 .LBB0_592
	s_cmpk_gt_u32 s40, 0x65f
	s_cbranch_scc0 .LBB0_570
	s_mov_b64 s[52:53], exec
	v_cmp_gt_u32_e32 vcc, 0x1e0, v226
	s_and_b64 exec, exec, vcc
	s_cbranch_execz .LBB0_569
	s_mov_b64 s[36:37], exec
	v_cmp_lt_u32_e32 vcc, 0xef, v226
	v_cndmask_b32_e64 v123, 0, 1, vcc
	v_mul_u32_u24_e32 v122, 0xf0, v123
	v_sub_u32_e32 v122, v226, v122
	v_lshlrev_b32_e32 v128, 4, v122
	s_add_i32 s100, s40, 0xfffff9a0
	s_lshl_b32 s100, s100, 5
	v_lshlrev_b32_e32 v134, 5, v122
	v_add_u32_e32 v135, 0x1e00, v134
	v_add_u32_e32 v130, 0x3c00, v134
	global_load_dwordx4 v[72:75], v134, s[76:77]
	global_load_dwordx4 v[76:79], v134, s[76:77] offset:16
	global_load_dwordx4 v[80:83], v135, s[76:77]
	global_load_dwordx4 v[84:87], v135, s[76:77] offset:16
	global_load_dwordx4 v[88:91], v130, s[76:77]
	global_load_dwordx4 v[92:95], v130, s[76:77] offset:16
	v_mul_u32_u24_e32 v129, 0xf000, v123
	v_add_u32_e32 v129, v129, v128
	v_readlane_b32 s0, v251, 49
	v_readlane_b32 s1, v251, 50
	s_sub_i32 s101, s100, 1
	s_mul_i32 s101, s101, 0xf00
	s_ashr_i32 s30, s101, 31
	s_add_u32 s0, s0, s101
	s_addc_u32 s1, s1, s30
	s_and_b32 s38, s100, 0xfffff000
	s_add_i32 s39, s38, 0x1000
	s_and_b32 s30, s100, 0xffffff00
	s_add_i32 s31, s30, 0x100
	s_cmp_lt_u32 s100, 0x8000
	s_cselect_b32 s38, s38, s30
	s_cselect_b32 s39, s39, s31
	s_cmp_lg_u32 s100, s38
	s_cselect_b32 s30, 1, 0
	s_add_i32 s101, s100, 32
	s_cmp_lg_u32 s101, s39
	s_cselect_b32 s31, 1, 0
	v_mov_b32_e32 v0, 0
	v_mov_b32_e32 v1, 0
	v_mov_b32_e32 v2, 0
	v_mov_b32_e32 v3, 0
	v_or_b32_e32 v134, s30, v123
	v_cmp_ne_u32_e32 vcc, 0, v134
	s_and_b64 exec, s[36:37], vcc
	global_load_dwordx4 v[0:3], v129, s[0:1]
	s_mov_b64 exec, s[36:37]
	s_add_u32 s0, s0, 0xf00
	s_addc_u32 s1, s1, 0
	global_load_dwordx4 v[4:7], v129, s[0:1]
	s_add_u32 s0, s0, 0xf00
	s_addc_u32 s1, s1, 0
	global_load_dwordx4 v[8:11], v129, s[0:1]
	s_add_u32 s0, s0, 0xf00
	s_addc_u32 s1, s1, 0
	global_load_dwordx4 v[12:15], v129, s[0:1]
	s_add_u32 s0, s0, 0xf00
	s_addc_u32 s1, s1, 0
	global_load_dwordx4 v[16:19], v129, s[0:1]
	s_add_u32 s0, s0, 0xf00
	s_addc_u32 s1, s1, 0
	global_load_dwordx4 v[20:23], v129, s[0:1]
	s_add_u32 s0, s0, 0xf00
	s_addc_u32 s1, s1, 0
	global_load_dwordx4 v[24:27], v129, s[0:1]
	s_add_u32 s0, s0, 0xf00
	s_addc_u32 s1, s1, 0
	global_load_dwordx4 v[28:31], v129, s[0:1]
	s_add_u32 s0, s0, 0xf00
	s_addc_u32 s1, s1, 0
	global_load_dwordx4 v[32:35], v129, s[0:1]
	s_add_u32 s0, s0, 0xf00
	s_addc_u32 s1, s1, 0
	global_load_dwordx4 v[36:39], v129, s[0:1]
	s_add_u32 s0, s0, 0xf00
	s_addc_u32 s1, s1, 0
	global_load_dwordx4 v[40:43], v129, s[0:1]
	s_add_u32 s0, s0, 0xf00
	s_addc_u32 s1, s1, 0
	global_load_dwordx4 v[44:47], v129, s[0:1]
	s_add_u32 s0, s0, 0xf00
	s_addc_u32 s1, s1, 0
	global_load_dwordx4 v[48:51], v129, s[0:1]
	s_add_u32 s0, s0, 0xf00
	s_addc_u32 s1, s1, 0
	global_load_dwordx4 v[52:55], v129, s[0:1]
	s_add_u32 s0, s0, 0xf00
	s_addc_u32 s1, s1, 0
	global_load_dwordx4 v[56:59], v129, s[0:1]
	s_add_u32 s0, s0, 0xf00
	s_addc_u32 s1, s1, 0
	global_load_dwordx4 v[60:63], v129, s[0:1]
	s_add_u32 s0, s0, 0xf00
	s_addc_u32 s1, s1, 0
	global_load_dwordx4 v[64:67], v129, s[0:1]
	s_add_u32 s0, s0, 0xf00
	s_addc_u32 s1, s1, 0
	v_mov_b32_e32 v68, 0
	v_mov_b32_e32 v69, 0
	v_mov_b32_e32 v70, 0
	v_mov_b32_e32 v71, 0
	v_xor_b32_e32 v134, 1, v123
	v_or_b32_e32 v134, s31, v134
	v_cmp_ne_u32_e32 vcc, 0, v134
	s_and_b64 exec, s[36:37], vcc
	global_load_dwordx4 v[68:71], v129, s[0:1]
	s_mov_b64 exec, s[36:37]
	v_lshl_add_u32 v130, v123, 4, s100
	v_mov_b32_e32 v126, 0xc00
	v_mov_b32_e32 v127, 0
	v_readlane_b32 s0, v253, 41
	v_readlane_b32 s1, v253, 42
	v_mov_b32_e32 v131, v128
	s_nop 0
	v_mov_b32_e32 v132, s0
	v_mov_b32_e32 v133, s1
	s_add_u32 s0, s74, 0x15400000
	s_addc_u32 s1, s75, 0
	v_cmp_lt_u32_e32 vcc, 0xbf, v122
	v_mov_b32_e32 v134, 0x200
	v_cndmask_b32_e32 v126, v126, v134, vcc
	v_mov_b32_e32 v134, s0
	v_cndmask_b32_e32 v132, v132, v134, vcc
	v_mov_b32_e32 v134, s1
	v_cndmask_b32_e32 v133, v133, v134, vcc
	v_add_u32_e32 v134, 0xfffff400, v128
	v_cndmask_b32_e32 v131, v131, v134, vcc
	s_add_u32 s0, s74, 0x1e6d0000
	s_addc_u32 s1, s75, 0
	v_cmp_lt_u32_e32 vcc, 0xdf, v122
	v_mov_b32_e32 v134, 0x100
	v_cndmask_b32_e32 v126, v126, v134, vcc
	v_mov_b32_e32 v134, s0
	v_cndmask_b32_e32 v132, v132, v134, vcc
	v_mov_b32_e32 v134, s1
	v_cndmask_b32_e32 v133, v133, v134, vcc
	v_add_u32_e32 v134, 0xfffff200, v128
	v_cndmask_b32_e32 v131, v131, v134, vcc
	v_mul_lo_u32 v134, v130, v126
	v_add_u32_e32 v134, v134, v131
	v_mov_b32_e32 v135, 0
	v_lshl_add_u64 v[124:125], v[134:135], 0, v[132:133]
	v_readfirstlane_b32 s101, v226
	v_cmp_lt_u32_e32 vcc, 0xbf, v122
	s_mov_b64 s[38:39], vcc
	v_cmp_gt_u32_e32 vcc, 0xd0, v122
	s_and_b64 s[38:39], s[38:39], vcc
	v_cmp_lt_u32_e32 vcc, 0xdf, v122
	s_mov_b64 s[30:31], vcc
	s_lshr_b32 s101, s101, 6
	s_cmp_eq_u32 s101, 3
	s_cbranch_scc1 .Lsh_full
	s_cmp_gt_u32 s101, 5
	s_cbranch_scc1 .Lsh_full
; DEV float lo_bf(unsigned u) { return __uint_as_float(u << 16); }
; DEV float hi_bf(unsigned u) { return __uint_as_float(u & 0xffff0000u); }
; DEV float sigmoidf_(float x) { return __builtin_amdgcn_rcpf(1.f + __expf(-x)); }
; DEV void shift_tile(const Params& p, int l, int tile) {
;     ...
; #pragma unroll
;   for (int i = 0; i < 16; ++i) {
;     const int row = rb + i;
;     const u32x4 pv = rows[i], cu = rows[i + 1], nx = rows[i + 2];
;     float y[8];
; #pragma unroll
;     for (int q = 0; q < 4; ++q) {
;       y[2 * q] = w0[2 * q] * lo_bf(pv[q]) + w1[2 * q] * lo_bf(cu[q]) + w2[2 * q] * lo_bf(nx[q]);
;       y[2 * q + 1] = w0[2 * q + 1] * hi_bf(pv[q]) + w1[2 * q + 1] * hi_bf(cu[q]) + w2[2 * q + 1] * hi_bf(nx[q]);
;     }
;     if (act == 1) {
; #pragma unroll
;       for (int j = 0; j < 8; ++j) y[j] = 1.f - 2.f * __builtin_amdgcn_rcpf(1.f + __expf(2.f * y[j]));
;     } else if (act == 2) {
; #pragma unroll
;       for (int j = 0; j < 8; ++j) y[j] = sigmoidf_(y[j]);
;     }
;     u32x4 o;
;     o[0] = pk2(y[0], y[1]); o[1] = pk2(y[2], y[3]); o[2] = pk2(y[4], y[5]); o[3] = pk2(y[6], y[7]);
;     if (col < 1536) *(u32x4*)(ZRS + (size_t)row * 1536 + col) = o;
;     else if (col < 1792) *(u32x4*)((bf16_t*)(p.ws + O_LIN) + (size_t)row * 256 + (col - 1536)) = o;
;     else *(u32x4*)((bf16_t*)(p.ws + O_GIN) + (size_t)row * 128 + (col - 1792)) = o;
;   }
	s_waitcnt vmcnt(15)
	v_lshlrev_b32_e32 v98, 16, v0
	v_and_b32_e32 v99, 0xffff0000, v0
	v_lshlrev_b32_e32 v100, 16, v1
	v_and_b32_e32 v101, 0xffff0000, v1
	v_lshlrev_b32_e32 v102, 16, v2
	v_and_b32_e32 v103, 0xffff0000, v2
	v_lshlrev_b32_e32 v104, 16, v3
	v_and_b32_e32 v105, 0xffff0000, v3
	v_lshlrev_b32_e32 v106, 16, v4
	v_and_b32_e32 v107, 0xffff0000, v4
	v_lshlrev_b32_e32 v108, 16, v5
	v_and_b32_e32 v109, 0xffff0000, v5
	v_lshlrev_b32_e32 v110, 16, v6
	v_and_b32_e32 v111, 0xffff0000, v6
	v_lshlrev_b32_e32 v112, 16, v7
	v_and_b32_e32 v113, 0xffff0000, v7
	v_lshlrev_b32_e32 v114, 16, v8
	v_and_b32_e32 v115, 0xffff0000, v8
	v_lshlrev_b32_e32 v116, 16, v9
	v_and_b32_e32 v117, 0xffff0000, v9
	v_lshlrev_b32_e32 v118, 16, v10
	v_and_b32_e32 v119, 0xffff0000, v10
	v_lshlrev_b32_e32 v120, 16, v11
	v_and_b32_e32 v121, 0xffff0000, v11
	v_pk_mul_f32 v[98:99], v[72:73], v[98:99]
	v_pk_mul_f32 v[100:101], v[74:75], v[100:101]
	v_pk_mul_f32 v[102:103], v[76:77], v[102:103]
	v_pk_mul_f32 v[104:105], v[78:79], v[104:105]
	v_pk_fma_f32 v[98:99], v[80:81], v[106:107], v[98:99]
	v_pk_fma_f32 v[100:101], v[82:83], v[108:109], v[100:101]
	v_pk_fma_f32 v[102:103], v[84:85], v[110:111], v[102:103]
	v_pk_fma_f32 v[104:105], v[86:87], v[112:113], v[104:105]
	v_pk_fma_f32 v[98:99], v[88:89], v[114:115], v[98:99]
	v_pk_fma_f32 v[100:101], v[90:91], v[116:117], v[100:101]
	v_pk_fma_f32 v[102:103], v[92:93], v[118:119], v[102:103]
	v_pk_fma_f32 v[104:105], v[94:95], v[120:121], v[104:105]
	v_cvt_pk_bf16_f32 v0, v98, v99
	v_cvt_pk_bf16_f32 v1, v100, v101
	v_cvt_pk_bf16_f32 v2, v102, v103
	v_cvt_pk_bf16_f32 v3, v104, v105
	global_store_dwordx4 v[124:125], v[0:3], off
	v_lshl_add_u64 v[124:125], v[126:127], 0, v[124:125]
	s_waitcnt vmcnt(15)
	v_lshlrev_b32_e32 v98, 16, v12
	v_and_b32_e32 v99, 0xffff0000, v12
	v_lshlrev_b32_e32 v100, 16, v13
	v_and_b32_e32 v101, 0xffff0000, v13
	v_lshlrev_b32_e32 v102, 16, v14
	v_and_b32_e32 v103, 0xffff0000, v14
	v_lshlrev_b32_e32 v104, 16, v15
	v_and_b32_e32 v105, 0xffff0000, v15
	v_pk_mul_f32 v[106:107], v[72:73], v[106:107]
	v_pk_mul_f32 v[108:109], v[74:75], v[108:109]
	v_pk_mul_f32 v[110:111], v[76:77], v[110:111]
	v_pk_mul_f32 v[112:113], v[78:79], v[112:113]
	v_pk_fma_f32 v[106:107], v[80:81], v[114:115], v[106:107]
	v_pk_fma_f32 v[108:109], v[82:83], v[116:117], v[108:109]
	v_pk_fma_f32 v[110:111], v[84:85], v[118:119], v[110:111]
	v_pk_fma_f32 v[112:113], v[86:87], v[120:121], v[112:113]
	v_pk_fma_f32 v[106:107], v[88:89], v[98:99], v[106:107]
	v_pk_fma_f32 v[108:109], v[90:91], v[100:101], v[108:109]
	v_pk_fma_f32 v[110:111], v[92:93], v[102:103], v[110:111]
	v_pk_fma_f32 v[112:113], v[94:95], v[104:105], v[112:113]
	v_cvt_pk_bf16_f32 v4, v106, v107
	v_cvt_pk_bf16_f32 v5, v108, v109
	v_cvt_pk_bf16_f32 v6, v110, v111
	v_cvt_pk_bf16_f32 v7, v112, v113
	global_store_dwordx4 v[124:125], v[4:7], off
	v_lshl_add_u64 v[124:125], v[126:127], 0, v[124:125]
	s_waitcnt vmcnt(15)
	v_lshlrev_b32_e32 v106, 16, v16
	v_and_b32_e32 v107, 0xffff0000, v16
	v_lshlrev_b32_e32 v108, 16, v17
	v_and_b32_e32 v109, 0xffff0000, v17
	v_lshlrev_b32_e32 v110, 16, v18
	v_and_b32_e32 v111, 0xffff0000, v18
	v_lshlrev_b32_e32 v112, 16, v19
	v_and_b32_e32 v113, 0xffff0000, v19
	v_pk_mul_f32 v[114:115], v[72:73], v[114:115]
	v_pk_mul_f32 v[116:117], v[74:75], v[116:117]
	v_pk_mul_f32 v[118:119], v[76:77], v[118:119]
	v_pk_mul_f32 v[120:121], v[78:79], v[120:121]
	v_pk_fma_f32 v[114:115], v[80:81], v[98:99], v[114:115]
	v_pk_fma_f32 v[116:117], v[82:83], v[100:101], v[116:117]
	v_pk_fma_f32 v[118:119], v[84:85], v[102:103], v[118:119]
	v_pk_fma_f32 v[120:121], v[86:87], v[104:105], v[120:121]
	v_pk_fma_f32 v[114:115], v[88:89], v[106:107], v[114:115]
	v_pk_fma_f32 v[116:117], v[90:91], v[108:109], v[116:117]
	v_pk_fma_f32 v[118:119], v[92:93], v[110:111], v[118:119]
	v_pk_fma_f32 v[120:121], v[94:95], v[112:113], v[120:121]
	v_cvt_pk_bf16_f32 v8, v114, v115
	v_cvt_pk_bf16_f32 v9, v116, v117
	v_cvt_pk_bf16_f32 v10, v118, v119
	v_cvt_pk_bf16_f32 v11, v120, v121
	global_store_dwordx4 v[124:125], v[8:11], off
	v_lshl_add_u64 v[124:125], v[126:127], 0, v[124:125]
	s_waitcnt vmcnt(15)
	v_lshlrev_b32_e32 v114, 16, v20
	v_and_b32_e32 v115, 0xffff0000, v20
	v_lshlrev_b32_e32 v116, 16, v21
	v_and_b32_e32 v117, 0xffff0000, v21
	v_lshlrev_b32_e32 v118, 16, v22
	v_and_b32_e32 v119, 0xffff0000, v22
	v_lshlrev_b32_e32 v120, 16, v23
	v_and_b32_e32 v121, 0xffff0000, v23
	v_pk_mul_f32 v[98:99], v[72:73], v[98:99]
	v_pk_mul_f32 v[100:101], v[74:75], v[100:101]
	v_pk_mul_f32 v[102:103], v[76:77], v[102:103]
	v_pk_mul_f32 v[104:105], v[78:79], v[104:105]
	v_pk_fma_f32 v[98:99], v[80:81], v[106:107], v[98:99]
	v_pk_fma_f32 v[100:101], v[82:83], v[108:109], v[100:101]
	v_pk_fma_f32 v[102:103], v[84:85], v[110:111], v[102:103]
	v_pk_fma_f32 v[104:105], v[86:87], v[112:113], v[104:105]
	v_pk_fma_f32 v[98:99], v[88:89], v[114:115], v[98:99]
	v_pk_fma_f32 v[100:101], v[90:91], v[116:117], v[100:101]
	v_pk_fma_f32 v[102:103], v[92:93], v[118:119], v[102:103]
	v_pk_fma_f32 v[104:105], v[94:95], v[120:121], v[104:105]
	v_cvt_pk_bf16_f32 v12, v98, v99
	v_cvt_pk_bf16_f32 v13, v100, v101
	v_cvt_pk_bf16_f32 v14, v102, v103
	v_cvt_pk_bf16_f32 v15, v104, v105
	global_store_dwordx4 v[124:125], v[12:15], off
	v_lshl_add_u64 v[124:125], v[126:127], 0, v[124:125]
	s_waitcnt vmcnt(15)
; DEV float lo_bf(unsigned u) { return __uint_as_float(u << 16); }
; DEV float hi_bf(unsigned u) { return __uint_as_float(u & 0xffff0000u); }
; DEV float sigmoidf_(float x) { return __builtin_amdgcn_rcpf(1.f + __expf(-x)); }
; DEV void shift_tile(const Params& p, int l, int tile) {
;     ...
; #pragma unroll
;   for (int i = 0; i < 16; ++i) {
;     const int row = rb + i;
;     const u32x4 pv = rows[i], cu = rows[i + 1], nx = rows[i + 2];
;     float y[8];
; #pragma unroll
;     for (int q = 0; q < 4; ++q) {
;       y[2 * q] = w0[2 * q] * lo_bf(pv[q]) + w1[2 * q] * lo_bf(cu[q]) + w2[2 * q] * lo_bf(nx[q]);
;       y[2 * q + 1] = w0[2 * q + 1] * hi_bf(pv[q]) + w1[2 * q + 1] * hi_bf(cu[q]) + w2[2 * q + 1] * hi_bf(nx[q]);
;     }
;     if (act == 1) {
; #pragma unroll
;       for (int j = 0; j < 8; ++j) y[j] = 1.f - 2.f * __builtin_amdgcn_rcpf(1.f + __expf(2.f * y[j]));
;     } else if (act == 2) {
; #pragma unroll
;       for (int j = 0; j < 8; ++j) y[j] = sigmoidf_(y[j]);
;     }
;     u32x4 o;
;     o[0] = pk2(y[0], y[1]); o[1] = pk2(y[2], y[3]); o[2] = pk2(y[4], y[5]); o[3] = pk2(y[6], y[7]);
;     if (col < 1536) *(u32x4*)(ZRS + (size_t)row * 1536 + col) = o;
;     else if (col < 1792) *(u32x4*)((bf16_t*)(p.ws + O_LIN) + (size_t)row * 256 + (col - 1536)) = o;
;     else *(u32x4*)((bf16_t*)(p.ws + O_GIN) + (size_t)row * 128 + (col - 1792)) = o;
;   }
	v_lshlrev_b32_e32 v98, 16, v24
	v_and_b32_e32 v99, 0xffff0000, v24
	v_lshlrev_b32_e32 v100, 16, v25
	v_and_b32_e32 v101, 0xffff0000, v25
	v_lshlrev_b32_e32 v102, 16, v26
	v_and_b32_e32 v103, 0xffff0000, v26
	v_lshlrev_b32_e32 v104, 16, v27
	v_and_b32_e32 v105, 0xffff0000, v27
	v_pk_mul_f32 v[106:107], v[72:73], v[106:107]
	v_pk_mul_f32 v[108:109], v[74:75], v[108:109]
	v_pk_mul_f32 v[110:111], v[76:77], v[110:111]
	v_pk_mul_f32 v[112:113], v[78:79], v[112:113]
	v_pk_fma_f32 v[106:107], v[80:81], v[114:115], v[106:107]
	v_pk_fma_f32 v[108:109], v[82:83], v[116:117], v[108:109]
	v_pk_fma_f32 v[110:111], v[84:85], v[118:119], v[110:111]
	v_pk_fma_f32 v[112:113], v[86:87], v[120:121], v[112:113]
	v_pk_fma_f32 v[106:107], v[88:89], v[98:99], v[106:107]
	v_pk_fma_f32 v[108:109], v[90:91], v[100:101], v[108:109]
	v_pk_fma_f32 v[110:111], v[92:93], v[102:103], v[110:111]
	v_pk_fma_f32 v[112:113], v[94:95], v[104:105], v[112:113]
	v_cvt_pk_bf16_f32 v16, v106, v107
	v_cvt_pk_bf16_f32 v17, v108, v109
	v_cvt_pk_bf16_f32 v18, v110, v111
	v_cvt_pk_bf16_f32 v19, v112, v113
	global_store_dwordx4 v[124:125], v[16:19], off
	v_lshl_add_u64 v[124:125], v[126:127], 0, v[124:125]
	s_waitcnt vmcnt(15)
	v_lshlrev_b32_e32 v106, 16, v28
	v_and_b32_e32 v107, 0xffff0000, v28
	v_lshlrev_b32_e32 v108, 16, v29
	v_and_b32_e32 v109, 0xffff0000, v29
	v_lshlrev_b32_e32 v110, 16, v30
	v_and_b32_e32 v111, 0xffff0000, v30
	v_lshlrev_b32_e32 v112, 16, v31
	v_and_b32_e32 v113, 0xffff0000, v31
	v_pk_mul_f32 v[114:115], v[72:73], v[114:115]
	v_pk_mul_f32 v[116:117], v[74:75], v[116:117]
	v_pk_mul_f32 v[118:119], v[76:77], v[118:119]
	v_pk_mul_f32 v[120:121], v[78:79], v[120:121]
	v_pk_fma_f32 v[114:115], v[80:81], v[98:99], v[114:115]
	v_pk_fma_f32 v[116:117], v[82:83], v[100:101], v[116:117]
	v_pk_fma_f32 v[118:119], v[84:85], v[102:103], v[118:119]
	v_pk_fma_f32 v[120:121], v[86:87], v[104:105], v[120:121]
	v_pk_fma_f32 v[114:115], v[88:89], v[106:107], v[114:115]
	v_pk_fma_f32 v[116:117], v[90:91], v[108:109], v[116:117]
	v_pk_fma_f32 v[118:119], v[92:93], v[110:111], v[118:119]
	v_pk_fma_f32 v[120:121], v[94:95], v[112:113], v[120:121]
	v_cvt_pk_bf16_f32 v20, v114, v115
	v_cvt_pk_bf16_f32 v21, v116, v117
	v_cvt_pk_bf16_f32 v22, v118, v119
	v_cvt_pk_bf16_f32 v23, v120, v121
	global_store_dwordx4 v[124:125], v[20:23], off
	v_lshl_add_u64 v[124:125], v[126:127], 0, v[124:125]
	s_waitcnt vmcnt(15)
	v_lshlrev_b32_e32 v114, 16, v32
	v_and_b32_e32 v115, 0xffff0000, v32
	v_lshlrev_b32_e32 v116, 16, v33
	v_and_b32_e32 v117, 0xffff0000, v33
	v_lshlrev_b32_e32 v118, 16, v34
	v_and_b32_e32 v119, 0xffff0000, v34
	v_lshlrev_b32_e32 v120, 16, v35
	v_and_b32_e32 v121, 0xffff0000, v35
	v_pk_mul_f32 v[98:99], v[72:73], v[98:99]
	v_pk_mul_f32 v[100:101], v[74:75], v[100:101]
	v_pk_mul_f32 v[102:103], v[76:77], v[102:103]
	v_pk_mul_f32 v[104:105], v[78:79], v[104:105]
	v_pk_fma_f32 v[98:99], v[80:81], v[106:107], v[98:99]
	v_pk_fma_f32 v[100:101], v[82:83], v[108:109], v[100:101]
	v_pk_fma_f32 v[102:103], v[84:85], v[110:111], v[102:103]
	v_pk_fma_f32 v[104:105], v[86:87], v[112:113], v[104:105]
	v_pk_fma_f32 v[98:99], v[88:89], v[114:115], v[98:99]
	v_pk_fma_f32 v[100:101], v[90:91], v[116:117], v[100:101]
	v_pk_fma_f32 v[102:103], v[92:93], v[118:119], v[102:103]
	v_pk_fma_f32 v[104:105], v[94:95], v[120:121], v[104:105]
	v_cvt_pk_bf16_f32 v24, v98, v99
	v_cvt_pk_bf16_f32 v25, v100, v101
	v_cvt_pk_bf16_f32 v26, v102, v103
	v_cvt_pk_bf16_f32 v27, v104, v105
	global_store_dwordx4 v[124:125], v[24:27], off
	v_lshl_add_u64 v[124:125], v[126:127], 0, v[124:125]
	s_waitcnt vmcnt(15)
	v_lshlrev_b32_e32 v98, 16, v36
	v_and_b32_e32 v99, 0xffff0000, v36
	v_lshlrev_b32_e32 v100, 16, v37
	v_and_b32_e32 v101, 0xffff0000, v37
	v_lshlrev_b32_e32 v102, 16, v38
	v_and_b32_e32 v103, 0xffff0000, v38
	v_lshlrev_b32_e32 v104, 16, v39
	v_and_b32_e32 v105, 0xffff0000, v39
	v_pk_mul_f32 v[106:107], v[72:73], v[106:107]
	v_pk_mul_f32 v[108:109], v[74:75], v[108:109]
	v_pk_mul_f32 v[110:111], v[76:77], v[110:111]
	v_pk_mul_f32 v[112:113], v[78:79], v[112:113]
	v_pk_fma_f32 v[106:107], v[80:81], v[114:115], v[106:107]
	v_pk_fma_f32 v[108:109], v[82:83], v[116:117], v[108:109]
	v_pk_fma_f32 v[110:111], v[84:85], v[118:119], v[110:111]
	v_pk_fma_f32 v[112:113], v[86:87], v[120:121], v[112:113]
	v_pk_fma_f32 v[106:107], v[88:89], v[98:99], v[106:107]
	v_pk_fma_f32 v[108:109], v[90:91], v[100:101], v[108:109]
	v_pk_fma_f32 v[110:111], v[92:93], v[102:103], v[110:111]
	v_pk_fma_f32 v[112:113], v[94:95], v[104:105], v[112:113]
	v_cvt_pk_bf16_f32 v28, v106, v107
	v_cvt_pk_bf16_f32 v29, v108, v109
	v_cvt_pk_bf16_f32 v30, v110, v111
	v_cvt_pk_bf16_f32 v31, v112, v113
	global_store_dwordx4 v[124:125], v[28:31], off
	v_lshl_add_u64 v[124:125], v[126:127], 0, v[124:125]
	s_waitcnt vmcnt(15)
	v_lshlrev_b32_e32 v106, 16, v40
	v_and_b32_e32 v107, 0xffff0000, v40
	v_lshlrev_b32_e32 v108, 16, v41
	v_and_b32_e32 v109, 0xffff0000, v41
	v_lshlrev_b32_e32 v110, 16, v42
	v_and_b32_e32 v111, 0xffff0000, v42
	v_lshlrev_b32_e32 v112, 16, v43
	v_and_b32_e32 v113, 0xffff0000, v43
	v_pk_mul_f32 v[114:115], v[72:73], v[114:115]
	v_pk_mul_f32 v[116:117], v[74:75], v[116:117]
	v_pk_mul_f32 v[118:119], v[76:77], v[118:119]
	v_pk_mul_f32 v[120:121], v[78:79], v[120:121]
	v_pk_fma_f32 v[114:115], v[80:81], v[98:99], v[114:115]
	v_pk_fma_f32 v[116:117], v[82:83], v[100:101], v[116:117]
	v_pk_fma_f32 v[118:119], v[84:85], v[102:103], v[118:119]
	v_pk_fma_f32 v[120:121], v[86:87], v[104:105], v[120:121]
	v_pk_fma_f32 v[114:115], v[88:89], v[106:107], v[114:115]
	v_pk_fma_f32 v[116:117], v[90:91], v[108:109], v[116:117]
	v_pk_fma_f32 v[118:119], v[92:93], v[110:111], v[118:119]
	v_pk_fma_f32 v[120:121], v[94:95], v[112:113], v[120:121]
	v_cvt_pk_bf16_f32 v32, v114, v115
	v_cvt_pk_bf16_f32 v33, v116, v117
	v_cvt_pk_bf16_f32 v34, v118, v119
	v_cvt_pk_bf16_f32 v35, v120, v121
	global_store_dwordx4 v[124:125], v[32:35], off
	v_lshl_add_u64 v[124:125], v[126:127], 0, v[124:125]
	s_waitcnt vmcnt(15)
; DEV float lo_bf(unsigned u) { return __uint_as_float(u << 16); }
; DEV float hi_bf(unsigned u) { return __uint_as_float(u & 0xffff0000u); }
; DEV float sigmoidf_(float x) { return __builtin_amdgcn_rcpf(1.f + __expf(-x)); }
; DEV void shift_tile(const Params& p, int l, int tile) {
;     ...
; #pragma unroll
;   for (int i = 0; i < 16; ++i) {
;     const int row = rb + i;
;     const u32x4 pv = rows[i], cu = rows[i + 1], nx = rows[i + 2];
;     float y[8];
; #pragma unroll
;     for (int q = 0; q < 4; ++q) {
;       y[2 * q] = w0[2 * q] * lo_bf(pv[q]) + w1[2 * q] * lo_bf(cu[q]) + w2[2 * q] * lo_bf(nx[q]);
;       y[2 * q + 1] = w0[2 * q + 1] * hi_bf(pv[q]) + w1[2 * q + 1] * hi_bf(cu[q]) + w2[2 * q + 1] * hi_bf(nx[q]);
;     }
;     if (act == 1) {
; #pragma unroll
;       for (int j = 0; j < 8; ++j) y[j] = 1.f - 2.f * __builtin_amdgcn_rcpf(1.f + __expf(2.f * y[j]));
;     } else if (act == 2) {
; #pragma unroll
;       for (int j = 0; j < 8; ++j) y[j] = sigmoidf_(y[j]);
;     }
;     u32x4 o;
;     o[0] = pk2(y[0], y[1]); o[1] = pk2(y[2], y[3]); o[2] = pk2(y[4], y[5]); o[3] = pk2(y[6], y[7]);
;     if (col < 1536) *(u32x4*)(ZRS + (size_t)row * 1536 + col) = o;
;     else if (col < 1792) *(u32x4*)((bf16_t*)(p.ws + O_LIN) + (size_t)row * 256 + (col - 1536)) = o;
;     else *(u32x4*)((bf16_t*)(p.ws + O_GIN) + (size_t)row * 128 + (col - 1792)) = o;
;   }
	v_lshlrev_b32_e32 v114, 16, v44
	v_and_b32_e32 v115, 0xffff0000, v44
	v_lshlrev_b32_e32 v116, 16, v45
	v_and_b32_e32 v117, 0xffff0000, v45
	v_lshlrev_b32_e32 v118, 16, v46
	v_and_b32_e32 v119, 0xffff0000, v46
	v_lshlrev_b32_e32 v120, 16, v47
	v_and_b32_e32 v121, 0xffff0000, v47
	v_pk_mul_f32 v[98:99], v[72:73], v[98:99]
	v_pk_mul_f32 v[100:101], v[74:75], v[100:101]
	v_pk_mul_f32 v[102:103], v[76:77], v[102:103]
	v_pk_mul_f32 v[104:105], v[78:79], v[104:105]
	v_pk_fma_f32 v[98:99], v[80:81], v[106:107], v[98:99]
	v_pk_fma_f32 v[100:101], v[82:83], v[108:109], v[100:101]
	v_pk_fma_f32 v[102:103], v[84:85], v[110:111], v[102:103]
	v_pk_fma_f32 v[104:105], v[86:87], v[112:113], v[104:105]
	v_pk_fma_f32 v[98:99], v[88:89], v[114:115], v[98:99]
	v_pk_fma_f32 v[100:101], v[90:91], v[116:117], v[100:101]
	v_pk_fma_f32 v[102:103], v[92:93], v[118:119], v[102:103]
	v_pk_fma_f32 v[104:105], v[94:95], v[120:121], v[104:105]
	v_cvt_pk_bf16_f32 v36, v98, v99
	v_cvt_pk_bf16_f32 v37, v100, v101
	v_cvt_pk_bf16_f32 v38, v102, v103
	v_cvt_pk_bf16_f32 v39, v104, v105
	global_store_dwordx4 v[124:125], v[36:39], off
	v_lshl_add_u64 v[124:125], v[126:127], 0, v[124:125]
	s_waitcnt vmcnt(15)
	v_lshlrev_b32_e32 v98, 16, v48
	v_and_b32_e32 v99, 0xffff0000, v48
	v_lshlrev_b32_e32 v100, 16, v49
	v_and_b32_e32 v101, 0xffff0000, v49
	v_lshlrev_b32_e32 v102, 16, v50
	v_and_b32_e32 v103, 0xffff0000, v50
	v_lshlrev_b32_e32 v104, 16, v51
	v_and_b32_e32 v105, 0xffff0000, v51
	v_pk_mul_f32 v[106:107], v[72:73], v[106:107]
	v_pk_mul_f32 v[108:109], v[74:75], v[108:109]
	v_pk_mul_f32 v[110:111], v[76:77], v[110:111]
	v_pk_mul_f32 v[112:113], v[78:79], v[112:113]
	v_pk_fma_f32 v[106:107], v[80:81], v[114:115], v[106:107]
	v_pk_fma_f32 v[108:109], v[82:83], v[116:117], v[108:109]
	v_pk_fma_f32 v[110:111], v[84:85], v[118:119], v[110:111]
	v_pk_fma_f32 v[112:113], v[86:87], v[120:121], v[112:113]
	v_pk_fma_f32 v[106:107], v[88:89], v[98:99], v[106:107]
	v_pk_fma_f32 v[108:109], v[90:91], v[100:101], v[108:109]
	v_pk_fma_f32 v[110:111], v[92:93], v[102:103], v[110:111]
	v_pk_fma_f32 v[112:113], v[94:95], v[104:105], v[112:113]
	v_cvt_pk_bf16_f32 v40, v106, v107
	v_cvt_pk_bf16_f32 v41, v108, v109
	v_cvt_pk_bf16_f32 v42, v110, v111
	v_cvt_pk_bf16_f32 v43, v112, v113
	global_store_dwordx4 v[124:125], v[40:43], off
	v_lshl_add_u64 v[124:125], v[126:127], 0, v[124:125]
	s_waitcnt vmcnt(15)
	v_lshlrev_b32_e32 v106, 16, v52
	v_and_b32_e32 v107, 0xffff0000, v52
	v_lshlrev_b32_e32 v108, 16, v53
	v_and_b32_e32 v109, 0xffff0000, v53
	v_lshlrev_b32_e32 v110, 16, v54
	v_and_b32_e32 v111, 0xffff0000, v54
	v_lshlrev_b32_e32 v112, 16, v55
	v_and_b32_e32 v113, 0xffff0000, v55
	v_pk_mul_f32 v[114:115], v[72:73], v[114:115]
	v_pk_mul_f32 v[116:117], v[74:75], v[116:117]
	v_pk_mul_f32 v[118:119], v[76:77], v[118:119]
	v_pk_mul_f32 v[120:121], v[78:79], v[120:121]
	v_pk_fma_f32 v[114:115], v[80:81], v[98:99], v[114:115]
	v_pk_fma_f32 v[116:117], v[82:83], v[100:101], v[116:117]
	v_pk_fma_f32 v[118:119], v[84:85], v[102:103], v[118:119]
	v_pk_fma_f32 v[120:121], v[86:87], v[104:105], v[120:121]
	v_pk_fma_f32 v[114:115], v[88:89], v[106:107], v[114:115]
	v_pk_fma_f32 v[116:117], v[90:91], v[108:109], v[116:117]
	v_pk_fma_f32 v[118:119], v[92:93], v[110:111], v[118:119]
	v_pk_fma_f32 v[120:121], v[94:95], v[112:113], v[120:121]
	v_cvt_pk_bf16_f32 v44, v114, v115
	v_cvt_pk_bf16_f32 v45, v116, v117
	v_cvt_pk_bf16_f32 v46, v118, v119
	v_cvt_pk_bf16_f32 v47, v120, v121
	global_store_dwordx4 v[124:125], v[44:47], off
	v_lshl_add_u64 v[124:125], v[126:127], 0, v[124:125]
	s_waitcnt vmcnt(15)
	v_lshlrev_b32_e32 v114, 16, v56
	v_and_b32_e32 v115, 0xffff0000, v56
	v_lshlrev_b32_e32 v116, 16, v57
	v_and_b32_e32 v117, 0xffff0000, v57
	v_lshlrev_b32_e32 v118, 16, v58
	v_and_b32_e32 v119, 0xffff0000, v58
	v_lshlrev_b32_e32 v120, 16, v59
	v_and_b32_e32 v121, 0xffff0000, v59
	v_pk_mul_f32 v[98:99], v[72:73], v[98:99]
	v_pk_mul_f32 v[100:101], v[74:75], v[100:101]
	v_pk_mul_f32 v[102:103], v[76:77], v[102:103]
	v_pk_mul_f32 v[104:105], v[78:79], v[104:105]
	v_pk_fma_f32 v[98:99], v[80:81], v[106:107], v[98:99]
	v_pk_fma_f32 v[100:101], v[82:83], v[108:109], v[100:101]
	v_pk_fma_f32 v[102:103], v[84:85], v[110:111], v[102:103]
	v_pk_fma_f32 v[104:105], v[86:87], v[112:113], v[104:105]
	v_pk_fma_f32 v[98:99], v[88:89], v[114:115], v[98:99]
	v_pk_fma_f32 v[100:101], v[90:91], v[116:117], v[100:101]
	v_pk_fma_f32 v[102:103], v[92:93], v[118:119], v[102:103]
	v_pk_fma_f32 v[104:105], v[94:95], v[120:121], v[104:105]
	v_cvt_pk_bf16_f32 v48, v98, v99
	v_cvt_pk_bf16_f32 v49, v100, v101
	v_cvt_pk_bf16_f32 v50, v102, v103
	v_cvt_pk_bf16_f32 v51, v104, v105
	global_store_dwordx4 v[124:125], v[48:51], off
	v_lshl_add_u64 v[124:125], v[126:127], 0, v[124:125]
	s_waitcnt vmcnt(15)
	v_lshlrev_b32_e32 v98, 16, v60
	v_and_b32_e32 v99, 0xffff0000, v60
	v_lshlrev_b32_e32 v100, 16, v61
	v_and_b32_e32 v101, 0xffff0000, v61
	v_lshlrev_b32_e32 v102, 16, v62
	v_and_b32_e32 v103, 0xffff0000, v62
	v_lshlrev_b32_e32 v104, 16, v63
	v_and_b32_e32 v105, 0xffff0000, v63
	v_pk_mul_f32 v[106:107], v[72:73], v[106:107]
	v_pk_mul_f32 v[108:109], v[74:75], v[108:109]
	v_pk_mul_f32 v[110:111], v[76:77], v[110:111]
	v_pk_mul_f32 v[112:113], v[78:79], v[112:113]
	v_pk_fma_f32 v[106:107], v[80:81], v[114:115], v[106:107]
	v_pk_fma_f32 v[108:109], v[82:83], v[116:117], v[108:109]
	v_pk_fma_f32 v[110:111], v[84:85], v[118:119], v[110:111]
	v_pk_fma_f32 v[112:113], v[86:87], v[120:121], v[112:113]
	v_pk_fma_f32 v[106:107], v[88:89], v[98:99], v[106:107]
	v_pk_fma_f32 v[108:109], v[90:91], v[100:101], v[108:109]
	v_pk_fma_f32 v[110:111], v[92:93], v[102:103], v[110:111]
	v_pk_fma_f32 v[112:113], v[94:95], v[104:105], v[112:113]
	v_cvt_pk_bf16_f32 v52, v106, v107
	v_cvt_pk_bf16_f32 v53, v108, v109
	v_cvt_pk_bf16_f32 v54, v110, v111
	v_cvt_pk_bf16_f32 v55, v112, v113
	global_store_dwordx4 v[124:125], v[52:55], off
	v_lshl_add_u64 v[124:125], v[126:127], 0, v[124:125]
	s_waitcnt vmcnt(15)
; DEV float lo_bf(unsigned u) { return __uint_as_float(u << 16); }
; DEV float hi_bf(unsigned u) { return __uint_as_float(u & 0xffff0000u); }
; DEV float sigmoidf_(float x) { return __builtin_amdgcn_rcpf(1.f + __expf(-x)); }
; DEV void shift_tile(const Params& p, int l, int tile) {
;     ...
; #pragma unroll
;   for (int i = 0; i < 16; ++i) {
;     const int row = rb + i;
;     const u32x4 pv = rows[i], cu = rows[i + 1], nx = rows[i + 2];
;     float y[8];
; #pragma unroll
;     for (int q = 0; q < 4; ++q) {
;       y[2 * q] = w0[2 * q] * lo_bf(pv[q]) + w1[2 * q] * lo_bf(cu[q]) + w2[2 * q] * lo_bf(nx[q]);
;       y[2 * q + 1] = w0[2 * q + 1] * hi_bf(pv[q]) + w1[2 * q + 1] * hi_bf(cu[q]) + w2[2 * q + 1] * hi_bf(nx[q]);
;     }
;     if (act == 1) {
; #pragma unroll
;       for (int j = 0; j < 8; ++j) y[j] = 1.f - 2.f * __builtin_amdgcn_rcpf(1.f + __expf(2.f * y[j]));
;     } else if (act == 2) {
; #pragma unroll
;       for (int j = 0; j < 8; ++j) y[j] = sigmoidf_(y[j]);
;     }
;     u32x4 o;
;     o[0] = pk2(y[0], y[1]); o[1] = pk2(y[2], y[3]); o[2] = pk2(y[4], y[5]); o[3] = pk2(y[6], y[7]);
;     if (col < 1536) *(u32x4*)(ZRS + (size_t)row * 1536 + col) = o;
;     else if (col < 1792) *(u32x4*)((bf16_t*)(p.ws + O_LIN) + (size_t)row * 256 + (col - 1536)) = o;
;     else *(u32x4*)((bf16_t*)(p.ws + O_GIN) + (size_t)row * 128 + (col - 1792)) = o;
;   }
	v_lshlrev_b32_e32 v106, 16, v64
	v_and_b32_e32 v107, 0xffff0000, v64
	v_lshlrev_b32_e32 v108, 16, v65
	v_and_b32_e32 v109, 0xffff0000, v65
	v_lshlrev_b32_e32 v110, 16, v66
	v_and_b32_e32 v111, 0xffff0000, v66
	v_lshlrev_b32_e32 v112, 16, v67
	v_and_b32_e32 v113, 0xffff0000, v67
	v_pk_mul_f32 v[114:115], v[72:73], v[114:115]
	v_pk_mul_f32 v[116:117], v[74:75], v[116:117]
	v_pk_mul_f32 v[118:119], v[76:77], v[118:119]
	v_pk_mul_f32 v[120:121], v[78:79], v[120:121]
	v_pk_fma_f32 v[114:115], v[80:81], v[98:99], v[114:115]
	v_pk_fma_f32 v[116:117], v[82:83], v[100:101], v[116:117]
	v_pk_fma_f32 v[118:119], v[84:85], v[102:103], v[118:119]
	v_pk_fma_f32 v[120:121], v[86:87], v[104:105], v[120:121]
	v_pk_fma_f32 v[114:115], v[88:89], v[106:107], v[114:115]
	v_pk_fma_f32 v[116:117], v[90:91], v[108:109], v[116:117]
	v_pk_fma_f32 v[118:119], v[92:93], v[110:111], v[118:119]
	v_pk_fma_f32 v[120:121], v[94:95], v[112:113], v[120:121]
	v_cvt_pk_bf16_f32 v56, v114, v115
	v_cvt_pk_bf16_f32 v57, v116, v117
	v_cvt_pk_bf16_f32 v58, v118, v119
	v_cvt_pk_bf16_f32 v59, v120, v121
	global_store_dwordx4 v[124:125], v[56:59], off
	v_lshl_add_u64 v[124:125], v[126:127], 0, v[124:125]
	s_waitcnt vmcnt(15)
	v_lshlrev_b32_e32 v114, 16, v68
	v_and_b32_e32 v115, 0xffff0000, v68
	v_lshlrev_b32_e32 v116, 16, v69
	v_and_b32_e32 v117, 0xffff0000, v69
	v_lshlrev_b32_e32 v118, 16, v70
	v_and_b32_e32 v119, 0xffff0000, v70
	v_lshlrev_b32_e32 v120, 16, v71
	v_and_b32_e32 v121, 0xffff0000, v71
	v_pk_mul_f32 v[98:99], v[72:73], v[98:99]
	v_pk_mul_f32 v[100:101], v[74:75], v[100:101]
	v_pk_mul_f32 v[102:103], v[76:77], v[102:103]
	v_pk_mul_f32 v[104:105], v[78:79], v[104:105]
	v_pk_fma_f32 v[98:99], v[80:81], v[106:107], v[98:99]
	v_pk_fma_f32 v[100:101], v[82:83], v[108:109], v[100:101]
	v_pk_fma_f32 v[102:103], v[84:85], v[110:111], v[102:103]
	v_pk_fma_f32 v[104:105], v[86:87], v[112:113], v[104:105]
	v_pk_fma_f32 v[98:99], v[88:89], v[114:115], v[98:99]
	v_pk_fma_f32 v[100:101], v[90:91], v[116:117], v[100:101]
	v_pk_fma_f32 v[102:103], v[92:93], v[118:119], v[102:103]
	v_pk_fma_f32 v[104:105], v[94:95], v[120:121], v[104:105]
	v_cvt_pk_bf16_f32 v60, v98, v99
	v_cvt_pk_bf16_f32 v61, v100, v101
	v_cvt_pk_bf16_f32 v62, v102, v103
	v_cvt_pk_bf16_f32 v63, v104, v105
	global_store_dwordx4 v[124:125], v[60:63], off
	s_branch .Lsh_end
.Lsh_full:
	s_waitcnt vmcnt(15)
	v_lshlrev_b32_e32 v98, 16, v0
	v_and_b32_e32 v99, 0xffff0000, v0
	v_lshlrev_b32_e32 v100, 16, v1
	v_and_b32_e32 v101, 0xffff0000, v1
	v_lshlrev_b32_e32 v102, 16, v2
	v_and_b32_e32 v103, 0xffff0000, v2
	v_lshlrev_b32_e32 v104, 16, v3
	v_and_b32_e32 v105, 0xffff0000, v3
	v_lshlrev_b32_e32 v106, 16, v4
	v_and_b32_e32 v107, 0xffff0000, v4
	v_lshlrev_b32_e32 v108, 16, v5
	v_and_b32_e32 v109, 0xffff0000, v5
	v_lshlrev_b32_e32 v110, 16, v6
	v_and_b32_e32 v111, 0xffff0000, v6
	v_lshlrev_b32_e32 v112, 16, v7
	v_and_b32_e32 v113, 0xffff0000, v7
	v_lshlrev_b32_e32 v114, 16, v8
	v_and_b32_e32 v115, 0xffff0000, v8
	v_lshlrev_b32_e32 v116, 16, v9
	v_and_b32_e32 v117, 0xffff0000, v9
	v_lshlrev_b32_e32 v118, 16, v10
	v_and_b32_e32 v119, 0xffff0000, v10
	v_lshlrev_b32_e32 v120, 16, v11
	v_and_b32_e32 v121, 0xffff0000, v11
	v_pk_mul_f32 v[98:99], v[72:73], v[98:99]
	v_pk_mul_f32 v[100:101], v[74:75], v[100:101]
	v_pk_mul_f32 v[102:103], v[76:77], v[102:103]
	v_pk_mul_f32 v[104:105], v[78:79], v[104:105]
	v_pk_fma_f32 v[98:99], v[80:81], v[106:107], v[98:99]
	v_pk_fma_f32 v[100:101], v[82:83], v[108:109], v[100:101]
	v_pk_fma_f32 v[102:103], v[84:85], v[110:111], v[102:103]
	v_pk_fma_f32 v[104:105], v[86:87], v[112:113], v[104:105]
	v_pk_fma_f32 v[98:99], v[88:89], v[114:115], v[98:99]
	v_pk_fma_f32 v[100:101], v[90:91], v[116:117], v[100:101]
	v_pk_fma_f32 v[102:103], v[92:93], v[118:119], v[102:103]
	v_pk_fma_f32 v[104:105], v[94:95], v[120:121], v[104:105]
	s_mov_b64 exec, s[38:39]
	v_mul_f32_e32 v98, 0x4038aa3b, v98
	v_mul_f32_e32 v99, 0x4038aa3b, v99
	v_mul_f32_e32 v100, 0x4038aa3b, v100
	v_mul_f32_e32 v101, 0x4038aa3b, v101
	v_mul_f32_e32 v102, 0x4038aa3b, v102
	v_mul_f32_e32 v103, 0x4038aa3b, v103
	v_mul_f32_e32 v104, 0x4038aa3b, v104
	v_mul_f32_e32 v105, 0x4038aa3b, v105
	v_exp_f32_e32 v98, v98
	v_exp_f32_e32 v99, v99
	v_exp_f32_e32 v100, v100
	v_exp_f32_e32 v101, v101
	v_exp_f32_e32 v102, v102
	v_exp_f32_e32 v103, v103
	v_exp_f32_e32 v104, v104
	v_exp_f32_e32 v105, v105
	v_add_f32_e32 v98, 1.0, v98
	v_add_f32_e32 v99, 1.0, v99
	v_add_f32_e32 v100, 1.0, v100
	v_add_f32_e32 v101, 1.0, v101
	v_add_f32_e32 v102, 1.0, v102
	v_add_f32_e32 v103, 1.0, v103
	v_add_f32_e32 v104, 1.0, v104
	v_add_f32_e32 v105, 1.0, v105
	v_rcp_f32_e32 v98, v98
	v_rcp_f32_e32 v99, v99
	v_rcp_f32_e32 v100, v100
	v_rcp_f32_e32 v101, v101
	v_rcp_f32_e32 v102, v102
	v_rcp_f32_e32 v103, v103
	v_rcp_f32_e32 v104, v104
	v_rcp_f32_e32 v105, v105
	s_nop 0
	v_pk_fma_f32 v[98:99], v[98:99], -2.0, 1.0 op_sel_hi:[1,0,0]
	v_pk_fma_f32 v[100:101], v[100:101], -2.0, 1.0 op_sel_hi:[1,0,0]
	v_pk_fma_f32 v[102:103], v[102:103], -2.0, 1.0 op_sel_hi:[1,0,0]
	v_pk_fma_f32 v[104:105], v[104:105], -2.0, 1.0 op_sel_hi:[1,0,0]
	s_mov_b64 exec, s[30:31]
	v_mul_f32_e32 v98, 0xbfb8aa3b, v98
	v_mul_f32_e32 v99, 0xbfb8aa3b, v99
	v_mul_f32_e32 v100, 0xbfb8aa3b, v100
	v_mul_f32_e32 v101, 0xbfb8aa3b, v101
	v_mul_f32_e32 v102, 0xbfb8aa3b, v102
	v_mul_f32_e32 v103, 0xbfb8aa3b, v103
	v_mul_f32_e32 v104, 0xbfb8aa3b, v104
	v_mul_f32_e32 v105, 0xbfb8aa3b, v105
	v_exp_f32_e32 v98, v98
	v_exp_f32_e32 v99, v99
	v_exp_f32_e32 v100, v100
	v_exp_f32_e32 v101, v101
	v_exp_f32_e32 v102, v102
	v_exp_f32_e32 v103, v103
	v_exp_f32_e32 v104, v104
	v_exp_f32_e32 v105, v105
	v_add_f32_e32 v98, 1.0, v98
	v_add_f32_e32 v99, 1.0, v99
	v_add_f32_e32 v100, 1.0, v100
	v_add_f32_e32 v101, 1.0, v101
	v_add_f32_e32 v102, 1.0, v102
	v_add_f32_e32 v103, 1.0, v103
	v_add_f32_e32 v104, 1.0, v104
	v_add_f32_e32 v105, 1.0, v105
	v_rcp_f32_e32 v98, v98
	v_rcp_f32_e32 v99, v99
	v_rcp_f32_e32 v100, v100
	v_rcp_f32_e32 v101, v101
	v_rcp_f32_e32 v102, v102
	v_rcp_f32_e32 v103, v103
	v_rcp_f32_e32 v104, v104
	v_rcp_f32_e32 v105, v105
	s_mov_b64 exec, s[36:37]
	s_nop 0
	v_cvt_pk_bf16_f32 v0, v98, v99
	v_cvt_pk_bf16_f32 v1, v100, v101
	v_cvt_pk_bf16_f32 v2, v102, v103
	v_cvt_pk_bf16_f32 v3, v104, v105
	global_store_dwordx4 v[124:125], v[0:3], off
	v_lshl_add_u64 v[124:125], v[126:127], 0, v[124:125]
	s_waitcnt vmcnt(15)
; DEV float lo_bf(unsigned u) { return __uint_as_float(u << 16); }
; DEV float hi_bf(unsigned u) { return __uint_as_float(u & 0xffff0000u); }
; DEV float sigmoidf_(float x) { return __builtin_amdgcn_rcpf(1.f + __expf(-x)); }
; DEV void shift_tile(const Params& p, int l, int tile) {
;     ...
; #pragma unroll
;   for (int i = 0; i < 16; ++i) {
;     const int row = rb + i;
;     const u32x4 pv = rows[i], cu = rows[i + 1], nx = rows[i + 2];
;     float y[8];
; #pragma unroll
;     for (int q = 0; q < 4; ++q) {
;       y[2 * q] = w0[2 * q] * lo_bf(pv[q]) + w1[2 * q] * lo_bf(cu[q]) + w2[2 * q] * lo_bf(nx[q]);
;       y[2 * q + 1] = w0[2 * q + 1] * hi_bf(pv[q]) + w1[2 * q + 1] * hi_bf(cu[q]) + w2[2 * q + 1] * hi_bf(nx[q]);
;     }
;     if (act == 1) {
; #pragma unroll
;       for (int j = 0; j < 8; ++j) y[j] = 1.f - 2.f * __builtin_amdgcn_rcpf(1.f + __expf(2.f * y[j]));
;     } else if (act == 2) {
; #pragma unroll
;       for (int j = 0; j < 8; ++j) y[j] = sigmoidf_(y[j]);
;     }
;     u32x4 o;
;     o[0] = pk2(y[0], y[1]); o[1] = pk2(y[2], y[3]); o[2] = pk2(y[4], y[5]); o[3] = pk2(y[6], y[7]);
;     if (col < 1536) *(u32x4*)(ZRS + (size_t)row * 1536 + col) = o;
;     else if (col < 1792) *(u32x4*)((bf16_t*)(p.ws + O_LIN) + (size_t)row * 256 + (col - 1536)) = o;
;     else *(u32x4*)((bf16_t*)(p.ws + O_GIN) + (size_t)row * 128 + (col - 1792)) = o;
;   }
	v_lshlrev_b32_e32 v98, 16, v12
	v_and_b32_e32 v99, 0xffff0000, v12
	v_lshlrev_b32_e32 v100, 16, v13
	v_and_b32_e32 v101, 0xffff0000, v13
	v_lshlrev_b32_e32 v102, 16, v14
	v_and_b32_e32 v103, 0xffff0000, v14
	v_lshlrev_b32_e32 v104, 16, v15
	v_and_b32_e32 v105, 0xffff0000, v15
	v_pk_mul_f32 v[106:107], v[72:73], v[106:107]
	v_pk_mul_f32 v[108:109], v[74:75], v[108:109]
	v_pk_mul_f32 v[110:111], v[76:77], v[110:111]
	v_pk_mul_f32 v[112:113], v[78:79], v[112:113]
	v_pk_fma_f32 v[106:107], v[80:81], v[114:115], v[106:107]
	v_pk_fma_f32 v[108:109], v[82:83], v[116:117], v[108:109]
	v_pk_fma_f32 v[110:111], v[84:85], v[118:119], v[110:111]
	v_pk_fma_f32 v[112:113], v[86:87], v[120:121], v[112:113]
	v_pk_fma_f32 v[106:107], v[88:89], v[98:99], v[106:107]
	v_pk_fma_f32 v[108:109], v[90:91], v[100:101], v[108:109]
	v_pk_fma_f32 v[110:111], v[92:93], v[102:103], v[110:111]
	v_pk_fma_f32 v[112:113], v[94:95], v[104:105], v[112:113]
	s_mov_b64 exec, s[38:39]
	v_mul_f32_e32 v106, 0x4038aa3b, v106
	v_mul_f32_e32 v107, 0x4038aa3b, v107
	v_mul_f32_e32 v108, 0x4038aa3b, v108
	v_mul_f32_e32 v109, 0x4038aa3b, v109
	v_mul_f32_e32 v110, 0x4038aa3b, v110
	v_mul_f32_e32 v111, 0x4038aa3b, v111
	v_mul_f32_e32 v112, 0x4038aa3b, v112
	v_mul_f32_e32 v113, 0x4038aa3b, v113
	v_exp_f32_e32 v106, v106
	v_exp_f32_e32 v107, v107
	v_exp_f32_e32 v108, v108
	v_exp_f32_e32 v109, v109
	v_exp_f32_e32 v110, v110
	v_exp_f32_e32 v111, v111
	v_exp_f32_e32 v112, v112
	v_exp_f32_e32 v113, v113
	v_add_f32_e32 v106, 1.0, v106
	v_add_f32_e32 v107, 1.0, v107
	v_add_f32_e32 v108, 1.0, v108
	v_add_f32_e32 v109, 1.0, v109
	v_add_f32_e32 v110, 1.0, v110
	v_add_f32_e32 v111, 1.0, v111
	v_add_f32_e32 v112, 1.0, v112
	v_add_f32_e32 v113, 1.0, v113
	v_rcp_f32_e32 v106, v106
	v_rcp_f32_e32 v107, v107
	v_rcp_f32_e32 v108, v108
	v_rcp_f32_e32 v109, v109
	v_rcp_f32_e32 v110, v110
	v_rcp_f32_e32 v111, v111
	v_rcp_f32_e32 v112, v112
	v_rcp_f32_e32 v113, v113
	s_nop 0
	v_pk_fma_f32 v[106:107], v[106:107], -2.0, 1.0 op_sel_hi:[1,0,0]
	v_pk_fma_f32 v[108:109], v[108:109], -2.0, 1.0 op_sel_hi:[1,0,0]
	v_pk_fma_f32 v[110:111], v[110:111], -2.0, 1.0 op_sel_hi:[1,0,0]
	v_pk_fma_f32 v[112:113], v[112:113], -2.0, 1.0 op_sel_hi:[1,0,0]
	s_mov_b64 exec, s[30:31]
	v_mul_f32_e32 v106, 0xbfb8aa3b, v106
	v_mul_f32_e32 v107, 0xbfb8aa3b, v107
	v_mul_f32_e32 v108, 0xbfb8aa3b, v108
	v_mul_f32_e32 v109, 0xbfb8aa3b, v109
	v_mul_f32_e32 v110, 0xbfb8aa3b, v110
	v_mul_f32_e32 v111, 0xbfb8aa3b, v111
	v_mul_f32_e32 v112, 0xbfb8aa3b, v112
	v_mul_f32_e32 v113, 0xbfb8aa3b, v113
	v_exp_f32_e32 v106, v106
	v_exp_f32_e32 v107, v107
	v_exp_f32_e32 v108, v108
	v_exp_f32_e32 v109, v109
	v_exp_f32_e32 v110, v110
	v_exp_f32_e32 v111, v111
	v_exp_f32_e32 v112, v112
	v_exp_f32_e32 v113, v113
	v_add_f32_e32 v106, 1.0, v106
	v_add_f32_e32 v107, 1.0, v107
	v_add_f32_e32 v108, 1.0, v108
	v_add_f32_e32 v109, 1.0, v109
	v_add_f32_e32 v110, 1.0, v110
	v_add_f32_e32 v111, 1.0, v111
	v_add_f32_e32 v112, 1.0, v112
	v_add_f32_e32 v113, 1.0, v113
	v_rcp_f32_e32 v106, v106
	v_rcp_f32_e32 v107, v107
	v_rcp_f32_e32 v108, v108
	v_rcp_f32_e32 v109, v109
	v_rcp_f32_e32 v110, v110
	v_rcp_f32_e32 v111, v111
	v_rcp_f32_e32 v112, v112
	v_rcp_f32_e32 v113, v113
	s_mov_b64 exec, s[36:37]
	s_nop 0
	v_cvt_pk_bf16_f32 v4, v106, v107
	v_cvt_pk_bf16_f32 v5, v108, v109
	v_cvt_pk_bf16_f32 v6, v110, v111
	v_cvt_pk_bf16_f32 v7, v112, v113
	global_store_dwordx4 v[124:125], v[4:7], off
	v_lshl_add_u64 v[124:125], v[126:127], 0, v[124:125]
	s_waitcnt vmcnt(15)
	v_lshlrev_b32_e32 v106, 16, v16
	v_and_b32_e32 v107, 0xffff0000, v16
	v_lshlrev_b32_e32 v108, 16, v17
	v_and_b32_e32 v109, 0xffff0000, v17
	v_lshlrev_b32_e32 v110, 16, v18
	v_and_b32_e32 v111, 0xffff0000, v18
	v_lshlrev_b32_e32 v112, 16, v19
	v_and_b32_e32 v113, 0xffff0000, v19
	v_pk_mul_f32 v[114:115], v[72:73], v[114:115]
	v_pk_mul_f32 v[116:117], v[74:75], v[116:117]
	v_pk_mul_f32 v[118:119], v[76:77], v[118:119]
	v_pk_mul_f32 v[120:121], v[78:79], v[120:121]
	v_pk_fma_f32 v[114:115], v[80:81], v[98:99], v[114:115]
	v_pk_fma_f32 v[116:117], v[82:83], v[100:101], v[116:117]
	v_pk_fma_f32 v[118:119], v[84:85], v[102:103], v[118:119]
	v_pk_fma_f32 v[120:121], v[86:87], v[104:105], v[120:121]
	v_pk_fma_f32 v[114:115], v[88:89], v[106:107], v[114:115]
	v_pk_fma_f32 v[116:117], v[90:91], v[108:109], v[116:117]
	v_pk_fma_f32 v[118:119], v[92:93], v[110:111], v[118:119]
	v_pk_fma_f32 v[120:121], v[94:95], v[112:113], v[120:121]
	s_mov_b64 exec, s[38:39]
	v_mul_f32_e32 v114, 0x4038aa3b, v114
	v_mul_f32_e32 v115, 0x4038aa3b, v115
	v_mul_f32_e32 v116, 0x4038aa3b, v116
	v_mul_f32_e32 v117, 0x4038aa3b, v117
	v_mul_f32_e32 v118, 0x4038aa3b, v118
	v_mul_f32_e32 v119, 0x4038aa3b, v119
	v_mul_f32_e32 v120, 0x4038aa3b, v120
	v_mul_f32_e32 v121, 0x4038aa3b, v121
	v_exp_f32_e32 v114, v114
	v_exp_f32_e32 v115, v115
	v_exp_f32_e32 v116, v116
	v_exp_f32_e32 v117, v117
	v_exp_f32_e32 v118, v118
	v_exp_f32_e32 v119, v119
	v_exp_f32_e32 v120, v120
	v_exp_f32_e32 v121, v121
	v_add_f32_e32 v114, 1.0, v114
	v_add_f32_e32 v115, 1.0, v115
	v_add_f32_e32 v116, 1.0, v116
	v_add_f32_e32 v117, 1.0, v117
	v_add_f32_e32 v118, 1.0, v118
	v_add_f32_e32 v119, 1.0, v119
	v_add_f32_e32 v120, 1.0, v120
	v_add_f32_e32 v121, 1.0, v121
	v_rcp_f32_e32 v114, v114
	v_rcp_f32_e32 v115, v115
	v_rcp_f32_e32 v116, v116
	v_rcp_f32_e32 v117, v117
	v_rcp_f32_e32 v118, v118
	v_rcp_f32_e32 v119, v119
	v_rcp_f32_e32 v120, v120
	v_rcp_f32_e32 v121, v121
	s_nop 0
	v_pk_fma_f32 v[114:115], v[114:115], -2.0, 1.0 op_sel_hi:[1,0,0]
	v_pk_fma_f32 v[116:117], v[116:117], -2.0, 1.0 op_sel_hi:[1,0,0]
	v_pk_fma_f32 v[118:119], v[118:119], -2.0, 1.0 op_sel_hi:[1,0,0]
	v_pk_fma_f32 v[120:121], v[120:121], -2.0, 1.0 op_sel_hi:[1,0,0]
	s_mov_b64 exec, s[30:31]
	v_mul_f32_e32 v114, 0xbfb8aa3b, v114
	v_mul_f32_e32 v115, 0xbfb8aa3b, v115
	v_mul_f32_e32 v116, 0xbfb8aa3b, v116
	v_mul_f32_e32 v117, 0xbfb8aa3b, v117
	v_mul_f32_e32 v118, 0xbfb8aa3b, v118
	v_mul_f32_e32 v119, 0xbfb8aa3b, v119
	v_mul_f32_e32 v120, 0xbfb8aa3b, v120
	v_mul_f32_e32 v121, 0xbfb8aa3b, v121
	v_exp_f32_e32 v114, v114
	v_exp_f32_e32 v115, v115
	v_exp_f32_e32 v116, v116
	v_exp_f32_e32 v117, v117
	v_exp_f32_e32 v118, v118
	v_exp_f32_e32 v119, v119
	v_exp_f32_e32 v120, v120
	v_exp_f32_e32 v121, v121
	v_add_f32_e32 v114, 1.0, v114
	v_add_f32_e32 v115, 1.0, v115
	v_add_f32_e32 v116, 1.0, v116
	v_add_f32_e32 v117, 1.0, v117
	v_add_f32_e32 v118, 1.0, v118
	v_add_f32_e32 v119, 1.0, v119
	v_add_f32_e32 v120, 1.0, v120
	v_add_f32_e32 v121, 1.0, v121
	v_rcp_f32_e32 v114, v114
	v_rcp_f32_e32 v115, v115
	v_rcp_f32_e32 v116, v116
	v_rcp_f32_e32 v117, v117
	v_rcp_f32_e32 v118, v118
	v_rcp_f32_e32 v119, v119
	v_rcp_f32_e32 v120, v120
	v_rcp_f32_e32 v121, v121
	s_mov_b64 exec, s[36:37]
	s_nop 0
	v_cvt_pk_bf16_f32 v8, v114, v115
	v_cvt_pk_bf16_f32 v9, v116, v117
	v_cvt_pk_bf16_f32 v10, v118, v119
	v_cvt_pk_bf16_f32 v11, v120, v121
	global_store_dwordx4 v[124:125], v[8:11], off
	v_lshl_add_u64 v[124:125], v[126:127], 0, v[124:125]
	s_waitcnt vmcnt(15)
; DEV float lo_bf(unsigned u) { return __uint_as_float(u << 16); }
; DEV float hi_bf(unsigned u) { return __uint_as_float(u & 0xffff0000u); }
; DEV float sigmoidf_(float x) { return __builtin_amdgcn_rcpf(1.f + __expf(-x)); }
; DEV void shift_tile(const Params& p, int l, int tile) {
;     ...
; #pragma unroll
;   for (int i = 0; i < 16; ++i) {
;     const int row = rb + i;
;     const u32x4 pv = rows[i], cu = rows[i + 1], nx = rows[i + 2];
;     float y[8];
; #pragma unroll
;     for (int q = 0; q < 4; ++q) {
;       y[2 * q] = w0[2 * q] * lo_bf(pv[q]) + w1[2 * q] * lo_bf(cu[q]) + w2[2 * q] * lo_bf(nx[q]);
;       y[2 * q + 1] = w0[2 * q + 1] * hi_bf(pv[q]) + w1[2 * q + 1] * hi_bf(cu[q]) + w2[2 * q + 1] * hi_bf(nx[q]);
;     }
;     if (act == 1) {
; #pragma unroll
;       for (int j = 0; j < 8; ++j) y[j] = 1.f - 2.f * __builtin_amdgcn_rcpf(1.f + __expf(2.f * y[j]));
;     } else if (act == 2) {
; #pragma unroll
;       for (int j = 0; j < 8; ++j) y[j] = sigmoidf_(y[j]);
;     }
;     u32x4 o;
;     o[0] = pk2(y[0], y[1]); o[1] = pk2(y[2], y[3]); o[2] = pk2(y[4], y[5]); o[3] = pk2(y[6], y[7]);
;     if (col < 1536) *(u32x4*)(ZRS + (size_t)row * 1536 + col) = o;
;     else if (col < 1792) *(u32x4*)((bf16_t*)(p.ws + O_LIN) + (size_t)row * 256 + (col - 1536)) = o;
;     else *(u32x4*)((bf16_t*)(p.ws + O_GIN) + (size_t)row * 128 + (col - 1792)) = o;
;   }
	v_lshlrev_b32_e32 v114, 16, v20
	v_and_b32_e32 v115, 0xffff0000, v20
	v_lshlrev_b32_e32 v116, 16, v21
	v_and_b32_e32 v117, 0xffff0000, v21
	v_lshlrev_b32_e32 v118, 16, v22
	v_and_b32_e32 v119, 0xffff0000, v22
	v_lshlrev_b32_e32 v120, 16, v23
	v_and_b32_e32 v121, 0xffff0000, v23
	v_pk_mul_f32 v[98:99], v[72:73], v[98:99]
	v_pk_mul_f32 v[100:101], v[74:75], v[100:101]
	v_pk_mul_f32 v[102:103], v[76:77], v[102:103]
	v_pk_mul_f32 v[104:105], v[78:79], v[104:105]
	v_pk_fma_f32 v[98:99], v[80:81], v[106:107], v[98:99]
	v_pk_fma_f32 v[100:101], v[82:83], v[108:109], v[100:101]
	v_pk_fma_f32 v[102:103], v[84:85], v[110:111], v[102:103]
	v_pk_fma_f32 v[104:105], v[86:87], v[112:113], v[104:105]
	v_pk_fma_f32 v[98:99], v[88:89], v[114:115], v[98:99]
	v_pk_fma_f32 v[100:101], v[90:91], v[116:117], v[100:101]
	v_pk_fma_f32 v[102:103], v[92:93], v[118:119], v[102:103]
	v_pk_fma_f32 v[104:105], v[94:95], v[120:121], v[104:105]
	s_mov_b64 exec, s[38:39]
	v_mul_f32_e32 v98, 0x4038aa3b, v98
	v_mul_f32_e32 v99, 0x4038aa3b, v99
	v_mul_f32_e32 v100, 0x4038aa3b, v100
	v_mul_f32_e32 v101, 0x4038aa3b, v101
	v_mul_f32_e32 v102, 0x4038aa3b, v102
	v_mul_f32_e32 v103, 0x4038aa3b, v103
	v_mul_f32_e32 v104, 0x4038aa3b, v104
	v_mul_f32_e32 v105, 0x4038aa3b, v105
	v_exp_f32_e32 v98, v98
	v_exp_f32_e32 v99, v99
	v_exp_f32_e32 v100, v100
	v_exp_f32_e32 v101, v101
	v_exp_f32_e32 v102, v102
	v_exp_f32_e32 v103, v103
	v_exp_f32_e32 v104, v104
	v_exp_f32_e32 v105, v105
	v_add_f32_e32 v98, 1.0, v98
	v_add_f32_e32 v99, 1.0, v99
	v_add_f32_e32 v100, 1.0, v100
	v_add_f32_e32 v101, 1.0, v101
	v_add_f32_e32 v102, 1.0, v102
	v_add_f32_e32 v103, 1.0, v103
	v_add_f32_e32 v104, 1.0, v104
	v_add_f32_e32 v105, 1.0, v105
	v_rcp_f32_e32 v98, v98
	v_rcp_f32_e32 v99, v99
	v_rcp_f32_e32 v100, v100
	v_rcp_f32_e32 v101, v101
	v_rcp_f32_e32 v102, v102
	v_rcp_f32_e32 v103, v103
	v_rcp_f32_e32 v104, v104
	v_rcp_f32_e32 v105, v105
	s_nop 0
	v_pk_fma_f32 v[98:99], v[98:99], -2.0, 1.0 op_sel_hi:[1,0,0]
	v_pk_fma_f32 v[100:101], v[100:101], -2.0, 1.0 op_sel_hi:[1,0,0]
	v_pk_fma_f32 v[102:103], v[102:103], -2.0, 1.0 op_sel_hi:[1,0,0]
	v_pk_fma_f32 v[104:105], v[104:105], -2.0, 1.0 op_sel_hi:[1,0,0]
	s_mov_b64 exec, s[30:31]
	v_mul_f32_e32 v98, 0xbfb8aa3b, v98
	v_mul_f32_e32 v99, 0xbfb8aa3b, v99
	v_mul_f32_e32 v100, 0xbfb8aa3b, v100
	v_mul_f32_e32 v101, 0xbfb8aa3b, v101
	v_mul_f32_e32 v102, 0xbfb8aa3b, v102
	v_mul_f32_e32 v103, 0xbfb8aa3b, v103
	v_mul_f32_e32 v104, 0xbfb8aa3b, v104
	v_mul_f32_e32 v105, 0xbfb8aa3b, v105
	v_exp_f32_e32 v98, v98
	v_exp_f32_e32 v99, v99
	v_exp_f32_e32 v100, v100
	v_exp_f32_e32 v101, v101
	v_exp_f32_e32 v102, v102
	v_exp_f32_e32 v103, v103
	v_exp_f32_e32 v104, v104
	v_exp_f32_e32 v105, v105
	v_add_f32_e32 v98, 1.0, v98
	v_add_f32_e32 v99, 1.0, v99
	v_add_f32_e32 v100, 1.0, v100
	v_add_f32_e32 v101, 1.0, v101
	v_add_f32_e32 v102, 1.0, v102
	v_add_f32_e32 v103, 1.0, v103
	v_add_f32_e32 v104, 1.0, v104
	v_add_f32_e32 v105, 1.0, v105
	v_rcp_f32_e32 v98, v98
	v_rcp_f32_e32 v99, v99
	v_rcp_f32_e32 v100, v100
	v_rcp_f32_e32 v101, v101
	v_rcp_f32_e32 v102, v102
	v_rcp_f32_e32 v103, v103
	v_rcp_f32_e32 v104, v104
	v_rcp_f32_e32 v105, v105
	s_mov_b64 exec, s[36:37]
	s_nop 0
	v_cvt_pk_bf16_f32 v12, v98, v99
	v_cvt_pk_bf16_f32 v13, v100, v101
	v_cvt_pk_bf16_f32 v14, v102, v103
	v_cvt_pk_bf16_f32 v15, v104, v105
	global_store_dwordx4 v[124:125], v[12:15], off
	v_lshl_add_u64 v[124:125], v[126:127], 0, v[124:125]
	s_waitcnt vmcnt(15)
	v_lshlrev_b32_e32 v98, 16, v24
	v_and_b32_e32 v99, 0xffff0000, v24
	v_lshlrev_b32_e32 v100, 16, v25
	v_and_b32_e32 v101, 0xffff0000, v25
	v_lshlrev_b32_e32 v102, 16, v26
	v_and_b32_e32 v103, 0xffff0000, v26
	v_lshlrev_b32_e32 v104, 16, v27
	v_and_b32_e32 v105, 0xffff0000, v27
	v_pk_mul_f32 v[106:107], v[72:73], v[106:107]
	v_pk_mul_f32 v[108:109], v[74:75], v[108:109]
	v_pk_mul_f32 v[110:111], v[76:77], v[110:111]
	v_pk_mul_f32 v[112:113], v[78:79], v[112:113]
	v_pk_fma_f32 v[106:107], v[80:81], v[114:115], v[106:107]
	v_pk_fma_f32 v[108:109], v[82:83], v[116:117], v[108:109]
	v_pk_fma_f32 v[110:111], v[84:85], v[118:119], v[110:111]
	v_pk_fma_f32 v[112:113], v[86:87], v[120:121], v[112:113]
	v_pk_fma_f32 v[106:107], v[88:89], v[98:99], v[106:107]
	v_pk_fma_f32 v[108:109], v[90:91], v[100:101], v[108:109]
	v_pk_fma_f32 v[110:111], v[92:93], v[102:103], v[110:111]
	v_pk_fma_f32 v[112:113], v[94:95], v[104:105], v[112:113]
	s_mov_b64 exec, s[38:39]
	v_mul_f32_e32 v106, 0x4038aa3b, v106
	v_mul_f32_e32 v107, 0x4038aa3b, v107
	v_mul_f32_e32 v108, 0x4038aa3b, v108
	v_mul_f32_e32 v109, 0x4038aa3b, v109
	v_mul_f32_e32 v110, 0x4038aa3b, v110
	v_mul_f32_e32 v111, 0x4038aa3b, v111
	v_mul_f32_e32 v112, 0x4038aa3b, v112
	v_mul_f32_e32 v113, 0x4038aa3b, v113
	v_exp_f32_e32 v106, v106
	v_exp_f32_e32 v107, v107
	v_exp_f32_e32 v108, v108
	v_exp_f32_e32 v109, v109
	v_exp_f32_e32 v110, v110
	v_exp_f32_e32 v111, v111
	v_exp_f32_e32 v112, v112
	v_exp_f32_e32 v113, v113
	v_add_f32_e32 v106, 1.0, v106
	v_add_f32_e32 v107, 1.0, v107
	v_add_f32_e32 v108, 1.0, v108
	v_add_f32_e32 v109, 1.0, v109
	v_add_f32_e32 v110, 1.0, v110
	v_add_f32_e32 v111, 1.0, v111
	v_add_f32_e32 v112, 1.0, v112
	v_add_f32_e32 v113, 1.0, v113
	v_rcp_f32_e32 v106, v106
	v_rcp_f32_e32 v107, v107
	v_rcp_f32_e32 v108, v108
	v_rcp_f32_e32 v109, v109
	v_rcp_f32_e32 v110, v110
	v_rcp_f32_e32 v111, v111
	v_rcp_f32_e32 v112, v112
	v_rcp_f32_e32 v113, v113
	s_nop 0
	v_pk_fma_f32 v[106:107], v[106:107], -2.0, 1.0 op_sel_hi:[1,0,0]
	v_pk_fma_f32 v[108:109], v[108:109], -2.0, 1.0 op_sel_hi:[1,0,0]
	v_pk_fma_f32 v[110:111], v[110:111], -2.0, 1.0 op_sel_hi:[1,0,0]
	v_pk_fma_f32 v[112:113], v[112:113], -2.0, 1.0 op_sel_hi:[1,0,0]
	s_mov_b64 exec, s[30:31]
	v_mul_f32_e32 v106, 0xbfb8aa3b, v106
	v_mul_f32_e32 v107, 0xbfb8aa3b, v107
	v_mul_f32_e32 v108, 0xbfb8aa3b, v108
	v_mul_f32_e32 v109, 0xbfb8aa3b, v109
	v_mul_f32_e32 v110, 0xbfb8aa3b, v110
	v_mul_f32_e32 v111, 0xbfb8aa3b, v111
	v_mul_f32_e32 v112, 0xbfb8aa3b, v112
	v_mul_f32_e32 v113, 0xbfb8aa3b, v113
	v_exp_f32_e32 v106, v106
	v_exp_f32_e32 v107, v107
	v_exp_f32_e32 v108, v108
	v_exp_f32_e32 v109, v109
	v_exp_f32_e32 v110, v110
	v_exp_f32_e32 v111, v111
	v_exp_f32_e32 v112, v112
	v_exp_f32_e32 v113, v113
	v_add_f32_e32 v106, 1.0, v106
	v_add_f32_e32 v107, 1.0, v107
	v_add_f32_e32 v108, 1.0, v108
	v_add_f32_e32 v109, 1.0, v109
	v_add_f32_e32 v110, 1.0, v110
	v_add_f32_e32 v111, 1.0, v111
	v_add_f32_e32 v112, 1.0, v112
	v_add_f32_e32 v113, 1.0, v113
	v_rcp_f32_e32 v106, v106
	v_rcp_f32_e32 v107, v107
	v_rcp_f32_e32 v108, v108
	v_rcp_f32_e32 v109, v109
	v_rcp_f32_e32 v110, v110
	v_rcp_f32_e32 v111, v111
	v_rcp_f32_e32 v112, v112
	v_rcp_f32_e32 v113, v113
	s_mov_b64 exec, s[36:37]
	s_nop 0
	v_cvt_pk_bf16_f32 v16, v106, v107
	v_cvt_pk_bf16_f32 v17, v108, v109
	v_cvt_pk_bf16_f32 v18, v110, v111
	v_cvt_pk_bf16_f32 v19, v112, v113
	global_store_dwordx4 v[124:125], v[16:19], off
	v_lshl_add_u64 v[124:125], v[126:127], 0, v[124:125]
	s_waitcnt vmcnt(15)
; DEV float lo_bf(unsigned u) { return __uint_as_float(u << 16); }
; DEV float hi_bf(unsigned u) { return __uint_as_float(u & 0xffff0000u); }
; DEV float sigmoidf_(float x) { return __builtin_amdgcn_rcpf(1.f + __expf(-x)); }
; DEV void shift_tile(const Params& p, int l, int tile) {
;     ...
; #pragma unroll
;   for (int i = 0; i < 16; ++i) {
;     const int row = rb + i;
;     const u32x4 pv = rows[i], cu = rows[i + 1], nx = rows[i + 2];
;     float y[8];
; #pragma unroll
;     for (int q = 0; q < 4; ++q) {
;       y[2 * q] = w0[2 * q] * lo_bf(pv[q]) + w1[2 * q] * lo_bf(cu[q]) + w2[2 * q] * lo_bf(nx[q]);
;       y[2 * q + 1] = w0[2 * q + 1] * hi_bf(pv[q]) + w1[2 * q + 1] * hi_bf(cu[q]) + w2[2 * q + 1] * hi_bf(nx[q]);
;     }
;     if (act == 1) {
; #pragma unroll
;       for (int j = 0; j < 8; ++j) y[j] = 1.f - 2.f * __builtin_amdgcn_rcpf(1.f + __expf(2.f * y[j]));
;     } else if (act == 2) {
; #pragma unroll
;       for (int j = 0; j < 8; ++j) y[j] = sigmoidf_(y[j]);
;     }
;     u32x4 o;
;     o[0] = pk2(y[0], y[1]); o[1] = pk2(y[2], y[3]); o[2] = pk2(y[4], y[5]); o[3] = pk2(y[6], y[7]);
;     if (col < 1536) *(u32x4*)(ZRS + (size_t)row * 1536 + col) = o;
;     else if (col < 1792) *(u32x4*)((bf16_t*)(p.ws + O_LIN) + (size_t)row * 256 + (col - 1536)) = o;
;     else *(u32x4*)((bf16_t*)(p.ws + O_GIN) + (size_t)row * 128 + (col - 1792)) = o;
;   }
	v_lshlrev_b32_e32 v106, 16, v28
	v_and_b32_e32 v107, 0xffff0000, v28
	v_lshlrev_b32_e32 v108, 16, v29
	v_and_b32_e32 v109, 0xffff0000, v29
	v_lshlrev_b32_e32 v110, 16, v30
	v_and_b32_e32 v111, 0xffff0000, v30
	v_lshlrev_b32_e32 v112, 16, v31
	v_and_b32_e32 v113, 0xffff0000, v31
	v_pk_mul_f32 v[114:115], v[72:73], v[114:115]
	v_pk_mul_f32 v[116:117], v[74:75], v[116:117]
	v_pk_mul_f32 v[118:119], v[76:77], v[118:119]
	v_pk_mul_f32 v[120:121], v[78:79], v[120:121]
	v_pk_fma_f32 v[114:115], v[80:81], v[98:99], v[114:115]
	v_pk_fma_f32 v[116:117], v[82:83], v[100:101], v[116:117]
	v_pk_fma_f32 v[118:119], v[84:85], v[102:103], v[118:119]
	v_pk_fma_f32 v[120:121], v[86:87], v[104:105], v[120:121]
	v_pk_fma_f32 v[114:115], v[88:89], v[106:107], v[114:115]
	v_pk_fma_f32 v[116:117], v[90:91], v[108:109], v[116:117]
	v_pk_fma_f32 v[118:119], v[92:93], v[110:111], v[118:119]
	v_pk_fma_f32 v[120:121], v[94:95], v[112:113], v[120:121]
	s_mov_b64 exec, s[38:39]
	v_mul_f32_e32 v114, 0x4038aa3b, v114
	v_mul_f32_e32 v115, 0x4038aa3b, v115
	v_mul_f32_e32 v116, 0x4038aa3b, v116
	v_mul_f32_e32 v117, 0x4038aa3b, v117
	v_mul_f32_e32 v118, 0x4038aa3b, v118
	v_mul_f32_e32 v119, 0x4038aa3b, v119
	v_mul_f32_e32 v120, 0x4038aa3b, v120
	v_mul_f32_e32 v121, 0x4038aa3b, v121
	v_exp_f32_e32 v114, v114
	v_exp_f32_e32 v115, v115
	v_exp_f32_e32 v116, v116
	v_exp_f32_e32 v117, v117
	v_exp_f32_e32 v118, v118
	v_exp_f32_e32 v119, v119
	v_exp_f32_e32 v120, v120
	v_exp_f32_e32 v121, v121
	v_add_f32_e32 v114, 1.0, v114
	v_add_f32_e32 v115, 1.0, v115
	v_add_f32_e32 v116, 1.0, v116
	v_add_f32_e32 v117, 1.0, v117
	v_add_f32_e32 v118, 1.0, v118
	v_add_f32_e32 v119, 1.0, v119
	v_add_f32_e32 v120, 1.0, v120
	v_add_f32_e32 v121, 1.0, v121
	v_rcp_f32_e32 v114, v114
	v_rcp_f32_e32 v115, v115
	v_rcp_f32_e32 v116, v116
	v_rcp_f32_e32 v117, v117
	v_rcp_f32_e32 v118, v118
	v_rcp_f32_e32 v119, v119
	v_rcp_f32_e32 v120, v120
	v_rcp_f32_e32 v121, v121
	s_nop 0
	v_pk_fma_f32 v[114:115], v[114:115], -2.0, 1.0 op_sel_hi:[1,0,0]
	v_pk_fma_f32 v[116:117], v[116:117], -2.0, 1.0 op_sel_hi:[1,0,0]
	v_pk_fma_f32 v[118:119], v[118:119], -2.0, 1.0 op_sel_hi:[1,0,0]
	v_pk_fma_f32 v[120:121], v[120:121], -2.0, 1.0 op_sel_hi:[1,0,0]
	s_mov_b64 exec, s[30:31]
	v_mul_f32_e32 v114, 0xbfb8aa3b, v114
	v_mul_f32_e32 v115, 0xbfb8aa3b, v115
	v_mul_f32_e32 v116, 0xbfb8aa3b, v116
	v_mul_f32_e32 v117, 0xbfb8aa3b, v117
	v_mul_f32_e32 v118, 0xbfb8aa3b, v118
	v_mul_f32_e32 v119, 0xbfb8aa3b, v119
	v_mul_f32_e32 v120, 0xbfb8aa3b, v120
	v_mul_f32_e32 v121, 0xbfb8aa3b, v121
	v_exp_f32_e32 v114, v114
	v_exp_f32_e32 v115, v115
	v_exp_f32_e32 v116, v116
	v_exp_f32_e32 v117, v117
	v_exp_f32_e32 v118, v118
	v_exp_f32_e32 v119, v119
	v_exp_f32_e32 v120, v120
	v_exp_f32_e32 v121, v121
	v_add_f32_e32 v114, 1.0, v114
	v_add_f32_e32 v115, 1.0, v115
	v_add_f32_e32 v116, 1.0, v116
	v_add_f32_e32 v117, 1.0, v117
	v_add_f32_e32 v118, 1.0, v118
	v_add_f32_e32 v119, 1.0, v119
	v_add_f32_e32 v120, 1.0, v120
	v_add_f32_e32 v121, 1.0, v121
	v_rcp_f32_e32 v114, v114
	v_rcp_f32_e32 v115, v115
	v_rcp_f32_e32 v116, v116
	v_rcp_f32_e32 v117, v117
	v_rcp_f32_e32 v118, v118
	v_rcp_f32_e32 v119, v119
	v_rcp_f32_e32 v120, v120
	v_rcp_f32_e32 v121, v121
	s_mov_b64 exec, s[36:37]
	s_nop 0
	v_cvt_pk_bf16_f32 v20, v114, v115
	v_cvt_pk_bf16_f32 v21, v116, v117
	v_cvt_pk_bf16_f32 v22, v118, v119
	v_cvt_pk_bf16_f32 v23, v120, v121
	global_store_dwordx4 v[124:125], v[20:23], off
	v_lshl_add_u64 v[124:125], v[126:127], 0, v[124:125]
	s_waitcnt vmcnt(15)
	v_lshlrev_b32_e32 v114, 16, v32
	v_and_b32_e32 v115, 0xffff0000, v32
	v_lshlrev_b32_e32 v116, 16, v33
	v_and_b32_e32 v117, 0xffff0000, v33
	v_lshlrev_b32_e32 v118, 16, v34
	v_and_b32_e32 v119, 0xffff0000, v34
	v_lshlrev_b32_e32 v120, 16, v35
	v_and_b32_e32 v121, 0xffff0000, v35
	v_pk_mul_f32 v[98:99], v[72:73], v[98:99]
	v_pk_mul_f32 v[100:101], v[74:75], v[100:101]
	v_pk_mul_f32 v[102:103], v[76:77], v[102:103]
	v_pk_mul_f32 v[104:105], v[78:79], v[104:105]
	v_pk_fma_f32 v[98:99], v[80:81], v[106:107], v[98:99]
	v_pk_fma_f32 v[100:101], v[82:83], v[108:109], v[100:101]
	v_pk_fma_f32 v[102:103], v[84:85], v[110:111], v[102:103]
	v_pk_fma_f32 v[104:105], v[86:87], v[112:113], v[104:105]
	v_pk_fma_f32 v[98:99], v[88:89], v[114:115], v[98:99]
	v_pk_fma_f32 v[100:101], v[90:91], v[116:117], v[100:101]
	v_pk_fma_f32 v[102:103], v[92:93], v[118:119], v[102:103]
	v_pk_fma_f32 v[104:105], v[94:95], v[120:121], v[104:105]
	s_mov_b64 exec, s[38:39]
	v_mul_f32_e32 v98, 0x4038aa3b, v98
	v_mul_f32_e32 v99, 0x4038aa3b, v99
	v_mul_f32_e32 v100, 0x4038aa3b, v100
	v_mul_f32_e32 v101, 0x4038aa3b, v101
	v_mul_f32_e32 v102, 0x4038aa3b, v102
	v_mul_f32_e32 v103, 0x4038aa3b, v103
	v_mul_f32_e32 v104, 0x4038aa3b, v104
	v_mul_f32_e32 v105, 0x4038aa3b, v105
	v_exp_f32_e32 v98, v98
	v_exp_f32_e32 v99, v99
	v_exp_f32_e32 v100, v100
	v_exp_f32_e32 v101, v101
	v_exp_f32_e32 v102, v102
	v_exp_f32_e32 v103, v103
	v_exp_f32_e32 v104, v104
	v_exp_f32_e32 v105, v105
	v_add_f32_e32 v98, 1.0, v98
	v_add_f32_e32 v99, 1.0, v99
	v_add_f32_e32 v100, 1.0, v100
	v_add_f32_e32 v101, 1.0, v101
	v_add_f32_e32 v102, 1.0, v102
	v_add_f32_e32 v103, 1.0, v103
	v_add_f32_e32 v104, 1.0, v104
	v_add_f32_e32 v105, 1.0, v105
	v_rcp_f32_e32 v98, v98
	v_rcp_f32_e32 v99, v99
	v_rcp_f32_e32 v100, v100
	v_rcp_f32_e32 v101, v101
	v_rcp_f32_e32 v102, v102
	v_rcp_f32_e32 v103, v103
	v_rcp_f32_e32 v104, v104
	v_rcp_f32_e32 v105, v105
	s_nop 0
	v_pk_fma_f32 v[98:99], v[98:99], -2.0, 1.0 op_sel_hi:[1,0,0]
	v_pk_fma_f32 v[100:101], v[100:101], -2.0, 1.0 op_sel_hi:[1,0,0]
	v_pk_fma_f32 v[102:103], v[102:103], -2.0, 1.0 op_sel_hi:[1,0,0]
	v_pk_fma_f32 v[104:105], v[104:105], -2.0, 1.0 op_sel_hi:[1,0,0]
	s_mov_b64 exec, s[30:31]
	v_mul_f32_e32 v98, 0xbfb8aa3b, v98
	v_mul_f32_e32 v99, 0xbfb8aa3b, v99
	v_mul_f32_e32 v100, 0xbfb8aa3b, v100
	v_mul_f32_e32 v101, 0xbfb8aa3b, v101
	v_mul_f32_e32 v102, 0xbfb8aa3b, v102
	v_mul_f32_e32 v103, 0xbfb8aa3b, v103
	v_mul_f32_e32 v104, 0xbfb8aa3b, v104
	v_mul_f32_e32 v105, 0xbfb8aa3b, v105
	v_exp_f32_e32 v98, v98
	v_exp_f32_e32 v99, v99
	v_exp_f32_e32 v100, v100
	v_exp_f32_e32 v101, v101
	v_exp_f32_e32 v102, v102
	v_exp_f32_e32 v103, v103
	v_exp_f32_e32 v104, v104
	v_exp_f32_e32 v105, v105
	v_add_f32_e32 v98, 1.0, v98
	v_add_f32_e32 v99, 1.0, v99
	v_add_f32_e32 v100, 1.0, v100
	v_add_f32_e32 v101, 1.0, v101
	v_add_f32_e32 v102, 1.0, v102
	v_add_f32_e32 v103, 1.0, v103
	v_add_f32_e32 v104, 1.0, v104
	v_add_f32_e32 v105, 1.0, v105
	v_rcp_f32_e32 v98, v98
	v_rcp_f32_e32 v99, v99
	v_rcp_f32_e32 v100, v100
	v_rcp_f32_e32 v101, v101
	v_rcp_f32_e32 v102, v102
	v_rcp_f32_e32 v103, v103
	v_rcp_f32_e32 v104, v104
	v_rcp_f32_e32 v105, v105
	s_mov_b64 exec, s[36:37]
	s_nop 0
	v_cvt_pk_bf16_f32 v24, v98, v99
	v_cvt_pk_bf16_f32 v25, v100, v101
	v_cvt_pk_bf16_f32 v26, v102, v103
	v_cvt_pk_bf16_f32 v27, v104, v105
	global_store_dwordx4 v[124:125], v[24:27], off
	v_lshl_add_u64 v[124:125], v[126:127], 0, v[124:125]
	s_waitcnt vmcnt(15)
; DEV float lo_bf(unsigned u) { return __uint_as_float(u << 16); }
; DEV float hi_bf(unsigned u) { return __uint_as_float(u & 0xffff0000u); }
; DEV float sigmoidf_(float x) { return __builtin_amdgcn_rcpf(1.f + __expf(-x)); }
; DEV void shift_tile(const Params& p, int l, int tile) {
;     ...
; #pragma unroll
;   for (int i = 0; i < 16; ++i) {
;     const int row = rb + i;
;     const u32x4 pv = rows[i], cu = rows[i + 1], nx = rows[i + 2];
;     float y[8];
; #pragma unroll
;     for (int q = 0; q < 4; ++q) {
;       y[2 * q] = w0[2 * q] * lo_bf(pv[q]) + w1[2 * q] * lo_bf(cu[q]) + w2[2 * q] * lo_bf(nx[q]);
;       y[2 * q + 1] = w0[2 * q + 1] * hi_bf(pv[q]) + w1[2 * q + 1] * hi_bf(cu[q]) + w2[2 * q + 1] * hi_bf(nx[q]);
;     }
;     if (act == 1) {
; #pragma unroll
;       for (int j = 0; j < 8; ++j) y[j] = 1.f - 2.f * __builtin_amdgcn_rcpf(1.f + __expf(2.f * y[j]));
;     } else if (act == 2) {
; #pragma unroll
;       for (int j = 0; j < 8; ++j) y[j] = sigmoidf_(y[j]);
;     }
;     u32x4 o;
;     o[0] = pk2(y[0], y[1]); o[1] = pk2(y[2], y[3]); o[2] = pk2(y[4], y[5]); o[3] = pk2(y[6], y[7]);
;     if (col < 1536) *(u32x4*)(ZRS + (size_t)row * 1536 + col) = o;
;     else if (col < 1792) *(u32x4*)((bf16_t*)(p.ws + O_LIN) + (size_t)row * 256 + (col - 1536)) = o;
;     else *(u32x4*)((bf16_t*)(p.ws + O_GIN) + (size_t)row * 128 + (col - 1792)) = o;
;   }
	v_lshlrev_b32_e32 v98, 16, v36
	v_and_b32_e32 v99, 0xffff0000, v36
	v_lshlrev_b32_e32 v100, 16, v37
	v_and_b32_e32 v101, 0xffff0000, v37
	v_lshlrev_b32_e32 v102, 16, v38
	v_and_b32_e32 v103, 0xffff0000, v38
	v_lshlrev_b32_e32 v104, 16, v39
	v_and_b32_e32 v105, 0xffff0000, v39
	v_pk_mul_f32 v[106:107], v[72:73], v[106:107]
	v_pk_mul_f32 v[108:109], v[74:75], v[108:109]
	v_pk_mul_f32 v[110:111], v[76:77], v[110:111]
	v_pk_mul_f32 v[112:113], v[78:79], v[112:113]
	v_pk_fma_f32 v[106:107], v[80:81], v[114:115], v[106:107]
	v_pk_fma_f32 v[108:109], v[82:83], v[116:117], v[108:109]
	v_pk_fma_f32 v[110:111], v[84:85], v[118:119], v[110:111]
	v_pk_fma_f32 v[112:113], v[86:87], v[120:121], v[112:113]
	v_pk_fma_f32 v[106:107], v[88:89], v[98:99], v[106:107]
	v_pk_fma_f32 v[108:109], v[90:91], v[100:101], v[108:109]
	v_pk_fma_f32 v[110:111], v[92:93], v[102:103], v[110:111]
	v_pk_fma_f32 v[112:113], v[94:95], v[104:105], v[112:113]
	s_mov_b64 exec, s[38:39]
	v_mul_f32_e32 v106, 0x4038aa3b, v106
	v_mul_f32_e32 v107, 0x4038aa3b, v107
	v_mul_f32_e32 v108, 0x4038aa3b, v108
	v_mul_f32_e32 v109, 0x4038aa3b, v109
	v_mul_f32_e32 v110, 0x4038aa3b, v110
	v_mul_f32_e32 v111, 0x4038aa3b, v111
	v_mul_f32_e32 v112, 0x4038aa3b, v112
	v_mul_f32_e32 v113, 0x4038aa3b, v113
	v_exp_f32_e32 v106, v106
	v_exp_f32_e32 v107, v107
	v_exp_f32_e32 v108, v108
	v_exp_f32_e32 v109, v109
	v_exp_f32_e32 v110, v110
	v_exp_f32_e32 v111, v111
	v_exp_f32_e32 v112, v112
	v_exp_f32_e32 v113, v113
	v_add_f32_e32 v106, 1.0, v106
	v_add_f32_e32 v107, 1.0, v107
	v_add_f32_e32 v108, 1.0, v108
	v_add_f32_e32 v109, 1.0, v109
	v_add_f32_e32 v110, 1.0, v110
	v_add_f32_e32 v111, 1.0, v111
	v_add_f32_e32 v112, 1.0, v112
	v_add_f32_e32 v113, 1.0, v113
	v_rcp_f32_e32 v106, v106
	v_rcp_f32_e32 v107, v107
	v_rcp_f32_e32 v108, v108
	v_rcp_f32_e32 v109, v109
	v_rcp_f32_e32 v110, v110
	v_rcp_f32_e32 v111, v111
	v_rcp_f32_e32 v112, v112
	v_rcp_f32_e32 v113, v113
	s_nop 0
	v_pk_fma_f32 v[106:107], v[106:107], -2.0, 1.0 op_sel_hi:[1,0,0]
	v_pk_fma_f32 v[108:109], v[108:109], -2.0, 1.0 op_sel_hi:[1,0,0]
	v_pk_fma_f32 v[110:111], v[110:111], -2.0, 1.0 op_sel_hi:[1,0,0]
	v_pk_fma_f32 v[112:113], v[112:113], -2.0, 1.0 op_sel_hi:[1,0,0]
	s_mov_b64 exec, s[30:31]
	v_mul_f32_e32 v106, 0xbfb8aa3b, v106
	v_mul_f32_e32 v107, 0xbfb8aa3b, v107
	v_mul_f32_e32 v108, 0xbfb8aa3b, v108
	v_mul_f32_e32 v109, 0xbfb8aa3b, v109
	v_mul_f32_e32 v110, 0xbfb8aa3b, v110
	v_mul_f32_e32 v111, 0xbfb8aa3b, v111
	v_mul_f32_e32 v112, 0xbfb8aa3b, v112
	v_mul_f32_e32 v113, 0xbfb8aa3b, v113
	v_exp_f32_e32 v106, v106
	v_exp_f32_e32 v107, v107
	v_exp_f32_e32 v108, v108
	v_exp_f32_e32 v109, v109
	v_exp_f32_e32 v110, v110
	v_exp_f32_e32 v111, v111
	v_exp_f32_e32 v112, v112
	v_exp_f32_e32 v113, v113
	v_add_f32_e32 v106, 1.0, v106
	v_add_f32_e32 v107, 1.0, v107
	v_add_f32_e32 v108, 1.0, v108
	v_add_f32_e32 v109, 1.0, v109
	v_add_f32_e32 v110, 1.0, v110
	v_add_f32_e32 v111, 1.0, v111
	v_add_f32_e32 v112, 1.0, v112
	v_add_f32_e32 v113, 1.0, v113
	v_rcp_f32_e32 v106, v106
	v_rcp_f32_e32 v107, v107
	v_rcp_f32_e32 v108, v108
	v_rcp_f32_e32 v109, v109
	v_rcp_f32_e32 v110, v110
	v_rcp_f32_e32 v111, v111
	v_rcp_f32_e32 v112, v112
	v_rcp_f32_e32 v113, v113
	s_mov_b64 exec, s[36:37]
	s_nop 0
	v_cvt_pk_bf16_f32 v28, v106, v107
	v_cvt_pk_bf16_f32 v29, v108, v109
	v_cvt_pk_bf16_f32 v30, v110, v111
	v_cvt_pk_bf16_f32 v31, v112, v113
	global_store_dwordx4 v[124:125], v[28:31], off
	v_lshl_add_u64 v[124:125], v[126:127], 0, v[124:125]
	s_waitcnt vmcnt(15)
	v_lshlrev_b32_e32 v106, 16, v40
	v_and_b32_e32 v107, 0xffff0000, v40
	v_lshlrev_b32_e32 v108, 16, v41
	v_and_b32_e32 v109, 0xffff0000, v41
	v_lshlrev_b32_e32 v110, 16, v42
	v_and_b32_e32 v111, 0xffff0000, v42
	v_lshlrev_b32_e32 v112, 16, v43
	v_and_b32_e32 v113, 0xffff0000, v43
	v_pk_mul_f32 v[114:115], v[72:73], v[114:115]
	v_pk_mul_f32 v[116:117], v[74:75], v[116:117]
	v_pk_mul_f32 v[118:119], v[76:77], v[118:119]
	v_pk_mul_f32 v[120:121], v[78:79], v[120:121]
	v_pk_fma_f32 v[114:115], v[80:81], v[98:99], v[114:115]
	v_pk_fma_f32 v[116:117], v[82:83], v[100:101], v[116:117]
	v_pk_fma_f32 v[118:119], v[84:85], v[102:103], v[118:119]
	v_pk_fma_f32 v[120:121], v[86:87], v[104:105], v[120:121]
	v_pk_fma_f32 v[114:115], v[88:89], v[106:107], v[114:115]
	v_pk_fma_f32 v[116:117], v[90:91], v[108:109], v[116:117]
	v_pk_fma_f32 v[118:119], v[92:93], v[110:111], v[118:119]
	v_pk_fma_f32 v[120:121], v[94:95], v[112:113], v[120:121]
	s_mov_b64 exec, s[38:39]
	v_mul_f32_e32 v114, 0x4038aa3b, v114
	v_mul_f32_e32 v115, 0x4038aa3b, v115
	v_mul_f32_e32 v116, 0x4038aa3b, v116
	v_mul_f32_e32 v117, 0x4038aa3b, v117
	v_mul_f32_e32 v118, 0x4038aa3b, v118
	v_mul_f32_e32 v119, 0x4038aa3b, v119
	v_mul_f32_e32 v120, 0x4038aa3b, v120
	v_mul_f32_e32 v121, 0x4038aa3b, v121
	v_exp_f32_e32 v114, v114
	v_exp_f32_e32 v115, v115
	v_exp_f32_e32 v116, v116
	v_exp_f32_e32 v117, v117
	v_exp_f32_e32 v118, v118
	v_exp_f32_e32 v119, v119
	v_exp_f32_e32 v120, v120
	v_exp_f32_e32 v121, v121
	v_add_f32_e32 v114, 1.0, v114
	v_add_f32_e32 v115, 1.0, v115
	v_add_f32_e32 v116, 1.0, v116
	v_add_f32_e32 v117, 1.0, v117
	v_add_f32_e32 v118, 1.0, v118
	v_add_f32_e32 v119, 1.0, v119
	v_add_f32_e32 v120, 1.0, v120
	v_add_f32_e32 v121, 1.0, v121
	v_rcp_f32_e32 v114, v114
	v_rcp_f32_e32 v115, v115
	v_rcp_f32_e32 v116, v116
	v_rcp_f32_e32 v117, v117
	v_rcp_f32_e32 v118, v118
	v_rcp_f32_e32 v119, v119
	v_rcp_f32_e32 v120, v120
	v_rcp_f32_e32 v121, v121
	s_nop 0
	v_pk_fma_f32 v[114:115], v[114:115], -2.0, 1.0 op_sel_hi:[1,0,0]
	v_pk_fma_f32 v[116:117], v[116:117], -2.0, 1.0 op_sel_hi:[1,0,0]
	v_pk_fma_f32 v[118:119], v[118:119], -2.0, 1.0 op_sel_hi:[1,0,0]
	v_pk_fma_f32 v[120:121], v[120:121], -2.0, 1.0 op_sel_hi:[1,0,0]
	s_mov_b64 exec, s[30:31]
	v_mul_f32_e32 v114, 0xbfb8aa3b, v114
	v_mul_f32_e32 v115, 0xbfb8aa3b, v115
	v_mul_f32_e32 v116, 0xbfb8aa3b, v116
	v_mul_f32_e32 v117, 0xbfb8aa3b, v117
	v_mul_f32_e32 v118, 0xbfb8aa3b, v118
	v_mul_f32_e32 v119, 0xbfb8aa3b, v119
	v_mul_f32_e32 v120, 0xbfb8aa3b, v120
	v_mul_f32_e32 v121, 0xbfb8aa3b, v121
	v_exp_f32_e32 v114, v114
	v_exp_f32_e32 v115, v115
	v_exp_f32_e32 v116, v116
	v_exp_f32_e32 v117, v117
	v_exp_f32_e32 v118, v118
	v_exp_f32_e32 v119, v119
	v_exp_f32_e32 v120, v120
	v_exp_f32_e32 v121, v121
	v_add_f32_e32 v114, 1.0, v114
	v_add_f32_e32 v115, 1.0, v115
	v_add_f32_e32 v116, 1.0, v116
	v_add_f32_e32 v117, 1.0, v117
	v_add_f32_e32 v118, 1.0, v118
	v_add_f32_e32 v119, 1.0, v119
	v_add_f32_e32 v120, 1.0, v120
	v_add_f32_e32 v121, 1.0, v121
	v_rcp_f32_e32 v114, v114
	v_rcp_f32_e32 v115, v115
	v_rcp_f32_e32 v116, v116
	v_rcp_f32_e32 v117, v117
	v_rcp_f32_e32 v118, v118
	v_rcp_f32_e32 v119, v119
	v_rcp_f32_e32 v120, v120
	v_rcp_f32_e32 v121, v121
	s_mov_b64 exec, s[36:37]
	s_nop 0
	v_cvt_pk_bf16_f32 v32, v114, v115
	v_cvt_pk_bf16_f32 v33, v116, v117
	v_cvt_pk_bf16_f32 v34, v118, v119
	v_cvt_pk_bf16_f32 v35, v120, v121
	global_store_dwordx4 v[124:125], v[32:35], off
	v_lshl_add_u64 v[124:125], v[126:127], 0, v[124:125]
	s_waitcnt vmcnt(15)
; DEV float lo_bf(unsigned u) { return __uint_as_float(u << 16); }
; DEV float hi_bf(unsigned u) { return __uint_as_float(u & 0xffff0000u); }
; DEV float sigmoidf_(float x) { return __builtin_amdgcn_rcpf(1.f + __expf(-x)); }
; DEV void shift_tile(const Params& p, int l, int tile) {
;     ...
;   for (int i = 0; i < 16; ++i) {
;     const int row = rb + i;
;     const u32x4 pv = rows[i], cu = rows[i + 1], nx = rows[i + 2];
;     float y[8];
; #pragma unroll
;     for (int q = 0; q < 4; ++q) {
;       y[2 * q] = w0[2 * q] * lo_bf(pv[q]) + w1[2 * q] * lo_bf(cu[q]) + w2[2 * q] * lo_bf(nx[q]);
;       y[2 * q + 1] = w0[2 * q + 1] * hi_bf(pv[q]) + w1[2 * q + 1] * hi_bf(cu[q]) + w2[2 * q + 1] * hi_bf(nx[q]);
;     }
;     if (act == 1) {
; #pragma unroll
;       for (int j = 0; j < 8; ++j) y[j] = 1.f - 2.f * __builtin_amdgcn_rcpf(1.f + __expf(2.f * y[j]));
;     } else if (act == 2) {
; #pragma unroll
;       for (int j = 0; j < 8; ++j) y[j] = sigmoidf_(y[j]);
;     }
;     u32x4 o;
;     o[0] = pk2(y[0], y[1]); o[1] = pk2(y[2], y[3]); o[2] = pk2(y[4], y[5]); o[3] = pk2(y[6], y[7]);
;     if (col < 1536) *(u32x4*)(ZRS + (size_t)row * 1536 + col) = o;
	v_lshlrev_b32_e32 v114, 16, v44
	v_and_b32_e32 v115, 0xffff0000, v44
	v_lshlrev_b32_e32 v116, 16, v45
	v_and_b32_e32 v117, 0xffff0000, v45
	v_lshlrev_b32_e32 v118, 16, v46
	v_and_b32_e32 v119, 0xffff0000, v46
	v_lshlrev_b32_e32 v120, 16, v47
	v_and_b32_e32 v121, 0xffff0000, v47
	v_pk_mul_f32 v[98:99], v[72:73], v[98:99]
	v_pk_mul_f32 v[100:101], v[74:75], v[100:101]
	v_pk_mul_f32 v[102:103], v[76:77], v[102:103]
	v_pk_mul_f32 v[104:105], v[78:79], v[104:105]
	v_pk_fma_f32 v[98:99], v[80:81], v[106:107], v[98:99]
	v_pk_fma_f32 v[100:101], v[82:83], v[108:109], v[100:101]
	v_pk_fma_f32 v[102:103], v[84:85], v[110:111], v[102:103]
	v_pk_fma_f32 v[104:105], v[86:87], v[112:113], v[104:105]
	v_pk_fma_f32 v[98:99], v[88:89], v[114:115], v[98:99]
	v_pk_fma_f32 v[100:101], v[90:91], v[116:117], v[100:101]
	v_pk_fma_f32 v[102:103], v[92:93], v[118:119], v[102:103]
	v_pk_fma_f32 v[104:105], v[94:95], v[120:121], v[104:105]
	s_mov_b64 exec, s[38:39]
	v_mul_f32_e32 v98, 0x4038aa3b, v98
	v_mul_f32_e32 v99, 0x4038aa3b, v99
	v_mul_f32_e32 v100, 0x4038aa3b, v100
	v_mul_f32_e32 v101, 0x4038aa3b, v101
	v_mul_f32_e32 v102, 0x4038aa3b, v102
	v_mul_f32_e32 v103, 0x4038aa3b, v103
	v_mul_f32_e32 v104, 0x4038aa3b, v104
	v_mul_f32_e32 v105, 0x4038aa3b, v105
	v_exp_f32_e32 v98, v98
	v_exp_f32_e32 v99, v99
	v_exp_f32_e32 v100, v100
	v_exp_f32_e32 v101, v101
	v_exp_f32_e32 v102, v102
	v_exp_f32_e32 v103, v103
	v_exp_f32_e32 v104, v104
	v_exp_f32_e32 v105, v105
	v_add_f32_e32 v98, 1.0, v98
	v_add_f32_e32 v99, 1.0, v99
	v_add_f32_e32 v100, 1.0, v100
	v_add_f32_e32 v101, 1.0, v101
	v_add_f32_e32 v102, 1.0, v102
	v_add_f32_e32 v103, 1.0, v103
	v_add_f32_e32 v104, 1.0, v104
	v_add_f32_e32 v105, 1.0, v105
	v_rcp_f32_e32 v98, v98
	v_rcp_f32_e32 v99, v99
	v_rcp_f32_e32 v100, v100
	v_rcp_f32_e32 v101, v101
	v_rcp_f32_e32 v102, v102
	v_rcp_f32_e32 v103, v103
	v_rcp_f32_e32 v104, v104
	v_rcp_f32_e32 v105, v105
	s_nop 0
	v_pk_fma_f32 v[98:99], v[98:99], -2.0, 1.0 op_sel_hi:[1,0,0]
	v_pk_fma_f32 v[100:101], v[100:101], -2.0, 1.0 op_sel_hi:[1,0,0]
	v_pk_fma_f32 v[102:103], v[102:103], -2.0, 1.0 op_sel_hi:[1,0,0]
	v_pk_fma_f32 v[104:105], v[104:105], -2.0, 1.0 op_sel_hi:[1,0,0]
	s_mov_b64 exec, s[30:31]
	v_mul_f32_e32 v98, 0xbfb8aa3b, v98
	v_mul_f32_e32 v99, 0xbfb8aa3b, v99
	v_mul_f32_e32 v100, 0xbfb8aa3b, v100
	v_mul_f32_e32 v101, 0xbfb8aa3b, v101
	v_mul_f32_e32 v102, 0xbfb8aa3b, v102
	v_mul_f32_e32 v103, 0xbfb8aa3b, v103
	v_mul_f32_e32 v104, 0xbfb8aa3b, v104
	v_mul_f32_e32 v105, 0xbfb8aa3b, v105
	v_exp_f32_e32 v98, v98
	v_exp_f32_e32 v99, v99
	v_exp_f32_e32 v100, v100
	v_exp_f32_e32 v101, v101
	v_exp_f32_e32 v102, v102
	v_exp_f32_e32 v103, v103
	v_exp_f32_e32 v104, v104
	v_exp_f32_e32 v105, v105
	v_add_f32_e32 v98, 1.0, v98
	v_add_f32_e32 v99, 1.0, v99
	v_add_f32_e32 v100, 1.0, v100
	v_add_f32_e32 v101, 1.0, v101
	v_add_f32_e32 v102, 1.0, v102
	v_add_f32_e32 v103, 1.0, v103
	v_add_f32_e32 v104, 1.0, v104
	v_add_f32_e32 v105, 1.0, v105
	v_rcp_f32_e32 v98, v98
	v_rcp_f32_e32 v99, v99
	v_rcp_f32_e32 v100, v100
	v_rcp_f32_e32 v101, v101
	v_rcp_f32_e32 v102, v102
	v_rcp_f32_e32 v103, v103
	v_rcp_f32_e32 v104, v104
	v_rcp_f32_e32 v105, v105
	s_mov_b64 exec, s[36:37]
	s_nop 0
	v_cvt_pk_bf16_f32 v36, v98, v99
	v_cvt_pk_bf16_f32 v37, v100, v101
	v_cvt_pk_bf16_f32 v38, v102, v103
	v_cvt_pk_bf16_f32 v39, v104, v105
	global_store_dwordx4 v[124:125], v[36:39], off
	v_lshl_add_u64 v[124:125], v[126:127], 0, v[124:125]
	s_waitcnt vmcnt(15)
	v_lshlrev_b32_e32 v98, 16, v48
	v_and_b32_e32 v99, 0xffff0000, v48
	v_lshlrev_b32_e32 v100, 16, v49
	v_and_b32_e32 v101, 0xffff0000, v49
	v_lshlrev_b32_e32 v102, 16, v50
	v_and_b32_e32 v103, 0xffff0000, v50
	v_lshlrev_b32_e32 v104, 16, v51
	v_and_b32_e32 v105, 0xffff0000, v51
	v_pk_mul_f32 v[106:107], v[72:73], v[106:107]
	v_pk_mul_f32 v[108:109], v[74:75], v[108:109]
	v_pk_mul_f32 v[110:111], v[76:77], v[110:111]
	v_pk_mul_f32 v[112:113], v[78:79], v[112:113]
	v_pk_fma_f32 v[106:107], v[80:81], v[114:115], v[106:107]
	v_pk_fma_f32 v[108:109], v[82:83], v[116:117], v[108:109]
	v_pk_fma_f32 v[110:111], v[84:85], v[118:119], v[110:111]
	v_pk_fma_f32 v[112:113], v[86:87], v[120:121], v[112:113]
	v_pk_fma_f32 v[106:107], v[88:89], v[98:99], v[106:107]
	v_pk_fma_f32 v[108:109], v[90:91], v[100:101], v[108:109]
	v_pk_fma_f32 v[110:111], v[92:93], v[102:103], v[110:111]
	v_pk_fma_f32 v[112:113], v[94:95], v[104:105], v[112:113]
	s_mov_b64 exec, s[38:39]
	v_mul_f32_e32 v106, 0x4038aa3b, v106
	v_mul_f32_e32 v107, 0x4038aa3b, v107
	v_mul_f32_e32 v108, 0x4038aa3b, v108
	v_mul_f32_e32 v109, 0x4038aa3b, v109
	v_mul_f32_e32 v110, 0x4038aa3b, v110
	v_mul_f32_e32 v111, 0x4038aa3b, v111
	v_mul_f32_e32 v112, 0x4038aa3b, v112
	v_mul_f32_e32 v113, 0x4038aa3b, v113
	v_exp_f32_e32 v106, v106
	v_exp_f32_e32 v107, v107
	v_exp_f32_e32 v108, v108
	v_exp_f32_e32 v109, v109
	v_exp_f32_e32 v110, v110
	v_exp_f32_e32 v111, v111
	v_exp_f32_e32 v112, v112
	v_exp_f32_e32 v113, v113
	v_add_f32_e32 v106, 1.0, v106
	v_add_f32_e32 v107, 1.0, v107
	v_add_f32_e32 v108, 1.0, v108
	v_add_f32_e32 v109, 1.0, v109
	v_add_f32_e32 v110, 1.0, v110
	v_add_f32_e32 v111, 1.0, v111
	v_add_f32_e32 v112, 1.0, v112
	v_add_f32_e32 v113, 1.0, v113
	v_rcp_f32_e32 v106, v106
	v_rcp_f32_e32 v107, v107
	v_rcp_f32_e32 v108, v108
	v_rcp_f32_e32 v109, v109
	v_rcp_f32_e32 v110, v110
	v_rcp_f32_e32 v111, v111
	v_rcp_f32_e32 v112, v112
	v_rcp_f32_e32 v113, v113
	s_nop 0
	v_pk_fma_f32 v[106:107], v[106:107], -2.0, 1.0 op_sel_hi:[1,0,0]
	v_pk_fma_f32 v[108:109], v[108:109], -2.0, 1.0 op_sel_hi:[1,0,0]
	v_pk_fma_f32 v[110:111], v[110:111], -2.0, 1.0 op_sel_hi:[1,0,0]
	v_pk_fma_f32 v[112:113], v[112:113], -2.0, 1.0 op_sel_hi:[1,0,0]
	s_mov_b64 exec, s[30:31]
	v_mul_f32_e32 v106, 0xbfb8aa3b, v106
	v_mul_f32_e32 v107, 0xbfb8aa3b, v107
	v_mul_f32_e32 v108, 0xbfb8aa3b, v108
	v_mul_f32_e32 v109, 0xbfb8aa3b, v109
	v_mul_f32_e32 v110, 0xbfb8aa3b, v110
	v_mul_f32_e32 v111, 0xbfb8aa3b, v111
	v_mul_f32_e32 v112, 0xbfb8aa3b, v112
	v_mul_f32_e32 v113, 0xbfb8aa3b, v113
	v_exp_f32_e32 v106, v106
	v_exp_f32_e32 v107, v107
	v_exp_f32_e32 v108, v108
	v_exp_f32_e32 v109, v109
	v_exp_f32_e32 v110, v110
	v_exp_f32_e32 v111, v111
	v_exp_f32_e32 v112, v112
	v_exp_f32_e32 v113, v113
	v_add_f32_e32 v106, 1.0, v106
	v_add_f32_e32 v107, 1.0, v107
	v_add_f32_e32 v108, 1.0, v108
	v_add_f32_e32 v109, 1.0, v109
	v_add_f32_e32 v110, 1.0, v110
	v_add_f32_e32 v111, 1.0, v111
	v_add_f32_e32 v112, 1.0, v112
	v_add_f32_e32 v113, 1.0, v113
	v_rcp_f32_e32 v106, v106
	v_rcp_f32_e32 v107, v107
	v_rcp_f32_e32 v108, v108
	v_rcp_f32_e32 v109, v109
	v_rcp_f32_e32 v110, v110
	v_rcp_f32_e32 v111, v111
	v_rcp_f32_e32 v112, v112
	v_rcp_f32_e32 v113, v113
	s_mov_b64 exec, s[36:37]
	s_nop 0
	v_cvt_pk_bf16_f32 v40, v106, v107
	v_cvt_pk_bf16_f32 v41, v108, v109
	v_cvt_pk_bf16_f32 v42, v110, v111
	v_cvt_pk_bf16_f32 v43, v112, v113
	global_store_dwordx4 v[124:125], v[40:43], off
	v_lshl_add_u64 v[124:125], v[126:127], 0, v[124:125]
	s_waitcnt vmcnt(15)
; DEV float lo_bf(unsigned u) { return __uint_as_float(u << 16); }
; DEV float hi_bf(unsigned u) { return __uint_as_float(u & 0xffff0000u); }
; DEV float sigmoidf_(float x) { return __builtin_amdgcn_rcpf(1.f + __expf(-x)); }
; DEV void shift_tile(const Params& p, int l, int tile) {
;     ...
;   for (int i = 0; i < 16; ++i) {
;     const int row = rb + i;
;     const u32x4 pv = rows[i], cu = rows[i + 1], nx = rows[i + 2];
;     float y[8];
; #pragma unroll
;     for (int q = 0; q < 4; ++q) {
;       y[2 * q] = w0[2 * q] * lo_bf(pv[q]) + w1[2 * q] * lo_bf(cu[q]) + w2[2 * q] * lo_bf(nx[q]);
;       y[2 * q + 1] = w0[2 * q + 1] * hi_bf(pv[q]) + w1[2 * q + 1] * hi_bf(cu[q]) + w2[2 * q + 1] * hi_bf(nx[q]);
;     }
;     if (act == 1) {
; #pragma unroll
;       for (int j = 0; j < 8; ++j) y[j] = 1.f - 2.f * __builtin_amdgcn_rcpf(1.f + __expf(2.f * y[j]));
;     } else if (act == 2) {
; #pragma unroll
;       for (int j = 0; j < 8; ++j) y[j] = sigmoidf_(y[j]);
;     }
;     u32x4 o;
;     o[0] = pk2(y[0], y[1]); o[1] = pk2(y[2], y[3]); o[2] = pk2(y[4], y[5]); o[3] = pk2(y[6], y[7]);
;     if (col < 1536) *(u32x4*)(ZRS + (size_t)row * 1536 + col) = o;
	v_lshlrev_b32_e32 v106, 16, v52
	v_and_b32_e32 v107, 0xffff0000, v52
	v_lshlrev_b32_e32 v108, 16, v53
	v_and_b32_e32 v109, 0xffff0000, v53
	v_lshlrev_b32_e32 v110, 16, v54
	v_and_b32_e32 v111, 0xffff0000, v54
	v_lshlrev_b32_e32 v112, 16, v55
	v_and_b32_e32 v113, 0xffff0000, v55
	v_pk_mul_f32 v[114:115], v[72:73], v[114:115]
	v_pk_mul_f32 v[116:117], v[74:75], v[116:117]
	v_pk_mul_f32 v[118:119], v[76:77], v[118:119]
	v_pk_mul_f32 v[120:121], v[78:79], v[120:121]
	v_pk_fma_f32 v[114:115], v[80:81], v[98:99], v[114:115]
	v_pk_fma_f32 v[116:117], v[82:83], v[100:101], v[116:117]
	v_pk_fma_f32 v[118:119], v[84:85], v[102:103], v[118:119]
	v_pk_fma_f32 v[120:121], v[86:87], v[104:105], v[120:121]
	v_pk_fma_f32 v[114:115], v[88:89], v[106:107], v[114:115]
	v_pk_fma_f32 v[116:117], v[90:91], v[108:109], v[116:117]
	v_pk_fma_f32 v[118:119], v[92:93], v[110:111], v[118:119]
	v_pk_fma_f32 v[120:121], v[94:95], v[112:113], v[120:121]
	s_mov_b64 exec, s[38:39]
	v_mul_f32_e32 v114, 0x4038aa3b, v114
	v_mul_f32_e32 v115, 0x4038aa3b, v115
	v_mul_f32_e32 v116, 0x4038aa3b, v116
	v_mul_f32_e32 v117, 0x4038aa3b, v117
	v_mul_f32_e32 v118, 0x4038aa3b, v118
	v_mul_f32_e32 v119, 0x4038aa3b, v119
	v_mul_f32_e32 v120, 0x4038aa3b, v120
	v_mul_f32_e32 v121, 0x4038aa3b, v121
	v_exp_f32_e32 v114, v114
	v_exp_f32_e32 v115, v115
	v_exp_f32_e32 v116, v116
	v_exp_f32_e32 v117, v117
	v_exp_f32_e32 v118, v118
	v_exp_f32_e32 v119, v119
	v_exp_f32_e32 v120, v120
	v_exp_f32_e32 v121, v121
	v_add_f32_e32 v114, 1.0, v114
	v_add_f32_e32 v115, 1.0, v115
	v_add_f32_e32 v116, 1.0, v116
	v_add_f32_e32 v117, 1.0, v117
	v_add_f32_e32 v118, 1.0, v118
	v_add_f32_e32 v119, 1.0, v119
	v_add_f32_e32 v120, 1.0, v120
	v_add_f32_e32 v121, 1.0, v121
	v_rcp_f32_e32 v114, v114
	v_rcp_f32_e32 v115, v115
	v_rcp_f32_e32 v116, v116
	v_rcp_f32_e32 v117, v117
	v_rcp_f32_e32 v118, v118
	v_rcp_f32_e32 v119, v119
	v_rcp_f32_e32 v120, v120
	v_rcp_f32_e32 v121, v121
	s_nop 0
	v_pk_fma_f32 v[114:115], v[114:115], -2.0, 1.0 op_sel_hi:[1,0,0]
	v_pk_fma_f32 v[116:117], v[116:117], -2.0, 1.0 op_sel_hi:[1,0,0]
	v_pk_fma_f32 v[118:119], v[118:119], -2.0, 1.0 op_sel_hi:[1,0,0]
	v_pk_fma_f32 v[120:121], v[120:121], -2.0, 1.0 op_sel_hi:[1,0,0]
	s_mov_b64 exec, s[30:31]
	v_mul_f32_e32 v114, 0xbfb8aa3b, v114
	v_mul_f32_e32 v115, 0xbfb8aa3b, v115
	v_mul_f32_e32 v116, 0xbfb8aa3b, v116
	v_mul_f32_e32 v117, 0xbfb8aa3b, v117
	v_mul_f32_e32 v118, 0xbfb8aa3b, v118
	v_mul_f32_e32 v119, 0xbfb8aa3b, v119
	v_mul_f32_e32 v120, 0xbfb8aa3b, v120
	v_mul_f32_e32 v121, 0xbfb8aa3b, v121
	v_exp_f32_e32 v114, v114
	v_exp_f32_e32 v115, v115
	v_exp_f32_e32 v116, v116
	v_exp_f32_e32 v117, v117
	v_exp_f32_e32 v118, v118
	v_exp_f32_e32 v119, v119
	v_exp_f32_e32 v120, v120
	v_exp_f32_e32 v121, v121
	v_add_f32_e32 v114, 1.0, v114
	v_add_f32_e32 v115, 1.0, v115
	v_add_f32_e32 v116, 1.0, v116
	v_add_f32_e32 v117, 1.0, v117
	v_add_f32_e32 v118, 1.0, v118
	v_add_f32_e32 v119, 1.0, v119
	v_add_f32_e32 v120, 1.0, v120
	v_add_f32_e32 v121, 1.0, v121
	v_rcp_f32_e32 v114, v114
	v_rcp_f32_e32 v115, v115
	v_rcp_f32_e32 v116, v116
	v_rcp_f32_e32 v117, v117
	v_rcp_f32_e32 v118, v118
	v_rcp_f32_e32 v119, v119
	v_rcp_f32_e32 v120, v120
	v_rcp_f32_e32 v121, v121
	s_mov_b64 exec, s[36:37]
	s_nop 0
	v_cvt_pk_bf16_f32 v44, v114, v115
	v_cvt_pk_bf16_f32 v45, v116, v117
	v_cvt_pk_bf16_f32 v46, v118, v119
	v_cvt_pk_bf16_f32 v47, v120, v121
	global_store_dwordx4 v[124:125], v[44:47], off
	v_lshl_add_u64 v[124:125], v[126:127], 0, v[124:125]
	s_waitcnt vmcnt(15)
	v_lshlrev_b32_e32 v114, 16, v56
	v_and_b32_e32 v115, 0xffff0000, v56
	v_lshlrev_b32_e32 v116, 16, v57
	v_and_b32_e32 v117, 0xffff0000, v57
	v_lshlrev_b32_e32 v118, 16, v58
	v_and_b32_e32 v119, 0xffff0000, v58
	v_lshlrev_b32_e32 v120, 16, v59
	v_and_b32_e32 v121, 0xffff0000, v59
	v_pk_mul_f32 v[98:99], v[72:73], v[98:99]
	v_pk_mul_f32 v[100:101], v[74:75], v[100:101]
	v_pk_mul_f32 v[102:103], v[76:77], v[102:103]
	v_pk_mul_f32 v[104:105], v[78:79], v[104:105]
	v_pk_fma_f32 v[98:99], v[80:81], v[106:107], v[98:99]
	v_pk_fma_f32 v[100:101], v[82:83], v[108:109], v[100:101]
	v_pk_fma_f32 v[102:103], v[84:85], v[110:111], v[102:103]
	v_pk_fma_f32 v[104:105], v[86:87], v[112:113], v[104:105]
	v_pk_fma_f32 v[98:99], v[88:89], v[114:115], v[98:99]
	v_pk_fma_f32 v[100:101], v[90:91], v[116:117], v[100:101]
	v_pk_fma_f32 v[102:103], v[92:93], v[118:119], v[102:103]
	v_pk_fma_f32 v[104:105], v[94:95], v[120:121], v[104:105]
	s_mov_b64 exec, s[38:39]
	v_mul_f32_e32 v98, 0x4038aa3b, v98
	v_mul_f32_e32 v99, 0x4038aa3b, v99
	v_mul_f32_e32 v100, 0x4038aa3b, v100
	v_mul_f32_e32 v101, 0x4038aa3b, v101
	v_mul_f32_e32 v102, 0x4038aa3b, v102
	v_mul_f32_e32 v103, 0x4038aa3b, v103
	v_mul_f32_e32 v104, 0x4038aa3b, v104
	v_mul_f32_e32 v105, 0x4038aa3b, v105
	v_exp_f32_e32 v98, v98
	v_exp_f32_e32 v99, v99
	v_exp_f32_e32 v100, v100
	v_exp_f32_e32 v101, v101
	v_exp_f32_e32 v102, v102
	v_exp_f32_e32 v103, v103
	v_exp_f32_e32 v104, v104
	v_exp_f32_e32 v105, v105
	v_add_f32_e32 v98, 1.0, v98
	v_add_f32_e32 v99, 1.0, v99
	v_add_f32_e32 v100, 1.0, v100
	v_add_f32_e32 v101, 1.0, v101
	v_add_f32_e32 v102, 1.0, v102
	v_add_f32_e32 v103, 1.0, v103
	v_add_f32_e32 v104, 1.0, v104
	v_add_f32_e32 v105, 1.0, v105
	v_rcp_f32_e32 v98, v98
	v_rcp_f32_e32 v99, v99
	v_rcp_f32_e32 v100, v100
	v_rcp_f32_e32 v101, v101
	v_rcp_f32_e32 v102, v102
	v_rcp_f32_e32 v103, v103
	v_rcp_f32_e32 v104, v104
	v_rcp_f32_e32 v105, v105
	s_nop 0
	v_pk_fma_f32 v[98:99], v[98:99], -2.0, 1.0 op_sel_hi:[1,0,0]
	v_pk_fma_f32 v[100:101], v[100:101], -2.0, 1.0 op_sel_hi:[1,0,0]
	v_pk_fma_f32 v[102:103], v[102:103], -2.0, 1.0 op_sel_hi:[1,0,0]
	v_pk_fma_f32 v[104:105], v[104:105], -2.0, 1.0 op_sel_hi:[1,0,0]
	s_mov_b64 exec, s[30:31]
	v_mul_f32_e32 v98, 0xbfb8aa3b, v98
	v_mul_f32_e32 v99, 0xbfb8aa3b, v99
	v_mul_f32_e32 v100, 0xbfb8aa3b, v100
	v_mul_f32_e32 v101, 0xbfb8aa3b, v101
	v_mul_f32_e32 v102, 0xbfb8aa3b, v102
	v_mul_f32_e32 v103, 0xbfb8aa3b, v103
	v_mul_f32_e32 v104, 0xbfb8aa3b, v104
	v_mul_f32_e32 v105, 0xbfb8aa3b, v105
	v_exp_f32_e32 v98, v98
	v_exp_f32_e32 v99, v99
	v_exp_f32_e32 v100, v100
	v_exp_f32_e32 v101, v101
	v_exp_f32_e32 v102, v102
	v_exp_f32_e32 v103, v103
	v_exp_f32_e32 v104, v104
	v_exp_f32_e32 v105, v105
	v_add_f32_e32 v98, 1.0, v98
	v_add_f32_e32 v99, 1.0, v99
	v_add_f32_e32 v100, 1.0, v100
	v_add_f32_e32 v101, 1.0, v101
	v_add_f32_e32 v102, 1.0, v102
	v_add_f32_e32 v103, 1.0, v103
	v_add_f32_e32 v104, 1.0, v104
	v_add_f32_e32 v105, 1.0, v105
	v_rcp_f32_e32 v98, v98
	v_rcp_f32_e32 v99, v99
	v_rcp_f32_e32 v100, v100
	v_rcp_f32_e32 v101, v101
	v_rcp_f32_e32 v102, v102
	v_rcp_f32_e32 v103, v103
	v_rcp_f32_e32 v104, v104
	v_rcp_f32_e32 v105, v105
	s_mov_b64 exec, s[36:37]
	s_nop 0
	v_cvt_pk_bf16_f32 v48, v98, v99
	v_cvt_pk_bf16_f32 v49, v100, v101
	v_cvt_pk_bf16_f32 v50, v102, v103
	v_cvt_pk_bf16_f32 v51, v104, v105
	global_store_dwordx4 v[124:125], v[48:51], off
	v_lshl_add_u64 v[124:125], v[126:127], 0, v[124:125]
	s_waitcnt vmcnt(15)
; DEV float lo_bf(unsigned u) { return __uint_as_float(u << 16); }
; DEV float hi_bf(unsigned u) { return __uint_as_float(u & 0xffff0000u); }
; DEV float sigmoidf_(float x) { return __builtin_amdgcn_rcpf(1.f + __expf(-x)); }
; DEV void shift_tile(const Params& p, int l, int tile) {
;     ...
;   for (int i = 0; i < 16; ++i) {
;     const int row = rb + i;
;     const u32x4 pv = rows[i], cu = rows[i + 1], nx = rows[i + 2];
;     float y[8];
; #pragma unroll
;     for (int q = 0; q < 4; ++q) {
;       y[2 * q] = w0[2 * q] * lo_bf(pv[q]) + w1[2 * q] * lo_bf(cu[q]) + w2[2 * q] * lo_bf(nx[q]);
;       y[2 * q + 1] = w0[2 * q + 1] * hi_bf(pv[q]) + w1[2 * q + 1] * hi_bf(cu[q]) + w2[2 * q + 1] * hi_bf(nx[q]);
;     }
;     if (act == 1) {
; #pragma unroll
;       for (int j = 0; j < 8; ++j) y[j] = 1.f - 2.f * __builtin_amdgcn_rcpf(1.f + __expf(2.f * y[j]));
;     } else if (act == 2) {
; #pragma unroll
;       for (int j = 0; j < 8; ++j) y[j] = sigmoidf_(y[j]);
;     }
;     u32x4 o;
;     o[0] = pk2(y[0], y[1]); o[1] = pk2(y[2], y[3]); o[2] = pk2(y[4], y[5]); o[3] = pk2(y[6], y[7]);
;     if (col < 1536) *(u32x4*)(ZRS + (size_t)row * 1536 + col) = o;
	v_lshlrev_b32_e32 v98, 16, v60
	v_and_b32_e32 v99, 0xffff0000, v60
	v_lshlrev_b32_e32 v100, 16, v61
	v_and_b32_e32 v101, 0xffff0000, v61
	v_lshlrev_b32_e32 v102, 16, v62
	v_and_b32_e32 v103, 0xffff0000, v62
	v_lshlrev_b32_e32 v104, 16, v63
	v_and_b32_e32 v105, 0xffff0000, v63
	v_pk_mul_f32 v[106:107], v[72:73], v[106:107]
	v_pk_mul_f32 v[108:109], v[74:75], v[108:109]
	v_pk_mul_f32 v[110:111], v[76:77], v[110:111]
	v_pk_mul_f32 v[112:113], v[78:79], v[112:113]
	v_pk_fma_f32 v[106:107], v[80:81], v[114:115], v[106:107]
	v_pk_fma_f32 v[108:109], v[82:83], v[116:117], v[108:109]
	v_pk_fma_f32 v[110:111], v[84:85], v[118:119], v[110:111]
	v_pk_fma_f32 v[112:113], v[86:87], v[120:121], v[112:113]
	v_pk_fma_f32 v[106:107], v[88:89], v[98:99], v[106:107]
	v_pk_fma_f32 v[108:109], v[90:91], v[100:101], v[108:109]
	v_pk_fma_f32 v[110:111], v[92:93], v[102:103], v[110:111]
	v_pk_fma_f32 v[112:113], v[94:95], v[104:105], v[112:113]
	s_mov_b64 exec, s[38:39]
	v_mul_f32_e32 v106, 0x4038aa3b, v106
	v_mul_f32_e32 v107, 0x4038aa3b, v107
	v_mul_f32_e32 v108, 0x4038aa3b, v108
	v_mul_f32_e32 v109, 0x4038aa3b, v109
	v_mul_f32_e32 v110, 0x4038aa3b, v110
	v_mul_f32_e32 v111, 0x4038aa3b, v111
	v_mul_f32_e32 v112, 0x4038aa3b, v112
	v_mul_f32_e32 v113, 0x4038aa3b, v113
	v_exp_f32_e32 v106, v106
	v_exp_f32_e32 v107, v107
	v_exp_f32_e32 v108, v108
	v_exp_f32_e32 v109, v109
	v_exp_f32_e32 v110, v110
	v_exp_f32_e32 v111, v111
	v_exp_f32_e32 v112, v112
	v_exp_f32_e32 v113, v113
	v_add_f32_e32 v106, 1.0, v106
	v_add_f32_e32 v107, 1.0, v107
	v_add_f32_e32 v108, 1.0, v108
	v_add_f32_e32 v109, 1.0, v109
	v_add_f32_e32 v110, 1.0, v110
	v_add_f32_e32 v111, 1.0, v111
	v_add_f32_e32 v112, 1.0, v112
	v_add_f32_e32 v113, 1.0, v113
	v_rcp_f32_e32 v106, v106
	v_rcp_f32_e32 v107, v107
	v_rcp_f32_e32 v108, v108
	v_rcp_f32_e32 v109, v109
	v_rcp_f32_e32 v110, v110
	v_rcp_f32_e32 v111, v111
	v_rcp_f32_e32 v112, v112
	v_rcp_f32_e32 v113, v113
	s_nop 0
	v_pk_fma_f32 v[106:107], v[106:107], -2.0, 1.0 op_sel_hi:[1,0,0]
	v_pk_fma_f32 v[108:109], v[108:109], -2.0, 1.0 op_sel_hi:[1,0,0]
	v_pk_fma_f32 v[110:111], v[110:111], -2.0, 1.0 op_sel_hi:[1,0,0]
	v_pk_fma_f32 v[112:113], v[112:113], -2.0, 1.0 op_sel_hi:[1,0,0]
	s_mov_b64 exec, s[30:31]
	v_mul_f32_e32 v106, 0xbfb8aa3b, v106
	v_mul_f32_e32 v107, 0xbfb8aa3b, v107
	v_mul_f32_e32 v108, 0xbfb8aa3b, v108
	v_mul_f32_e32 v109, 0xbfb8aa3b, v109
	v_mul_f32_e32 v110, 0xbfb8aa3b, v110
	v_mul_f32_e32 v111, 0xbfb8aa3b, v111
	v_mul_f32_e32 v112, 0xbfb8aa3b, v112
	v_mul_f32_e32 v113, 0xbfb8aa3b, v113
	v_exp_f32_e32 v106, v106
	v_exp_f32_e32 v107, v107
	v_exp_f32_e32 v108, v108
	v_exp_f32_e32 v109, v109
	v_exp_f32_e32 v110, v110
	v_exp_f32_e32 v111, v111
	v_exp_f32_e32 v112, v112
	v_exp_f32_e32 v113, v113
	v_add_f32_e32 v106, 1.0, v106
	v_add_f32_e32 v107, 1.0, v107
	v_add_f32_e32 v108, 1.0, v108
	v_add_f32_e32 v109, 1.0, v109
	v_add_f32_e32 v110, 1.0, v110
	v_add_f32_e32 v111, 1.0, v111
	v_add_f32_e32 v112, 1.0, v112
	v_add_f32_e32 v113, 1.0, v113
	v_rcp_f32_e32 v106, v106
	v_rcp_f32_e32 v107, v107
	v_rcp_f32_e32 v108, v108
	v_rcp_f32_e32 v109, v109
	v_rcp_f32_e32 v110, v110
	v_rcp_f32_e32 v111, v111
	v_rcp_f32_e32 v112, v112
	v_rcp_f32_e32 v113, v113
	s_mov_b64 exec, s[36:37]
	s_nop 0
	v_cvt_pk_bf16_f32 v52, v106, v107
	v_cvt_pk_bf16_f32 v53, v108, v109
	v_cvt_pk_bf16_f32 v54, v110, v111
	v_cvt_pk_bf16_f32 v55, v112, v113
	global_store_dwordx4 v[124:125], v[52:55], off
	v_lshl_add_u64 v[124:125], v[126:127], 0, v[124:125]
	s_waitcnt vmcnt(15)
; DEV float lo_bf(unsigned u) { return __uint_as_float(u << 16); }
; DEV float hi_bf(unsigned u) { return __uint_as_float(u & 0xffff0000u); }
; DEV float sigmoidf_(float x) { return __builtin_amdgcn_rcpf(1.f + __expf(-x)); }
; DEV void shift_tile(const Params& p, int l, int tile) {
;     ...
;   for (int i = 0; i < 16; ++i) {
;     const int row = rb + i;
;     const u32x4 pv = rows[i], cu = rows[i + 1], nx = rows[i + 2];
;     float y[8];
; #pragma unroll
;     for (int q = 0; q < 4; ++q) {
;       y[2 * q] = w0[2 * q] * lo_bf(pv[q]) + w1[2 * q] * lo_bf(cu[q]) + w2[2 * q] * lo_bf(nx[q]);
;       y[2 * q + 1] = w0[2 * q + 1] * hi_bf(pv[q]) + w1[2 * q + 1] * hi_bf(cu[q]) + w2[2 * q + 1] * hi_bf(nx[q]);
;     }
;     if (act == 1) {
; #pragma unroll
;       for (int j = 0; j < 8; ++j) y[j] = 1.f - 2.f * __builtin_amdgcn_rcpf(1.f + __expf(2.f * y[j]));
;     } else if (act == 2) {
; #pragma unroll
;       for (int j = 0; j < 8; ++j) y[j] = sigmoidf_(y[j]);
;     }
;     u32x4 o;
;     o[0] = pk2(y[0], y[1]); o[1] = pk2(y[2], y[3]); o[2] = pk2(y[4], y[5]); o[3] = pk2(y[6], y[7]);
;     if (col < 1536) *(u32x4*)(ZRS + (size_t)row * 1536 + col) = o;
	v_lshlrev_b32_e32 v106, 16, v64
	v_and_b32_e32 v107, 0xffff0000, v64
	v_lshlrev_b32_e32 v108, 16, v65
	v_and_b32_e32 v109, 0xffff0000, v65
	v_lshlrev_b32_e32 v110, 16, v66
	v_and_b32_e32 v111, 0xffff0000, v66
	v_lshlrev_b32_e32 v112, 16, v67
	v_and_b32_e32 v113, 0xffff0000, v67
	v_pk_mul_f32 v[114:115], v[72:73], v[114:115]
	v_pk_mul_f32 v[116:117], v[74:75], v[116:117]
	v_pk_mul_f32 v[118:119], v[76:77], v[118:119]
	v_pk_mul_f32 v[120:121], v[78:79], v[120:121]
	v_pk_fma_f32 v[114:115], v[80:81], v[98:99], v[114:115]
	v_pk_fma_f32 v[116:117], v[82:83], v[100:101], v[116:117]
	v_pk_fma_f32 v[118:119], v[84:85], v[102:103], v[118:119]
	v_pk_fma_f32 v[120:121], v[86:87], v[104:105], v[120:121]
	v_pk_fma_f32 v[114:115], v[88:89], v[106:107], v[114:115]
	v_pk_fma_f32 v[116:117], v[90:91], v[108:109], v[116:117]
	v_pk_fma_f32 v[118:119], v[92:93], v[110:111], v[118:119]
	v_pk_fma_f32 v[120:121], v[94:95], v[112:113], v[120:121]
	s_mov_b64 exec, s[38:39]
	v_mul_f32_e32 v114, 0x4038aa3b, v114
	v_mul_f32_e32 v115, 0x4038aa3b, v115
	v_mul_f32_e32 v116, 0x4038aa3b, v116
	v_mul_f32_e32 v117, 0x4038aa3b, v117
	v_mul_f32_e32 v118, 0x4038aa3b, v118
	v_mul_f32_e32 v119, 0x4038aa3b, v119
	v_mul_f32_e32 v120, 0x4038aa3b, v120
	v_mul_f32_e32 v121, 0x4038aa3b, v121
	v_exp_f32_e32 v114, v114
	v_exp_f32_e32 v115, v115
	v_exp_f32_e32 v116, v116
	v_exp_f32_e32 v117, v117
	v_exp_f32_e32 v118, v118
	v_exp_f32_e32 v119, v119
	v_exp_f32_e32 v120, v120
	v_exp_f32_e32 v121, v121
	v_add_f32_e32 v114, 1.0, v114
	v_add_f32_e32 v115, 1.0, v115
	v_add_f32_e32 v116, 1.0, v116
	v_add_f32_e32 v117, 1.0, v117
	v_add_f32_e32 v118, 1.0, v118
	v_add_f32_e32 v119, 1.0, v119
	v_add_f32_e32 v120, 1.0, v120
	v_add_f32_e32 v121, 1.0, v121
	v_rcp_f32_e32 v114, v114
	v_rcp_f32_e32 v115, v115
	v_rcp_f32_e32 v116, v116
	v_rcp_f32_e32 v117, v117
	v_rcp_f32_e32 v118, v118
	v_rcp_f32_e32 v119, v119
	v_rcp_f32_e32 v120, v120
	v_rcp_f32_e32 v121, v121
	s_nop 0
	v_pk_fma_f32 v[114:115], v[114:115], -2.0, 1.0 op_sel_hi:[1,0,0]
	v_pk_fma_f32 v[116:117], v[116:117], -2.0, 1.0 op_sel_hi:[1,0,0]
	v_pk_fma_f32 v[118:119], v[118:119], -2.0, 1.0 op_sel_hi:[1,0,0]
	v_pk_fma_f32 v[120:121], v[120:121], -2.0, 1.0 op_sel_hi:[1,0,0]
	s_mov_b64 exec, s[30:31]
	v_mul_f32_e32 v114, 0xbfb8aa3b, v114
	v_mul_f32_e32 v115, 0xbfb8aa3b, v115
	v_mul_f32_e32 v116, 0xbfb8aa3b, v116
	v_mul_f32_e32 v117, 0xbfb8aa3b, v117
	v_mul_f32_e32 v118, 0xbfb8aa3b, v118
	v_mul_f32_e32 v119, 0xbfb8aa3b, v119
	v_mul_f32_e32 v120, 0xbfb8aa3b, v120
	v_mul_f32_e32 v121, 0xbfb8aa3b, v121
	v_exp_f32_e32 v114, v114
	v_exp_f32_e32 v115, v115
	v_exp_f32_e32 v116, v116
	v_exp_f32_e32 v117, v117
	v_exp_f32_e32 v118, v118
	v_exp_f32_e32 v119, v119
	v_exp_f32_e32 v120, v120
	v_exp_f32_e32 v121, v121
	v_add_f32_e32 v114, 1.0, v114
	v_add_f32_e32 v115, 1.0, v115
	v_add_f32_e32 v116, 1.0, v116
	v_add_f32_e32 v117, 1.0, v117
	v_add_f32_e32 v118, 1.0, v118
	v_add_f32_e32 v119, 1.0, v119
	v_add_f32_e32 v120, 1.0, v120
	v_add_f32_e32 v121, 1.0, v121
	v_rcp_f32_e32 v114, v114
	v_rcp_f32_e32 v115, v115
	v_rcp_f32_e32 v116, v116
	v_rcp_f32_e32 v117, v117
	v_rcp_f32_e32 v118, v118
	v_rcp_f32_e32 v119, v119
	v_rcp_f32_e32 v120, v120
	v_rcp_f32_e32 v121, v121
	s_mov_b64 exec, s[36:37]
	s_nop 0
	v_cvt_pk_bf16_f32 v56, v114, v115
	v_cvt_pk_bf16_f32 v57, v116, v117
	v_cvt_pk_bf16_f32 v58, v118, v119
	v_cvt_pk_bf16_f32 v59, v120, v121
	global_store_dwordx4 v[124:125], v[56:59], off
	v_lshl_add_u64 v[124:125], v[126:127], 0, v[124:125]
	s_waitcnt vmcnt(15)
	v_lshlrev_b32_e32 v114, 16, v68
	v_and_b32_e32 v115, 0xffff0000, v68
	v_lshlrev_b32_e32 v116, 16, v69
	v_and_b32_e32 v117, 0xffff0000, v69
	v_lshlrev_b32_e32 v118, 16, v70
	v_and_b32_e32 v119, 0xffff0000, v70
	v_lshlrev_b32_e32 v120, 16, v71
	v_and_b32_e32 v121, 0xffff0000, v71
	v_pk_mul_f32 v[98:99], v[72:73], v[98:99]
	v_pk_mul_f32 v[100:101], v[74:75], v[100:101]
	v_pk_mul_f32 v[102:103], v[76:77], v[102:103]
	v_pk_mul_f32 v[104:105], v[78:79], v[104:105]
	v_pk_fma_f32 v[98:99], v[80:81], v[106:107], v[98:99]
	v_pk_fma_f32 v[100:101], v[82:83], v[108:109], v[100:101]
	v_pk_fma_f32 v[102:103], v[84:85], v[110:111], v[102:103]
	v_pk_fma_f32 v[104:105], v[86:87], v[112:113], v[104:105]
	v_pk_fma_f32 v[98:99], v[88:89], v[114:115], v[98:99]
	v_pk_fma_f32 v[100:101], v[90:91], v[116:117], v[100:101]
	v_pk_fma_f32 v[102:103], v[92:93], v[118:119], v[102:103]
	v_pk_fma_f32 v[104:105], v[94:95], v[120:121], v[104:105]
	s_mov_b64 exec, s[38:39]
	v_mul_f32_e32 v98, 0x4038aa3b, v98
	v_mul_f32_e32 v99, 0x4038aa3b, v99
	v_mul_f32_e32 v100, 0x4038aa3b, v100
	v_mul_f32_e32 v101, 0x4038aa3b, v101
	v_mul_f32_e32 v102, 0x4038aa3b, v102
	v_mul_f32_e32 v103, 0x4038aa3b, v103
	v_mul_f32_e32 v104, 0x4038aa3b, v104
	v_mul_f32_e32 v105, 0x4038aa3b, v105
	v_exp_f32_e32 v98, v98
	v_exp_f32_e32 v99, v99
	v_exp_f32_e32 v100, v100
	v_exp_f32_e32 v101, v101
	v_exp_f32_e32 v102, v102
	v_exp_f32_e32 v103, v103
	v_exp_f32_e32 v104, v104
	v_exp_f32_e32 v105, v105
	v_add_f32_e32 v98, 1.0, v98
	v_add_f32_e32 v99, 1.0, v99
	v_add_f32_e32 v100, 1.0, v100
	v_add_f32_e32 v101, 1.0, v101
	v_add_f32_e32 v102, 1.0, v102
	v_add_f32_e32 v103, 1.0, v103
	v_add_f32_e32 v104, 1.0, v104
	v_add_f32_e32 v105, 1.0, v105
	v_rcp_f32_e32 v98, v98
	v_rcp_f32_e32 v99, v99
	v_rcp_f32_e32 v100, v100
	v_rcp_f32_e32 v101, v101
	v_rcp_f32_e32 v102, v102
	v_rcp_f32_e32 v103, v103
	v_rcp_f32_e32 v104, v104
	v_rcp_f32_e32 v105, v105
	s_nop 0
	v_pk_fma_f32 v[98:99], v[98:99], -2.0, 1.0 op_sel_hi:[1,0,0]
	v_pk_fma_f32 v[100:101], v[100:101], -2.0, 1.0 op_sel_hi:[1,0,0]
	v_pk_fma_f32 v[102:103], v[102:103], -2.0, 1.0 op_sel_hi:[1,0,0]
	v_pk_fma_f32 v[104:105], v[104:105], -2.0, 1.0 op_sel_hi:[1,0,0]
	s_mov_b64 exec, s[30:31]
	v_mul_f32_e32 v98, 0xbfb8aa3b, v98
	v_mul_f32_e32 v99, 0xbfb8aa3b, v99
	v_mul_f32_e32 v100, 0xbfb8aa3b, v100
	v_mul_f32_e32 v101, 0xbfb8aa3b, v101
	v_mul_f32_e32 v102, 0xbfb8aa3b, v102
	v_mul_f32_e32 v103, 0xbfb8aa3b, v103
	v_mul_f32_e32 v104, 0xbfb8aa3b, v104
	v_mul_f32_e32 v105, 0xbfb8aa3b, v105
	v_exp_f32_e32 v98, v98
	v_exp_f32_e32 v99, v99
	v_exp_f32_e32 v100, v100
	v_exp_f32_e32 v101, v101
	v_exp_f32_e32 v102, v102
	v_exp_f32_e32 v103, v103
	v_exp_f32_e32 v104, v104
	v_exp_f32_e32 v105, v105
	v_add_f32_e32 v98, 1.0, v98
	v_add_f32_e32 v99, 1.0, v99
	v_add_f32_e32 v100, 1.0, v100
	v_add_f32_e32 v101, 1.0, v101
	v_add_f32_e32 v102, 1.0, v102
	v_add_f32_e32 v103, 1.0, v103
	v_add_f32_e32 v104, 1.0, v104
	v_add_f32_e32 v105, 1.0, v105
	v_rcp_f32_e32 v98, v98
	v_rcp_f32_e32 v99, v99
	v_rcp_f32_e32 v100, v100
	v_rcp_f32_e32 v101, v101
	v_rcp_f32_e32 v102, v102
	v_rcp_f32_e32 v103, v103
	v_rcp_f32_e32 v104, v104
	v_rcp_f32_e32 v105, v105
	s_mov_b64 exec, s[36:37]
	s_nop 0
	v_cvt_pk_bf16_f32 v60, v98, v99
	v_cvt_pk_bf16_f32 v61, v100, v101
	v_cvt_pk_bf16_f32 v62, v102, v103
	v_cvt_pk_bf16_f32 v63, v104, v105
	global_store_dwordx4 v[124:125], v[60:63], off
.Lsh_end:
.LBB0_569:
	s_or_b64 exec, exec, s[52:53]
	s_mov_b64 s[0:1], 0

; DEV void attn_tile(const Params& p, int l, int tile, char* smem, bool do_store = true) {
;     ...
;     for (int ks = 0; ks < 4; ++ks) { kf0[ks] = *(const bf16x8*)(kp + ks * 32); kf1[ks] = *(const bf16x8*)(kp + 32 * KROW + ks * 32); }
;     f32x16 s0, s1;
; #pragma unroll
;     for (int e = 0; e < 16; ++e) { s0[e] = 0.f; s1[e] = 0.f; }
; #pragma unroll
;     for (int ks = 0; ks < 4; ++ks) s0 = __builtin_amdgcn_mfma_f32_32x32x16_bf16(kf0[ks], qf[ks], s0, 0, 0, 0);
; #pragma unroll
;     for (int ks = 0; ks < 4; ++ks) s1 = __builtin_amdgcn_mfma_f32_32x32x16_bf16(kf1[ks], qf[ks], s1, 0, 0, 0);
;     bf16x8 vf[8];
; #pragma unroll
;     for (int dt = 0; dt < 4; ++dt)
; #pragma unroll
;       for (int k2 = 0; k2 < 2; ++k2) vf[dt * 2 + k2] = *(const bf16x8*)(vp + dt * 32 * KROW + (k2 * 16) * 2);
;     float mx = fmaxf(s0[0], s1[0]);
; #pragma unroll
;     for (int e = 1; e < 16; ++e) mx = fmaxf(mx, fmaxf(s0[e], s1[e]));
;     mx = xor32_max(mx);
;     const float mnew = (mx > m + 8.f) ? mx : m;
;     if (__any(mnew > m)) {
;       const float alpha = __builtin_amdgcn_exp2f(m - mnew);
;       lsum *= alpha;
; #pragma unroll
;       for (int dt = 0; dt < 4; ++dt)
; #pragma unroll
;         for (int e = 0; e < 16; ++e) o[dt][e] *= alpha;
;     }
;     m = mnew;
;     bf16x8 pb0[2], pb1[2];
;     {
;       float pe[16];
; #pragma unroll
;       for (int e = 0; e < 16; ++e) { pe[e] = __builtin_amdgcn_exp2f(s0[e] - m); lsum += pe[e]; }
; #pragma unroll
;       for (int k2 = 0; k2 < 2; ++k2) {
;         u32x4 u;
;         u[0] = pk2(pe[8 * k2 + 0], pe[8 * k2 + 1]); u[1] = pk2(pe[8 * k2 + 2], pe[8 * k2 + 3]);
;         u[2] = pk2(pe[8 * k2 + 4], pe[8 * k2 + 5]); u[3] = pk2(pe[8 * k2 + 6], pe[8 * k2 + 7]);
;         pb0[k2] = __builtin_bit_cast(bf16x8, u);
;       }
;     }
; #pragma unroll
;     for (int dt = 0; dt < 4; ++dt)
; #pragma unroll
;       for (int k2 = 0; k2 < 2; ++k2) o[dt] = __builtin_amdgcn_mfma_f32_32x32x16_bf16(vf[dt * 2 + k2], pb0[k2], o[dt], 0, 0, 0);
.Latt_a3_qk:
	s_waitcnt lgkmcnt(6)
	v_mfma_f32_32x32x16_bf16 v[80:95], v[68:71], v[110:113], 0
	s_waitcnt lgkmcnt(5)
	v_mfma_f32_32x32x16_bf16 v[80:95], v[72:75], v[106:109], v[80:95]
	s_waitcnt lgkmcnt(3)
	v_mfma_f32_32x32x16_bf16 v[80:95], v[76:79], v[102:105], v[80:95]
	v_mfma_f32_32x32x16_bf16 v[64:79], v[64:67], v[110:113], 0
	v_mfma_f32_32x32x16_bf16 v[64:79], v[212:215], v[106:109], v[64:79]
	s_waitcnt lgkmcnt(2)
	v_mfma_f32_32x32x16_bf16 v[64:79], v[216:219], v[102:105], v[64:79]
	s_waitcnt lgkmcnt(1)
	v_mfma_f32_32x32x16_bf16 v[80:95], v[146:149], v[98:101], v[80:95]
	ds_read_b128 v[174:177], v205 offset:34816
	ds_read_b128 v[170:173], v205 offset:34848
	ds_read_b128 v[166:169], v205 offset:43520
	ds_read_b128 v[162:165], v205 offset:43552
	ds_read_b128 v[146:149], v205 offset:52224
	ds_read_b128 v[150:153], v205 offset:52256
	ds_read_b128 v[154:157], v205 offset:60928
	ds_read_b128 v[158:161], v205 offset:60960
	s_waitcnt lgkmcnt(8)
	v_mfma_f32_32x32x16_bf16 v[64:79], v[178:181], v[98:101], v[64:79]
	s_nop 1
	v_max3_f32 v178, v80, v81, v82
	v_max3_f32 v179, v83, v84, v85
	v_max3_f32 v180, v86, v87, v88
	v_max3_f32 v181, v89, v90, v91
	v_max3_f32 v178, v178, v92, v93
	v_max3_f32 v179, v179, v94, v95
	v_add_f32_e32 v241, 0x41000000, v208
	s_nop 2
	v_max3_f32 v180, v180, v64, v65
	v_max3_f32 v181, v181, v66, v67
	v_max3_f32 v178, v178, v68, v69
	v_max3_f32 v179, v179, v70, v71
	v_max3_f32 v180, v180, v72, v73
	v_max3_f32 v181, v181, v74, v75
	v_max3_f32 v178, v178, v76, v77
	v_max3_f32 v179, v179, v78, v79
	v_max3_f32 v178, v178, v179, v180
	v_max_f32_e32 v178, v178, v181
	v_mov_b32_e32 v179, v178
	s_nop 1
	v_permlane32_swap_b32_e32 v178, v179
	v_max_f32_e32 v178, v178, v179
	v_cmp_gt_f32_e32 vcc, v178, v241
	s_nop 1
	v_cndmask_b32_e32 v211, v208, v178, vcc
	s_cbranch_vccz .LBB0_602
	v_sub_f32_e32 v178, v208, v211
	v_exp_f32_e32 v178, v178
	s_nop 0
	v_pk_mul_f32 v[62:63], v[62:63], v[178:179] op_sel_hi:[1,0]
	v_pk_mul_f32 v[60:61], v[60:61], v[178:179] op_sel_hi:[1,0]
	v_pk_mul_f32 v[58:59], v[58:59], v[178:179] op_sel_hi:[1,0]
	v_pk_mul_f32 v[56:57], v[56:57], v[178:179] op_sel_hi:[1,0]
	v_pk_mul_f32 v[54:55], v[54:55], v[178:179] op_sel_hi:[1,0]
	v_pk_mul_f32 v[52:53], v[52:53], v[178:179] op_sel_hi:[1,0]
	v_pk_mul_f32 v[50:51], v[50:51], v[178:179] op_sel_hi:[1,0]
	v_pk_mul_f32 v[48:49], v[48:49], v[178:179] op_sel_hi:[1,0]
	v_pk_mul_f32 v[46:47], v[46:47], v[178:179] op_sel_hi:[1,0]
	v_pk_mul_f32 v[44:45], v[44:45], v[178:179] op_sel_hi:[1,0]
	v_pk_mul_f32 v[42:43], v[42:43], v[178:179] op_sel_hi:[1,0]
	v_pk_mul_f32 v[40:41], v[40:41], v[178:179] op_sel_hi:[1,0]
	v_pk_mul_f32 v[38:39], v[38:39], v[178:179] op_sel_hi:[1,0]
	v_pk_mul_f32 v[36:37], v[36:37], v[178:179] op_sel_hi:[1,0]
	v_pk_mul_f32 v[34:35], v[34:35], v[178:179] op_sel_hi:[1,0]
	v_pk_mul_f32 v[32:33], v[32:33], v[178:179] op_sel_hi:[1,0]
	v_pk_mul_f32 v[30:31], v[30:31], v[178:179] op_sel_hi:[1,0]
	v_pk_mul_f32 v[28:29], v[28:29], v[178:179] op_sel_hi:[1,0]
	v_pk_mul_f32 v[26:27], v[26:27], v[178:179] op_sel_hi:[1,0]
	v_pk_mul_f32 v[24:25], v[24:25], v[178:179] op_sel_hi:[1,0]
	v_pk_mul_f32 v[22:23], v[22:23], v[178:179] op_sel_hi:[1,0]
	v_pk_mul_f32 v[20:21], v[20:21], v[178:179] op_sel_hi:[1,0]
	v_pk_mul_f32 v[18:19], v[18:19], v[178:179] op_sel_hi:[1,0]
	v_pk_mul_f32 v[16:17], v[16:17], v[178:179] op_sel_hi:[1,0]
	v_pk_mul_f32 v[14:15], v[14:15], v[178:179] op_sel_hi:[1,0]
	v_pk_mul_f32 v[12:13], v[12:13], v[178:179] op_sel_hi:[1,0]
	v_pk_mul_f32 v[10:11], v[10:11], v[178:179] op_sel_hi:[1,0]
	v_pk_mul_f32 v[8:9], v[8:9], v[178:179] op_sel_hi:[1,0]
	v_pk_mul_f32 v[6:7], v[6:7], v[178:179] op_sel_hi:[1,0]
	v_pk_mul_f32 v[4:5], v[4:5], v[178:179] op_sel_hi:[1,0]
	v_pk_mul_f32 v[2:3], v[2:3], v[178:179] op_sel_hi:[1,0]
	v_pk_mul_f32 v[0:1], v[0:1], v[178:179] op_sel_hi:[1,0]
	v_mul_f32_e32 v209, v209, v178
.LBB0_602:
	v_sub_f32_e32 v80, v80, v211
	v_exp_f32_e32 v178, v80
	v_sub_f32_e32 v80, v81, v211
	v_exp_f32_e32 v179, v80
	v_sub_f32_e32 v80, v82, v211
	v_exp_f32_e32 v180, v80
	v_sub_f32_e32 v80, v83, v211
	v_exp_f32_e32 v181, v80
	v_sub_f32_e32 v80, v84, v211
	v_exp_f32_e32 v208, v80
	v_sub_f32_e32 v80, v85, v211
	v_exp_f32_e32 v212, v80
	v_sub_f32_e32 v80, v86, v211
	v_exp_f32_e32 v213, v80
	v_sub_f32_e32 v80, v87, v211
	v_exp_f32_e32 v214, v80
	v_sub_f32_e32 v80, v88, v211
	v_exp_f32_e32 v88, v80
	v_sub_f32_e32 v80, v89, v211
	v_exp_f32_e32 v89, v80
	v_sub_f32_e32 v80, v90, v211
	v_exp_f32_e32 v90, v80
	v_sub_f32_e32 v80, v91, v211
	v_exp_f32_e32 v91, v80
	v_sub_f32_e32 v80, v92, v211
	v_exp_f32_e32 v92, v80
	v_sub_f32_e32 v80, v93, v211
	v_exp_f32_e32 v93, v80
	v_sub_f32_e32 v80, v94, v211
	v_exp_f32_e32 v94, v80
	v_sub_f32_e32 v80, v95, v211
	v_exp_f32_e32 v215, v80
	v_cvt_pk_bf16_f32 v80, v178, v179
	v_cvt_pk_bf16_f32 v81, v180, v181
	v_cvt_pk_bf16_f32 v82, v208, v212
	v_cvt_pk_bf16_f32 v83, v213, v214
	v_add_f32_e32 v95, v178, v209
	v_add_f32_e32 v95, v179, v95
	s_waitcnt lgkmcnt(5)
	v_mfma_f32_32x32x16_bf16 v[32:47], v[166:169], v[80:83], v[32:47]
	v_add_f32_e32 v95, v180, v95
	v_add_f32_e32 v95, v181, v95
	v_add_f32_e32 v95, v208, v95
	v_add_f32_e32 v95, v212, v95
	v_cvt_pk_bf16_f32 v84, v88, v89
	v_cvt_pk_bf16_f32 v85, v90, v91
	v_cvt_pk_bf16_f32 v86, v92, v93
	v_cvt_pk_bf16_f32 v87, v94, v215
	v_add_f32_e32 v95, v213, v95
	v_mfma_f32_32x32x16_bf16 v[48:63], v[174:177], v[80:83], v[48:63]
	v_sub_f32_e32 v64, v64, v211
	v_add_f32_e32 v95, v214, v95
	v_add_f32_e32 v88, v88, v95
	v_add_f32_e32 v88, v89, v88
	v_add_f32_e32 v88, v90, v88
	v_add_f32_e32 v88, v91, v88
	v_add_f32_e32 v88, v92, v88
	s_waitcnt lgkmcnt(4)
; DEV void attn_tile(const Params& p, int l, int tile, char* smem, bool do_store = true) {
;     ...
;     for (int ks = 0; ks < 4; ++ks) { kf0[ks] = *(const bf16x8*)(kp + ks * 32); kf1[ks] = *(const bf16x8*)(kp + 32 * KROW + ks * 32); }
;     f32x16 s0, s1;
; #pragma unroll
;     for (int e = 0; e < 16; ++e) { s0[e] = 0.f; s1[e] = 0.f; }
; #pragma unroll
;     for (int ks = 0; ks < 4; ++ks) s0 = __builtin_amdgcn_mfma_f32_32x32x16_bf16(kf0[ks], qf[ks], s0, 0, 0, 0);
; #pragma unroll
;     for (int ks = 0; ks < 4; ++ks) s1 = __builtin_amdgcn_mfma_f32_32x32x16_bf16(kf1[ks], qf[ks], s1, 0, 0, 0);
;     bf16x8 vf[8];
; #pragma unroll
;     for (int dt = 0; dt < 4; ++dt)
; #pragma unroll
;       for (int k2 = 0; k2 < 2; ++k2) vf[dt * 2 + k2] = *(const bf16x8*)(vp + dt * 32 * KROW + (k2 * 16) * 2);
;     float mx = fmaxf(s0[0], s1[0]);
; #pragma unroll
;     for (int e = 1; e < 16; ++e) mx = fmaxf(mx, fmaxf(s0[e], s1[e]));
;     mx = xor32_max(mx);
;     const float mnew = (mx > m + 8.f) ? mx : m;
;     if (__any(mnew > m)) {
;       const float alpha = __builtin_amdgcn_exp2f(m - mnew);
;       lsum *= alpha;
; #pragma unroll
;       for (int dt = 0; dt < 4; ++dt)
; #pragma unroll
;         for (int e = 0; e < 16; ++e) o[dt][e] *= alpha;
;     }
;     m = mnew;
;     bf16x8 pb0[2], pb1[2];
;     {
;       float pe[16];
; #pragma unroll
;       for (int e = 0; e < 16; ++e) { pe[e] = __builtin_amdgcn_exp2f(s0[e] - m); lsum += pe[e]; }
; #pragma unroll
;       for (int k2 = 0; k2 < 2; ++k2) {
;         u32x4 u;
;         u[0] = pk2(pe[8 * k2 + 0], pe[8 * k2 + 1]); u[1] = pk2(pe[8 * k2 + 2], pe[8 * k2 + 3]);
;         u[2] = pk2(pe[8 * k2 + 4], pe[8 * k2 + 5]); u[3] = pk2(pe[8 * k2 + 6], pe[8 * k2 + 7]);
;         pb0[k2] = __builtin_bit_cast(bf16x8, u);
;       }
;     }
; #pragma unroll
;     for (int dt = 0; dt < 4; ++dt)
; #pragma unroll
;       for (int k2 = 0; k2 < 2; ++k2) o[dt] = __builtin_amdgcn_mfma_f32_32x32x16_bf16(vf[dt * 2 + k2], pb0[k2], o[dt], 0, 0, 0);
; #pragma unroll
;     for (int dt = 0; dt < 4; ++dt)
; #pragma unroll
;       for (int k2 = 0; k2 < 2; ++k2) vf[dt * 2 + k2] = *(const bf16x8*)(vp + dt * 32 * KROW + (32 + k2 * 16) * 2);
;     {
;       float pe[16];
; #pragma unroll
;       for (int e = 0; e < 16; ++e) { pe[e] = __builtin_amdgcn_exp2f(s1[e] - m); lsum += pe[e]; }
; #pragma unroll
;       for (int k2 = 0; k2 < 2; ++k2) {
;         u32x4 u;
	v_mfma_f32_32x32x16_bf16 v[32:47], v[162:165], v[84:87], v[32:47]
	v_exp_f32_e32 v163, v64
	v_sub_f32_e32 v64, v65, v211
	v_exp_f32_e32 v164, v64
	v_sub_f32_e32 v64, v66, v211
	v_exp_f32_e32 v165, v64
	v_sub_f32_e32 v64, v67, v211
	v_exp_f32_e32 v166, v64
	s_waitcnt lgkmcnt(3)
	v_mfma_f32_32x32x16_bf16 v[16:31], v[146:149], v[80:83], v[16:31]
	v_sub_f32_e32 v64, v68, v211
	v_exp_f32_e32 v167, v64
	v_sub_f32_e32 v64, v69, v211
	v_exp_f32_e32 v168, v64
	v_sub_f32_e32 v64, v70, v211
	v_add_f32_e32 v88, v93, v88
	v_exp_f32_e32 v169, v64
	s_waitcnt lgkmcnt(1)
	v_mfma_f32_32x32x16_bf16 v[0:15], v[154:157], v[80:83], v[0:15]
	v_sub_f32_e32 v64, v71, v211
	v_add_f32_e32 v178, v94, v88
	v_add_f32_e32 v162, v215, v178
	v_add_f32_e32 v162, v163, v162
	v_add_f32_e32 v162, v164, v162
	v_add_f32_e32 v162, v165, v162
	v_add_f32_e32 v162, v166, v162
	v_mfma_f32_32x32x16_bf16 v[48:63], v[170:173], v[84:87], v[48:63]
	v_exp_f32_e32 v170, v64
	v_sub_f32_e32 v64, v72, v211
	v_exp_f32_e32 v72, v64
	v_sub_f32_e32 v64, v73, v211
	v_exp_f32_e32 v73, v64
	v_sub_f32_e32 v64, v74, v211
	v_exp_f32_e32 v74, v64
	v_mfma_f32_32x32x16_bf16 v[16:31], v[150:153], v[84:87], v[16:31]
	v_sub_f32_e32 v64, v75, v211
	v_exp_f32_e32 v75, v64
	v_sub_f32_e32 v64, v76, v211
	v_exp_f32_e32 v76, v64
	v_sub_f32_e32 v64, v77, v211
	v_exp_f32_e32 v77, v64
	v_sub_f32_e32 v64, v78, v211
	s_waitcnt lgkmcnt(0)
	v_mfma_f32_32x32x16_bf16 v[0:15], v[158:161], v[84:87], v[0:15]
	ds_read_b128 v[80:83], v205 offset:34880
	ds_read_b128 v[84:87], v205 offset:34912
	ds_read_b128 v[88:91], v205 offset:43584
	ds_read_b128 v[92:95], v205 offset:43616
	ds_read_b128 v[146:149], v205 offset:52288
	ds_read_b128 v[150:153], v205 offset:52320
	ds_read_b128 v[154:157], v205 offset:60992
	ds_read_b128 v[158:161], v205 offset:61024
	v_add_f32_e32 v162, v167, v162
	v_exp_f32_e32 v78, v64
	v_sub_f32_e32 v64, v79, v211
	v_add_f32_e32 v162, v168, v162
	v_exp_f32_e32 v79, v64
	v_cvt_pk_bf16_f32 v64, v163, v164
	v_cvt_pk_bf16_f32 v65, v165, v166
	v_cvt_pk_bf16_f32 v66, v167, v168
	v_cvt_pk_bf16_f32 v67, v169, v170
	v_add_f32_e32 v162, v169, v162
	v_add_f32_e32 v162, v170, v162
	s_waitcnt lgkmcnt(7)
	v_mfma_f32_32x32x16_bf16 v[48:63], v[80:83], v[64:67], v[48:63]
	v_cvt_pk_bf16_f32 v68, v72, v73
	v_add_f32_e32 v72, v72, v162
	v_add_f32_e32 v72, v73, v72
	v_add_f32_e32 v72, v74, v72
	v_add_f32_e32 v72, v75, v72
	v_add_f32_e32 v72, v76, v72
	v_add_f32_e32 v72, v77, v72
	s_waitcnt lgkmcnt(5)
	v_mfma_f32_32x32x16_bf16 v[32:47], v[88:91], v[64:67], v[32:47]
	v_cvt_pk_bf16_f32 v69, v74, v75
	v_cvt_pk_bf16_f32 v70, v76, v77
	v_cvt_pk_bf16_f32 v71, v78, v79
	v_add_f32_e32 v72, v78, v72
	v_add_f32_e32 v209, v79, v72
	s_waitcnt lgkmcnt(3)
	v_mfma_f32_32x32x16_bf16 v[16:31], v[146:149], v[64:67], v[16:31]
	s_waitcnt lgkmcnt(1)
	v_mfma_f32_32x32x16_bf16 v[0:15], v[154:157], v[64:67], v[0:15]
	v_mfma_f32_32x32x16_bf16 v[48:63], v[84:87], v[68:71], v[48:63]
	v_mfma_f32_32x32x16_bf16 v[32:47], v[92:95], v[68:71], v[32:47]
	v_mfma_f32_32x32x16_bf16 v[16:31], v[150:153], v[68:71], v[16:31]
	s_waitcnt lgkmcnt(0)
	v_mfma_f32_32x32x16_bf16 v[0:15], v[158:161], v[68:71], v[0:15]
	ds_read_b128 v[64:67], v210 offset:26112
	ds_read_b128 v[68:71], v210 offset:17408
	ds_read_b128 v[72:75], v210 offset:17440
	ds_read_b128 v[212:215], v210 offset:26144
	ds_read_b128 v[76:79], v210 offset:17472
	ds_read_b128 v[216:219], v210 offset:26176
	ds_read_b128 v[146:149], v210 offset:17504
	ds_read_b128 v[178:181], v210 offset:26208
	s_waitcnt lgkmcnt(6)
	v_mfma_f32_32x32x16_bf16 v[80:95], v[68:71], v[110:113], 0
	s_waitcnt lgkmcnt(5)
	v_mfma_f32_32x32x16_bf16 v[80:95], v[72:75], v[106:109], v[80:95]
	s_waitcnt lgkmcnt(3)
	v_mfma_f32_32x32x16_bf16 v[80:95], v[76:79], v[102:105], v[80:95]
	v_mfma_f32_32x32x16_bf16 v[64:79], v[64:67], v[110:113], 0
	v_mfma_f32_32x32x16_bf16 v[64:79], v[212:215], v[106:109], v[64:79]
	s_waitcnt lgkmcnt(2)
	v_mfma_f32_32x32x16_bf16 v[64:79], v[216:219], v[102:105], v[64:79]
	s_waitcnt lgkmcnt(1)
	v_mfma_f32_32x32x16_bf16 v[80:95], v[146:149], v[98:101], v[80:95]
	ds_read_b128 v[174:177], v205 offset:34944
	ds_read_b128 v[170:173], v205 offset:34976
	ds_read_b128 v[166:169], v205 offset:43648
	ds_read_b128 v[162:165], v205 offset:43680
	ds_read_b128 v[146:149], v205 offset:52352
	ds_read_b128 v[150:153], v205 offset:52384
	ds_read_b128 v[154:157], v205 offset:61056
	ds_read_b128 v[158:161], v205 offset:61088
	s_waitcnt lgkmcnt(8)
	v_mfma_f32_32x32x16_bf16 v[64:79], v[178:181], v[98:101], v[64:79]
	s_nop 1
	v_max3_f32 v178, v80, v81, v82
	v_max3_f32 v179, v83, v84, v85
	v_max3_f32 v180, v86, v87, v88
	v_max3_f32 v181, v89, v90, v91
	v_max3_f32 v178, v178, v92, v93
	v_max3_f32 v179, v179, v94, v95
	v_add_f32_e32 v241, 0x41000000, v211
	s_nop 2
	v_max3_f32 v180, v180, v64, v65
	v_max3_f32 v181, v181, v66, v67
	v_max3_f32 v178, v178, v68, v69
	v_max3_f32 v179, v179, v70, v71
	v_max3_f32 v180, v180, v72, v73
	v_max3_f32 v181, v181, v74, v75
	v_max3_f32 v178, v178, v76, v77
	v_max3_f32 v179, v179, v78, v79
	v_max3_f32 v178, v178, v179, v180
	v_max_f32_e32 v178, v178, v181
	v_mov_b32_e32 v179, v178
	s_nop 1
	v_permlane32_swap_b32_e32 v178, v179
	v_max_f32_e32 v178, v178, v179
	v_cmp_gt_f32_e32 vcc, v178, v241
	s_nop 1
	v_cndmask_b32_e32 v208, v211, v178, vcc
	s_cbranch_vccz .LBB0_599
; DEV void attn_tile(const Params& p, int l, int tile, char* smem, bool do_store = true) {
;     ...
;     if (__any(mnew > m)) {
;       const float alpha = __builtin_amdgcn_exp2f(m - mnew);
;       lsum *= alpha;
; #pragma unroll
;       for (int dt = 0; dt < 4; ++dt)
; #pragma unroll
;         for (int e = 0; e < 16; ++e) o[dt][e] *= alpha;
;     }
	v_sub_f32_e32 v178, v211, v208
	v_exp_f32_e32 v178, v178
	s_nop 0
	v_pk_mul_f32 v[62:63], v[62:63], v[178:179] op_sel_hi:[1,0]
	v_pk_mul_f32 v[60:61], v[60:61], v[178:179] op_sel_hi:[1,0]
	v_pk_mul_f32 v[58:59], v[58:59], v[178:179] op_sel_hi:[1,0]
	v_pk_mul_f32 v[56:57], v[56:57], v[178:179] op_sel_hi:[1,0]
	v_pk_mul_f32 v[54:55], v[54:55], v[178:179] op_sel_hi:[1,0]
	v_pk_mul_f32 v[52:53], v[52:53], v[178:179] op_sel_hi:[1,0]
	v_pk_mul_f32 v[50:51], v[50:51], v[178:179] op_sel_hi:[1,0]
	v_pk_mul_f32 v[48:49], v[48:49], v[178:179] op_sel_hi:[1,0]
	v_pk_mul_f32 v[46:47], v[46:47], v[178:179] op_sel_hi:[1,0]
	v_pk_mul_f32 v[44:45], v[44:45], v[178:179] op_sel_hi:[1,0]
	v_pk_mul_f32 v[42:43], v[42:43], v[178:179] op_sel_hi:[1,0]
	v_pk_mul_f32 v[40:41], v[40:41], v[178:179] op_sel_hi:[1,0]
	v_pk_mul_f32 v[38:39], v[38:39], v[178:179] op_sel_hi:[1,0]
	v_pk_mul_f32 v[36:37], v[36:37], v[178:179] op_sel_hi:[1,0]
	v_pk_mul_f32 v[34:35], v[34:35], v[178:179] op_sel_hi:[1,0]
	v_pk_mul_f32 v[32:33], v[32:33], v[178:179] op_sel_hi:[1,0]
	v_pk_mul_f32 v[30:31], v[30:31], v[178:179] op_sel_hi:[1,0]
	v_pk_mul_f32 v[28:29], v[28:29], v[178:179] op_sel_hi:[1,0]
	v_pk_mul_f32 v[26:27], v[26:27], v[178:179] op_sel_hi:[1,0]
	v_pk_mul_f32 v[24:25], v[24:25], v[178:179] op_sel_hi:[1,0]
	v_pk_mul_f32 v[22:23], v[22:23], v[178:179] op_sel_hi:[1,0]
	v_pk_mul_f32 v[20:21], v[20:21], v[178:179] op_sel_hi:[1,0]
	v_pk_mul_f32 v[18:19], v[18:19], v[178:179] op_sel_hi:[1,0]
	v_pk_mul_f32 v[16:17], v[16:17], v[178:179] op_sel_hi:[1,0]
	v_pk_mul_f32 v[14:15], v[14:15], v[178:179] op_sel_hi:[1,0]
	v_pk_mul_f32 v[12:13], v[12:13], v[178:179] op_sel_hi:[1,0]
	v_pk_mul_f32 v[10:11], v[10:11], v[178:179] op_sel_hi:[1,0]
	v_pk_mul_f32 v[8:9], v[8:9], v[178:179] op_sel_hi:[1,0]
	v_pk_mul_f32 v[6:7], v[6:7], v[178:179] op_sel_hi:[1,0]
	v_pk_mul_f32 v[4:5], v[4:5], v[178:179] op_sel_hi:[1,0]
	v_pk_mul_f32 v[2:3], v[2:3], v[178:179] op_sel_hi:[1,0]
	v_pk_mul_f32 v[0:1], v[0:1], v[178:179] op_sel_hi:[1,0]
	v_mul_f32_e32 v209, v209, v178
	s_branch .LBB0_599

; #define PG8_STAGE(bufoff, gbase, voff) do { _Pragma("unroll") for (int _i = 0; _i < 2; ++_i) \
;         __builtin_amdgcn_global_load_lds((const unsigned*)((const char*)(gbase) + (voff)[_i]), (PG8_LAS unsigned*)(lds + (bufoff) + ldsw + _i * 8192), 16, 0, 0); } while (0)
; #define PG8_LDA(dst, b, h) do { _Pragma("unroll") for (int m = 0; m < 4; ++m) _Pragma("unroll") for (int k = 0; k < 2; ++k) dst[m][k] = *(const PG8_LAS bf16x8*)(lds + PG8_SA(b, h) + aoff + m * 2048 + k * 1024); } while (0)
; #define PG8_LDB(dst, b, h) do { _Pragma("unroll") for (int n = 0; n < 2; ++n) _Pragma("unroll") for (int k = 0; k < 2; ++k) dst[n][k] = *(const PG8_LAS bf16x8*)(lds + PG8_SB(b, h) + boff + n * 2048 + k * 1024); } while (0)
; #define PG8_MMA(ai, bj, At, Bt) do { __builtin_amdgcn_s_setprio(1); _Pragma("unroll") for (int m = 0; m < 4; ++m) _Pragma("unroll") for (int n = 0; n < 2; ++n) _Pragma("unroll") for (int k = 0; k < 2; ++k) \
;         acc[ai][bj][m][n] = __builtin_amdgcn_mfma_f32_16x16x32_bf16(Bt[n][k], At[m][k], acc[ai][bj][m][n], 0, 0, 0); __builtin_amdgcn_s_setprio(0); } while (0)
; #define PG8_WAIT_V(n) asm volatile("s_waitcnt vmcnt(" #n ")" ::: "memory")
; #define PG8_WAIT_L(n) asm volatile("s_waitcnt lgkmcnt(" #n ")" ::: "memory")
; #define PG8_BAR __builtin_amdgcn_s_barrier()
; #define PG8_SCHED __builtin_amdgcn_sched_barrier(0)
; template <class Epi, class Sched>
; __device__ __forceinline__ void gemm_phase(PG8_LAS unsigned char* lds, const Gemm g, const Sched& S, const Epi& E) {
;     ...
;             PG8_LDB(B0, 0, 0); PG8_SCHED; PG8_LDA(At, 0, 0); PG8_STAGE(PG8_SA(1, 1), a1 + hstep, voffA);
;             PG8_WAIT_L(8); PG8_BAR; PG8_WAIT_L(0); PG8_MMA(0, 0, At, B0); PG8_BAR; PG8_SCHED;
;             PG8_LDB(B1, 0, 1); PG8_STAGE(PG8_SB(0, 0), b2, voffB);
;             PG8_BAR; PG8_WAIT_L(0); PG8_MMA(0, 1, At, B1); PG8_BAR;
;             PG8_LDA(At, 0, 1); PG8_STAGE(PG8_SA(0, 0), a2, voffA);
;             PG8_BAR; PG8_WAIT_L(0); PG8_MMA(1, 0, At, B0); PG8_BAR; PG8_SCHED;
;             PG8_STAGE(PG8_SB(0, 1), b2 + hstep, voffB);
;             PG8_WAIT_V(6); PG8_BAR; PG8_MMA(1, 1, At, B1); PG8_BAR;
.Lgp_21593:
.LBB0_654:
	s_add_u32 s30, s0, 0xfffc0080
	s_addc_u32 s31, s1, -1
	s_add_i32 s62, 0, 0x10000
	v_add_u32_e32 v96, s62, v162
	ds_read_b128 v[144:147], v96
	ds_read_b128 v[148:151], v96 offset:1024
	ds_read_b128 v[152:155], v96 offset:2048
	ds_read_b128 v[156:159], v96 offset:3072
	s_cmp_eq_u32 s61, 12
	s_cselect_b32 s49, s43, s31
	s_cselect_b32 s48, s57, s30
	s_cselect_b32 s31, s41, s60
	s_cselect_b32 s30, s58, s59
	v_lshl_add_u64 v[160:161], s[0:1], 0, v[140:141]
	s_add_i32 m0, s52, 0xc000
	ds_read_b128 v[170:173], v168
	ds_read_b128 v[174:177], v168 offset:1024
	ds_read_b128 v[178:181], v168 offset:2048
	ds_read_b128 v[182:185], v168 offset:3072
	ds_read_b128 v[186:189], v168 offset:4096
	ds_read_b128 v[190:193], v168 offset:5120
	ds_read_b128 v[194:197], v168 offset:6144
	ds_read_b128 v[198:201], v168 offset:7168
	global_load_lds_dwordx4 v[160:161], off
	v_lshl_add_u64 v[160:161], s[0:1], 0, v[142:143]
	s_add_i32 m0, s52, 0xe000
	s_nop 0
	global_load_lds_dwordx4 v[160:161], off
	s_waitcnt lgkmcnt(8)
	s_barrier
	s_waitcnt lgkmcnt(0)
	v_mfma_f32_16x16x32_bf16 v[126:129], v[144:147], v[170:173], v[126:129]
	v_mfma_f32_16x16x32_bf16 v[118:121], v[152:155], v[170:173], v[118:121]
	v_mfma_f32_16x16x32_bf16 v[110:113], v[144:147], v[178:181], v[110:113]
	v_mfma_f32_16x16x32_bf16 v[102:105], v[152:155], v[178:181], v[102:105]
	v_mfma_f32_16x16x32_bf16 v[92:95], v[144:147], v[186:189], v[92:95]
	v_mfma_f32_16x16x32_bf16 v[84:87], v[152:155], v[186:189], v[84:87]
	v_mfma_f32_16x16x32_bf16 v[76:79], v[144:147], v[194:197], v[76:79]
	v_mfma_f32_16x16x32_bf16 v[68:71], v[152:155], v[194:197], v[68:71]
	v_mfma_f32_16x16x32_bf16 v[126:129], v[148:151], v[174:177], v[126:129]
	v_mfma_f32_16x16x32_bf16 v[118:121], v[156:159], v[174:177], v[118:121]
	v_mfma_f32_16x16x32_bf16 v[110:113], v[148:151], v[182:185], v[110:113]
	v_mfma_f32_16x16x32_bf16 v[102:105], v[156:159], v[182:185], v[102:105]
	v_mfma_f32_16x16x32_bf16 v[92:95], v[148:151], v[190:193], v[92:95]
	v_mfma_f32_16x16x32_bf16 v[84:87], v[156:159], v[190:193], v[84:87]
	v_mfma_f32_16x16x32_bf16 v[76:79], v[148:151], v[198:201], v[76:79]
	v_mfma_f32_16x16x32_bf16 v[68:71], v[156:159], v[198:201], v[68:71]
	s_barrier
	s_add_i32 s64, 0, 0x14000
	s_add_i32 s62, s62, s51
	v_add_u32_e32 v96, s64, v162
	v_lshl_add_u64 v[160:161], s[30:31], 0, v[134:135]
	s_mov_b32 m0, s62
	ds_read_b128 v[202:205], v96
	ds_read_b128 v[208:211], v96 offset:1024
	ds_read_b128 v[212:215], v96 offset:2048
	ds_read_b128 v[216:219], v96 offset:3072
	global_load_lds_dwordx4 v[160:161], off
	v_lshl_add_u64 v[220:221], s[30:31], 0, v[130:131]
	s_add_i32 m0, s62, 0x2000
	s_nop 0
	global_load_lds_dwordx4 v[220:221], off
	s_barrier
	s_waitcnt lgkmcnt(0)
	v_mfma_f32_16x16x32_bf16 v[122:125], v[202:205], v[170:173], v[122:125]
	v_mfma_f32_16x16x32_bf16 v[114:117], v[212:215], v[170:173], v[114:117]
	v_mfma_f32_16x16x32_bf16 v[106:109], v[202:205], v[178:181], v[106:109]
	v_mfma_f32_16x16x32_bf16 v[98:101], v[212:215], v[178:181], v[98:101]
	v_mfma_f32_16x16x32_bf16 v[88:91], v[202:205], v[186:189], v[88:91]
	v_mfma_f32_16x16x32_bf16 v[80:83], v[212:215], v[186:189], v[80:83]
	v_mfma_f32_16x16x32_bf16 v[72:75], v[202:205], v[194:197], v[72:75]
	v_mfma_f32_16x16x32_bf16 v[64:67], v[212:215], v[194:197], v[64:67]
	v_mfma_f32_16x16x32_bf16 v[122:125], v[208:211], v[174:177], v[122:125]
	v_mfma_f32_16x16x32_bf16 v[114:117], v[216:219], v[174:177], v[114:117]
	v_mfma_f32_16x16x32_bf16 v[106:109], v[208:211], v[182:185], v[106:109]
	v_mfma_f32_16x16x32_bf16 v[98:101], v[216:219], v[182:185], v[98:101]
	v_mfma_f32_16x16x32_bf16 v[88:91], v[208:211], v[190:193], v[88:91]
	v_mfma_f32_16x16x32_bf16 v[80:83], v[216:219], v[190:193], v[80:83]
	v_mfma_f32_16x16x32_bf16 v[72:75], v[208:211], v[198:201], v[72:75]
	v_mfma_f32_16x16x32_bf16 v[64:67], v[216:219], v[198:201], v[64:67]
	s_mov_b32 m0, s52
	v_lshl_add_u64 v[222:223], s[48:49], 0, v[136:137]
	s_barrier
	ds_read_b128 v[170:173], v168 offset:16384
	ds_read_b128 v[174:177], v168 offset:17408
	ds_read_b128 v[178:181], v168 offset:18432
	ds_read_b128 v[182:185], v168 offset:19456
	ds_read_b128 v[186:189], v168 offset:20480
	ds_read_b128 v[190:193], v168 offset:21504
	ds_read_b128 v[194:197], v168 offset:22528
	ds_read_b128 v[198:201], v168 offset:23552
	global_load_lds_dwordx4 v[222:223], off
	v_lshl_add_u64 v[224:225], s[48:49], 0, v[132:133]
	s_mov_b32 m0, s53
	s_nop 0
	global_load_lds_dwordx4 v[224:225], off
	s_barrier
	s_waitcnt lgkmcnt(0)
	v_mfma_f32_16x16x32_bf16 v[60:63], v[144:147], v[170:173], v[60:63]
	v_mfma_f32_16x16x32_bf16 v[52:55], v[152:155], v[170:173], v[52:55]
	v_mfma_f32_16x16x32_bf16 v[44:47], v[144:147], v[178:181], v[44:47]
	v_mfma_f32_16x16x32_bf16 v[36:39], v[152:155], v[178:181], v[36:39]
	v_mfma_f32_16x16x32_bf16 v[28:31], v[144:147], v[186:189], v[28:31]
	v_mfma_f32_16x16x32_bf16 v[20:23], v[152:155], v[186:189], v[20:23]
	v_mfma_f32_16x16x32_bf16 v[12:15], v[144:147], v[194:197], v[12:15]
	v_mfma_f32_16x16x32_bf16 v[4:7], v[152:155], v[194:197], v[4:7]
	v_mfma_f32_16x16x32_bf16 v[60:63], v[148:151], v[174:177], v[60:63]
	v_mfma_f32_16x16x32_bf16 v[52:55], v[156:159], v[174:177], v[52:55]
	v_mfma_f32_16x16x32_bf16 v[44:47], v[148:151], v[182:185], v[44:47]
	v_mfma_f32_16x16x32_bf16 v[36:39], v[156:159], v[182:185], v[36:39]
	v_mfma_f32_16x16x32_bf16 v[28:31], v[148:151], v[190:193], v[28:31]
	v_mfma_f32_16x16x32_bf16 v[20:23], v[156:159], v[190:193], v[20:23]
	v_mfma_f32_16x16x32_bf16 v[12:15], v[148:151], v[198:201], v[12:15]
	v_mfma_f32_16x16x32_bf16 v[4:7], v[156:159], v[198:201], v[4:7]
	s_barrier
; #define PG8_STAGE(bufoff, gbase, voff) do { _Pragma("unroll") for (int _i = 0; _i < 2; ++_i) \
;         __builtin_amdgcn_global_load_lds((const unsigned*)((const char*)(gbase) + (voff)[_i]), (PG8_LAS unsigned*)(lds + (bufoff) + ldsw + _i * 8192), 16, 0, 0); } while (0)
; #define PG8_LDA(dst, b, h) do { _Pragma("unroll") for (int m = 0; m < 4; ++m) _Pragma("unroll") for (int k = 0; k < 2; ++k) dst[m][k] = *(const PG8_LAS bf16x8*)(lds + PG8_SA(b, h) + aoff + m * 2048 + k * 1024); } while (0)
; #define PG8_LDB(dst, b, h) do { _Pragma("unroll") for (int n = 0; n < 2; ++n) _Pragma("unroll") for (int k = 0; k < 2; ++k) dst[n][k] = *(const PG8_LAS bf16x8*)(lds + PG8_SB(b, h) + boff + n * 2048 + k * 1024); } while (0)
; #define PG8_MMA(ai, bj, At, Bt) do { __builtin_amdgcn_s_setprio(1); _Pragma("unroll") for (int m = 0; m < 4; ++m) _Pragma("unroll") for (int n = 0; n < 2; ++n) _Pragma("unroll") for (int k = 0; k < 2; ++k) \
;         acc[ai][bj][m][n] = __builtin_amdgcn_mfma_f32_16x16x32_bf16(Bt[n][k], At[m][k], acc[ai][bj][m][n], 0, 0, 0); __builtin_amdgcn_s_setprio(0); } while (0)
; #define PG8_WAIT_V(n) asm volatile("s_waitcnt vmcnt(" #n ")" ::: "memory")
; #define PG8_WAIT_L(n) asm volatile("s_waitcnt lgkmcnt(" #n ")" ::: "memory")
; #define PG8_BAR __builtin_amdgcn_s_barrier()
; #define PG8_SCHED __builtin_amdgcn_sched_barrier(0)
; template <class Epi, class Sched>
; __device__ __forceinline__ void gemm_phase(PG8_LAS unsigned char* lds, const Gemm g, const Sched& S, const Epi& E) {
;     ...
;             PG8_WAIT_V(6); PG8_BAR; PG8_MMA(1, 1, At, B1); PG8_BAR;
;             PG8_LDB(B0, 1, 0); PG8_SCHED; PG8_LDA(At, 1, 0); PG8_STAGE(PG8_SA(0, 1), a2 + hstep, voffA);
;             PG8_WAIT_L(8); PG8_BAR; PG8_WAIT_L(0); PG8_MMA(0, 0, At, B0); PG8_BAR; PG8_SCHED;
;             PG8_LDB(B1, 1, 1); PG8_STAGE(PG8_SB(1, 0), b3, voffB);
;             PG8_BAR; PG8_WAIT_L(0); PG8_MMA(0, 1, At, B1); PG8_BAR;
;             PG8_LDA(At, 1, 1); PG8_STAGE(PG8_SA(1, 0), a3, voffA);
;             PG8_BAR; PG8_WAIT_L(0); PG8_MMA(1, 0, At, B0); PG8_BAR; PG8_SCHED;
	s_add_u32 s62, s30, 0x40000
	s_addc_u32 s63, s31, 0
	s_add_i32 s64, s64, s51
	v_lshl_add_u64 v[144:145], s[62:63], 0, v[134:135]
	s_mov_b32 m0, s64
	s_nop 0
	global_load_lds_dwordx4 v[144:145], off
	v_lshl_add_u64 v[144:145], s[62:63], 0, v[130:131]
	s_add_i32 m0, s64, 0x2000
	s_nop 0
	global_load_lds_dwordx4 v[144:145], off
	s_waitcnt vmcnt(6)
	s_barrier
	v_mfma_f32_16x16x32_bf16 v[56:59], v[202:205], v[170:173], v[56:59]
	v_mfma_f32_16x16x32_bf16 v[48:51], v[212:215], v[170:173], v[48:51]
	v_mfma_f32_16x16x32_bf16 v[40:43], v[202:205], v[178:181], v[40:43]
	v_mfma_f32_16x16x32_bf16 v[32:35], v[212:215], v[178:181], v[32:35]
	v_mfma_f32_16x16x32_bf16 v[24:27], v[202:205], v[186:189], v[24:27]
	v_mfma_f32_16x16x32_bf16 v[16:19], v[212:215], v[186:189], v[16:19]
	v_mfma_f32_16x16x32_bf16 v[8:11], v[202:205], v[194:197], v[8:11]
	v_mfma_f32_16x16x32_bf16 v[0:3], v[212:215], v[194:197], v[0:3]
	v_mfma_f32_16x16x32_bf16 v[56:59], v[208:211], v[174:177], v[56:59]
	v_mfma_f32_16x16x32_bf16 v[48:51], v[216:219], v[174:177], v[48:51]
	v_mfma_f32_16x16x32_bf16 v[40:43], v[208:211], v[182:185], v[40:43]
	v_mfma_f32_16x16x32_bf16 v[32:35], v[216:219], v[182:185], v[32:35]
	v_mfma_f32_16x16x32_bf16 v[24:27], v[208:211], v[190:193], v[24:27]
	v_mfma_f32_16x16x32_bf16 v[16:19], v[216:219], v[190:193], v[16:19]
	v_mfma_f32_16x16x32_bf16 v[8:11], v[208:211], v[198:201], v[8:11]
	v_mfma_f32_16x16x32_bf16 v[0:3], v[216:219], v[198:201], v[0:3]
	s_add_i32 s62, 0, 0x18000
	v_add_u32_e32 v96, s62, v162
	s_barrier
	ds_read_b128 v[144:147], v96
	ds_read_b128 v[148:151], v96 offset:1024
	ds_read_b128 v[152:155], v96 offset:2048
	ds_read_b128 v[156:159], v96 offset:3072
	s_add_u32 s48, s48, 0x40000
	s_addc_u32 s49, s49, 0
	s_mov_b32 m0, s54
	v_lshl_add_u64 v[202:203], s[48:49], 0, v[136:137]
	ds_read_b128 v[170:173], v168 offset:32768
	ds_read_b128 v[174:177], v168 offset:33792
	ds_read_b128 v[178:181], v168 offset:34816
	ds_read_b128 v[182:185], v168 offset:35840
	ds_read_b128 v[186:189], v168 offset:36864
	ds_read_b128 v[190:193], v168 offset:37888
	ds_read_b128 v[194:197], v168 offset:38912
	ds_read_b128 v[198:201], v168 offset:39936
	global_load_lds_dwordx4 v[202:203], off
	v_lshl_add_u64 v[202:203], s[48:49], 0, v[132:133]
	s_mov_b32 m0, s96
	s_nop 0
	global_load_lds_dwordx4 v[202:203], off
	s_waitcnt lgkmcnt(8)
	s_barrier
	s_waitcnt lgkmcnt(0)
	v_mfma_f32_16x16x32_bf16 v[126:129], v[144:147], v[170:173], v[126:129]
	v_mfma_f32_16x16x32_bf16 v[118:121], v[152:155], v[170:173], v[118:121]
	v_mfma_f32_16x16x32_bf16 v[110:113], v[144:147], v[178:181], v[110:113]
	v_mfma_f32_16x16x32_bf16 v[102:105], v[152:155], v[178:181], v[102:105]
	v_mfma_f32_16x16x32_bf16 v[92:95], v[144:147], v[186:189], v[92:95]
	v_mfma_f32_16x16x32_bf16 v[84:87], v[152:155], v[186:189], v[84:87]
	v_mfma_f32_16x16x32_bf16 v[76:79], v[144:147], v[194:197], v[76:79]
	v_mfma_f32_16x16x32_bf16 v[68:71], v[152:155], v[194:197], v[68:71]
	v_mfma_f32_16x16x32_bf16 v[126:129], v[148:151], v[174:177], v[126:129]
	v_mfma_f32_16x16x32_bf16 v[118:121], v[156:159], v[174:177], v[118:121]
	v_mfma_f32_16x16x32_bf16 v[110:113], v[148:151], v[182:185], v[110:113]
	v_mfma_f32_16x16x32_bf16 v[102:105], v[156:159], v[182:185], v[102:105]
	v_mfma_f32_16x16x32_bf16 v[92:95], v[148:151], v[190:193], v[92:95]
	v_mfma_f32_16x16x32_bf16 v[84:87], v[156:159], v[190:193], v[84:87]
	v_mfma_f32_16x16x32_bf16 v[76:79], v[148:151], v[198:201], v[76:79]
	v_mfma_f32_16x16x32_bf16 v[68:71], v[156:159], v[198:201], v[68:71]
	s_barrier
	s_add_i32 s48, 0, 0x1c000
	s_add_i32 s49, s62, s51
	v_add_u32_e32 v96, s48, v162
	v_lshl_add_u64 v[160:161], v[160:161], 0, s[2:3]
	s_mov_b32 m0, s49
	ds_read_b128 v[202:205], v96
	ds_read_b128 v[208:211], v96 offset:1024
	ds_read_b128 v[212:215], v96 offset:2048
	ds_read_b128 v[216:219], v96 offset:3072
	global_load_lds_dwordx4 v[160:161], off
	v_lshl_add_u64 v[160:161], v[220:221], 0, s[2:3]
	s_add_i32 m0, s49, 0x2000
	s_nop 0
	global_load_lds_dwordx4 v[160:161], off
	s_barrier
	s_waitcnt lgkmcnt(0)
	v_mfma_f32_16x16x32_bf16 v[122:125], v[202:205], v[170:173], v[122:125]
	v_mfma_f32_16x16x32_bf16 v[114:117], v[212:215], v[170:173], v[114:117]
	v_mfma_f32_16x16x32_bf16 v[106:109], v[202:205], v[178:181], v[106:109]
	v_mfma_f32_16x16x32_bf16 v[98:101], v[212:215], v[178:181], v[98:101]
	v_mfma_f32_16x16x32_bf16 v[88:91], v[202:205], v[186:189], v[88:91]
	v_mfma_f32_16x16x32_bf16 v[80:83], v[212:215], v[186:189], v[80:83]
	v_mfma_f32_16x16x32_bf16 v[72:75], v[202:205], v[194:197], v[72:75]
	v_mfma_f32_16x16x32_bf16 v[64:67], v[212:215], v[194:197], v[64:67]
	v_mfma_f32_16x16x32_bf16 v[122:125], v[208:211], v[174:177], v[122:125]
	v_mfma_f32_16x16x32_bf16 v[114:117], v[216:219], v[174:177], v[114:117]
	v_mfma_f32_16x16x32_bf16 v[106:109], v[208:211], v[182:185], v[106:109]
	v_mfma_f32_16x16x32_bf16 v[98:101], v[216:219], v[182:185], v[98:101]
	v_mfma_f32_16x16x32_bf16 v[88:91], v[208:211], v[190:193], v[88:91]
	v_mfma_f32_16x16x32_bf16 v[80:83], v[216:219], v[190:193], v[80:83]
	v_mfma_f32_16x16x32_bf16 v[72:75], v[208:211], v[198:201], v[72:75]
	v_mfma_f32_16x16x32_bf16 v[64:67], v[216:219], v[198:201], v[64:67]
	s_mov_b32 m0, s97
	v_lshl_add_u64 v[160:161], v[222:223], 0, s[2:3]
	s_barrier
; #define PG8_STAGE(bufoff, gbase, voff) do { _Pragma("unroll") for (int _i = 0; _i < 2; ++_i) \
;         __builtin_amdgcn_global_load_lds((const unsigned*)((const char*)(gbase) + (voff)[_i]), (PG8_LAS unsigned*)(lds + (bufoff) + ldsw + _i * 8192), 16, 0, 0); } while (0)
; #define PG8_MMA(ai, bj, At, Bt) do { __builtin_amdgcn_s_setprio(1); _Pragma("unroll") for (int m = 0; m < 4; ++m) _Pragma("unroll") for (int n = 0; n < 2; ++n) _Pragma("unroll") for (int k = 0; k < 2; ++k) \
;         acc[ai][bj][m][n] = __builtin_amdgcn_mfma_f32_16x16x32_bf16(Bt[n][k], At[m][k], acc[ai][bj][m][n], 0, 0, 0); __builtin_amdgcn_s_setprio(0); } while (0)
; #define PG8_WAIT_V(n) asm volatile("s_waitcnt vmcnt(" #n ")" ::: "memory")
; #define PG8_WAIT_L(n) asm volatile("s_waitcnt lgkmcnt(" #n ")" ::: "memory")
; #define PG8_BAR __builtin_amdgcn_s_barrier()
; #define PG8_SCHED __builtin_amdgcn_sched_barrier(0)
; template <class Epi, class Sched>
; __device__ __forceinline__ void gemm_phase(PG8_LAS unsigned char* lds, const Gemm g, const Sched& S, const Epi& E) {
;     ...
;             PG8_BAR; PG8_WAIT_L(0); PG8_MMA(1, 0, At, B0); PG8_BAR; PG8_SCHED;
;             PG8_STAGE(PG8_SB(1, 1), b3 + hstep, voffB);
;             PG8_WAIT_V(6); PG8_BAR; PG8_MMA(1, 1, At, B1); PG8_BAR;
;   DEV void operator()(const f32x4 (&acc)[2][2][4][2], const pg8::Unit& u, int wr, int wc, int fr, int fq) const {
;     ...
;     } else {
; #pragma unroll
;       for (int ai = 0; ai < 2; ++ai)
; #pragma unroll
;         for (int m = 0; m < 4; ++m) {
;           const int row = row0 + ai * 128 + m * 16;
; #pragma unroll
;           for (int bj = 0; bj < 2; ++bj) {
;             const int c = (pn - 10) * 256 + bj * 128 + cl;
;             if (c < 1920) {
;               u32x4 o;
;               o[0] = pk2(acc[ai][bj][m][0][0], acc[ai][bj][m][0][1]); o[1] = pk2(acc[ai][bj][m][0][2], acc[ai][bj][m][0][3]);
;               o[2] = pk2(acc[ai][bj][m][1][0], acc[ai][bj][m][1][1]); o[3] = pk2(acc[ai][bj][m][1][2], acc[ai][bj][m][1][3]);
;               *(u32x4*)(ZRW + (size_t)row * 1920 + c) = o;
	ds_read_b128 v[170:173], v168 offset:49152
	ds_read_b128 v[174:177], v168 offset:50176
	ds_read_b128 v[178:181], v168 offset:51200
	ds_read_b128 v[182:185], v168 offset:52224
	ds_read_b128 v[186:189], v168 offset:53248
	ds_read_b128 v[190:193], v168 offset:54272
	ds_read_b128 v[194:197], v168 offset:55296
	ds_read_b128 v[198:201], v168 offset:56320
	global_load_lds_dwordx4 v[160:161], off
	v_lshl_add_u64 v[160:161], v[224:225], 0, s[2:3]
	s_mov_b32 m0, s50
	s_nop 0
	global_load_lds_dwordx4 v[160:161], off
	s_barrier
	s_waitcnt lgkmcnt(0)
	v_mfma_f32_16x16x32_bf16 v[60:63], v[144:147], v[170:173], v[60:63]
	v_mfma_f32_16x16x32_bf16 v[52:55], v[152:155], v[170:173], v[52:55]
	v_mfma_f32_16x16x32_bf16 v[44:47], v[144:147], v[178:181], v[44:47]
	v_mfma_f32_16x16x32_bf16 v[36:39], v[152:155], v[178:181], v[36:39]
	v_mfma_f32_16x16x32_bf16 v[28:31], v[144:147], v[186:189], v[28:31]
	v_mfma_f32_16x16x32_bf16 v[20:23], v[152:155], v[186:189], v[20:23]
	v_mfma_f32_16x16x32_bf16 v[12:15], v[144:147], v[194:197], v[12:15]
	v_mfma_f32_16x16x32_bf16 v[4:7], v[152:155], v[194:197], v[4:7]
	v_mfma_f32_16x16x32_bf16 v[60:63], v[148:151], v[174:177], v[60:63]
	v_mfma_f32_16x16x32_bf16 v[52:55], v[156:159], v[174:177], v[52:55]
	v_mfma_f32_16x16x32_bf16 v[44:47], v[148:151], v[182:185], v[44:47]
	v_mfma_f32_16x16x32_bf16 v[36:39], v[156:159], v[182:185], v[36:39]
	v_mfma_f32_16x16x32_bf16 v[28:31], v[148:151], v[190:193], v[28:31]
	v_mfma_f32_16x16x32_bf16 v[20:23], v[156:159], v[190:193], v[20:23]
	v_mfma_f32_16x16x32_bf16 v[12:15], v[148:151], v[198:201], v[12:15]
	v_mfma_f32_16x16x32_bf16 v[4:7], v[156:159], v[198:201], v[4:7]
	s_barrier
	s_add_u32 s30, s30, 0x40080
	s_addc_u32 s31, s31, 0
	s_add_i32 s48, s48, s51
	v_lshl_add_u64 v[144:145], s[30:31], 0, v[134:135]
	s_mov_b32 m0, s48
	s_nop 0
	global_load_lds_dwordx4 v[144:145], off
	v_lshl_add_u64 v[144:145], s[30:31], 0, v[130:131]
	s_add_i32 m0, s48, 0x2000
	s_nop 0
	global_load_lds_dwordx4 v[144:145], off
	s_waitcnt vmcnt(6)
	s_barrier
	v_mfma_f32_16x16x32_bf16 v[56:59], v[202:205], v[170:173], v[56:59]
	v_mfma_f32_16x16x32_bf16 v[48:51], v[212:215], v[170:173], v[48:51]
	v_mfma_f32_16x16x32_bf16 v[40:43], v[202:205], v[178:181], v[40:43]
	v_mfma_f32_16x16x32_bf16 v[32:35], v[212:215], v[178:181], v[32:35]
	v_mfma_f32_16x16x32_bf16 v[24:27], v[202:205], v[186:189], v[24:27]
	v_mfma_f32_16x16x32_bf16 v[16:19], v[212:215], v[186:189], v[16:19]
	v_mfma_f32_16x16x32_bf16 v[8:11], v[202:205], v[194:197], v[8:11]
	v_mfma_f32_16x16x32_bf16 v[0:3], v[212:215], v[194:197], v[0:3]
	v_mfma_f32_16x16x32_bf16 v[56:59], v[208:211], v[174:177], v[56:59]
	v_mfma_f32_16x16x32_bf16 v[48:51], v[216:219], v[174:177], v[48:51]
	v_mfma_f32_16x16x32_bf16 v[40:43], v[208:211], v[182:185], v[40:43]
	v_mfma_f32_16x16x32_bf16 v[32:35], v[216:219], v[182:185], v[32:35]
	v_mfma_f32_16x16x32_bf16 v[24:27], v[208:211], v[190:193], v[24:27]
	v_mfma_f32_16x16x32_bf16 v[16:19], v[216:219], v[190:193], v[16:19]
	v_mfma_f32_16x16x32_bf16 v[8:11], v[208:211], v[198:201], v[8:11]
	v_mfma_f32_16x16x32_bf16 v[0:3], v[216:219], v[198:201], v[0:3]
	s_add_i32 s61, s61, 2
	s_add_u32 s0, s0, 0x100
	s_addc_u32 s1, s1, 0
	s_add_u32 s59, s59, 0x100
	s_addc_u32 s60, s60, 0
	s_cmp_gt_u32 s61, 13
	s_barrier
	s_cbranch_scc0 .LBB0_654
	s_lshl_b32 s41, s56, 8
	s_add_i32 s41, s41, s79
	v_readlane_b32 s60, v255, 32
	v_readlane_b32 s64, v255, 38
	v_or_b32_e32 v144, s41, v139
	s_cmp_gt_i32 s37, 3
	s_mov_b64 s[0:1], -1
	v_readlane_b32 s61, v255, 33
	v_readlane_b32 s65, v255, 39
	s_movk_i32 s56, 0x2000
	s_cbranch_scc0 .LBB0_729
	s_cmp_gt_u32 s37, 7
	s_cbranch_scc0 .LBB0_694
	s_lshl_b32 s43, s37, 8
	s_cmp_lt_u32 s37, 10
	s_cbranch_scc1 .LBB0_691
	s_movk_i32 s0, 0xf00
	v_mad_i64_i32 v[146:147], s[0:1], v144, s0, 0
	v_add_u32_e32 v96, s43, v163
	s_movk_i32 s0, 0x780
	v_cmp_gt_i32_e32 vcc, s0, v96
	v_readlane_b32 s0, v251, 49
	v_readlane_b32 s1, v251, 50
	s_nop 1
	v_lshl_add_u64 v[146:147], s[0:1], 0, v[146:147]
	s_and_saveexec_b64 s[0:1], vcc
	s_cbranch_execz .LBB0_660
	v_cvt_pk_bf16_f32 v148, v126, v127
	v_cvt_pk_bf16_f32 v149, v128, v129
	v_cvt_pk_bf16_f32 v150, v118, v119
	v_cvt_pk_bf16_f32 v151, v120, v121
	v_lshl_add_u64 v[152:153], v[96:97], 1, v[146:147]
	global_store_dwordx4 v[152:153], v[148:151], off
